# v46
# baseline (speedup 1.0000x reference)
; #define PG8_STAGE(bufoff, gbase, voff) do { _Pragma("unroll") for (int _i = 0; _i < 2; ++_i) \
;         __builtin_amdgcn_global_load_lds((const unsigned*)((const char*)(gbase) + (voff)[_i]), (PG8_LAS unsigned*)(lds + (bufoff) + ldsw + _i * 8192), 16, 0, 0); } while (0)
; #define PG8_LDA(dst, b, h) do { _Pragma("unroll") for (int m = 0; m < 4; ++m) _Pragma("unroll") for (int k = 0; k < 2; ++k) dst[m][k] = *(const PG8_LAS bf16x8*)(lds + PG8_SA(b, h) + aoff + m * 2048 + k * 1024); } while (0)
; #define PG8_LDB(dst, b, h) do { _Pragma("unroll") for (int n = 0; n < 2; ++n) _Pragma("unroll") for (int k = 0; k < 2; ++k) dst[n][k] = *(const PG8_LAS bf16x8*)(lds + PG8_SB(b, h) + boff + n * 2048 + k * 1024); } while (0)
; #define PG8_WAIT_V(n) asm volatile("s_waitcnt vmcnt(" #n ")" ::: "memory")
; #define PG8_WAIT_L(n) asm volatile("s_waitcnt lgkmcnt(" #n ")" ::: "memory")
; #define PG8_BAR __builtin_amdgcn_s_barrier()
; #define PG8_SCHED __builtin_amdgcn_sched_barrier(0)
; template <class Epi, class Sched, bool ALIGN_EPI = false, bool SP2 = false>
; __device__ __forceinline__ void gemm_phase(PG8_LAS unsigned char* lds, const Gemm g, const Sched& S, const Epi& E) {
;     ...
;         const bool has_next = S.next(ui + 1, nxt);
;         const char* nA = has_next ? (const char*)g.A + (size_t)nxt.pm * tstep : cA; const char* nB = has_next ? (const char*)g.Bt + (size_t)nxt.pn * tstep : cB;
;         for (int t = 0; t < nt; t += 2) {
;             const bool last = (t == nt - 2);
;             const char* a1 = cA + (size_t)(t + 1) * kstep;
;             const char* a2 = last ? nA : cA + (size_t)(t + 2) * kstep; const char* b2 = last ? nB : cB + (size_t)(t + 2) * kstep;
;             const char* a3 = a2 + kstep; const char* b3 = b2 + kstep;
;             if (last && has_next) S.a_ready(nxt);
;             if constexpr (SP2) {
;             PG8_LDB(B0, 0, 0); PG8_LDB(B1, 0, 1); PG8_SCHED; PG8_LDA(At, 0, 0); PG8_STAGE(PG8_SA(1, 1), a1 + hstep, voffA);
;             PG8_WAIT_V(8); PG8_WAIT_L(0); PG8_BAR; PG8_MMA(0, 0, At, B0); PG8_MMA(0, 1, At, B1); PG8_BAR; PG8_SCHED;
;             PG8_LDA(At, 0, 1); PG8_STAGE(PG8_SB(0, 0), b2, voffB); PG8_STAGE(PG8_SB(0, 1), b2 + hstep, voffB); PG8_STAGE(PG8_SA(0, 0), a2, voffA);
;             PG8_WAIT_V(8); PG8_WAIT_L(0); PG8_BAR; PG8_MMA(1, 0, At, B0); PG8_MMA(1, 1, At, B1); PG8_BAR; PG8_SCHED;
.LBB0_168:
	s_ashr_i32 s29, s28, 31
	v_cmp_lt_i64_e32 vcc, s[30:31], v[140:141]
	s_lshl_b64 s[30:31], s[28:29], 20
	s_add_u32 s30, s6, s30
	s_addc_u32 s31, s7, s31
	s_and_b64 s[34:35], vcc, exec
	s_cselect_b32 s29, s31, s39
	s_cselect_b32 s57, s30, s38
	s_ashr_i32 s27, s26, 31
	s_lshl_b64 s[34:35], s[26:27], 20
	s_add_u32 s34, s22, s34
	s_addc_u32 s35, s23, s35
	s_and_b64 s[42:43], vcc, exec
	s_cselect_b32 s27, s35, s41
	s_cselect_b32 s58, s34, s40
	s_add_u32 s38, s38, 0x80080
	s_addc_u32 s39, s39, 0
	s_add_u32 s59, s40, 0x100
	s_addc_u32 s60, s41, 0
	s_mov_b32 s61, -2
	v_add_u32_e32 v144, 0x18000, v147
	v_add_u32_e32 v145, 0x1c000, v147
	ds_read_b128 v[152:155], v149
	ds_read_b128 v[156:159], v149 offset:1024
	ds_read_b128 v[160:163], v149 offset:2048
	ds_read_b128 v[164:167], v149 offset:3072
	ds_read_b128 v[168:171], v150
	ds_read_b128 v[172:175], v150 offset:1024
	ds_read_b128 v[176:179], v150 offset:2048
	ds_read_b128 v[180:183], v150 offset:3072
	s_add_u32 s40, s38, 0xfff80080
	s_addc_u32 s41, s39, -1
	s_cmp_eq_u32 s61, 28
	s_cselect_b32 s43, s29, s41
	s_cselect_b32 s42, s57, s40
	s_cselect_b32 s41, s27, s60
	s_cselect_b32 s40, s58, s59
	s_add_i32 m0, s37, 0xc000
	ds_read_b128 v[184:187], v151
	ds_read_b128 v[188:191], v151 offset:1024
	ds_read_b128 v[192:195], v151 offset:2048
	ds_read_b128 v[196:199], v151 offset:3072
	ds_read_b128 v[200:203], v151 offset:4096
	ds_read_b128 v[204:207], v151 offset:5120
	ds_read_b128 v[208:211], v151 offset:6144
	ds_read_b128 v[214:217], v151 offset:7168
	global_load_lds_dwordx4 v136, s[38:39]
	s_add_i32 m0, s37, 0xe000
	s_nop 0
	global_load_lds_dwordx4 v138, s[38:39]
	s_waitcnt vmcnt(8) lgkmcnt(0)
	s_barrier
	v_mfma_f32_16x16x32_bf16 v[124:127], v[152:155], v[184:187], 0
	v_mfma_f32_16x16x32_bf16 v[120:123], v[160:163], v[184:187], 0
	v_mfma_f32_16x16x32_bf16 v[108:111], v[152:155], v[192:195], 0
	v_mfma_f32_16x16x32_bf16 v[104:107], v[160:163], v[192:195], 0
	v_mfma_f32_16x16x32_bf16 v[92:95], v[152:155], v[200:203], 0
	v_mfma_f32_16x16x32_bf16 v[88:91], v[160:163], v[200:203], 0
	v_mfma_f32_16x16x32_bf16 v[76:79], v[152:155], v[208:211], 0
	v_mfma_f32_16x16x32_bf16 v[72:75], v[160:163], v[208:211], 0
	v_mfma_f32_16x16x32_bf16 v[124:127], v[156:159], v[188:191], v[124:127]
	v_mfma_f32_16x16x32_bf16 v[120:123], v[164:167], v[188:191], v[120:123]
	v_mfma_f32_16x16x32_bf16 v[108:111], v[156:159], v[196:199], v[108:111]
	v_mfma_f32_16x16x32_bf16 v[104:107], v[164:167], v[196:199], v[104:107]
	v_mfma_f32_16x16x32_bf16 v[92:95], v[156:159], v[204:207], v[92:95]
	v_mfma_f32_16x16x32_bf16 v[88:91], v[164:167], v[204:207], v[88:91]
	v_mfma_f32_16x16x32_bf16 v[76:79], v[156:159], v[214:217], v[76:79]
	v_mfma_f32_16x16x32_bf16 v[72:75], v[164:167], v[214:217], v[72:75]
	v_mfma_f32_16x16x32_bf16 v[116:119], v[168:171], v[184:187], 0
	v_mfma_f32_16x16x32_bf16 v[112:115], v[176:179], v[184:187], 0
	v_mfma_f32_16x16x32_bf16 v[100:103], v[168:171], v[192:195], 0
	v_mfma_f32_16x16x32_bf16 v[96:99], v[176:179], v[192:195], 0
	v_mfma_f32_16x16x32_bf16 v[84:87], v[168:171], v[200:203], 0
	v_mfma_f32_16x16x32_bf16 v[80:83], v[176:179], v[200:203], 0
	v_mfma_f32_16x16x32_bf16 v[68:71], v[168:171], v[208:211], 0
	v_mfma_f32_16x16x32_bf16 v[64:67], v[176:179], v[208:211], 0
	v_mfma_f32_16x16x32_bf16 v[116:119], v[172:175], v[188:191], v[116:119]
	v_mfma_f32_16x16x32_bf16 v[112:115], v[180:183], v[188:191], v[112:115]
	v_mfma_f32_16x16x32_bf16 v[100:103], v[172:175], v[196:199], v[100:103]
	v_mfma_f32_16x16x32_bf16 v[96:99], v[180:183], v[196:199], v[96:99]
	v_mfma_f32_16x16x32_bf16 v[84:87], v[172:175], v[204:207], v[84:87]
	v_mfma_f32_16x16x32_bf16 v[80:83], v[180:183], v[204:207], v[80:83]
	v_mfma_f32_16x16x32_bf16 v[68:71], v[172:175], v[214:217], v[68:71]
	v_mfma_f32_16x16x32_bf16 v[64:67], v[180:183], v[214:217], v[64:67]
	s_barrier
	s_add_i32 s62, s53, s24
	s_mov_b32 m0, s62
	ds_read_b128 v[184:187], v151 offset:16384
	ds_read_b128 v[188:191], v151 offset:17408
	ds_read_b128 v[192:195], v151 offset:18432
	ds_read_b128 v[196:199], v151 offset:19456
	ds_read_b128 v[200:203], v151 offset:20480
	ds_read_b128 v[204:207], v151 offset:21504
	ds_read_b128 v[208:211], v151 offset:22528
	ds_read_b128 v[214:217], v151 offset:23552
	global_load_lds_dwordx4 v132, s[40:41]
	s_add_i32 m0, s62, 0x2000
	s_add_u32 s62, s40, 0x80000
	s_addc_u32 s63, s41, 0
	s_add_i32 s64, s54, s24
	global_load_lds_dwordx4 v128, s[40:41]
	s_mov_b32 m0, s64
	s_nop 0
	global_load_lds_dwordx4 v132, s[62:63]
	s_add_i32 m0, s64, 0x2000
	s_nop 0
	global_load_lds_dwordx4 v128, s[62:63]
	s_mov_b32 m0, s37
	s_nop 0
	global_load_lds_dwordx4 v134, s[42:43]
	s_mov_b32 m0, s45
	s_nop 0
	global_load_lds_dwordx4 v130, s[42:43]
	s_waitcnt vmcnt(8) lgkmcnt(0)
	s_barrier
; #define PG8_STAGE(bufoff, gbase, voff) do { _Pragma("unroll") for (int _i = 0; _i < 2; ++_i) \
;         __builtin_amdgcn_global_load_lds((const unsigned*)((const char*)(gbase) + (voff)[_i]), (PG8_LAS unsigned*)(lds + (bufoff) + ldsw + _i * 8192), 16, 0, 0); } while (0)
; #define PG8_LDA(dst, b, h) do { _Pragma("unroll") for (int m = 0; m < 4; ++m) _Pragma("unroll") for (int k = 0; k < 2; ++k) dst[m][k] = *(const PG8_LAS bf16x8*)(lds + PG8_SA(b, h) + aoff + m * 2048 + k * 1024); } while (0)
; #define PG8_LDB(dst, b, h) do { _Pragma("unroll") for (int n = 0; n < 2; ++n) _Pragma("unroll") for (int k = 0; k < 2; ++k) dst[n][k] = *(const PG8_LAS bf16x8*)(lds + PG8_SB(b, h) + boff + n * 2048 + k * 1024); } while (0)
; #define PG8_MMA(ai, bj, At, Bt) do { __builtin_amdgcn_s_setprio(1); _Pragma("unroll") for (int m = 0; m < 4; ++m) _Pragma("unroll") for (int n = 0; n < 2; ++n) _Pragma("unroll") for (int k = 0; k < 2; ++k) \
;         acc[ai][bj][m][n] = __builtin_amdgcn_mfma_f32_16x16x32_bf16(Bt[n][k], At[m][k], acc[ai][bj][m][n], 0, 0, 0); __builtin_amdgcn_s_setprio(0); } while (0)
; #define PG8_WAIT_V(n) asm volatile("s_waitcnt vmcnt(" #n ")" ::: "memory")
; #define PG8_WAIT_L(n) asm volatile("s_waitcnt lgkmcnt(" #n ")" ::: "memory")
; #define PG8_BAR __builtin_amdgcn_s_barrier()
; #define PG8_SCHED __builtin_amdgcn_sched_barrier(0)
; template <class Epi, class Sched, bool ALIGN_EPI = false, bool SP2 = false>
; __device__ __forceinline__ void gemm_phase(PG8_LAS unsigned char* lds, const Gemm g, const Sched& S, const Epi& E) {
;     ...
;             PG8_WAIT_V(8); PG8_WAIT_L(0); PG8_BAR; PG8_MMA(0, 0, At, B0); PG8_MMA(0, 1, At, B1); PG8_BAR; PG8_SCHED;
;             PG8_LDA(At, 0, 1); PG8_STAGE(PG8_SB(0, 0), b2, voffB); PG8_STAGE(PG8_SB(0, 1), b2 + hstep, voffB); PG8_STAGE(PG8_SA(0, 0), a2, voffA);
;             PG8_WAIT_V(8); PG8_WAIT_L(0); PG8_BAR; PG8_MMA(1, 0, At, B0); PG8_MMA(1, 1, At, B1); PG8_BAR; PG8_SCHED;
;             PG8_LDB(B0, 1, 0); PG8_LDB(B1, 1, 1); PG8_SCHED; PG8_LDA(At, 1, 0); PG8_STAGE(PG8_SA(0, 1), a2 + hstep, voffA);
;             PG8_WAIT_V(8); PG8_WAIT_L(0); PG8_BAR; PG8_MMA(0, 0, At, B0); PG8_MMA(0, 1, At, B1); PG8_BAR; PG8_SCHED;
	v_mfma_f32_16x16x32_bf16 v[60:63], v[152:155], v[184:187], 0
	v_mfma_f32_16x16x32_bf16 v[56:59], v[160:163], v[184:187], 0
	v_mfma_f32_16x16x32_bf16 v[44:47], v[152:155], v[192:195], 0
	v_mfma_f32_16x16x32_bf16 v[40:43], v[160:163], v[192:195], 0
	v_mfma_f32_16x16x32_bf16 v[28:31], v[152:155], v[200:203], 0
	v_mfma_f32_16x16x32_bf16 v[24:27], v[160:163], v[200:203], 0
	v_mfma_f32_16x16x32_bf16 v[12:15], v[152:155], v[208:211], 0
	v_mfma_f32_16x16x32_bf16 v[8:11], v[160:163], v[208:211], 0
	v_mfma_f32_16x16x32_bf16 v[60:63], v[156:159], v[188:191], v[60:63]
	v_mfma_f32_16x16x32_bf16 v[56:59], v[164:167], v[188:191], v[56:59]
	v_mfma_f32_16x16x32_bf16 v[44:47], v[156:159], v[196:199], v[44:47]
	v_mfma_f32_16x16x32_bf16 v[40:43], v[164:167], v[196:199], v[40:43]
	v_mfma_f32_16x16x32_bf16 v[28:31], v[156:159], v[204:207], v[28:31]
	v_mfma_f32_16x16x32_bf16 v[24:27], v[164:167], v[204:207], v[24:27]
	v_mfma_f32_16x16x32_bf16 v[12:15], v[156:159], v[214:217], v[12:15]
	v_mfma_f32_16x16x32_bf16 v[8:11], v[164:167], v[214:217], v[8:11]
	v_mfma_f32_16x16x32_bf16 v[52:55], v[168:171], v[184:187], 0
	v_mfma_f32_16x16x32_bf16 v[48:51], v[176:179], v[184:187], 0
	v_mfma_f32_16x16x32_bf16 v[36:39], v[168:171], v[192:195], 0
	v_mfma_f32_16x16x32_bf16 v[32:35], v[176:179], v[192:195], 0
	v_mfma_f32_16x16x32_bf16 v[20:23], v[168:171], v[200:203], 0
	v_mfma_f32_16x16x32_bf16 v[16:19], v[176:179], v[200:203], 0
	v_mfma_f32_16x16x32_bf16 v[4:7], v[168:171], v[208:211], 0
	v_mfma_f32_16x16x32_bf16 v[0:3], v[176:179], v[208:211], 0
	v_mfma_f32_16x16x32_bf16 v[52:55], v[172:175], v[188:191], v[52:55]
	v_mfma_f32_16x16x32_bf16 v[48:51], v[180:183], v[188:191], v[48:51]
	v_mfma_f32_16x16x32_bf16 v[36:39], v[172:175], v[196:199], v[36:39]
	v_mfma_f32_16x16x32_bf16 v[32:35], v[180:183], v[196:199], v[32:35]
	v_mfma_f32_16x16x32_bf16 v[20:23], v[172:175], v[204:207], v[20:23]
	v_mfma_f32_16x16x32_bf16 v[16:19], v[180:183], v[204:207], v[16:19]
	v_mfma_f32_16x16x32_bf16 v[4:7], v[172:175], v[214:217], v[4:7]
	v_mfma_f32_16x16x32_bf16 v[0:3], v[180:183], v[214:217], v[0:3]
	s_barrier
	s_add_i32 s62, 0, 0x18000
	s_add_i32 s63, 0, 0x1c000
	ds_read_b128 v[152:155], v144
	ds_read_b128 v[156:159], v144 offset:1024
	ds_read_b128 v[160:163], v144 offset:2048
	ds_read_b128 v[164:167], v144 offset:3072
	ds_read_b128 v[168:171], v145
	ds_read_b128 v[172:175], v145 offset:1024
	ds_read_b128 v[176:179], v145 offset:2048
	ds_read_b128 v[180:183], v145 offset:3072
	s_add_u32 s84, s42, 0x80
	s_addc_u32 s85, s43, 0
	s_add_u32 s42, s42, 0x80000
	s_addc_u32 s43, s43, 0
	s_mov_b32 m0, s46
	ds_read_b128 v[184:187], v151 offset:32768
	ds_read_b128 v[188:191], v151 offset:33792
	ds_read_b128 v[192:195], v151 offset:34816
	ds_read_b128 v[196:199], v151 offset:35840
	ds_read_b128 v[200:203], v151 offset:36864
	ds_read_b128 v[204:207], v151 offset:37888
	ds_read_b128 v[208:211], v151 offset:38912
	ds_read_b128 v[214:217], v151 offset:39936
	global_load_lds_dwordx4 v134, s[42:43]
	s_mov_b32 m0, s47
	s_nop 0
	global_load_lds_dwordx4 v130, s[42:43]
	s_waitcnt vmcnt(8) lgkmcnt(0)
	s_barrier
	v_mfma_f32_16x16x32_bf16 v[124:127], v[152:155], v[184:187], v[124:127]
	v_mfma_f32_16x16x32_bf16 v[120:123], v[160:163], v[184:187], v[120:123]
	v_mfma_f32_16x16x32_bf16 v[108:111], v[152:155], v[192:195], v[108:111]
	v_mfma_f32_16x16x32_bf16 v[104:107], v[160:163], v[192:195], v[104:107]
	v_mfma_f32_16x16x32_bf16 v[92:95], v[152:155], v[200:203], v[92:95]
	v_mfma_f32_16x16x32_bf16 v[88:91], v[160:163], v[200:203], v[88:91]
	v_mfma_f32_16x16x32_bf16 v[76:79], v[152:155], v[208:211], v[76:79]
	v_mfma_f32_16x16x32_bf16 v[72:75], v[160:163], v[208:211], v[72:75]
	v_mfma_f32_16x16x32_bf16 v[124:127], v[156:159], v[188:191], v[124:127]
	v_mfma_f32_16x16x32_bf16 v[120:123], v[164:167], v[188:191], v[120:123]
	v_mfma_f32_16x16x32_bf16 v[108:111], v[156:159], v[196:199], v[108:111]
	v_mfma_f32_16x16x32_bf16 v[104:107], v[164:167], v[196:199], v[104:107]
	v_mfma_f32_16x16x32_bf16 v[92:95], v[156:159], v[204:207], v[92:95]
	v_mfma_f32_16x16x32_bf16 v[88:91], v[164:167], v[204:207], v[88:91]
	v_mfma_f32_16x16x32_bf16 v[76:79], v[156:159], v[214:217], v[76:79]
	v_mfma_f32_16x16x32_bf16 v[72:75], v[164:167], v[214:217], v[72:75]
	v_mfma_f32_16x16x32_bf16 v[116:119], v[168:171], v[184:187], v[116:119]
	v_mfma_f32_16x16x32_bf16 v[112:115], v[176:179], v[184:187], v[112:115]
	v_mfma_f32_16x16x32_bf16 v[100:103], v[168:171], v[192:195], v[100:103]
	v_mfma_f32_16x16x32_bf16 v[96:99], v[176:179], v[192:195], v[96:99]
	v_mfma_f32_16x16x32_bf16 v[84:87], v[168:171], v[200:203], v[84:87]
	v_mfma_f32_16x16x32_bf16 v[80:83], v[176:179], v[200:203], v[80:83]
	v_mfma_f32_16x16x32_bf16 v[68:71], v[168:171], v[208:211], v[68:71]
	v_mfma_f32_16x16x32_bf16 v[64:67], v[176:179], v[208:211], v[64:67]
	v_mfma_f32_16x16x32_bf16 v[116:119], v[172:175], v[188:191], v[116:119]
	v_mfma_f32_16x16x32_bf16 v[112:115], v[180:183], v[188:191], v[112:115]
	v_mfma_f32_16x16x32_bf16 v[100:103], v[172:175], v[196:199], v[100:103]
	v_mfma_f32_16x16x32_bf16 v[96:99], v[180:183], v[196:199], v[96:99]
	v_mfma_f32_16x16x32_bf16 v[84:87], v[172:175], v[204:207], v[84:87]
	v_mfma_f32_16x16x32_bf16 v[80:83], v[180:183], v[204:207], v[80:83]
	v_mfma_f32_16x16x32_bf16 v[68:71], v[172:175], v[214:217], v[68:71]
	v_mfma_f32_16x16x32_bf16 v[64:67], v[180:183], v[214:217], v[64:67]
	s_barrier
; #define PG8_STAGE(bufoff, gbase, voff) do { _Pragma("unroll") for (int _i = 0; _i < 2; ++_i) \
;         __builtin_amdgcn_global_load_lds((const unsigned*)((const char*)(gbase) + (voff)[_i]), (PG8_LAS unsigned*)(lds + (bufoff) + ldsw + _i * 8192), 16, 0, 0); } while (0)
; #define PG8_LDA(dst, b, h) do { _Pragma("unroll") for (int m = 0; m < 4; ++m) _Pragma("unroll") for (int k = 0; k < 2; ++k) dst[m][k] = *(const PG8_LAS bf16x8*)(lds + PG8_SA(b, h) + aoff + m * 2048 + k * 1024); } while (0)
; #define PG8_LDB(dst, b, h) do { _Pragma("unroll") for (int n = 0; n < 2; ++n) _Pragma("unroll") for (int k = 0; k < 2; ++k) dst[n][k] = *(const PG8_LAS bf16x8*)(lds + PG8_SB(b, h) + boff + n * 2048 + k * 1024); } while (0)
; template <class Epi, class Sched, bool ALIGN_EPI = false, bool SP2 = false>
; __device__ __forceinline__ void gemm_phase(PG8_LAS unsigned char* lds, const Gemm g, const Sched& S, const Epi& E) {
;     ...
;         for (int t = 0; t < nt; t += 2) {
;             const bool last = (t == nt - 2);
;             const char* a1 = cA + (size_t)(t + 1) * kstep;
;             const char* a2 = last ? nA : cA + (size_t)(t + 2) * kstep; const char* b2 = last ? nB : cB + (size_t)(t + 2) * kstep;
;             const char* a3 = a2 + kstep; const char* b3 = b2 + kstep;
;             if (last && has_next) S.a_ready(nxt);
;             if constexpr (SP2) {
;             PG8_LDB(B0, 0, 0); PG8_LDB(B1, 0, 1); PG8_SCHED; PG8_LDA(At, 0, 0); PG8_STAGE(PG8_SA(1, 1), a1 + hstep, voffA);
;             PG8_WAIT_V(8); PG8_WAIT_L(0); PG8_BAR; PG8_MMA(0, 0, At, B0); PG8_MMA(0, 1, At, B1); PG8_BAR; PG8_SCHED;
;             PG8_LDA(At, 0, 1); PG8_STAGE(PG8_SB(0, 0), b2, voffB); PG8_STAGE(PG8_SB(0, 1), b2 + hstep, voffB); PG8_STAGE(PG8_SA(0, 0), a2, voffA);
;             PG8_WAIT_V(8); PG8_WAIT_L(0); PG8_BAR; PG8_MMA(1, 0, At, B0); PG8_MMA(1, 1, At, B1); PG8_BAR; PG8_SCHED;
;             PG8_LDB(B0, 1, 0); PG8_LDB(B1, 1, 1); PG8_SCHED; PG8_LDA(At, 1, 0); PG8_STAGE(PG8_SA(0, 1), a2 + hstep, voffA);
;             PG8_WAIT_V(8); PG8_WAIT_L(0); PG8_BAR; PG8_MMA(0, 0, At, B0); PG8_MMA(0, 1, At, B1); PG8_BAR; PG8_SCHED;
;             PG8_LDA(At, 1, 1); PG8_STAGE(PG8_SB(1, 0), b3, voffB); PG8_STAGE(PG8_SB(1, 1), b3 + hstep, voffB); PG8_STAGE(PG8_SA(1, 0), a3, voffA);
;             PG8_WAIT_V(8); PG8_WAIT_L(0); PG8_BAR; PG8_MMA(1, 0, At, B0); PG8_MMA(1, 1, At, B1); PG8_BAR; PG8_SCHED;
	s_add_i32 s42, s62, s24
	s_add_u32 s86, s40, 0x80
	s_addc_u32 s87, s41, 0
	s_mov_b32 m0, s42
	ds_read_b128 v[184:187], v151 offset:49152
	ds_read_b128 v[188:191], v151 offset:50176
	ds_read_b128 v[192:195], v151 offset:51200
	ds_read_b128 v[196:199], v151 offset:52224
	ds_read_b128 v[200:203], v151 offset:53248
	ds_read_b128 v[204:207], v151 offset:54272
	ds_read_b128 v[208:211], v151 offset:55296
	ds_read_b128 v[214:217], v151 offset:56320
	global_load_lds_dwordx4 v132, s[86:87]
	s_add_i32 m0, s42, 0x2000
	s_add_u32 s40, s40, 0x80080
	s_addc_u32 s41, s41, 0
	s_add_i32 s42, s63, s24
	global_load_lds_dwordx4 v128, s[86:87]
	s_mov_b32 m0, s42
	s_nop 0
	global_load_lds_dwordx4 v132, s[40:41]
	s_add_i32 m0, s42, 0x2000
	s_nop 0
	global_load_lds_dwordx4 v128, s[40:41]
	s_mov_b32 m0, s49
	s_nop 0
	global_load_lds_dwordx4 v134, s[84:85]
	s_mov_b32 m0, s50
	s_nop 0
	global_load_lds_dwordx4 v130, s[84:85]
	s_waitcnt vmcnt(8) lgkmcnt(0)
	s_barrier
	v_mfma_f32_16x16x32_bf16 v[60:63], v[152:155], v[184:187], v[60:63]
	v_mfma_f32_16x16x32_bf16 v[56:59], v[160:163], v[184:187], v[56:59]
	v_mfma_f32_16x16x32_bf16 v[44:47], v[152:155], v[192:195], v[44:47]
	v_mfma_f32_16x16x32_bf16 v[40:43], v[160:163], v[192:195], v[40:43]
	v_mfma_f32_16x16x32_bf16 v[28:31], v[152:155], v[200:203], v[28:31]
	v_mfma_f32_16x16x32_bf16 v[24:27], v[160:163], v[200:203], v[24:27]
	v_mfma_f32_16x16x32_bf16 v[12:15], v[152:155], v[208:211], v[12:15]
	v_mfma_f32_16x16x32_bf16 v[8:11], v[160:163], v[208:211], v[8:11]
	v_mfma_f32_16x16x32_bf16 v[60:63], v[156:159], v[188:191], v[60:63]
	v_mfma_f32_16x16x32_bf16 v[56:59], v[164:167], v[188:191], v[56:59]
	v_mfma_f32_16x16x32_bf16 v[44:47], v[156:159], v[196:199], v[44:47]
	v_mfma_f32_16x16x32_bf16 v[40:43], v[164:167], v[196:199], v[40:43]
	v_mfma_f32_16x16x32_bf16 v[28:31], v[156:159], v[204:207], v[28:31]
	v_mfma_f32_16x16x32_bf16 v[24:27], v[164:167], v[204:207], v[24:27]
	v_mfma_f32_16x16x32_bf16 v[12:15], v[156:159], v[214:217], v[12:15]
	v_mfma_f32_16x16x32_bf16 v[8:11], v[164:167], v[214:217], v[8:11]
	v_mfma_f32_16x16x32_bf16 v[52:55], v[168:171], v[184:187], v[52:55]
	v_mfma_f32_16x16x32_bf16 v[48:51], v[176:179], v[184:187], v[48:51]
	v_mfma_f32_16x16x32_bf16 v[36:39], v[168:171], v[192:195], v[36:39]
	v_mfma_f32_16x16x32_bf16 v[32:35], v[176:179], v[192:195], v[32:35]
	v_mfma_f32_16x16x32_bf16 v[20:23], v[168:171], v[200:203], v[20:23]
	v_mfma_f32_16x16x32_bf16 v[16:19], v[176:179], v[200:203], v[16:19]
	v_mfma_f32_16x16x32_bf16 v[4:7], v[168:171], v[208:211], v[4:7]
	v_mfma_f32_16x16x32_bf16 v[0:3], v[176:179], v[208:211], v[0:3]
	v_mfma_f32_16x16x32_bf16 v[52:55], v[172:175], v[188:191], v[52:55]
	v_mfma_f32_16x16x32_bf16 v[48:51], v[180:183], v[188:191], v[48:51]
	v_mfma_f32_16x16x32_bf16 v[36:39], v[172:175], v[196:199], v[36:39]
	v_mfma_f32_16x16x32_bf16 v[32:35], v[180:183], v[196:199], v[32:35]
	v_mfma_f32_16x16x32_bf16 v[20:23], v[172:175], v[204:207], v[20:23]
	v_mfma_f32_16x16x32_bf16 v[16:19], v[180:183], v[204:207], v[16:19]
	v_mfma_f32_16x16x32_bf16 v[4:7], v[172:175], v[214:217], v[4:7]
	v_mfma_f32_16x16x32_bf16 v[0:3], v[180:183], v[214:217], v[0:3]
	s_barrier
	s_add_i32 s61, s61, 2
	s_add_u32 s38, s38, 0x100
	s_addc_u32 s39, s39, 0
	s_add_u32 s59, s59, 0x100
	s_addc_u32 s60, s60, 0
	s_cmp_gt_u32 s61, 29
.LBB0_169:
	ds_read_b128 v[152:155], v149
	ds_read_b128 v[156:159], v149 offset:1024
	ds_read_b128 v[160:163], v149 offset:2048
	ds_read_b128 v[164:167], v149 offset:3072
	ds_read_b128 v[168:171], v150
	ds_read_b128 v[172:175], v150 offset:1024
	ds_read_b128 v[176:179], v150 offset:2048
	ds_read_b128 v[180:183], v150 offset:3072
	s_add_u32 s40, s38, 0xfff80080
	s_addc_u32 s41, s39, -1
	s_cmp_eq_u32 s61, 28
	s_cselect_b32 s43, s29, s41
	s_cselect_b32 s42, s57, s40
	s_cselect_b32 s41, s27, s60
	s_cselect_b32 s40, s58, s59
	s_add_i32 m0, s37, 0xc000
	ds_read_b128 v[184:187], v151
	ds_read_b128 v[188:191], v151 offset:1024
	ds_read_b128 v[192:195], v151 offset:2048
	ds_read_b128 v[196:199], v151 offset:3072
	ds_read_b128 v[200:203], v151 offset:4096
	ds_read_b128 v[204:207], v151 offset:5120
	ds_read_b128 v[208:211], v151 offset:6144
	ds_read_b128 v[214:217], v151 offset:7168
	global_load_lds_dwordx4 v136, s[38:39]
	s_add_i32 m0, s37, 0xe000
	s_nop 0
	global_load_lds_dwordx4 v138, s[38:39]
	s_waitcnt vmcnt(8) lgkmcnt(0)
	s_barrier
	v_mfma_f32_16x16x32_bf16 v[124:127], v[152:155], v[184:187], v[124:127]
	v_mfma_f32_16x16x32_bf16 v[120:123], v[160:163], v[184:187], v[120:123]
	v_mfma_f32_16x16x32_bf16 v[108:111], v[152:155], v[192:195], v[108:111]
	v_mfma_f32_16x16x32_bf16 v[104:107], v[160:163], v[192:195], v[104:107]
	v_mfma_f32_16x16x32_bf16 v[92:95], v[152:155], v[200:203], v[92:95]
	v_mfma_f32_16x16x32_bf16 v[88:91], v[160:163], v[200:203], v[88:91]
	v_mfma_f32_16x16x32_bf16 v[76:79], v[152:155], v[208:211], v[76:79]
	v_mfma_f32_16x16x32_bf16 v[72:75], v[160:163], v[208:211], v[72:75]
	v_mfma_f32_16x16x32_bf16 v[124:127], v[156:159], v[188:191], v[124:127]
	v_mfma_f32_16x16x32_bf16 v[120:123], v[164:167], v[188:191], v[120:123]
	v_mfma_f32_16x16x32_bf16 v[108:111], v[156:159], v[196:199], v[108:111]
	v_mfma_f32_16x16x32_bf16 v[104:107], v[164:167], v[196:199], v[104:107]
	v_mfma_f32_16x16x32_bf16 v[92:95], v[156:159], v[204:207], v[92:95]
	v_mfma_f32_16x16x32_bf16 v[88:91], v[164:167], v[204:207], v[88:91]
	v_mfma_f32_16x16x32_bf16 v[76:79], v[156:159], v[214:217], v[76:79]
	v_mfma_f32_16x16x32_bf16 v[72:75], v[164:167], v[214:217], v[72:75]
	v_mfma_f32_16x16x32_bf16 v[116:119], v[168:171], v[184:187], v[116:119]
	v_mfma_f32_16x16x32_bf16 v[112:115], v[176:179], v[184:187], v[112:115]
	v_mfma_f32_16x16x32_bf16 v[100:103], v[168:171], v[192:195], v[100:103]
	v_mfma_f32_16x16x32_bf16 v[96:99], v[176:179], v[192:195], v[96:99]
	v_mfma_f32_16x16x32_bf16 v[84:87], v[168:171], v[200:203], v[84:87]
	v_mfma_f32_16x16x32_bf16 v[80:83], v[176:179], v[200:203], v[80:83]
	v_mfma_f32_16x16x32_bf16 v[68:71], v[168:171], v[208:211], v[68:71]
	v_mfma_f32_16x16x32_bf16 v[64:67], v[176:179], v[208:211], v[64:67]
	v_mfma_f32_16x16x32_bf16 v[116:119], v[172:175], v[188:191], v[116:119]
	v_mfma_f32_16x16x32_bf16 v[112:115], v[180:183], v[188:191], v[112:115]
	v_mfma_f32_16x16x32_bf16 v[100:103], v[172:175], v[196:199], v[100:103]
	v_mfma_f32_16x16x32_bf16 v[96:99], v[180:183], v[196:199], v[96:99]
	v_mfma_f32_16x16x32_bf16 v[84:87], v[172:175], v[204:207], v[84:87]
	v_mfma_f32_16x16x32_bf16 v[80:83], v[180:183], v[204:207], v[80:83]
	v_mfma_f32_16x16x32_bf16 v[68:71], v[172:175], v[214:217], v[68:71]
	v_mfma_f32_16x16x32_bf16 v[64:67], v[180:183], v[214:217], v[64:67]
	s_barrier
; #define PG8_STAGE(bufoff, gbase, voff) do { _Pragma("unroll") for (int _i = 0; _i < 2; ++_i) \
;         __builtin_amdgcn_global_load_lds((const unsigned*)((const char*)(gbase) + (voff)[_i]), (PG8_LAS unsigned*)(lds + (bufoff) + ldsw + _i * 8192), 16, 0, 0); } while (0)
; #define PG8_LDA(dst, b, h) do { _Pragma("unroll") for (int m = 0; m < 4; ++m) _Pragma("unroll") for (int k = 0; k < 2; ++k) dst[m][k] = *(const PG8_LAS bf16x8*)(lds + PG8_SA(b, h) + aoff + m * 2048 + k * 1024); } while (0)
; #define PG8_LDB(dst, b, h) do { _Pragma("unroll") for (int n = 0; n < 2; ++n) _Pragma("unroll") for (int k = 0; k < 2; ++k) dst[n][k] = *(const PG8_LAS bf16x8*)(lds + PG8_SB(b, h) + boff + n * 2048 + k * 1024); } while (0)
; #define PG8_MMA(ai, bj, At, Bt) do { __builtin_amdgcn_s_setprio(1); _Pragma("unroll") for (int m = 0; m < 4; ++m) _Pragma("unroll") for (int n = 0; n < 2; ++n) _Pragma("unroll") for (int k = 0; k < 2; ++k) \
;         acc[ai][bj][m][n] = __builtin_amdgcn_mfma_f32_16x16x32_bf16(Bt[n][k], At[m][k], acc[ai][bj][m][n], 0, 0, 0); __builtin_amdgcn_s_setprio(0); } while (0)
; #define PG8_WAIT_V(n) asm volatile("s_waitcnt vmcnt(" #n ")" ::: "memory")
; #define PG8_WAIT_L(n) asm volatile("s_waitcnt lgkmcnt(" #n ")" ::: "memory")
; #define PG8_BAR __builtin_amdgcn_s_barrier()
; #define PG8_SCHED __builtin_amdgcn_sched_barrier(0)
; template <class Epi, class Sched, bool ALIGN_EPI = false, bool SP2 = false>
; __device__ __forceinline__ void gemm_phase(PG8_LAS unsigned char* lds, const Gemm g, const Sched& S, const Epi& E) {
;     ...
;             PG8_LDA(At, 0, 1); PG8_STAGE(PG8_SB(0, 0), b2, voffB); PG8_STAGE(PG8_SB(0, 1), b2 + hstep, voffB); PG8_STAGE(PG8_SA(0, 0), a2, voffA);
;             PG8_WAIT_V(8); PG8_WAIT_L(0); PG8_BAR; PG8_MMA(1, 0, At, B0); PG8_MMA(1, 1, At, B1); PG8_BAR; PG8_SCHED;
;             PG8_LDB(B0, 1, 0); PG8_LDB(B1, 1, 1); PG8_SCHED; PG8_LDA(At, 1, 0); PG8_STAGE(PG8_SA(0, 1), a2 + hstep, voffA);
;             PG8_WAIT_V(8); PG8_WAIT_L(0); PG8_BAR; PG8_MMA(0, 0, At, B0); PG8_MMA(0, 1, At, B1); PG8_BAR; PG8_SCHED;
	s_add_i32 s62, s53, s24
	s_mov_b32 m0, s62
	ds_read_b128 v[184:187], v151 offset:16384
	ds_read_b128 v[188:191], v151 offset:17408
	ds_read_b128 v[192:195], v151 offset:18432
	ds_read_b128 v[196:199], v151 offset:19456
	ds_read_b128 v[200:203], v151 offset:20480
	ds_read_b128 v[204:207], v151 offset:21504
	ds_read_b128 v[208:211], v151 offset:22528
	ds_read_b128 v[214:217], v151 offset:23552
	global_load_lds_dwordx4 v132, s[40:41]
	s_add_i32 m0, s62, 0x2000
	s_add_u32 s62, s40, 0x80000
	s_addc_u32 s63, s41, 0
	s_add_i32 s64, s54, s24
	global_load_lds_dwordx4 v128, s[40:41]
	s_mov_b32 m0, s64
	s_nop 0
	global_load_lds_dwordx4 v132, s[62:63]
	s_add_i32 m0, s64, 0x2000
	s_nop 0
	global_load_lds_dwordx4 v128, s[62:63]
	s_mov_b32 m0, s37
	s_nop 0
	global_load_lds_dwordx4 v134, s[42:43]
	s_mov_b32 m0, s45
	s_nop 0
	global_load_lds_dwordx4 v130, s[42:43]
	s_waitcnt vmcnt(8) lgkmcnt(0)
	s_barrier
	v_mfma_f32_16x16x32_bf16 v[60:63], v[152:155], v[184:187], v[60:63]
	v_mfma_f32_16x16x32_bf16 v[56:59], v[160:163], v[184:187], v[56:59]
	v_mfma_f32_16x16x32_bf16 v[44:47], v[152:155], v[192:195], v[44:47]
	v_mfma_f32_16x16x32_bf16 v[40:43], v[160:163], v[192:195], v[40:43]
	v_mfma_f32_16x16x32_bf16 v[28:31], v[152:155], v[200:203], v[28:31]
	v_mfma_f32_16x16x32_bf16 v[24:27], v[160:163], v[200:203], v[24:27]
	v_mfma_f32_16x16x32_bf16 v[12:15], v[152:155], v[208:211], v[12:15]
	v_mfma_f32_16x16x32_bf16 v[8:11], v[160:163], v[208:211], v[8:11]
	v_mfma_f32_16x16x32_bf16 v[60:63], v[156:159], v[188:191], v[60:63]
	v_mfma_f32_16x16x32_bf16 v[56:59], v[164:167], v[188:191], v[56:59]
	v_mfma_f32_16x16x32_bf16 v[44:47], v[156:159], v[196:199], v[44:47]
	v_mfma_f32_16x16x32_bf16 v[40:43], v[164:167], v[196:199], v[40:43]
	v_mfma_f32_16x16x32_bf16 v[28:31], v[156:159], v[204:207], v[28:31]
	v_mfma_f32_16x16x32_bf16 v[24:27], v[164:167], v[204:207], v[24:27]
	v_mfma_f32_16x16x32_bf16 v[12:15], v[156:159], v[214:217], v[12:15]
	v_mfma_f32_16x16x32_bf16 v[8:11], v[164:167], v[214:217], v[8:11]
	v_mfma_f32_16x16x32_bf16 v[52:55], v[168:171], v[184:187], v[52:55]
	v_mfma_f32_16x16x32_bf16 v[48:51], v[176:179], v[184:187], v[48:51]
	v_mfma_f32_16x16x32_bf16 v[36:39], v[168:171], v[192:195], v[36:39]
	v_mfma_f32_16x16x32_bf16 v[32:35], v[176:179], v[192:195], v[32:35]
	v_mfma_f32_16x16x32_bf16 v[20:23], v[168:171], v[200:203], v[20:23]
	v_mfma_f32_16x16x32_bf16 v[16:19], v[176:179], v[200:203], v[16:19]
	v_mfma_f32_16x16x32_bf16 v[4:7], v[168:171], v[208:211], v[4:7]
	v_mfma_f32_16x16x32_bf16 v[0:3], v[176:179], v[208:211], v[0:3]
	v_mfma_f32_16x16x32_bf16 v[52:55], v[172:175], v[188:191], v[52:55]
	v_mfma_f32_16x16x32_bf16 v[48:51], v[180:183], v[188:191], v[48:51]
	v_mfma_f32_16x16x32_bf16 v[36:39], v[172:175], v[196:199], v[36:39]
	v_mfma_f32_16x16x32_bf16 v[32:35], v[180:183], v[196:199], v[32:35]
	v_mfma_f32_16x16x32_bf16 v[20:23], v[172:175], v[204:207], v[20:23]
	v_mfma_f32_16x16x32_bf16 v[16:19], v[180:183], v[204:207], v[16:19]
	v_mfma_f32_16x16x32_bf16 v[4:7], v[172:175], v[214:217], v[4:7]
	v_mfma_f32_16x16x32_bf16 v[0:3], v[180:183], v[214:217], v[0:3]
	s_barrier
	s_add_i32 s62, 0, 0x18000
	s_add_i32 s63, 0, 0x1c000
	ds_read_b128 v[152:155], v144
	ds_read_b128 v[156:159], v144 offset:1024
	ds_read_b128 v[160:163], v144 offset:2048
	ds_read_b128 v[164:167], v144 offset:3072
	ds_read_b128 v[168:171], v145
	ds_read_b128 v[172:175], v145 offset:1024
	ds_read_b128 v[176:179], v145 offset:2048
	ds_read_b128 v[180:183], v145 offset:3072
	s_add_u32 s84, s42, 0x80
	s_addc_u32 s85, s43, 0
	s_add_u32 s42, s42, 0x80000
	s_addc_u32 s43, s43, 0
	s_mov_b32 m0, s46
	ds_read_b128 v[184:187], v151 offset:32768
	ds_read_b128 v[188:191], v151 offset:33792
	ds_read_b128 v[192:195], v151 offset:34816
	ds_read_b128 v[196:199], v151 offset:35840
	ds_read_b128 v[200:203], v151 offset:36864
	ds_read_b128 v[204:207], v151 offset:37888
	ds_read_b128 v[208:211], v151 offset:38912
	ds_read_b128 v[214:217], v151 offset:39936
	global_load_lds_dwordx4 v134, s[42:43]
	s_mov_b32 m0, s47
	s_nop 0
	global_load_lds_dwordx4 v130, s[42:43]
	s_waitcnt vmcnt(8) lgkmcnt(0)
	s_barrier
	v_mfma_f32_16x16x32_bf16 v[124:127], v[152:155], v[184:187], v[124:127]
	v_mfma_f32_16x16x32_bf16 v[120:123], v[160:163], v[184:187], v[120:123]
	v_mfma_f32_16x16x32_bf16 v[108:111], v[152:155], v[192:195], v[108:111]
	v_mfma_f32_16x16x32_bf16 v[104:107], v[160:163], v[192:195], v[104:107]
	v_mfma_f32_16x16x32_bf16 v[92:95], v[152:155], v[200:203], v[92:95]
	v_mfma_f32_16x16x32_bf16 v[88:91], v[160:163], v[200:203], v[88:91]
	v_mfma_f32_16x16x32_bf16 v[76:79], v[152:155], v[208:211], v[76:79]
	v_mfma_f32_16x16x32_bf16 v[72:75], v[160:163], v[208:211], v[72:75]
	v_mfma_f32_16x16x32_bf16 v[124:127], v[156:159], v[188:191], v[124:127]
	v_mfma_f32_16x16x32_bf16 v[120:123], v[164:167], v[188:191], v[120:123]
	v_mfma_f32_16x16x32_bf16 v[108:111], v[156:159], v[196:199], v[108:111]
	v_mfma_f32_16x16x32_bf16 v[104:107], v[164:167], v[196:199], v[104:107]
	v_mfma_f32_16x16x32_bf16 v[92:95], v[156:159], v[204:207], v[92:95]
	v_mfma_f32_16x16x32_bf16 v[88:91], v[164:167], v[204:207], v[88:91]
	v_mfma_f32_16x16x32_bf16 v[76:79], v[156:159], v[214:217], v[76:79]
	v_mfma_f32_16x16x32_bf16 v[72:75], v[164:167], v[214:217], v[72:75]
	v_mfma_f32_16x16x32_bf16 v[116:119], v[168:171], v[184:187], v[116:119]
	v_mfma_f32_16x16x32_bf16 v[112:115], v[176:179], v[184:187], v[112:115]
	v_mfma_f32_16x16x32_bf16 v[100:103], v[168:171], v[192:195], v[100:103]
	v_mfma_f32_16x16x32_bf16 v[96:99], v[176:179], v[192:195], v[96:99]
	v_mfma_f32_16x16x32_bf16 v[84:87], v[168:171], v[200:203], v[84:87]
	v_mfma_f32_16x16x32_bf16 v[80:83], v[176:179], v[200:203], v[80:83]
	v_mfma_f32_16x16x32_bf16 v[68:71], v[168:171], v[208:211], v[68:71]
	v_mfma_f32_16x16x32_bf16 v[64:67], v[176:179], v[208:211], v[64:67]
	v_mfma_f32_16x16x32_bf16 v[116:119], v[172:175], v[188:191], v[116:119]
	v_mfma_f32_16x16x32_bf16 v[112:115], v[180:183], v[188:191], v[112:115]
	v_mfma_f32_16x16x32_bf16 v[100:103], v[172:175], v[196:199], v[100:103]
	v_mfma_f32_16x16x32_bf16 v[96:99], v[180:183], v[196:199], v[96:99]
	v_mfma_f32_16x16x32_bf16 v[84:87], v[172:175], v[204:207], v[84:87]
	v_mfma_f32_16x16x32_bf16 v[80:83], v[180:183], v[204:207], v[80:83]
	v_mfma_f32_16x16x32_bf16 v[68:71], v[172:175], v[214:217], v[68:71]
	v_mfma_f32_16x16x32_bf16 v[64:67], v[180:183], v[214:217], v[64:67]
	s_barrier
; __device__ __forceinline__ float fsilu(float v) { return v * fsigmoid(v); }
; __device__ __forceinline__ u32x4 pack8(const f32x4 a, const f32x4 b) { u32x4 w; w.x = cvt_pk_bf16(a[0], a[1]); w.y = cvt_pk_bf16(a[2], a[3]); w.z = cvt_pk_bf16(b[0], b[1]); w.w = cvt_pk_bf16(b[2], b[3]); return w; }
; #define PG8_STAGE(bufoff, gbase, voff) do { _Pragma("unroll") for (int _i = 0; _i < 2; ++_i) \
;         __builtin_amdgcn_global_load_lds((const unsigned*)((const char*)(gbase) + (voff)[_i]), (PG8_LAS unsigned*)(lds + (bufoff) + ldsw + _i * 8192), 16, 0, 0); } while (0)
; #define PG8_LDA(dst, b, h) do { _Pragma("unroll") for (int m = 0; m < 4; ++m) _Pragma("unroll") for (int k = 0; k < 2; ++k) dst[m][k] = *(const PG8_LAS bf16x8*)(lds + PG8_SA(b, h) + aoff + m * 2048 + k * 1024); } while (0)
; #define PG8_MMA(ai, bj, At, Bt) do { __builtin_amdgcn_s_setprio(1); _Pragma("unroll") for (int m = 0; m < 4; ++m) _Pragma("unroll") for (int n = 0; n < 2; ++n) _Pragma("unroll") for (int k = 0; k < 2; ++k) \
;         acc[ai][bj][m][n] = __builtin_amdgcn_mfma_f32_16x16x32_bf16(Bt[n][k], At[m][k], acc[ai][bj][m][n], 0, 0, 0); __builtin_amdgcn_s_setprio(0); } while (0)
; #define PG8_BAR __builtin_amdgcn_s_barrier()
;     __device__ __forceinline__ void operator()(const f32x4 (&acc)[2][2][4][2], const Unit& u, int wr, int wc, int fr, int fq) const {
;         const int row0 = u.pm * BM + wr * 64 + fr, col0 = u.pn * 128 + wc * 32 + 8 * fq;
; #pragma unroll
;         for (int ai = 0; ai < 2; ++ai)
; #pragma unroll
;             for (int m = 0; m < 4; ++m) {
;                 bf16_t* rowp = O + (size_t)(row0 + ai * HALF + m * 16) * ldc + col0;
;                 f32x4 h0, h1;
; #pragma unroll
;                 for (int j = 0; j < 4; ++j) { h0[j] = fsilu(acc[ai][0][m][0][j]) * acc[ai][1][m][0][j]; h1[j] = fsilu(acc[ai][0][m][1][j]) * acc[ai][1][m][1][j]; }
;                 *(u32x4*)rowp = pack8(h0, h1);
; template <class Epi, class Sched, bool ALIGN_EPI = false, bool SP2 = false>
; __device__ __forceinline__ void gemm_phase(PG8_LAS unsigned char* lds, const Gemm g, const Sched& S, const Epi& E) {
;     ...
;             PG8_LDA(At, 1, 1); PG8_STAGE(PG8_SB(1, 0), b3, voffB); PG8_STAGE(PG8_SB(1, 1), b3 + hstep, voffB); PG8_STAGE(PG8_SA(1, 0), a3, voffA);
;             PG8_WAIT_V(8); PG8_WAIT_L(0); PG8_BAR; PG8_MMA(1, 0, At, B0); PG8_MMA(1, 1, At, B1); PG8_BAR; PG8_SCHED;
	s_add_i32 s42, s62, s24
	s_add_u32 s86, s40, 0x80
	s_addc_u32 s87, s41, 0
	s_mov_b32 m0, s42
	ds_read_b128 v[184:187], v151 offset:49152
	ds_read_b128 v[188:191], v151 offset:50176
	ds_read_b128 v[192:195], v151 offset:51200
	ds_read_b128 v[196:199], v151 offset:52224
	ds_read_b128 v[200:203], v151 offset:53248
	ds_read_b128 v[204:207], v151 offset:54272
	ds_read_b128 v[208:211], v151 offset:55296
	ds_read_b128 v[214:217], v151 offset:56320
	global_load_lds_dwordx4 v132, s[86:87]
	s_add_i32 m0, s42, 0x2000
	s_add_u32 s40, s40, 0x80080
	s_addc_u32 s41, s41, 0
	s_add_i32 s42, s63, s24
	global_load_lds_dwordx4 v128, s[86:87]
	s_mov_b32 m0, s42
	s_nop 0
	global_load_lds_dwordx4 v132, s[40:41]
	s_add_i32 m0, s42, 0x2000
	s_nop 0
	global_load_lds_dwordx4 v128, s[40:41]
	s_mov_b32 m0, s49
	s_nop 0
	global_load_lds_dwordx4 v134, s[84:85]
	s_mov_b32 m0, s50
	s_nop 0
	global_load_lds_dwordx4 v130, s[84:85]
	s_waitcnt vmcnt(8) lgkmcnt(0)
	s_barrier
	v_mfma_f32_16x16x32_bf16 v[60:63], v[152:155], v[184:187], v[60:63]
	v_mfma_f32_16x16x32_bf16 v[56:59], v[160:163], v[184:187], v[56:59]
	v_mfma_f32_16x16x32_bf16 v[44:47], v[152:155], v[192:195], v[44:47]
	v_mfma_f32_16x16x32_bf16 v[40:43], v[160:163], v[192:195], v[40:43]
	v_mfma_f32_16x16x32_bf16 v[28:31], v[152:155], v[200:203], v[28:31]
	v_mfma_f32_16x16x32_bf16 v[24:27], v[160:163], v[200:203], v[24:27]
	v_mfma_f32_16x16x32_bf16 v[12:15], v[152:155], v[208:211], v[12:15]
	v_mfma_f32_16x16x32_bf16 v[8:11], v[160:163], v[208:211], v[8:11]
	v_mfma_f32_16x16x32_bf16 v[60:63], v[156:159], v[188:191], v[60:63]
	v_mfma_f32_16x16x32_bf16 v[56:59], v[164:167], v[188:191], v[56:59]
	v_mfma_f32_16x16x32_bf16 v[44:47], v[156:159], v[196:199], v[44:47]
	v_mfma_f32_16x16x32_bf16 v[40:43], v[164:167], v[196:199], v[40:43]
	v_mfma_f32_16x16x32_bf16 v[28:31], v[156:159], v[204:207], v[28:31]
	v_mfma_f32_16x16x32_bf16 v[24:27], v[164:167], v[204:207], v[24:27]
	v_mfma_f32_16x16x32_bf16 v[12:15], v[156:159], v[214:217], v[12:15]
	v_mfma_f32_16x16x32_bf16 v[8:11], v[164:167], v[214:217], v[8:11]
	v_mfma_f32_16x16x32_bf16 v[52:55], v[168:171], v[184:187], v[52:55]
	v_mfma_f32_16x16x32_bf16 v[48:51], v[176:179], v[184:187], v[48:51]
	v_mfma_f32_16x16x32_bf16 v[36:39], v[168:171], v[192:195], v[36:39]
	v_mfma_f32_16x16x32_bf16 v[32:35], v[176:179], v[192:195], v[32:35]
	v_mfma_f32_16x16x32_bf16 v[20:23], v[168:171], v[200:203], v[20:23]
	v_mfma_f32_16x16x32_bf16 v[16:19], v[176:179], v[200:203], v[16:19]
	v_mfma_f32_16x16x32_bf16 v[4:7], v[168:171], v[208:211], v[4:7]
	v_mfma_f32_16x16x32_bf16 v[0:3], v[176:179], v[208:211], v[0:3]
	v_mfma_f32_16x16x32_bf16 v[52:55], v[172:175], v[188:191], v[52:55]
	v_mfma_f32_16x16x32_bf16 v[48:51], v[180:183], v[188:191], v[48:51]
	v_mfma_f32_16x16x32_bf16 v[36:39], v[172:175], v[196:199], v[36:39]
	v_mfma_f32_16x16x32_bf16 v[32:35], v[180:183], v[196:199], v[32:35]
	v_mfma_f32_16x16x32_bf16 v[20:23], v[172:175], v[204:207], v[20:23]
	v_mfma_f32_16x16x32_bf16 v[16:19], v[180:183], v[204:207], v[16:19]
	v_mfma_f32_16x16x32_bf16 v[4:7], v[172:175], v[214:217], v[4:7]
	v_mfma_f32_16x16x32_bf16 v[0:3], v[180:183], v[214:217], v[0:3]
	s_barrier
	s_add_i32 s61, s61, 2
	s_add_u32 s38, s38, 0x100
	s_addc_u32 s39, s39, 0
	s_add_u32 s59, s59, 0x100
	s_addc_u32 s60, s60, 0
	s_cmp_gt_u32 s61, 29
	s_cbranch_scc0 .LBB0_169
	v_mul_f32_e32 v153, 0xbfb8aa3b, v124
	v_mul_f32_e32 v158, 0xbfb8aa3b, v120
	v_exp_f32_e32 v153, v153
	v_exp_f32_e32 v159, v158
	v_mul_f32_e32 v158, 0xbfb8aa3b, v125
	v_exp_f32_e32 v160, v158
	v_add_f32_e32 v153, 1.0, v153
	v_rcp_f32_e32 v158, v153
	v_add_f32_e32 v153, 1.0, v159
	v_add_f32_e32 v159, 1.0, v160
	v_rcp_f32_e32 v159, v159
	v_mul_f32_e32 v160, 0xbfb8aa3b, v121
	v_exp_f32_e32 v161, v160
	v_rcp_f32_e32 v160, v153
	v_pk_mul_f32 v[124:125], v[124:125], v[158:159]
	v_mul_f32_e32 v153, 0xbfb8aa3b, v127
	v_pk_mul_f32 v[116:117], v[124:125], v[116:117]
	v_add_f32_e32 v124, 1.0, v161
	v_mul_f32_e32 v125, 0xbfb8aa3b, v122
	v_rcp_f32_e32 v161, v124
	v_mul_f32_e32 v124, 0xbfb8aa3b, v126
	v_exp_f32_e32 v125, v125
	v_exp_f32_e32 v124, v124
	v_exp_f32_e32 v153, v153
	v_mul_f32_e32 v158, 0xbfb8aa3b, v123
	v_exp_f32_e32 v159, v158
	v_add_f32_e32 v125, 1.0, v125
	v_add_f32_e32 v124, 1.0, v124
	v_rcp_f32_e32 v158, v125
	v_add_f32_e32 v125, 1.0, v153
	v_rcp_f32_e32 v124, v124
	v_rcp_f32_e32 v125, v125
	v_add_f32_e32 v153, 1.0, v159
	v_rcp_f32_e32 v159, v153
	v_pk_mul_f32 v[120:121], v[120:121], v[160:161]
	v_lshl_or_b32 v154, s56, 7, v148
	v_pk_mul_f32 v[120:121], v[120:121], v[112:113]
	v_pk_mul_f32 v[112:113], v[126:127], v[124:125]
	v_lshl_add_u32 v152, s36, 8, v146
	v_ashrrev_i32_e32 v155, 31, v154
	v_mov_b64_e32 v[144:145], s[10:11]
	v_pk_mul_f32 v[118:119], v[112:113], v[118:119]
	v_pk_mul_f32 v[112:113], v[122:123], v[158:159]
	v_mad_i64_i32 v[156:157], s[38:39], v152, s55, v[144:145]
	v_pk_mul_f32 v[122:123], v[112:113], v[114:115]
	v_lshlrev_b64 v[112:113], 1, v[154:155]
	v_lshl_add_u64 v[124:125], v[156:157], 0, v[112:113]
	v_cvt_pk_bf16_f32 v114, v116, v117
	v_cvt_pk_bf16_f32 v115, v118, v119
	v_cvt_pk_bf16_f32 v116, v120, v121
	v_cvt_pk_bf16_f32 v117, v122, v123
	global_store_dwordx4 v[124:125], v[114:117], off
	v_mul_f32_e32 v118, 0xbfb8aa3b, v109
	v_exp_f32_e32 v118, v118
	v_mul_f32_e32 v116, 0xbfb8aa3b, v108
	v_mul_f32_e32 v117, 0xbfb8aa3b, v104
	v_exp_f32_e32 v116, v116
	v_exp_f32_e32 v117, v117
	v_or_b32_e32 v114, 16, v152
	v_mad_i64_i32 v[114:115], s[38:39], v114, s55, v[144:145]
	v_add_f32_e32 v116, 1.0, v116
	v_add_f32_e32 v119, 1.0, v117
	v_add_f32_e32 v117, 1.0, v118
	v_rcp_f32_e32 v116, v116
	v_rcp_f32_e32 v117, v117
	v_mul_f32_e32 v118, 0xbfb8aa3b, v105
; __device__ __forceinline__ float fsilu(float v) { return v * fsigmoid(v); }
; __device__ __forceinline__ u32x4 pack8(const f32x4 a, const f32x4 b) { u32x4 w; w.x = cvt_pk_bf16(a[0], a[1]); w.y = cvt_pk_bf16(a[2], a[3]); w.z = cvt_pk_bf16(b[0], b[1]); w.w = cvt_pk_bf16(b[2], b[3]); return w; }
;     __device__ __forceinline__ void operator()(const f32x4 (&acc)[2][2][4][2], const Unit& u, int wr, int wc, int fr, int fq) const {
;         const int row0 = u.pm * BM + wr * 64 + fr, col0 = u.pn * 128 + wc * 32 + 8 * fq;
; #pragma unroll
;         for (int ai = 0; ai < 2; ++ai)
; #pragma unroll
;             for (int m = 0; m < 4; ++m) {
;                 bf16_t* rowp = O + (size_t)(row0 + ai * HALF + m * 16) * ldc + col0;
;                 f32x4 h0, h1;
; #pragma unroll
;                 for (int j = 0; j < 4; ++j) { h0[j] = fsilu(acc[ai][0][m][0][j]) * acc[ai][1][m][0][j]; h1[j] = fsilu(acc[ai][0][m][1][j]) * acc[ai][1][m][1][j]; }
;                 *(u32x4*)rowp = pack8(h0, h1);
	v_exp_f32_e32 v120, v118
	v_rcp_f32_e32 v118, v119
	v_pk_mul_f32 v[108:109], v[108:109], v[116:117]
	v_mul_f32_e32 v116, 0xbfb8aa3b, v111
	v_pk_mul_f32 v[100:101], v[108:109], v[100:101]
	v_add_f32_e32 v108, 1.0, v120
	v_rcp_f32_e32 v119, v108
	v_mul_f32_e32 v109, 0xbfb8aa3b, v106
	v_mul_f32_e32 v108, 0xbfb8aa3b, v110
	v_exp_f32_e32 v109, v109
	v_exp_f32_e32 v108, v108
	v_exp_f32_e32 v117, v116
	v_mul_f32_e32 v116, 0xbfb8aa3b, v107
	v_pk_mul_f32 v[104:105], v[104:105], v[118:119]
	v_exp_f32_e32 v118, v116
	v_add_f32_e32 v109, 1.0, v109
	v_add_f32_e32 v108, 1.0, v108
	v_rcp_f32_e32 v116, v109
	v_add_f32_e32 v109, 1.0, v117
	v_rcp_f32_e32 v108, v108
	v_rcp_f32_e32 v109, v109
	v_add_f32_e32 v117, 1.0, v118
	v_rcp_f32_e32 v117, v117
	v_pk_mul_f32 v[104:105], v[104:105], v[96:97]
	v_pk_mul_f32 v[96:97], v[110:111], v[108:109]
	v_lshl_add_u64 v[108:109], v[114:115], 0, v[112:113]
	v_pk_mul_f32 v[102:103], v[96:97], v[102:103]
	v_pk_mul_f32 v[96:97], v[106:107], v[116:117]
	s_and_b64 vcc, exec, s[8:9]
	v_pk_mul_f32 v[106:107], v[96:97], v[98:99]
	v_cvt_pk_bf16_f32 v96, v100, v101
	v_cvt_pk_bf16_f32 v97, v102, v103
	v_cvt_pk_bf16_f32 v98, v104, v105
	v_cvt_pk_bf16_f32 v99, v106, v107
	global_store_dwordx4 v[108:109], v[96:99], off
	v_mul_f32_e32 v100, 0xbfb8aa3b, v93
	v_exp_f32_e32 v100, v100
	v_mul_f32_e32 v98, 0xbfb8aa3b, v92
	v_mul_f32_e32 v99, 0xbfb8aa3b, v88
	v_exp_f32_e32 v98, v98
	v_exp_f32_e32 v99, v99
	v_or_b32_e32 v96, 32, v152
	v_mad_i64_i32 v[96:97], s[38:39], v96, s55, v[144:145]
	v_add_f32_e32 v98, 1.0, v98
	v_add_f32_e32 v101, 1.0, v99
	v_add_f32_e32 v99, 1.0, v100
	v_rcp_f32_e32 v98, v98
	v_rcp_f32_e32 v99, v99
	v_mul_f32_e32 v100, 0xbfb8aa3b, v89
	v_exp_f32_e32 v102, v100
	v_rcp_f32_e32 v100, v101
	v_pk_mul_f32 v[92:93], v[92:93], v[98:99]
	v_mul_f32_e32 v98, 0xbfb8aa3b, v95
	v_pk_mul_f32 v[84:85], v[92:93], v[84:85]
	v_add_f32_e32 v92, 1.0, v102
	v_rcp_f32_e32 v101, v92
	v_mul_f32_e32 v93, 0xbfb8aa3b, v90
	v_mul_f32_e32 v92, 0xbfb8aa3b, v94
	v_exp_f32_e32 v93, v93
	v_exp_f32_e32 v92, v92
	v_exp_f32_e32 v99, v98
	v_mul_f32_e32 v98, 0xbfb8aa3b, v91
	v_pk_mul_f32 v[88:89], v[88:89], v[100:101]
	v_exp_f32_e32 v100, v98
	v_add_f32_e32 v93, 1.0, v93
	v_add_f32_e32 v92, 1.0, v92
	v_rcp_f32_e32 v98, v93
	v_add_f32_e32 v93, 1.0, v99
	v_rcp_f32_e32 v92, v92
	v_rcp_f32_e32 v93, v93
	v_add_f32_e32 v99, 1.0, v100
	v_rcp_f32_e32 v99, v99
	v_pk_mul_f32 v[88:89], v[88:89], v[80:81]
	v_pk_mul_f32 v[80:81], v[94:95], v[92:93]
	v_lshl_add_u64 v[92:93], v[96:97], 0, v[112:113]
	v_pk_mul_f32 v[86:87], v[80:81], v[86:87]
	v_pk_mul_f32 v[80:81], v[90:91], v[98:99]
	s_mov_b32 s56, s26
	v_pk_mul_f32 v[90:91], v[80:81], v[82:83]
	v_cvt_pk_bf16_f32 v80, v84, v85
	v_cvt_pk_bf16_f32 v81, v86, v87
	v_cvt_pk_bf16_f32 v82, v88, v89
	v_cvt_pk_bf16_f32 v83, v90, v91
	global_store_dwordx4 v[92:93], v[80:83], off
	v_mul_f32_e32 v84, 0xbfb8aa3b, v77
	v_exp_f32_e32 v84, v84
	v_mul_f32_e32 v82, 0xbfb8aa3b, v76
	v_mul_f32_e32 v83, 0xbfb8aa3b, v72
	v_exp_f32_e32 v82, v82
	v_exp_f32_e32 v83, v83
	v_or_b32_e32 v80, 48, v152
	v_mad_i64_i32 v[80:81], s[38:39], v80, s55, v[144:145]
	v_add_f32_e32 v82, 1.0, v82
	v_add_f32_e32 v85, 1.0, v83
	v_add_f32_e32 v83, 1.0, v84
	v_rcp_f32_e32 v82, v82
	v_rcp_f32_e32 v83, v83
	v_mul_f32_e32 v84, 0xbfb8aa3b, v73
	v_exp_f32_e32 v86, v84
	v_rcp_f32_e32 v84, v85
	v_pk_mul_f32 v[76:77], v[76:77], v[82:83]
	v_mul_f32_e32 v82, 0xbfb8aa3b, v79
	v_pk_mul_f32 v[68:69], v[76:77], v[68:69]
	v_add_f32_e32 v76, 1.0, v86
	v_rcp_f32_e32 v85, v76
	v_mul_f32_e32 v77, 0xbfb8aa3b, v74
	v_mul_f32_e32 v76, 0xbfb8aa3b, v78
	v_exp_f32_e32 v77, v77
	v_exp_f32_e32 v76, v76
	v_exp_f32_e32 v83, v82
	v_mul_f32_e32 v82, 0xbfb8aa3b, v75
	v_pk_mul_f32 v[72:73], v[72:73], v[84:85]
	v_exp_f32_e32 v84, v82
	v_add_f32_e32 v77, 1.0, v77
	v_add_f32_e32 v76, 1.0, v76
	v_rcp_f32_e32 v82, v77
	v_add_f32_e32 v77, 1.0, v83
	v_rcp_f32_e32 v76, v76
	v_rcp_f32_e32 v77, v77
	v_add_f32_e32 v83, 1.0, v84
	v_rcp_f32_e32 v83, v83
	v_pk_mul_f32 v[72:73], v[72:73], v[64:65]
	v_pk_mul_f32 v[64:65], v[78:79], v[76:77]
	v_lshl_add_u64 v[76:77], v[80:81], 0, v[112:113]
	v_pk_mul_f32 v[70:71], v[64:65], v[70:71]
	v_pk_mul_f32 v[64:65], v[74:75], v[82:83]
	s_mov_b32 s36, s28
	v_pk_mul_f32 v[74:75], v[64:65], v[66:67]
	v_cvt_pk_bf16_f32 v64, v68, v69
	v_cvt_pk_bf16_f32 v65, v70, v71
	v_cvt_pk_bf16_f32 v66, v72, v73
	v_cvt_pk_bf16_f32 v67, v74, v75
	global_store_dwordx4 v[76:77], v[64:67], off
	v_mul_f32_e32 v68, 0xbfb8aa3b, v61
	v_exp_f32_e32 v68, v68
	v_mul_f32_e32 v66, 0xbfb8aa3b, v60
	v_mul_f32_e32 v67, 0xbfb8aa3b, v56
	v_exp_f32_e32 v66, v66
	v_exp_f32_e32 v67, v67
	v_add_u32_e32 v64, 0x80, v152
	v_mad_i64_i32 v[64:65], s[38:39], v64, s55, v[144:145]
	v_add_f32_e32 v66, 1.0, v66
	v_add_f32_e32 v69, 1.0, v67
	v_add_f32_e32 v67, 1.0, v68
	v_rcp_f32_e32 v66, v66
	v_rcp_f32_e32 v67, v67
	v_mul_f32_e32 v68, 0xbfb8aa3b, v57
	v_exp_f32_e32 v70, v68
	v_rcp_f32_e32 v68, v69
	v_pk_mul_f32 v[60:61], v[60:61], v[66:67]
	v_mul_f32_e32 v66, 0xbfb8aa3b, v63
	v_pk_mul_f32 v[52:53], v[60:61], v[52:53]
	v_add_f32_e32 v60, 1.0, v70
	v_rcp_f32_e32 v69, v60
	v_mul_f32_e32 v61, 0xbfb8aa3b, v58
	v_mul_f32_e32 v60, 0xbfb8aa3b, v62
	v_exp_f32_e32 v61, v61
	v_exp_f32_e32 v60, v60
	v_exp_f32_e32 v67, v66
	v_mul_f32_e32 v66, 0xbfb8aa3b, v59
	v_pk_mul_f32 v[56:57], v[56:57], v[68:69]
	v_exp_f32_e32 v68, v66
	v_add_f32_e32 v61, 1.0, v61
	v_add_f32_e32 v60, 1.0, v60
	v_rcp_f32_e32 v66, v61
; __device__ __forceinline__ float fsilu(float v) { return v * fsigmoid(v); }
; __device__ __forceinline__ u32x4 pack8(const f32x4 a, const f32x4 b) { u32x4 w; w.x = cvt_pk_bf16(a[0], a[1]); w.y = cvt_pk_bf16(a[2], a[3]); w.z = cvt_pk_bf16(b[0], b[1]); w.w = cvt_pk_bf16(b[2], b[3]); return w; }
; #define PG8_WAIT_V(n) asm volatile("s_waitcnt vmcnt(" #n ")" ::: "memory")
; #define PG8_BAR __builtin_amdgcn_s_barrier()
;     __device__ __forceinline__ void operator()(const f32x4 (&acc)[2][2][4][2], const Unit& u, int wr, int wc, int fr, int fq) const {
;         const int row0 = u.pm * BM + wr * 64 + fr, col0 = u.pn * 128 + wc * 32 + 8 * fq;
; #pragma unroll
;         for (int ai = 0; ai < 2; ++ai)
; #pragma unroll
;             for (int m = 0; m < 4; ++m) {
;                 bf16_t* rowp = O + (size_t)(row0 + ai * HALF + m * 16) * ldc + col0;
;                 f32x4 h0, h1;
; #pragma unroll
;                 for (int j = 0; j < 4; ++j) { h0[j] = fsilu(acc[ai][0][m][0][j]) * acc[ai][1][m][0][j]; h1[j] = fsilu(acc[ai][0][m][1][j]) * acc[ai][1][m][1][j]; }
;                 *(u32x4*)rowp = pack8(h0, h1);
; template <class Epi, class Sched, bool ALIGN_EPI = false, bool SP2 = false>
; __device__ __forceinline__ void gemm_phase(PG8_LAS unsigned char* lds, const Gemm g, const Sched& S, const Epi& E) {
;     ...
;         if (!has_next) break;
; #pragma unroll
;         for (int a = 0; a < 2; ++a)
; #pragma unroll
;             for (int b = 0; b < 2; ++b)
; #pragma unroll
;                 for (int m = 0; m < 4; ++m)
; #pragma unroll
;                     for (int n = 0; n < 2; ++n) acc[a][b][m][n] = (f32x4){0.f, 0.f, 0.f, 0.f};
;         cur = nxt; cA = nA; cB = nB; ++ui;
;         if constexpr (ALIGN_EPI) { if (wr == 1) PG8_BAR; }
;     }
;     PG8_WAIT_V(0);
;     if constexpr (!ALIGN_EPI) { if (wr == 0) PG8_BAR; }
	v_add_f32_e32 v61, 1.0, v67
	v_rcp_f32_e32 v60, v60
	v_rcp_f32_e32 v61, v61
	v_add_f32_e32 v67, 1.0, v68
	v_rcp_f32_e32 v67, v67
	v_pk_mul_f32 v[56:57], v[56:57], v[48:49]
	v_pk_mul_f32 v[48:49], v[62:63], v[60:61]
	v_lshl_add_u64 v[60:61], v[64:65], 0, v[112:113]
	v_pk_mul_f32 v[54:55], v[48:49], v[54:55]
	v_pk_mul_f32 v[48:49], v[58:59], v[66:67]
	s_mov_b64 s[40:41], s[34:35]
	v_pk_mul_f32 v[58:59], v[48:49], v[50:51]
	v_cvt_pk_bf16_f32 v48, v52, v53
	v_cvt_pk_bf16_f32 v49, v54, v55
	v_cvt_pk_bf16_f32 v50, v56, v57
	v_cvt_pk_bf16_f32 v51, v58, v59
	global_store_dwordx4 v[60:61], v[48:51], off
	v_mul_f32_e32 v52, 0xbfb8aa3b, v45
	v_exp_f32_e32 v52, v52
	v_mul_f32_e32 v50, 0xbfb8aa3b, v44
	v_mul_f32_e32 v51, 0xbfb8aa3b, v40
	v_exp_f32_e32 v50, v50
	v_exp_f32_e32 v51, v51
	v_add_u32_e32 v48, 0x90, v152
	v_mad_i64_i32 v[48:49], s[38:39], v48, s55, v[144:145]
	v_add_f32_e32 v50, 1.0, v50
	v_add_f32_e32 v53, 1.0, v51
	v_add_f32_e32 v51, 1.0, v52
	v_rcp_f32_e32 v50, v50
	v_rcp_f32_e32 v51, v51
	v_mul_f32_e32 v52, 0xbfb8aa3b, v41
	v_exp_f32_e32 v54, v52
	v_rcp_f32_e32 v52, v53
	v_pk_mul_f32 v[44:45], v[44:45], v[50:51]
	v_mul_f32_e32 v50, 0xbfb8aa3b, v47
	v_pk_mul_f32 v[36:37], v[44:45], v[36:37]
	v_add_f32_e32 v44, 1.0, v54
	v_rcp_f32_e32 v53, v44
	v_mul_f32_e32 v45, 0xbfb8aa3b, v42
	v_mul_f32_e32 v44, 0xbfb8aa3b, v46
	v_exp_f32_e32 v45, v45
	v_exp_f32_e32 v44, v44
	v_exp_f32_e32 v51, v50
	v_mul_f32_e32 v50, 0xbfb8aa3b, v43
	v_pk_mul_f32 v[40:41], v[40:41], v[52:53]
	v_exp_f32_e32 v52, v50
	v_add_f32_e32 v45, 1.0, v45
	v_add_f32_e32 v44, 1.0, v44
	v_rcp_f32_e32 v50, v45
	v_add_f32_e32 v45, 1.0, v51
	v_rcp_f32_e32 v44, v44
	v_rcp_f32_e32 v45, v45
	v_add_f32_e32 v51, 1.0, v52
	v_rcp_f32_e32 v51, v51
	v_pk_mul_f32 v[40:41], v[40:41], v[32:33]
	v_pk_mul_f32 v[32:33], v[46:47], v[44:45]
	v_lshl_add_u64 v[44:45], v[48:49], 0, v[112:113]
	v_pk_mul_f32 v[38:39], v[32:33], v[38:39]
	v_pk_mul_f32 v[32:33], v[42:43], v[50:51]
	s_nop 0
	v_pk_mul_f32 v[42:43], v[32:33], v[34:35]
	v_cvt_pk_bf16_f32 v32, v36, v37
	v_cvt_pk_bf16_f32 v33, v38, v39
	v_cvt_pk_bf16_f32 v34, v40, v41
	v_cvt_pk_bf16_f32 v35, v42, v43
	global_store_dwordx4 v[44:45], v[32:35], off
	v_mul_f32_e32 v36, 0xbfb8aa3b, v29
	v_exp_f32_e32 v36, v36
	v_mul_f32_e32 v34, 0xbfb8aa3b, v28
	v_mul_f32_e32 v35, 0xbfb8aa3b, v24
	v_exp_f32_e32 v34, v34
	v_exp_f32_e32 v35, v35
	v_add_u32_e32 v32, 0xa0, v152
	v_mad_i64_i32 v[32:33], s[38:39], v32, s55, v[144:145]
	v_add_f32_e32 v34, 1.0, v34
	v_add_f32_e32 v37, 1.0, v35
	v_add_f32_e32 v35, 1.0, v36
	v_rcp_f32_e32 v34, v34
	v_rcp_f32_e32 v35, v35
	v_mul_f32_e32 v36, 0xbfb8aa3b, v25
	v_exp_f32_e32 v38, v36
	v_rcp_f32_e32 v36, v37
	v_pk_mul_f32 v[28:29], v[28:29], v[34:35]
	v_mul_f32_e32 v34, 0xbfb8aa3b, v31
	v_pk_mul_f32 v[20:21], v[28:29], v[20:21]
	v_add_f32_e32 v28, 1.0, v38
	v_rcp_f32_e32 v37, v28
	v_mul_f32_e32 v29, 0xbfb8aa3b, v26
	v_mul_f32_e32 v28, 0xbfb8aa3b, v30
	v_exp_f32_e32 v29, v29
	v_exp_f32_e32 v28, v28
	v_exp_f32_e32 v35, v34
	v_mul_f32_e32 v34, 0xbfb8aa3b, v27
	v_pk_mul_f32 v[24:25], v[24:25], v[36:37]
	v_exp_f32_e32 v36, v34
	v_add_f32_e32 v29, 1.0, v29
	v_add_f32_e32 v28, 1.0, v28
	v_rcp_f32_e32 v34, v29
	v_add_f32_e32 v29, 1.0, v35
	v_rcp_f32_e32 v28, v28
	v_rcp_f32_e32 v29, v29
	v_add_f32_e32 v35, 1.0, v36
	v_rcp_f32_e32 v35, v35
	v_pk_mul_f32 v[24:25], v[24:25], v[16:17]
	v_pk_mul_f32 v[16:17], v[30:31], v[28:29]
	v_lshl_add_u64 v[28:29], v[32:33], 0, v[112:113]
	v_pk_mul_f32 v[22:23], v[16:17], v[22:23]
	v_pk_mul_f32 v[16:17], v[26:27], v[34:35]
	s_nop 0
	v_pk_mul_f32 v[26:27], v[16:17], v[18:19]
	v_cvt_pk_bf16_f32 v16, v20, v21
	v_cvt_pk_bf16_f32 v17, v22, v23
	v_cvt_pk_bf16_f32 v18, v24, v25
	v_cvt_pk_bf16_f32 v19, v26, v27
	global_store_dwordx4 v[28:29], v[16:19], off
	v_mul_f32_e32 v20, 0xbfb8aa3b, v13
	v_exp_f32_e32 v20, v20
	v_mul_f32_e32 v18, 0xbfb8aa3b, v12
	v_mul_f32_e32 v19, 0xbfb8aa3b, v8
	v_exp_f32_e32 v18, v18
	v_exp_f32_e32 v19, v19
	v_add_u32_e32 v16, 0xb0, v152
	v_mad_i64_i32 v[16:17], s[38:39], v16, s55, v[144:145]
	v_add_f32_e32 v18, 1.0, v18
	v_add_f32_e32 v21, 1.0, v19
	v_add_f32_e32 v19, 1.0, v20
	v_rcp_f32_e32 v18, v18
	v_rcp_f32_e32 v19, v19
	v_mul_f32_e32 v20, 0xbfb8aa3b, v9
	v_exp_f32_e32 v22, v20
	v_rcp_f32_e32 v20, v21
	v_pk_mul_f32 v[12:13], v[12:13], v[18:19]
	v_mul_f32_e32 v18, 0xbfb8aa3b, v15
	v_pk_mul_f32 v[4:5], v[12:13], v[4:5]
	v_add_f32_e32 v12, 1.0, v22
	v_rcp_f32_e32 v21, v12
	v_mul_f32_e32 v13, 0xbfb8aa3b, v10
	v_mul_f32_e32 v12, 0xbfb8aa3b, v14
	v_exp_f32_e32 v13, v13
	v_exp_f32_e32 v12, v12
	v_exp_f32_e32 v19, v18
	v_mul_f32_e32 v18, 0xbfb8aa3b, v11
	v_pk_mul_f32 v[8:9], v[8:9], v[20:21]
	v_exp_f32_e32 v20, v18
	v_add_f32_e32 v13, 1.0, v13
	v_add_f32_e32 v12, 1.0, v12
	v_rcp_f32_e32 v18, v13
	v_add_f32_e32 v13, 1.0, v19
	v_rcp_f32_e32 v12, v12
	v_rcp_f32_e32 v13, v13
	v_add_f32_e32 v19, 1.0, v20
	v_rcp_f32_e32 v19, v19
	v_pk_mul_f32 v[8:9], v[8:9], v[0:1]
	v_pk_mul_f32 v[0:1], v[14:15], v[12:13]
	v_lshl_add_u64 v[12:13], v[16:17], 0, v[112:113]
	v_pk_mul_f32 v[6:7], v[0:1], v[6:7]
	v_pk_mul_f32 v[0:1], v[10:11], v[18:19]
	s_mov_b64 s[38:39], s[30:31]
	v_pk_mul_f32 v[10:11], v[0:1], v[2:3]
	v_cvt_pk_bf16_f32 v0, v4, v5
	v_cvt_pk_bf16_f32 v1, v6, v7
	v_cvt_pk_bf16_f32 v2, v8, v9
	v_cvt_pk_bf16_f32 v3, v10, v11
	global_store_dwordx4 v[12:13], v[0:3], off
	s_cbranch_vccz .LBB0_166
	s_waitcnt vmcnt(0)
	s_cmpk_gt_u32 s3, 0xff
	s_cbranch_scc1 .LBB0_173
	s_barrier

; #define PG8_STAGE(bufoff, gbase, voff) do { _Pragma("unroll") for (int _i = 0; _i < 2; ++_i) \
;         __builtin_amdgcn_global_load_lds((const unsigned*)((const char*)(gbase) + (voff)[_i]), (PG8_LAS unsigned*)(lds + (bufoff) + ldsw + _i * 8192), 16, 0, 0); } while (0)
; #define PG8_LDA(dst, b, h) do { _Pragma("unroll") for (int m = 0; m < 4; ++m) _Pragma("unroll") for (int k = 0; k < 2; ++k) dst[m][k] = *(const PG8_LAS bf16x8*)(lds + PG8_SA(b, h) + aoff + m * 2048 + k * 1024); } while (0)
; #define PG8_LDB(dst, b, h) do { _Pragma("unroll") for (int n = 0; n < 2; ++n) _Pragma("unroll") for (int k = 0; k < 2; ++k) dst[n][k] = *(const PG8_LAS bf16x8*)(lds + PG8_SB(b, h) + boff + n * 2048 + k * 1024); } while (0)
; #define PG8_WAIT_V(n) asm volatile("s_waitcnt vmcnt(" #n ")" ::: "memory")
; #define PG8_WAIT_L(n) asm volatile("s_waitcnt lgkmcnt(" #n ")" ::: "memory")
; #define PG8_BAR __builtin_amdgcn_s_barrier()
; #define PG8_SCHED __builtin_amdgcn_sched_barrier(0)
; template <class Epi, class Sched, bool ALIGN_EPI = false, bool SP2 = false>
; __device__ __forceinline__ void gemm_phase(PG8_LAS unsigned char* lds, const Gemm g, const Sched& S, const Epi& E) {
;     ...
;         const bool has_next = S.next(ui + 1, nxt);
;         const char* nA = has_next ? (const char*)g.A + (size_t)nxt.pm * tstep : cA; const char* nB = has_next ? (const char*)g.Bt + (size_t)nxt.pn * tstep : cB;
;         for (int t = 0; t < nt; t += 2) {
;             const bool last = (t == nt - 2);
;             const char* a1 = cA + (size_t)(t + 1) * kstep;
;             const char* a2 = last ? nA : cA + (size_t)(t + 2) * kstep; const char* b2 = last ? nB : cB + (size_t)(t + 2) * kstep;
;             const char* a3 = a2 + kstep; const char* b3 = b2 + kstep;
;             if (last && has_next) S.a_ready(nxt);
;             if constexpr (SP2) {
;             PG8_LDB(B0, 0, 0); PG8_LDB(B1, 0, 1); PG8_SCHED; PG8_LDA(At, 0, 0); PG8_STAGE(PG8_SA(1, 1), a1 + hstep, voffA);
;             PG8_WAIT_V(8); PG8_WAIT_L(0); PG8_BAR; PG8_MMA(0, 0, At, B0); PG8_MMA(0, 1, At, B1); PG8_BAR; PG8_SCHED;
;             PG8_LDA(At, 0, 1); PG8_STAGE(PG8_SB(0, 0), b2, voffB); PG8_STAGE(PG8_SB(0, 1), b2 + hstep, voffB); PG8_STAGE(PG8_SA(0, 0), a2, voffA);
;             PG8_WAIT_V(8); PG8_WAIT_L(0); PG8_BAR; PG8_MMA(1, 0, At, B0); PG8_MMA(1, 1, At, B1); PG8_BAR; PG8_SCHED;
.LBB0_244:
	s_add_u32 s67, s46, 0x100
	v_mov_b32_e32 v220, v251
	s_addc_u32 s68, s47, 0
	s_mov_b32 s69, -2
	v_add_u32_e32 v164, 0x18000, v167
	v_add_u32_e32 v165, 0x1c000, v167
	ds_read_b128 v[140:143], v169
	ds_read_b128 v[144:147], v169 offset:1024
	ds_read_b128 v[148:151], v169 offset:2048
	ds_read_b128 v[152:155], v169 offset:3072
	ds_read_b128 v[156:159], v170
	ds_read_b128 v[160:163], v170 offset:1024
	ds_read_b128 v[172:175], v170 offset:2048
	ds_read_b128 v[176:179], v170 offset:3072
	s_add_u32 s46, s44, 0x100
	s_addc_u32 s47, s45, 0
	s_cmpk_eq_i32 s69, 0x54
	s_cselect_b32 s51, s11, s47
	s_cselect_b32 s50, s10, s46
	s_cselect_b32 s49, s13, s68
	s_cselect_b32 s48, s12, s67
	s_add_i32 m0, s26, 0xc000
	ds_read_b128 v[180:183], v171
	ds_read_b128 v[184:187], v171 offset:1024
	ds_read_b128 v[188:191], v171 offset:2048
	ds_read_b128 v[192:195], v171 offset:3072
	ds_read_b128 v[196:199], v171 offset:4096
	ds_read_b128 v[200:203], v171 offset:5120
	ds_read_b128 v[204:207], v171 offset:6144
	ds_read_b128 v[208:211], v171 offset:7168
	global_load_lds_dwordx4 v136, s[44:45]
	s_add_i32 m0, s26, 0xe000
	s_nop 0
	global_load_lds_dwordx4 v138, s[44:45]
	s_waitcnt vmcnt(8) lgkmcnt(0)
	s_barrier
	v_mfma_f32_16x16x32_bf16 v[124:127], v[140:143], v[180:183], 0
	v_mfma_f32_16x16x32_bf16 v[120:123], v[148:151], v[180:183], 0
	v_mfma_f32_16x16x32_bf16 v[116:119], v[140:143], v[188:191], 0
	v_mfma_f32_16x16x32_bf16 v[112:115], v[148:151], v[188:191], 0
	v_mfma_f32_16x16x32_bf16 v[108:111], v[140:143], v[196:199], 0
	v_mfma_f32_16x16x32_bf16 v[96:99], v[148:151], v[196:199], 0
	v_mfma_f32_16x16x32_bf16 v[84:87], v[140:143], v[204:207], 0
	v_mfma_f32_16x16x32_bf16 v[76:79], v[148:151], v[204:207], 0
	v_mfma_f32_16x16x32_bf16 v[124:127], v[144:147], v[184:187], v[124:127]
	v_mfma_f32_16x16x32_bf16 v[120:123], v[152:155], v[184:187], v[120:123]
	v_mfma_f32_16x16x32_bf16 v[116:119], v[144:147], v[192:195], v[116:119]
	v_mfma_f32_16x16x32_bf16 v[112:115], v[152:155], v[192:195], v[112:115]
	v_mfma_f32_16x16x32_bf16 v[108:111], v[144:147], v[200:203], v[108:111]
	v_mfma_f32_16x16x32_bf16 v[96:99], v[152:155], v[200:203], v[96:99]
	v_mfma_f32_16x16x32_bf16 v[84:87], v[144:147], v[208:211], v[84:87]
	v_mfma_f32_16x16x32_bf16 v[76:79], v[152:155], v[208:211], v[76:79]
	v_mfma_f32_16x16x32_bf16 v[104:107], v[156:159], v[180:183], 0
	v_mfma_f32_16x16x32_bf16 v[100:103], v[172:175], v[180:183], 0
	v_mfma_f32_16x16x32_bf16 v[92:95], v[156:159], v[188:191], 0
	v_mfma_f32_16x16x32_bf16 v[88:91], v[172:175], v[188:191], 0
	v_mfma_f32_16x16x32_bf16 v[80:83], v[156:159], v[196:199], 0
	v_mfma_f32_16x16x32_bf16 v[72:75], v[172:175], v[196:199], 0
	v_mfma_f32_16x16x32_bf16 v[68:71], v[156:159], v[204:207], 0
	v_mfma_f32_16x16x32_bf16 v[64:67], v[172:175], v[204:207], 0
	v_mfma_f32_16x16x32_bf16 v[104:107], v[160:163], v[184:187], v[104:107]
	v_mfma_f32_16x16x32_bf16 v[100:103], v[176:179], v[184:187], v[100:103]
	v_mfma_f32_16x16x32_bf16 v[92:95], v[160:163], v[192:195], v[92:95]
	v_mfma_f32_16x16x32_bf16 v[88:91], v[176:179], v[192:195], v[88:91]
	v_mfma_f32_16x16x32_bf16 v[80:83], v[160:163], v[200:203], v[80:83]
	v_mfma_f32_16x16x32_bf16 v[72:75], v[176:179], v[200:203], v[72:75]
	v_mfma_f32_16x16x32_bf16 v[68:71], v[160:163], v[208:211], v[68:71]
	v_mfma_f32_16x16x32_bf16 v[64:67], v[176:179], v[208:211], v[64:67]
	s_barrier
	s_add_i32 s44, s61, s25
	s_mov_b32 m0, s44
	ds_read_b128 v[180:183], v171 offset:16384
	ds_read_b128 v[184:187], v171 offset:17408
	ds_read_b128 v[188:191], v171 offset:18432
	ds_read_b128 v[192:195], v171 offset:19456
	ds_read_b128 v[196:199], v171 offset:20480
	ds_read_b128 v[200:203], v171 offset:21504
	ds_read_b128 v[204:207], v171 offset:22528
	ds_read_b128 v[208:211], v171 offset:23552
	global_load_lds_dwordx4 v130, s[48:49]
	s_add_i32 m0, s44, 0x2000
	s_add_u32 s44, s48, 0x160000
	s_addc_u32 s45, s49, 0
	s_add_i32 s70, s62, s25
	global_load_lds_dwordx4 v134, s[48:49]
	s_mov_b32 m0, s70
	s_nop 0
	global_load_lds_dwordx4 v130, s[44:45]
	s_add_i32 m0, s70, 0x2000
	s_nop 0
	global_load_lds_dwordx4 v134, s[44:45]
	s_mov_b32 m0, s26
	s_nop 0
	global_load_lds_dwordx4 v128, s[50:51]
	s_mov_b32 m0, s27
	s_nop 0
	global_load_lds_dwordx4 v132, s[50:51]
	s_waitcnt vmcnt(8) lgkmcnt(0)
	s_barrier
	v_mfma_f32_16x16x32_bf16 v[60:63], v[140:143], v[180:183], 0
	v_mfma_f32_16x16x32_bf16 v[56:59], v[148:151], v[180:183], 0
	v_mfma_f32_16x16x32_bf16 v[52:55], v[140:143], v[188:191], 0
	v_mfma_f32_16x16x32_bf16 v[48:51], v[148:151], v[188:191], 0
	v_mfma_f32_16x16x32_bf16 v[44:47], v[140:143], v[196:199], 0
	v_mfma_f32_16x16x32_bf16 v[32:35], v[148:151], v[196:199], 0
	v_mfma_f32_16x16x32_bf16 v[20:23], v[140:143], v[204:207], 0
	v_mfma_f32_16x16x32_bf16 v[12:15], v[148:151], v[204:207], 0
	v_mfma_f32_16x16x32_bf16 v[60:63], v[144:147], v[184:187], v[60:63]
	v_mfma_f32_16x16x32_bf16 v[56:59], v[152:155], v[184:187], v[56:59]
	v_mfma_f32_16x16x32_bf16 v[52:55], v[144:147], v[192:195], v[52:55]
	v_mfma_f32_16x16x32_bf16 v[48:51], v[152:155], v[192:195], v[48:51]
	v_mfma_f32_16x16x32_bf16 v[44:47], v[144:147], v[200:203], v[44:47]
	v_mfma_f32_16x16x32_bf16 v[32:35], v[152:155], v[200:203], v[32:35]
	v_mfma_f32_16x16x32_bf16 v[20:23], v[144:147], v[208:211], v[20:23]
	v_mfma_f32_16x16x32_bf16 v[12:15], v[152:155], v[208:211], v[12:15]
	v_mfma_f32_16x16x32_bf16 v[40:43], v[156:159], v[180:183], 0
	v_mfma_f32_16x16x32_bf16 v[36:39], v[172:175], v[180:183], 0
	v_mfma_f32_16x16x32_bf16 v[28:31], v[156:159], v[188:191], 0
	v_mfma_f32_16x16x32_bf16 v[24:27], v[172:175], v[188:191], 0
	v_mfma_f32_16x16x32_bf16 v[16:19], v[156:159], v[196:199], 0
	v_mfma_f32_16x16x32_bf16 v[8:11], v[172:175], v[196:199], 0
	v_mfma_f32_16x16x32_bf16 v[4:7], v[156:159], v[204:207], 0
	v_mfma_f32_16x16x32_bf16 v[0:3], v[172:175], v[204:207], 0
	v_mfma_f32_16x16x32_bf16 v[40:43], v[160:163], v[184:187], v[40:43]
	v_mfma_f32_16x16x32_bf16 v[36:39], v[176:179], v[184:187], v[36:39]
	v_mfma_f32_16x16x32_bf16 v[28:31], v[160:163], v[192:195], v[28:31]
	v_mfma_f32_16x16x32_bf16 v[24:27], v[176:179], v[192:195], v[24:27]
	v_mfma_f32_16x16x32_bf16 v[16:19], v[160:163], v[200:203], v[16:19]
	v_mfma_f32_16x16x32_bf16 v[8:11], v[176:179], v[200:203], v[8:11]
	v_mfma_f32_16x16x32_bf16 v[4:7], v[160:163], v[208:211], v[4:7]
	v_mfma_f32_16x16x32_bf16 v[0:3], v[176:179], v[208:211], v[0:3]
	s_barrier
; #define PG8_STAGE(bufoff, gbase, voff) do { _Pragma("unroll") for (int _i = 0; _i < 2; ++_i) \
;         __builtin_amdgcn_global_load_lds((const unsigned*)((const char*)(gbase) + (voff)[_i]), (PG8_LAS unsigned*)(lds + (bufoff) + ldsw + _i * 8192), 16, 0, 0); } while (0)
; #define PG8_LDA(dst, b, h) do { _Pragma("unroll") for (int m = 0; m < 4; ++m) _Pragma("unroll") for (int k = 0; k < 2; ++k) dst[m][k] = *(const PG8_LAS bf16x8*)(lds + PG8_SA(b, h) + aoff + m * 2048 + k * 1024); } while (0)
; #define PG8_LDB(dst, b, h) do { _Pragma("unroll") for (int n = 0; n < 2; ++n) _Pragma("unroll") for (int k = 0; k < 2; ++k) dst[n][k] = *(const PG8_LAS bf16x8*)(lds + PG8_SB(b, h) + boff + n * 2048 + k * 1024); } while (0)
; #define PG8_MMA(ai, bj, At, Bt) do { __builtin_amdgcn_s_setprio(1); _Pragma("unroll") for (int m = 0; m < 4; ++m) _Pragma("unroll") for (int n = 0; n < 2; ++n) _Pragma("unroll") for (int k = 0; k < 2; ++k) \
;         acc[ai][bj][m][n] = __builtin_amdgcn_mfma_f32_16x16x32_bf16(Bt[n][k], At[m][k], acc[ai][bj][m][n], 0, 0, 0); __builtin_amdgcn_s_setprio(0); } while (0)
; #define PG8_WAIT_V(n) asm volatile("s_waitcnt vmcnt(" #n ")" ::: "memory")
; #define PG8_WAIT_L(n) asm volatile("s_waitcnt lgkmcnt(" #n ")" ::: "memory")
; #define PG8_BAR __builtin_amdgcn_s_barrier()
; #define PG8_SCHED __builtin_amdgcn_sched_barrier(0)
; template <class Epi, class Sched, bool ALIGN_EPI = false, bool SP2 = false>
; __device__ __forceinline__ void gemm_phase(PG8_LAS unsigned char* lds, const Gemm g, const Sched& S, const Epi& E) {
;     ...
;             PG8_LDB(B0, 1, 0); PG8_LDB(B1, 1, 1); PG8_SCHED; PG8_LDA(At, 1, 0); PG8_STAGE(PG8_SA(0, 1), a2 + hstep, voffA);
;             PG8_WAIT_V(8); PG8_WAIT_L(0); PG8_BAR; PG8_MMA(0, 0, At, B0); PG8_MMA(0, 1, At, B1); PG8_BAR; PG8_SCHED;
;             PG8_LDA(At, 1, 1); PG8_STAGE(PG8_SB(1, 0), b3, voffB); PG8_STAGE(PG8_SB(1, 1), b3 + hstep, voffB); PG8_STAGE(PG8_SA(1, 0), a3, voffA);
;             PG8_WAIT_V(8); PG8_WAIT_L(0); PG8_BAR; PG8_MMA(1, 0, At, B0); PG8_MMA(1, 1, At, B1); PG8_BAR; PG8_SCHED;
	s_add_i32 s70, 0, 0x18000
	s_add_i32 s71, 0, 0x1c000
	ds_read_b128 v[140:143], v164
	ds_read_b128 v[144:147], v164 offset:1024
	ds_read_b128 v[148:151], v164 offset:2048
	ds_read_b128 v[152:155], v164 offset:3072
	ds_read_b128 v[156:159], v165
	ds_read_b128 v[160:163], v165 offset:1024
	ds_read_b128 v[172:175], v165 offset:2048
	ds_read_b128 v[176:179], v165 offset:3072
	s_add_u32 s44, s50, 0x160000
	s_addc_u32 s45, s51, 0
	s_mov_b32 m0, s52
	ds_read_b128 v[180:183], v171 offset:32768
	ds_read_b128 v[184:187], v171 offset:33792
	ds_read_b128 v[188:191], v171 offset:34816
	ds_read_b128 v[192:195], v171 offset:35840
	ds_read_b128 v[196:199], v171 offset:36864
	ds_read_b128 v[200:203], v171 offset:37888
	ds_read_b128 v[204:207], v171 offset:38912
	ds_read_b128 v[208:211], v171 offset:39936
	global_load_lds_dwordx4 v128, s[44:45]
	s_mov_b32 m0, s53
	s_nop 0
	global_load_lds_dwordx4 v132, s[44:45]
	s_waitcnt vmcnt(8) lgkmcnt(0)
	s_barrier
	v_mfma_f32_16x16x32_bf16 v[124:127], v[140:143], v[180:183], v[124:127]
	v_mfma_f32_16x16x32_bf16 v[120:123], v[148:151], v[180:183], v[120:123]
	v_mfma_f32_16x16x32_bf16 v[116:119], v[140:143], v[188:191], v[116:119]
	v_mfma_f32_16x16x32_bf16 v[112:115], v[148:151], v[188:191], v[112:115]
	v_mfma_f32_16x16x32_bf16 v[108:111], v[140:143], v[196:199], v[108:111]
	v_mfma_f32_16x16x32_bf16 v[96:99], v[148:151], v[196:199], v[96:99]
	v_mfma_f32_16x16x32_bf16 v[84:87], v[140:143], v[204:207], v[84:87]
	v_mfma_f32_16x16x32_bf16 v[76:79], v[148:151], v[204:207], v[76:79]
	v_mfma_f32_16x16x32_bf16 v[124:127], v[144:147], v[184:187], v[124:127]
	v_mfma_f32_16x16x32_bf16 v[120:123], v[152:155], v[184:187], v[120:123]
	v_mfma_f32_16x16x32_bf16 v[116:119], v[144:147], v[192:195], v[116:119]
	v_mfma_f32_16x16x32_bf16 v[112:115], v[152:155], v[192:195], v[112:115]
	v_mfma_f32_16x16x32_bf16 v[108:111], v[144:147], v[200:203], v[108:111]
	v_mfma_f32_16x16x32_bf16 v[96:99], v[152:155], v[200:203], v[96:99]
	v_mfma_f32_16x16x32_bf16 v[84:87], v[144:147], v[208:211], v[84:87]
	v_mfma_f32_16x16x32_bf16 v[76:79], v[152:155], v[208:211], v[76:79]
	v_mfma_f32_16x16x32_bf16 v[104:107], v[156:159], v[180:183], v[104:107]
	v_mfma_f32_16x16x32_bf16 v[100:103], v[172:175], v[180:183], v[100:103]
	v_mfma_f32_16x16x32_bf16 v[92:95], v[156:159], v[188:191], v[92:95]
	v_mfma_f32_16x16x32_bf16 v[88:91], v[172:175], v[188:191], v[88:91]
	v_mfma_f32_16x16x32_bf16 v[80:83], v[156:159], v[196:199], v[80:83]
	v_mfma_f32_16x16x32_bf16 v[72:75], v[172:175], v[196:199], v[72:75]
	v_mfma_f32_16x16x32_bf16 v[68:71], v[156:159], v[204:207], v[68:71]
	v_mfma_f32_16x16x32_bf16 v[64:67], v[172:175], v[204:207], v[64:67]
	v_mfma_f32_16x16x32_bf16 v[104:107], v[160:163], v[184:187], v[104:107]
	v_mfma_f32_16x16x32_bf16 v[100:103], v[176:179], v[184:187], v[100:103]
	v_mfma_f32_16x16x32_bf16 v[92:95], v[160:163], v[192:195], v[92:95]
	v_mfma_f32_16x16x32_bf16 v[88:91], v[176:179], v[192:195], v[88:91]
	v_mfma_f32_16x16x32_bf16 v[80:83], v[160:163], v[200:203], v[80:83]
	v_mfma_f32_16x16x32_bf16 v[72:75], v[176:179], v[200:203], v[72:75]
	v_mfma_f32_16x16x32_bf16 v[68:71], v[160:163], v[208:211], v[68:71]
	v_mfma_f32_16x16x32_bf16 v[64:67], v[176:179], v[208:211], v[64:67]
	s_barrier
	s_add_i32 s44, s70, s25
	s_add_u32 s86, s48, 0x80
	s_addc_u32 s87, s49, 0
	s_mov_b32 m0, s44
	ds_read_b128 v[180:183], v171 offset:49152
	ds_read_b128 v[184:187], v171 offset:50176
	ds_read_b128 v[188:191], v171 offset:51200
	ds_read_b128 v[192:195], v171 offset:52224
	ds_read_b128 v[196:199], v171 offset:53248
	ds_read_b128 v[200:203], v171 offset:54272
	ds_read_b128 v[204:207], v171 offset:55296
	ds_read_b128 v[208:211], v171 offset:56320
	global_load_lds_dwordx4 v130, s[86:87]
	s_add_i32 m0, s44, 0x2000
	s_add_u32 s44, s48, 0x160080
	s_addc_u32 s45, s49, 0
	s_add_i32 s48, s71, s25
	global_load_lds_dwordx4 v134, s[86:87]
	s_mov_b32 m0, s48
	s_nop 0
	global_load_lds_dwordx4 v130, s[44:45]
	s_add_i32 m0, s48, 0x2000
	s_nop 0
	global_load_lds_dwordx4 v134, s[44:45]
	s_add_u32 s84, s50, 0x80
	s_addc_u32 s85, s51, 0
	s_mov_b32 m0, s57
	s_nop 0
	global_load_lds_dwordx4 v128, s[84:85]
	s_mov_b32 m0, s58
	s_nop 0
	global_load_lds_dwordx4 v132, s[84:85]
	s_waitcnt vmcnt(8) lgkmcnt(0)
	s_barrier
	v_mfma_f32_16x16x32_bf16 v[60:63], v[140:143], v[180:183], v[60:63]
	v_mfma_f32_16x16x32_bf16 v[56:59], v[148:151], v[180:183], v[56:59]
	v_mfma_f32_16x16x32_bf16 v[52:55], v[140:143], v[188:191], v[52:55]
	v_mfma_f32_16x16x32_bf16 v[48:51], v[148:151], v[188:191], v[48:51]
	v_mfma_f32_16x16x32_bf16 v[44:47], v[140:143], v[196:199], v[44:47]
	v_mfma_f32_16x16x32_bf16 v[32:35], v[148:151], v[196:199], v[32:35]
	v_mfma_f32_16x16x32_bf16 v[20:23], v[140:143], v[204:207], v[20:23]
	v_mfma_f32_16x16x32_bf16 v[12:15], v[148:151], v[204:207], v[12:15]
	v_mfma_f32_16x16x32_bf16 v[60:63], v[144:147], v[184:187], v[60:63]
	v_mfma_f32_16x16x32_bf16 v[56:59], v[152:155], v[184:187], v[56:59]
	v_mfma_f32_16x16x32_bf16 v[52:55], v[144:147], v[192:195], v[52:55]
	v_mfma_f32_16x16x32_bf16 v[48:51], v[152:155], v[192:195], v[48:51]
	v_mfma_f32_16x16x32_bf16 v[44:47], v[144:147], v[200:203], v[44:47]
	v_mfma_f32_16x16x32_bf16 v[32:35], v[152:155], v[200:203], v[32:35]
	v_mfma_f32_16x16x32_bf16 v[20:23], v[144:147], v[208:211], v[20:23]
	v_mfma_f32_16x16x32_bf16 v[12:15], v[152:155], v[208:211], v[12:15]
	v_mfma_f32_16x16x32_bf16 v[40:43], v[156:159], v[180:183], v[40:43]
	v_mfma_f32_16x16x32_bf16 v[36:39], v[172:175], v[180:183], v[36:39]
	v_mfma_f32_16x16x32_bf16 v[28:31], v[156:159], v[188:191], v[28:31]
	v_mfma_f32_16x16x32_bf16 v[24:27], v[172:175], v[188:191], v[24:27]
	v_mfma_f32_16x16x32_bf16 v[16:19], v[156:159], v[196:199], v[16:19]
	v_mfma_f32_16x16x32_bf16 v[8:11], v[172:175], v[196:199], v[8:11]
	v_mfma_f32_16x16x32_bf16 v[4:7], v[156:159], v[204:207], v[4:7]
	v_mfma_f32_16x16x32_bf16 v[0:3], v[172:175], v[204:207], v[0:3]
	v_mfma_f32_16x16x32_bf16 v[40:43], v[160:163], v[184:187], v[40:43]
	v_mfma_f32_16x16x32_bf16 v[36:39], v[176:179], v[184:187], v[36:39]
	v_mfma_f32_16x16x32_bf16 v[28:31], v[160:163], v[192:195], v[28:31]
	v_mfma_f32_16x16x32_bf16 v[24:27], v[176:179], v[192:195], v[24:27]
	v_mfma_f32_16x16x32_bf16 v[16:19], v[160:163], v[200:203], v[16:19]
	v_mfma_f32_16x16x32_bf16 v[8:11], v[176:179], v[200:203], v[8:11]
	v_mfma_f32_16x16x32_bf16 v[4:7], v[160:163], v[208:211], v[4:7]
	v_mfma_f32_16x16x32_bf16 v[0:3], v[176:179], v[208:211], v[0:3]
	s_barrier
	s_add_i32 s69, s69, 2
	s_add_u32 s67, s67, 0x100
	s_addc_u32 s68, s68, 0
	s_cmpk_gt_u32 s69, 0x55
	s_mov_b64 s[44:45], s[46:47]
; #define PG8_STAGE(bufoff, gbase, voff) do { _Pragma("unroll") for (int _i = 0; _i < 2; ++_i) \
;         __builtin_amdgcn_global_load_lds((const unsigned*)((const char*)(gbase) + (voff)[_i]), (PG8_LAS unsigned*)(lds + (bufoff) + ldsw + _i * 8192), 16, 0, 0); } while (0)
; #define PG8_LDA(dst, b, h) do { _Pragma("unroll") for (int m = 0; m < 4; ++m) _Pragma("unroll") for (int k = 0; k < 2; ++k) dst[m][k] = *(const PG8_LAS bf16x8*)(lds + PG8_SA(b, h) + aoff + m * 2048 + k * 1024); } while (0)
; #define PG8_LDB(dst, b, h) do { _Pragma("unroll") for (int n = 0; n < 2; ++n) _Pragma("unroll") for (int k = 0; k < 2; ++k) dst[n][k] = *(const PG8_LAS bf16x8*)(lds + PG8_SB(b, h) + boff + n * 2048 + k * 1024); } while (0)
; #define PG8_MMA(ai, bj, At, Bt) do { __builtin_amdgcn_s_setprio(1); _Pragma("unroll") for (int m = 0; m < 4; ++m) _Pragma("unroll") for (int n = 0; n < 2; ++n) _Pragma("unroll") for (int k = 0; k < 2; ++k) \
;         acc[ai][bj][m][n] = __builtin_amdgcn_mfma_f32_16x16x32_bf16(Bt[n][k], At[m][k], acc[ai][bj][m][n], 0, 0, 0); __builtin_amdgcn_s_setprio(0); } while (0)
; #define PG8_WAIT_V(n) asm volatile("s_waitcnt vmcnt(" #n ")" ::: "memory")
; #define PG8_WAIT_L(n) asm volatile("s_waitcnt lgkmcnt(" #n ")" ::: "memory")
; #define PG8_BAR __builtin_amdgcn_s_barrier()
; #define PG8_SCHED __builtin_amdgcn_sched_barrier(0)
; template <class Epi, class Sched, bool ALIGN_EPI = false, bool SP2 = false>
; __device__ __forceinline__ void gemm_phase(PG8_LAS unsigned char* lds, const Gemm g, const Sched& S, const Epi& E) {
;     ...
;             PG8_LDB(B0, 0, 0); PG8_LDB(B1, 0, 1); PG8_SCHED; PG8_LDA(At, 0, 0); PG8_STAGE(PG8_SA(1, 1), a1 + hstep, voffA);
;             PG8_WAIT_V(8); PG8_WAIT_L(0); PG8_BAR; PG8_MMA(0, 0, At, B0); PG8_MMA(0, 1, At, B1); PG8_BAR; PG8_SCHED;
;             PG8_LDA(At, 0, 1); PG8_STAGE(PG8_SB(0, 0), b2, voffB); PG8_STAGE(PG8_SB(0, 1), b2 + hstep, voffB); PG8_STAGE(PG8_SA(0, 0), a2, voffA);
;             PG8_WAIT_V(8); PG8_WAIT_L(0); PG8_BAR; PG8_MMA(1, 0, At, B0); PG8_MMA(1, 1, At, B1); PG8_BAR; PG8_SCHED;
.LBB0_245:
	ds_read_b128 v[140:143], v169
	ds_read_b128 v[144:147], v169 offset:1024
	ds_read_b128 v[148:151], v169 offset:2048
	ds_read_b128 v[152:155], v169 offset:3072
	ds_read_b128 v[156:159], v170
	ds_read_b128 v[160:163], v170 offset:1024
	ds_read_b128 v[172:175], v170 offset:2048
	ds_read_b128 v[176:179], v170 offset:3072
	s_add_u32 s46, s44, 0x100
	s_addc_u32 s47, s45, 0
	s_cmpk_eq_i32 s69, 0x54
	s_cselect_b32 s51, s11, s47
	s_cselect_b32 s50, s10, s46
	s_cselect_b32 s49, s13, s68
	s_cselect_b32 s48, s12, s67
	s_add_i32 m0, s26, 0xc000
	ds_read_b128 v[180:183], v171
	ds_read_b128 v[184:187], v171 offset:1024
	ds_read_b128 v[188:191], v171 offset:2048
	ds_read_b128 v[192:195], v171 offset:3072
	ds_read_b128 v[196:199], v171 offset:4096
	ds_read_b128 v[200:203], v171 offset:5120
	ds_read_b128 v[204:207], v171 offset:6144
	ds_read_b128 v[208:211], v171 offset:7168
	global_load_lds_dwordx4 v136, s[44:45]
	s_add_i32 m0, s26, 0xe000
	s_nop 0
	global_load_lds_dwordx4 v138, s[44:45]
	s_waitcnt vmcnt(8) lgkmcnt(0)
	s_barrier
	v_mfma_f32_16x16x32_bf16 v[124:127], v[140:143], v[180:183], v[124:127]
	v_mfma_f32_16x16x32_bf16 v[120:123], v[148:151], v[180:183], v[120:123]
	v_mfma_f32_16x16x32_bf16 v[116:119], v[140:143], v[188:191], v[116:119]
	v_mfma_f32_16x16x32_bf16 v[112:115], v[148:151], v[188:191], v[112:115]
	v_mfma_f32_16x16x32_bf16 v[108:111], v[140:143], v[196:199], v[108:111]
	v_mfma_f32_16x16x32_bf16 v[96:99], v[148:151], v[196:199], v[96:99]
	v_mfma_f32_16x16x32_bf16 v[84:87], v[140:143], v[204:207], v[84:87]
	v_mfma_f32_16x16x32_bf16 v[76:79], v[148:151], v[204:207], v[76:79]
	v_mfma_f32_16x16x32_bf16 v[124:127], v[144:147], v[184:187], v[124:127]
	v_mfma_f32_16x16x32_bf16 v[120:123], v[152:155], v[184:187], v[120:123]
	v_mfma_f32_16x16x32_bf16 v[116:119], v[144:147], v[192:195], v[116:119]
	v_mfma_f32_16x16x32_bf16 v[112:115], v[152:155], v[192:195], v[112:115]
	v_mfma_f32_16x16x32_bf16 v[108:111], v[144:147], v[200:203], v[108:111]
	v_mfma_f32_16x16x32_bf16 v[96:99], v[152:155], v[200:203], v[96:99]
	v_mfma_f32_16x16x32_bf16 v[84:87], v[144:147], v[208:211], v[84:87]
	v_mfma_f32_16x16x32_bf16 v[76:79], v[152:155], v[208:211], v[76:79]
	v_mfma_f32_16x16x32_bf16 v[104:107], v[156:159], v[180:183], v[104:107]
	v_mfma_f32_16x16x32_bf16 v[100:103], v[172:175], v[180:183], v[100:103]
	v_mfma_f32_16x16x32_bf16 v[92:95], v[156:159], v[188:191], v[92:95]
	v_mfma_f32_16x16x32_bf16 v[88:91], v[172:175], v[188:191], v[88:91]
	v_mfma_f32_16x16x32_bf16 v[80:83], v[156:159], v[196:199], v[80:83]
	v_mfma_f32_16x16x32_bf16 v[72:75], v[172:175], v[196:199], v[72:75]
	v_mfma_f32_16x16x32_bf16 v[68:71], v[156:159], v[204:207], v[68:71]
	v_mfma_f32_16x16x32_bf16 v[64:67], v[172:175], v[204:207], v[64:67]
	v_mfma_f32_16x16x32_bf16 v[104:107], v[160:163], v[184:187], v[104:107]
	v_mfma_f32_16x16x32_bf16 v[100:103], v[176:179], v[184:187], v[100:103]
	v_mfma_f32_16x16x32_bf16 v[92:95], v[160:163], v[192:195], v[92:95]
	v_mfma_f32_16x16x32_bf16 v[88:91], v[176:179], v[192:195], v[88:91]
	v_mfma_f32_16x16x32_bf16 v[80:83], v[160:163], v[200:203], v[80:83]
	v_mfma_f32_16x16x32_bf16 v[72:75], v[176:179], v[200:203], v[72:75]
	v_mfma_f32_16x16x32_bf16 v[68:71], v[160:163], v[208:211], v[68:71]
	v_mfma_f32_16x16x32_bf16 v[64:67], v[176:179], v[208:211], v[64:67]
	s_barrier
	s_add_i32 s44, s61, s25
	s_mov_b32 m0, s44
	ds_read_b128 v[180:183], v171 offset:16384
	ds_read_b128 v[184:187], v171 offset:17408
	ds_read_b128 v[188:191], v171 offset:18432
	ds_read_b128 v[192:195], v171 offset:19456
	ds_read_b128 v[196:199], v171 offset:20480
	ds_read_b128 v[200:203], v171 offset:21504
	ds_read_b128 v[204:207], v171 offset:22528
	ds_read_b128 v[208:211], v171 offset:23552
	global_load_lds_dwordx4 v130, s[48:49]
	s_add_i32 m0, s44, 0x2000
	s_add_u32 s44, s48, 0x160000
	s_addc_u32 s45, s49, 0
	s_add_i32 s70, s62, s25
	global_load_lds_dwordx4 v134, s[48:49]
	s_mov_b32 m0, s70
	s_nop 0
	global_load_lds_dwordx4 v130, s[44:45]
	s_add_i32 m0, s70, 0x2000
	s_nop 0
	global_load_lds_dwordx4 v134, s[44:45]
	s_mov_b32 m0, s26
	s_nop 0
	global_load_lds_dwordx4 v128, s[50:51]
	s_mov_b32 m0, s27
	s_nop 0
	global_load_lds_dwordx4 v132, s[50:51]
	s_waitcnt vmcnt(8) lgkmcnt(0)
	s_barrier
	v_mfma_f32_16x16x32_bf16 v[60:63], v[140:143], v[180:183], v[60:63]
	v_mfma_f32_16x16x32_bf16 v[56:59], v[148:151], v[180:183], v[56:59]
	v_mfma_f32_16x16x32_bf16 v[52:55], v[140:143], v[188:191], v[52:55]
	v_mfma_f32_16x16x32_bf16 v[48:51], v[148:151], v[188:191], v[48:51]
	v_mfma_f32_16x16x32_bf16 v[44:47], v[140:143], v[196:199], v[44:47]
	v_mfma_f32_16x16x32_bf16 v[32:35], v[148:151], v[196:199], v[32:35]
	v_mfma_f32_16x16x32_bf16 v[20:23], v[140:143], v[204:207], v[20:23]
	v_mfma_f32_16x16x32_bf16 v[12:15], v[148:151], v[204:207], v[12:15]
	v_mfma_f32_16x16x32_bf16 v[60:63], v[144:147], v[184:187], v[60:63]
	v_mfma_f32_16x16x32_bf16 v[56:59], v[152:155], v[184:187], v[56:59]
	v_mfma_f32_16x16x32_bf16 v[52:55], v[144:147], v[192:195], v[52:55]
	v_mfma_f32_16x16x32_bf16 v[48:51], v[152:155], v[192:195], v[48:51]
	v_mfma_f32_16x16x32_bf16 v[44:47], v[144:147], v[200:203], v[44:47]
	v_mfma_f32_16x16x32_bf16 v[32:35], v[152:155], v[200:203], v[32:35]
	v_mfma_f32_16x16x32_bf16 v[20:23], v[144:147], v[208:211], v[20:23]
	v_mfma_f32_16x16x32_bf16 v[12:15], v[152:155], v[208:211], v[12:15]
	v_mfma_f32_16x16x32_bf16 v[40:43], v[156:159], v[180:183], v[40:43]
	v_mfma_f32_16x16x32_bf16 v[36:39], v[172:175], v[180:183], v[36:39]
	v_mfma_f32_16x16x32_bf16 v[28:31], v[156:159], v[188:191], v[28:31]
	v_mfma_f32_16x16x32_bf16 v[24:27], v[172:175], v[188:191], v[24:27]
	v_mfma_f32_16x16x32_bf16 v[16:19], v[156:159], v[196:199], v[16:19]
	v_mfma_f32_16x16x32_bf16 v[8:11], v[172:175], v[196:199], v[8:11]
	v_mfma_f32_16x16x32_bf16 v[4:7], v[156:159], v[204:207], v[4:7]
	v_mfma_f32_16x16x32_bf16 v[0:3], v[172:175], v[204:207], v[0:3]
	v_mfma_f32_16x16x32_bf16 v[40:43], v[160:163], v[184:187], v[40:43]
	v_mfma_f32_16x16x32_bf16 v[36:39], v[176:179], v[184:187], v[36:39]
	v_mfma_f32_16x16x32_bf16 v[28:31], v[160:163], v[192:195], v[28:31]
	v_mfma_f32_16x16x32_bf16 v[24:27], v[176:179], v[192:195], v[24:27]
	v_mfma_f32_16x16x32_bf16 v[16:19], v[160:163], v[200:203], v[16:19]
	v_mfma_f32_16x16x32_bf16 v[8:11], v[176:179], v[200:203], v[8:11]
	v_mfma_f32_16x16x32_bf16 v[4:7], v[160:163], v[208:211], v[4:7]
	v_mfma_f32_16x16x32_bf16 v[0:3], v[176:179], v[208:211], v[0:3]
	s_barrier
; #define PG8_STAGE(bufoff, gbase, voff) do { _Pragma("unroll") for (int _i = 0; _i < 2; ++_i) \
;         __builtin_amdgcn_global_load_lds((const unsigned*)((const char*)(gbase) + (voff)[_i]), (PG8_LAS unsigned*)(lds + (bufoff) + ldsw + _i * 8192), 16, 0, 0); } while (0)
; #define PG8_LDA(dst, b, h) do { _Pragma("unroll") for (int m = 0; m < 4; ++m) _Pragma("unroll") for (int k = 0; k < 2; ++k) dst[m][k] = *(const PG8_LAS bf16x8*)(lds + PG8_SA(b, h) + aoff + m * 2048 + k * 1024); } while (0)
; #define PG8_LDB(dst, b, h) do { _Pragma("unroll") for (int n = 0; n < 2; ++n) _Pragma("unroll") for (int k = 0; k < 2; ++k) dst[n][k] = *(const PG8_LAS bf16x8*)(lds + PG8_SB(b, h) + boff + n * 2048 + k * 1024); } while (0)
; #define PG8_MMA(ai, bj, At, Bt) do { __builtin_amdgcn_s_setprio(1); _Pragma("unroll") for (int m = 0; m < 4; ++m) _Pragma("unroll") for (int n = 0; n < 2; ++n) _Pragma("unroll") for (int k = 0; k < 2; ++k) \
;         acc[ai][bj][m][n] = __builtin_amdgcn_mfma_f32_16x16x32_bf16(Bt[n][k], At[m][k], acc[ai][bj][m][n], 0, 0, 0); __builtin_amdgcn_s_setprio(0); } while (0)
; #define PG8_WAIT_V(n) asm volatile("s_waitcnt vmcnt(" #n ")" ::: "memory")
; #define PG8_WAIT_L(n) asm volatile("s_waitcnt lgkmcnt(" #n ")" ::: "memory")
; #define PG8_BAR __builtin_amdgcn_s_barrier()
; #define PG8_SCHED __builtin_amdgcn_sched_barrier(0)
; template <class Epi, class Sched, bool ALIGN_EPI = false, bool SP2 = false>
; __device__ __forceinline__ void gemm_phase(PG8_LAS unsigned char* lds, const Gemm g, const Sched& S, const Epi& E) {
;     ...
;             PG8_LDB(B0, 1, 0); PG8_LDB(B1, 1, 1); PG8_SCHED; PG8_LDA(At, 1, 0); PG8_STAGE(PG8_SA(0, 1), a2 + hstep, voffA);
;             PG8_WAIT_V(8); PG8_WAIT_L(0); PG8_BAR; PG8_MMA(0, 0, At, B0); PG8_MMA(0, 1, At, B1); PG8_BAR; PG8_SCHED;
;             PG8_LDA(At, 1, 1); PG8_STAGE(PG8_SB(1, 0), b3, voffB); PG8_STAGE(PG8_SB(1, 1), b3 + hstep, voffB); PG8_STAGE(PG8_SA(1, 0), a3, voffA);
;             PG8_WAIT_V(8); PG8_WAIT_L(0); PG8_BAR; PG8_MMA(1, 0, At, B0); PG8_MMA(1, 1, At, B1); PG8_BAR; PG8_SCHED;
	s_add_i32 s70, 0, 0x18000
	s_add_i32 s71, 0, 0x1c000
	ds_read_b128 v[140:143], v164
	ds_read_b128 v[144:147], v164 offset:1024
	ds_read_b128 v[148:151], v164 offset:2048
	ds_read_b128 v[152:155], v164 offset:3072
	ds_read_b128 v[156:159], v165
	ds_read_b128 v[160:163], v165 offset:1024
	ds_read_b128 v[172:175], v165 offset:2048
	ds_read_b128 v[176:179], v165 offset:3072
	s_add_u32 s44, s50, 0x160000
	s_addc_u32 s45, s51, 0
	s_mov_b32 m0, s52
	ds_read_b128 v[180:183], v171 offset:32768
	ds_read_b128 v[184:187], v171 offset:33792
	ds_read_b128 v[188:191], v171 offset:34816
	ds_read_b128 v[192:195], v171 offset:35840
	ds_read_b128 v[196:199], v171 offset:36864
	ds_read_b128 v[200:203], v171 offset:37888
	ds_read_b128 v[204:207], v171 offset:38912
	ds_read_b128 v[208:211], v171 offset:39936
	global_load_lds_dwordx4 v128, s[44:45]
	s_mov_b32 m0, s53
	s_nop 0
	global_load_lds_dwordx4 v132, s[44:45]
	s_waitcnt vmcnt(8) lgkmcnt(0)
	s_barrier
	v_mfma_f32_16x16x32_bf16 v[124:127], v[140:143], v[180:183], v[124:127]
	v_mfma_f32_16x16x32_bf16 v[120:123], v[148:151], v[180:183], v[120:123]
	v_mfma_f32_16x16x32_bf16 v[116:119], v[140:143], v[188:191], v[116:119]
	v_mfma_f32_16x16x32_bf16 v[112:115], v[148:151], v[188:191], v[112:115]
	v_mfma_f32_16x16x32_bf16 v[108:111], v[140:143], v[196:199], v[108:111]
	v_mfma_f32_16x16x32_bf16 v[96:99], v[148:151], v[196:199], v[96:99]
	v_mfma_f32_16x16x32_bf16 v[84:87], v[140:143], v[204:207], v[84:87]
	v_mfma_f32_16x16x32_bf16 v[76:79], v[148:151], v[204:207], v[76:79]
	v_mfma_f32_16x16x32_bf16 v[124:127], v[144:147], v[184:187], v[124:127]
	v_mfma_f32_16x16x32_bf16 v[120:123], v[152:155], v[184:187], v[120:123]
	v_mfma_f32_16x16x32_bf16 v[116:119], v[144:147], v[192:195], v[116:119]
	v_mfma_f32_16x16x32_bf16 v[112:115], v[152:155], v[192:195], v[112:115]
	v_mfma_f32_16x16x32_bf16 v[108:111], v[144:147], v[200:203], v[108:111]
	v_mfma_f32_16x16x32_bf16 v[96:99], v[152:155], v[200:203], v[96:99]
	v_mfma_f32_16x16x32_bf16 v[84:87], v[144:147], v[208:211], v[84:87]
	v_mfma_f32_16x16x32_bf16 v[76:79], v[152:155], v[208:211], v[76:79]
	v_mfma_f32_16x16x32_bf16 v[104:107], v[156:159], v[180:183], v[104:107]
	v_mfma_f32_16x16x32_bf16 v[100:103], v[172:175], v[180:183], v[100:103]
	v_mfma_f32_16x16x32_bf16 v[92:95], v[156:159], v[188:191], v[92:95]
	v_mfma_f32_16x16x32_bf16 v[88:91], v[172:175], v[188:191], v[88:91]
	v_mfma_f32_16x16x32_bf16 v[80:83], v[156:159], v[196:199], v[80:83]
	v_mfma_f32_16x16x32_bf16 v[72:75], v[172:175], v[196:199], v[72:75]
	v_mfma_f32_16x16x32_bf16 v[68:71], v[156:159], v[204:207], v[68:71]
	v_mfma_f32_16x16x32_bf16 v[64:67], v[172:175], v[204:207], v[64:67]
	v_mfma_f32_16x16x32_bf16 v[104:107], v[160:163], v[184:187], v[104:107]
	v_mfma_f32_16x16x32_bf16 v[100:103], v[176:179], v[184:187], v[100:103]
	v_mfma_f32_16x16x32_bf16 v[92:95], v[160:163], v[192:195], v[92:95]
	v_mfma_f32_16x16x32_bf16 v[88:91], v[176:179], v[192:195], v[88:91]
	v_mfma_f32_16x16x32_bf16 v[80:83], v[160:163], v[200:203], v[80:83]
	v_mfma_f32_16x16x32_bf16 v[72:75], v[176:179], v[200:203], v[72:75]
	v_mfma_f32_16x16x32_bf16 v[68:71], v[160:163], v[208:211], v[68:71]
	v_mfma_f32_16x16x32_bf16 v[64:67], v[176:179], v[208:211], v[64:67]
	s_barrier
	s_add_i32 s44, s70, s25
	s_add_u32 s86, s48, 0x80
	s_addc_u32 s87, s49, 0
	s_mov_b32 m0, s44
	ds_read_b128 v[180:183], v171 offset:49152
	ds_read_b128 v[184:187], v171 offset:50176
	ds_read_b128 v[188:191], v171 offset:51200
	ds_read_b128 v[192:195], v171 offset:52224
	ds_read_b128 v[196:199], v171 offset:53248
	ds_read_b128 v[200:203], v171 offset:54272
	ds_read_b128 v[204:207], v171 offset:55296
	ds_read_b128 v[208:211], v171 offset:56320
	global_load_lds_dwordx4 v130, s[86:87]
	s_add_i32 m0, s44, 0x2000
	s_add_u32 s44, s48, 0x160080
	s_addc_u32 s45, s49, 0
	s_add_i32 s48, s71, s25
	global_load_lds_dwordx4 v134, s[86:87]
	s_mov_b32 m0, s48
	s_nop 0
	global_load_lds_dwordx4 v130, s[44:45]
	s_add_i32 m0, s48, 0x2000
	s_nop 0
	global_load_lds_dwordx4 v134, s[44:45]
	s_add_u32 s84, s50, 0x80
	s_addc_u32 s85, s51, 0
	s_mov_b32 m0, s57
	s_nop 0
	global_load_lds_dwordx4 v128, s[84:85]
	s_mov_b32 m0, s58
	s_nop 0
	global_load_lds_dwordx4 v132, s[84:85]
	s_waitcnt vmcnt(8) lgkmcnt(0)
	s_barrier
	v_mfma_f32_16x16x32_bf16 v[60:63], v[140:143], v[180:183], v[60:63]
	v_mfma_f32_16x16x32_bf16 v[56:59], v[148:151], v[180:183], v[56:59]
	v_mfma_f32_16x16x32_bf16 v[52:55], v[140:143], v[188:191], v[52:55]
	v_mfma_f32_16x16x32_bf16 v[48:51], v[148:151], v[188:191], v[48:51]
	v_mfma_f32_16x16x32_bf16 v[44:47], v[140:143], v[196:199], v[44:47]
	v_mfma_f32_16x16x32_bf16 v[32:35], v[148:151], v[196:199], v[32:35]
	v_mfma_f32_16x16x32_bf16 v[20:23], v[140:143], v[204:207], v[20:23]
	v_mfma_f32_16x16x32_bf16 v[12:15], v[148:151], v[204:207], v[12:15]
	v_mfma_f32_16x16x32_bf16 v[60:63], v[144:147], v[184:187], v[60:63]
	v_mfma_f32_16x16x32_bf16 v[56:59], v[152:155], v[184:187], v[56:59]
	v_mfma_f32_16x16x32_bf16 v[52:55], v[144:147], v[192:195], v[52:55]
	v_mfma_f32_16x16x32_bf16 v[48:51], v[152:155], v[192:195], v[48:51]
	v_mfma_f32_16x16x32_bf16 v[44:47], v[144:147], v[200:203], v[44:47]
	v_mfma_f32_16x16x32_bf16 v[32:35], v[152:155], v[200:203], v[32:35]
	v_mfma_f32_16x16x32_bf16 v[20:23], v[144:147], v[208:211], v[20:23]
	v_mfma_f32_16x16x32_bf16 v[12:15], v[152:155], v[208:211], v[12:15]
	v_mfma_f32_16x16x32_bf16 v[40:43], v[156:159], v[180:183], v[40:43]
	v_mfma_f32_16x16x32_bf16 v[36:39], v[172:175], v[180:183], v[36:39]
	v_mfma_f32_16x16x32_bf16 v[28:31], v[156:159], v[188:191], v[28:31]
	v_mfma_f32_16x16x32_bf16 v[24:27], v[172:175], v[188:191], v[24:27]
	v_mfma_f32_16x16x32_bf16 v[16:19], v[156:159], v[196:199], v[16:19]
	v_mfma_f32_16x16x32_bf16 v[8:11], v[172:175], v[196:199], v[8:11]
	v_mfma_f32_16x16x32_bf16 v[4:7], v[156:159], v[204:207], v[4:7]
	v_mfma_f32_16x16x32_bf16 v[0:3], v[172:175], v[204:207], v[0:3]
	v_mfma_f32_16x16x32_bf16 v[40:43], v[160:163], v[184:187], v[40:43]
	v_mfma_f32_16x16x32_bf16 v[36:39], v[176:179], v[184:187], v[36:39]
	v_mfma_f32_16x16x32_bf16 v[28:31], v[160:163], v[192:195], v[28:31]
	v_mfma_f32_16x16x32_bf16 v[24:27], v[176:179], v[192:195], v[24:27]
	v_mfma_f32_16x16x32_bf16 v[16:19], v[160:163], v[200:203], v[16:19]
	v_mfma_f32_16x16x32_bf16 v[8:11], v[176:179], v[200:203], v[8:11]
	v_mfma_f32_16x16x32_bf16 v[4:7], v[160:163], v[208:211], v[4:7]
	v_mfma_f32_16x16x32_bf16 v[0:3], v[176:179], v[208:211], v[0:3]
	s_barrier
;     __device__ __forceinline__ void operator()(const f32x4 (&acc)[2][2][4][2], const Unit& u, int wr, int wc, int fr, int fq) const {
;         const int row0 = u.pm * BM + wr * 64 + fr, col0 = u.pn * BM + wc * 32 + 8 * fq;
;         const float* gp = gate + (u.pm >> 5) * 18432 + col0;
;         f32x4 gv[2][2];
; #pragma unroll
;         for (int bj = 0; bj < 2; ++bj)
; #pragma unroll
;             for (int n = 0; n < 2; ++n) gv[bj][n] = *(const f32x4*)(gp + bj * HALF + 4 * n) * scale;
; #pragma unroll
;         for (int ai = 0; ai < 2; ++ai) { f32x4 r[4][2][2];
; #pragma unroll
;             for (int m = 0; m < 4; ++m) { const size_t off = (size_t)(row0 + ai * HALF + m * 16) * 2048 + col0;
; #pragma unroll
;                 for (int bj = 0; bj < 2; ++bj)
; #pragma unroll
;                     for (int n = 0; n < 2; ++n) r[m][bj][n] = *(const f32x4*)(res + off + bj * HALF + 4 * n); }
; #pragma unroll
;             for (int m = 0; m < 4; ++m) { const size_t off = (size_t)(row0 + ai * HALF + m * 16) * 2048 + col0;
; #pragma unroll
;                 for (int bj = 0; bj < 2; ++bj)
; #pragma unroll
;                     for (int n = 0; n < 2; ++n) *(f32x4*)(out + off + bj * HALF + 4 * n) = r[m][bj][n] + gv[bj][n] * acc[ai][bj][m][n]; } }
	s_add_i32 s69, s69, 2
	s_add_u32 s67, s67, 0x100
	s_addc_u32 s68, s68, 0
	s_cmpk_gt_u32 s69, 0x55
	s_mov_b64 s[44:45], s[46:47]
	s_cbranch_scc0 .LBB0_245
	s_lshr_b32 s44, s65, 5
	s_mulk_i32 s44, 0x4800
	s_ashr_i32 s45, s44, 31
	v_lshl_or_b32 v140, s66, 8, v168
	s_lshl_b64 s[44:45], s[44:45], 2
	s_add_u32 s44, s55, s44
	v_ashrrev_i32_e32 v141, 31, v140
	s_addc_u32 s45, s56, s45
	v_lshlrev_b64 v[144:145], 2, v[140:141]
	v_lshl_add_u64 v[140:141], s[44:45], 0, v[144:145]
	global_load_dwordx4 v[146:149], v[140:141], off offset:16
	global_load_dwordx4 v[150:153], v[140:141], off
	global_load_dwordx4 v[172:175], v[140:141], off offset:528
	global_load_dwordx4 v[176:179], v[140:141], off offset:512
	v_lshl_add_u32 v140, s65, 8, v166
	v_ashrrev_i32_e32 v141, 31, v140
	v_lshl_add_u64 v[162:163], s[28:29], 0, v[144:145]
	v_lshlrev_b64 v[164:165], 13, v[140:141]
	v_lshl_add_u64 v[142:143], v[162:163], 0, v[164:165]
	global_load_dwordx4 v[180:183], v[142:143], off
	global_load_dwordx4 v[184:187], v[142:143], off offset:16
	global_load_dwordx4 v[188:191], v[142:143], off offset:528
	global_load_dwordx4 v[192:195], v[142:143], off offset:512
	v_or_b32_e32 v142, 16, v140
	v_ashrrev_i32_e32 v143, 31, v142
	v_lshlrev_b64 v[154:155], 13, v[142:143]
	v_lshl_add_u64 v[142:143], v[162:163], 0, v[154:155]
	global_load_dwordx4 v[196:199], v[142:143], off
	global_load_dwordx4 v[200:203], v[142:143], off offset:16
	global_load_dwordx4 v[204:207], v[142:143], off offset:528
	global_load_dwordx4 v[208:211], v[142:143], off offset:512
	v_or_b32_e32 v142, 32, v140
	v_ashrrev_i32_e32 v143, 31, v142
	v_lshlrev_b64 v[156:157], 13, v[142:143]
	v_or_b32_e32 v140, 48, v140
	v_lshl_add_u64 v[142:143], v[162:163], 0, v[156:157]
	v_ashrrev_i32_e32 v141, 31, v140
	global_load_dwordx4 v[214:217], v[142:143], off
	global_load_dwordx4 v[222:225], v[142:143], off offset:16
	global_load_dwordx4 v[232:235], v[142:143], off offset:512
	global_load_dwordx4 v[236:239], v[142:143], off offset:528
	v_lshlrev_b64 v[212:213], 13, v[140:141]
	v_lshl_add_u64 v[140:141], v[162:163], 0, v[212:213]
	global_load_dwordx4 v[240:243], v[140:141], off
	global_load_dwordx4 v[244:247], v[140:141], off offset:16
	global_load_dwordx4 v[248:251], v[140:141], off offset:512
	s_nop 0
	global_load_dwordx4 v[140:143], v[140:141], off offset:528
	v_lshl_add_u64 v[158:159], s[30:31], 0, v[164:165]
	v_lshl_add_u64 v[230:231], v[158:159], 0, v[144:145]
	v_lshl_add_u64 v[154:155], s[30:31], 0, v[154:155]
	v_lshl_add_u64 v[156:157], s[30:31], 0, v[156:157]
	v_lshl_add_u64 v[218:219], v[154:155], 0, v[144:145]
	v_lshl_add_u64 v[252:253], v[156:157], 0, v[144:145]
	s_and_b64 vcc, exec, s[8:9]
	s_mov_b32 s66, s63
	s_mov_b32 s65, s64
	s_mov_b64 s[46:47], s[12:13]
	s_mov_b64 s[44:45], s[10:11]
	s_waitcnt vmcnt(0)
	v_pk_mul_f32 v[154:155], v[148:149], 0.5 op_sel_hi:[1,0]
	v_pk_mul_f32 v[158:159], v[152:153], 0.5 op_sel_hi:[1,0]
	v_pk_mul_f32 v[160:161], v[150:151], 0.5 op_sel_hi:[1,0]
	v_pk_mul_f32 v[150:151], v[178:179], 0.5 op_sel_hi:[1,0]
	v_pk_mul_f32 v[152:153], v[176:177], 0.5 op_sel_hi:[1,0]
	v_pk_mul_f32 v[156:157], v[146:147], 0.5 op_sel_hi:[1,0]
	v_pk_mul_f32 v[146:147], v[174:175], 0.5 op_sel_hi:[1,0]
	v_pk_mul_f32 v[148:149], v[172:173], 0.5 op_sel_hi:[1,0]
	v_pk_fma_f32 v[126:127], v[126:127], v[158:159], v[182:183]
	v_pk_fma_f32 v[124:125], v[124:125], v[160:161], v[180:181]
	v_pk_fma_f32 v[122:123], v[122:123], v[154:155], v[186:187]
	v_pk_fma_f32 v[120:121], v[120:121], v[156:157], v[184:185]
	v_pk_fma_f32 v[106:107], v[106:107], v[150:151], v[194:195]
	v_pk_fma_f32 v[104:105], v[104:105], v[152:153], v[192:193]
	v_pk_fma_f32 v[102:103], v[102:103], v[146:147], v[190:191]
	v_pk_fma_f32 v[100:101], v[100:101], v[148:149], v[188:189]
	v_pk_fma_f32 v[118:119], v[118:119], v[158:159], v[198:199]
	v_pk_fma_f32 v[116:117], v[116:117], v[160:161], v[196:197]
	v_pk_fma_f32 v[114:115], v[114:115], v[154:155], v[202:203]
	v_pk_fma_f32 v[112:113], v[112:113], v[156:157], v[200:201]
	v_pk_fma_f32 v[82:83], v[82:83], v[150:151], v[234:235]
	v_pk_fma_f32 v[80:81], v[80:81], v[152:153], v[232:233]
	v_pk_fma_f32 v[94:95], v[94:95], v[150:151], v[210:211]
	v_pk_fma_f32 v[92:93], v[92:93], v[152:153], v[208:209]
	v_pk_fma_f32 v[90:91], v[90:91], v[146:147], v[206:207]
	v_pk_fma_f32 v[88:89], v[88:89], v[148:149], v[204:205]
	v_pk_fma_f32 v[110:111], v[110:111], v[158:159], v[216:217]
	v_pk_fma_f32 v[108:109], v[108:109], v[160:161], v[214:215]
	v_pk_fma_f32 v[98:99], v[98:99], v[154:155], v[224:225]
	v_pk_fma_f32 v[96:97], v[96:97], v[156:157], v[222:223]
	global_store_dwordx4 v[230:231], v[124:127], off
	global_store_dwordx4 v[230:231], v[120:123], off offset:16
	global_store_dwordx4 v[230:231], v[104:107], off offset:512
	global_store_dwordx4 v[230:231], v[100:103], off offset:528
	global_store_dwordx4 v[218:219], v[116:119], off
	global_store_dwordx4 v[218:219], v[112:115], off offset:16
	global_store_dwordx4 v[218:219], v[92:95], off offset:512
	global_store_dwordx4 v[218:219], v[88:91], off offset:528
	global_store_dwordx4 v[252:253], v[108:111], off
	global_store_dwordx4 v[252:253], v[96:99], off offset:16
	global_store_dwordx4 v[252:253], v[80:83], off offset:512
	v_pk_fma_f32 v[74:75], v[74:75], v[146:147], v[238:239]
	v_pk_fma_f32 v[72:73], v[72:73], v[148:149], v[236:237]
	v_lshl_add_u64 v[80:81], s[30:31], 0, v[212:213]
	global_store_dwordx4 v[252:253], v[72:75], off offset:528
; #define PG8_WAIT_V(n) asm volatile("s_waitcnt vmcnt(" #n ")" ::: "memory")
; #define PG8_BAR __builtin_amdgcn_s_barrier()
;     __device__ __forceinline__ void operator()(const f32x4 (&acc)[2][2][4][2], const Unit& u, int wr, int wc, int fr, int fq) const {
;     ...
;         for (int ai = 0; ai < 2; ++ai) { f32x4 r[4][2][2];
; #pragma unroll
;             for (int m = 0; m < 4; ++m) { const size_t off = (size_t)(row0 + ai * HALF + m * 16) * 2048 + col0;
; #pragma unroll
;                 for (int bj = 0; bj < 2; ++bj)
; #pragma unroll
;                     for (int n = 0; n < 2; ++n) r[m][bj][n] = *(const f32x4*)(res + off + bj * HALF + 4 * n); }
; #pragma unroll
;             for (int m = 0; m < 4; ++m) { const size_t off = (size_t)(row0 + ai * HALF + m * 16) * 2048 + col0;
; #pragma unroll
;                 for (int bj = 0; bj < 2; ++bj)
; #pragma unroll
;                     for (int n = 0; n < 2; ++n) *(f32x4*)(out + off + bj * HALF + 4 * n) = r[m][bj][n] + gv[bj][n] * acc[ai][bj][m][n]; } }
; template <class Epi, class Sched, bool ALIGN_EPI = false, bool SP2 = false>
; __device__ __forceinline__ void gemm_phase(PG8_LAS unsigned char* lds, const Gemm g, const Sched& S, const Epi& E) {
;     ...
;         if (!has_next) break;
; #pragma unroll
;         for (int a = 0; a < 2; ++a)
; #pragma unroll
;             for (int b = 0; b < 2; ++b)
; #pragma unroll
;                 for (int m = 0; m < 4; ++m)
; #pragma unroll
;                     for (int n = 0; n < 2; ++n) acc[a][b][m][n] = (f32x4){0.f, 0.f, 0.f, 0.f};
;         cur = nxt; cA = nA; cB = nB; ++ui;
;         if constexpr (ALIGN_EPI) { if (wr == 1) PG8_BAR; }
;     }
;     PG8_WAIT_V(0);
;     if constexpr (!ALIGN_EPI) { if (wr == 0) PG8_BAR; }
	v_lshl_add_u64 v[80:81], v[80:81], 0, v[144:145]
	v_pk_fma_f32 v[70:71], v[70:71], v[150:151], v[250:251]
	v_pk_fma_f32 v[74:75], v[86:87], v[158:159], v[242:243]
	v_pk_fma_f32 v[72:73], v[84:85], v[160:161], v[240:241]
	global_store_dwordx4 v[80:81], v[72:75], off
	v_pk_fma_f32 v[68:69], v[68:69], v[152:153], v[248:249]
	v_pk_fma_f32 v[66:67], v[66:67], v[146:147], v[142:143]
	v_pk_fma_f32 v[74:75], v[78:79], v[154:155], v[246:247]
	v_pk_fma_f32 v[72:73], v[76:77], v[156:157], v[244:245]
	v_pk_fma_f32 v[64:65], v[64:65], v[148:149], v[140:141]
	v_lshl_add_u64 v[140:141], v[164:165], 0, s[38:39]
	v_lshl_add_u64 v[142:143], v[164:165], 0, s[40:41]
	v_lshl_add_u64 v[172:173], v[164:165], 0, s[42:43]
	global_store_dwordx4 v[80:81], v[72:75], off offset:16
	global_store_dwordx4 v[80:81], v[68:71], off offset:512
	global_store_dwordx4 v[80:81], v[64:67], off offset:528
	v_lshl_add_u64 v[76:77], v[162:163], 0, v[140:141]
	v_lshl_add_u64 v[92:93], v[162:163], 0, v[142:143]
	v_lshl_add_u64 v[108:109], v[162:163], 0, v[172:173]
	global_load_dwordx4 v[64:67], v[76:77], off
	global_load_dwordx4 v[68:71], v[76:77], off offset:16
	global_load_dwordx4 v[72:75], v[76:77], off offset:512
	s_nop 0
	global_load_dwordx4 v[76:79], v[76:77], off offset:528
	s_nop 0
	global_load_dwordx4 v[80:83], v[92:93], off
	global_load_dwordx4 v[84:87], v[92:93], off offset:16
	global_load_dwordx4 v[88:91], v[92:93], off offset:512
	s_nop 0
	global_load_dwordx4 v[92:95], v[92:93], off offset:528
	s_nop 0
	global_load_dwordx4 v[96:99], v[108:109], off
	global_load_dwordx4 v[100:103], v[108:109], off offset:16
	global_load_dwordx4 v[104:107], v[108:109], off offset:512
	s_nop 0
	global_load_dwordx4 v[108:111], v[108:109], off offset:528
	v_lshl_add_u64 v[164:165], v[164:165], 0, s[34:35]
	v_lshl_add_u64 v[124:125], v[162:163], 0, v[164:165]
	global_load_dwordx4 v[112:115], v[124:125], off
	global_load_dwordx4 v[116:119], v[124:125], off offset:16
	global_load_dwordx4 v[120:123], v[124:125], off offset:512
	s_nop 0
	global_load_dwordx4 v[124:127], v[124:125], off offset:528
	v_lshl_add_u64 v[140:141], s[30:31], 0, v[140:141]
	v_lshl_add_u64 v[162:163], s[30:31], 0, v[172:173]
	v_lshl_add_u64 v[142:143], s[30:31], 0, v[142:143]
	v_lshl_add_u64 v[140:141], v[140:141], 0, v[144:145]
	v_lshl_add_u64 v[162:163], v[162:163], 0, v[144:145]
	v_lshl_add_u64 v[142:143], v[142:143], 0, v[144:145]
	v_mov_b32_e32 v251, v220
	s_waitcnt vmcnt(15)
	v_pk_fma_f32 v[62:63], v[62:63], v[158:159], v[66:67]
	v_pk_fma_f32 v[60:61], v[60:61], v[160:161], v[64:65]
	s_waitcnt vmcnt(14)
	v_pk_fma_f32 v[58:59], v[58:59], v[154:155], v[70:71]
	v_pk_fma_f32 v[56:57], v[56:57], v[156:157], v[68:69]
	s_waitcnt vmcnt(5)
	v_pk_fma_f32 v[18:19], v[18:19], v[150:151], v[106:107]
	v_pk_fma_f32 v[16:17], v[16:17], v[152:153], v[104:105]
	v_pk_fma_f32 v[42:43], v[42:43], v[150:151], v[74:75]
	v_pk_fma_f32 v[40:41], v[40:41], v[152:153], v[72:73]
	v_pk_fma_f32 v[38:39], v[38:39], v[146:147], v[78:79]
	v_pk_fma_f32 v[36:37], v[36:37], v[148:149], v[76:77]
	v_pk_fma_f32 v[54:55], v[54:55], v[158:159], v[82:83]
	v_pk_fma_f32 v[52:53], v[52:53], v[160:161], v[80:81]
	v_pk_fma_f32 v[50:51], v[50:51], v[154:155], v[86:87]
	v_pk_fma_f32 v[48:49], v[48:49], v[156:157], v[84:85]
	v_pk_fma_f32 v[30:31], v[30:31], v[150:151], v[90:91]
	v_pk_fma_f32 v[28:29], v[28:29], v[152:153], v[88:89]
	v_pk_fma_f32 v[26:27], v[26:27], v[146:147], v[94:95]
	v_pk_fma_f32 v[24:25], v[24:25], v[148:149], v[92:93]
	v_pk_fma_f32 v[46:47], v[46:47], v[158:159], v[98:99]
	v_pk_fma_f32 v[44:45], v[44:45], v[160:161], v[96:97]
	v_pk_fma_f32 v[34:35], v[34:35], v[154:155], v[102:103]
	v_pk_fma_f32 v[32:33], v[32:33], v[156:157], v[100:101]
	global_store_dwordx4 v[140:141], v[60:63], off
	global_store_dwordx4 v[140:141], v[56:59], off offset:16
	global_store_dwordx4 v[140:141], v[40:43], off offset:512
	global_store_dwordx4 v[140:141], v[36:39], off offset:528
	global_store_dwordx4 v[142:143], v[52:55], off
	global_store_dwordx4 v[142:143], v[48:51], off offset:16
	global_store_dwordx4 v[142:143], v[28:31], off offset:512
	global_store_dwordx4 v[142:143], v[24:27], off offset:528
	global_store_dwordx4 v[162:163], v[44:47], off
	global_store_dwordx4 v[162:163], v[32:35], off offset:16
	global_store_dwordx4 v[162:163], v[16:19], off offset:512
	s_waitcnt vmcnt(15)
	v_pk_fma_f32 v[10:11], v[10:11], v[146:147], v[110:111]
	v_pk_fma_f32 v[8:9], v[8:9], v[148:149], v[108:109]
	v_lshl_add_u64 v[16:17], s[30:31], 0, v[164:165]
	global_store_dwordx4 v[162:163], v[8:11], off offset:528
	v_lshl_add_u64 v[16:17], v[16:17], 0, v[144:145]
	s_waitcnt vmcnt(13)
	v_pk_fma_f32 v[6:7], v[6:7], v[150:151], v[122:123]
	v_pk_fma_f32 v[10:11], v[22:23], v[158:159], v[114:115]
	v_pk_fma_f32 v[8:9], v[20:21], v[160:161], v[112:113]
	global_store_dwordx4 v[16:17], v[8:11], off
	v_pk_fma_f32 v[4:5], v[4:5], v[152:153], v[120:121]
	s_waitcnt vmcnt(13)
	v_pk_fma_f32 v[2:3], v[2:3], v[146:147], v[126:127]
	v_pk_fma_f32 v[10:11], v[14:15], v[154:155], v[118:119]
	v_pk_fma_f32 v[8:9], v[12:13], v[156:157], v[116:117]
	v_pk_fma_f32 v[0:1], v[0:1], v[148:149], v[124:125]
	global_store_dwordx4 v[16:17], v[8:11], off offset:16
	global_store_dwordx4 v[16:17], v[4:7], off offset:512
	global_store_dwordx4 v[16:17], v[0:3], off offset:528
	s_cbranch_vccz .LBB0_234
	s_waitcnt vmcnt(0)
	s_cmpk_gt_u32 s3, 0xff
	s_cbranch_scc1 .LBB0_249
	s_barrier

; #define PG8_STAGE(bufoff, gbase, voff) do { _Pragma("unroll") for (int _i = 0; _i < 2; ++_i) \
;         __builtin_amdgcn_global_load_lds((const unsigned*)((const char*)(gbase) + (voff)[_i]), (PG8_LAS unsigned*)(lds + (bufoff) + ldsw + _i * 8192), 16, 0, 0); } while (0)
; #define PG8_LDA(dst, b, h) do { _Pragma("unroll") for (int m = 0; m < 4; ++m) _Pragma("unroll") for (int k = 0; k < 2; ++k) dst[m][k] = *(const PG8_LAS bf16x8*)(lds + PG8_SA(b, h) + aoff + m * 2048 + k * 1024); } while (0)
; #define PG8_LDB(dst, b, h) do { _Pragma("unroll") for (int n = 0; n < 2; ++n) _Pragma("unroll") for (int k = 0; k < 2; ++k) dst[n][k] = *(const PG8_LAS bf16x8*)(lds + PG8_SB(b, h) + boff + n * 2048 + k * 1024); } while (0)
; #define PG8_WAIT_V(n) asm volatile("s_waitcnt vmcnt(" #n ")" ::: "memory")
; #define PG8_WAIT_L(n) asm volatile("s_waitcnt lgkmcnt(" #n ")" ::: "memory")
; #define PG8_BAR __builtin_amdgcn_s_barrier()
; #define PG8_SCHED __builtin_amdgcn_sched_barrier(0)
; template <class Epi, class Sched, bool ALIGN_EPI = false, bool SP2 = false>
; __device__ __forceinline__ void gemm_phase(PG8_LAS unsigned char* lds, const Gemm g, const Sched& S, const Epi& E) {
;     ...
;         const bool has_next = S.next(ui + 1, nxt);
;         const char* nA = has_next ? (const char*)g.A + (size_t)nxt.pm * tstep : cA; const char* nB = has_next ? (const char*)g.Bt + (size_t)nxt.pn * tstep : cB;
;         for (int t = 0; t < nt; t += 2) {
;             const bool last = (t == nt - 2);
;             const char* a1 = cA + (size_t)(t + 1) * kstep;
;             const char* a2 = last ? nA : cA + (size_t)(t + 2) * kstep; const char* b2 = last ? nB : cB + (size_t)(t + 2) * kstep;
;             const char* a3 = a2 + kstep; const char* b3 = b2 + kstep;
;             if (last && has_next) S.a_ready(nxt);
;             if constexpr (SP2) {
;             PG8_LDB(B0, 0, 0); PG8_LDB(B1, 0, 1); PG8_SCHED; PG8_LDA(At, 0, 0); PG8_STAGE(PG8_SA(1, 1), a1 + hstep, voffA);
;             PG8_WAIT_V(8); PG8_WAIT_L(0); PG8_BAR; PG8_MMA(0, 0, At, B0); PG8_MMA(0, 1, At, B1); PG8_BAR; PG8_SCHED;
;             PG8_LDA(At, 0, 1); PG8_STAGE(PG8_SB(0, 0), b2, voffB); PG8_STAGE(PG8_SB(0, 1), b2 + hstep, voffB); PG8_STAGE(PG8_SA(0, 0), a2, voffA);
;             PG8_WAIT_V(8); PG8_WAIT_L(0); PG8_BAR; PG8_MMA(1, 0, At, B0); PG8_MMA(1, 1, At, B1); PG8_BAR; PG8_SCHED;
.LBB0_363:
	s_ashr_i32 s77, s76, 31
	s_lshl_b64 s[38:39], s[76:77], 20
	v_cmp_lt_i64_e32 vcc, s[78:79], v[178:179]
	s_add_u32 s78, s73, s38
	s_addc_u32 s79, s96, s39
	s_and_b64 s[38:39], vcc, exec
	s_cselect_b32 s77, s79, s85
	s_cselect_b32 s83, s78, s84
	s_ashr_i32 s75, s74, 31
	s_lshl_b64 s[38:39], s[74:75], 20
	s_add_u32 s80, s97, s38
	s_addc_u32 s81, s90, s39
	s_and_b64 s[38:39], vcc, exec
	s_cselect_b32 s75, s81, s87
	s_cselect_b32 vcc_lo, s80, s86
	s_add_u32 s84, s84, 0x80080
	s_addc_u32 s85, s85, 0
	s_add_u32 vcc_hi, s86, 0x100
	s_addc_u32 s38, s87, 0
	s_mov_b32 s39, -2
	v_add_u32_e32 v248, 0x18000, v197
	v_add_u32_e32 v249, 0x1c000, v197
	ds_read_b128 v[128:131], v214
	ds_read_b128 v[132:135], v214 offset:1024
	ds_read_b128 v[136:139], v214 offset:2048
	ds_read_b128 v[140:143], v214 offset:3072
	ds_read_b128 v[144:147], v215
	ds_read_b128 v[148:151], v215 offset:1024
	ds_read_b128 v[152:155], v215 offset:2048
	ds_read_b128 v[156:159], v215 offset:3072
	s_add_u32 s58, s84, 0xfff80080
	s_addc_u32 s59, s85, -1
	s_cmp_eq_u32 s39, 28
	s_cselect_b32 s89, s77, s59
	s_cselect_b32 s88, s83, s58
	s_cselect_b32 s87, s75, s38
	s_cselect_b32 s86, vcc_lo, vcc_hi
	s_add_i32 m0, s7, 0xc000
	ds_read_b128 v[160:163], v216
	ds_read_b128 v[182:185], v216 offset:1024
	ds_read_b128 v[186:189], v216 offset:2048
	ds_read_b128 v[190:193], v216 offset:3072
	ds_read_b128 v[222:225], v216 offset:4096
	ds_read_b128 v[232:235], v216 offset:5120
	ds_read_b128 v[236:239], v216 offset:6144
	ds_read_b128 v[240:243], v216 offset:7168
	global_load_lds_dwordx4 v174, s[84:85]
	s_add_i32 m0, s7, 0xe000
	s_nop 0
	global_load_lds_dwordx4 v176, s[84:85]
	s_waitcnt vmcnt(8) lgkmcnt(0)
	s_barrier
	v_mfma_f32_16x16x32_bf16 v[124:127], v[128:131], v[160:163], 0
	v_mfma_f32_16x16x32_bf16 v[120:123], v[136:139], v[160:163], 0
	v_mfma_f32_16x16x32_bf16 v[116:119], v[128:131], v[186:189], 0
	v_mfma_f32_16x16x32_bf16 v[112:115], v[136:139], v[186:189], 0
	v_mfma_f32_16x16x32_bf16 v[100:103], v[128:131], v[222:225], 0
	v_mfma_f32_16x16x32_bf16 v[96:99], v[136:139], v[222:225], 0
	v_mfma_f32_16x16x32_bf16 v[84:87], v[128:131], v[236:239], 0
	v_mfma_f32_16x16x32_bf16 v[80:83], v[136:139], v[236:239], 0
	v_mfma_f32_16x16x32_bf16 v[124:127], v[132:135], v[182:185], v[124:127]
	v_mfma_f32_16x16x32_bf16 v[120:123], v[140:143], v[182:185], v[120:123]
	v_mfma_f32_16x16x32_bf16 v[116:119], v[132:135], v[190:193], v[116:119]
	v_mfma_f32_16x16x32_bf16 v[112:115], v[140:143], v[190:193], v[112:115]
	v_mfma_f32_16x16x32_bf16 v[100:103], v[132:135], v[232:235], v[100:103]
	v_mfma_f32_16x16x32_bf16 v[96:99], v[140:143], v[232:235], v[96:99]
	v_mfma_f32_16x16x32_bf16 v[84:87], v[132:135], v[240:243], v[84:87]
	v_mfma_f32_16x16x32_bf16 v[80:83], v[140:143], v[240:243], v[80:83]
	v_mfma_f32_16x16x32_bf16 v[108:111], v[144:147], v[160:163], 0
	v_mfma_f32_16x16x32_bf16 v[104:107], v[152:155], v[160:163], 0
	v_mfma_f32_16x16x32_bf16 v[92:95], v[144:147], v[186:189], 0
	v_mfma_f32_16x16x32_bf16 v[88:91], v[152:155], v[186:189], 0
	v_mfma_f32_16x16x32_bf16 v[76:79], v[144:147], v[222:225], 0
	v_mfma_f32_16x16x32_bf16 v[72:75], v[152:155], v[222:225], 0
	v_mfma_f32_16x16x32_bf16 v[68:71], v[144:147], v[236:239], 0
	v_mfma_f32_16x16x32_bf16 v[64:67], v[152:155], v[236:239], 0
	v_mfma_f32_16x16x32_bf16 v[108:111], v[148:151], v[182:185], v[108:111]
	v_mfma_f32_16x16x32_bf16 v[104:107], v[156:159], v[182:185], v[104:107]
	v_mfma_f32_16x16x32_bf16 v[92:95], v[148:151], v[190:193], v[92:95]
	v_mfma_f32_16x16x32_bf16 v[88:91], v[156:159], v[190:193], v[88:91]
	v_mfma_f32_16x16x32_bf16 v[76:79], v[148:151], v[232:235], v[76:79]
	v_mfma_f32_16x16x32_bf16 v[72:75], v[156:159], v[232:235], v[72:75]
	v_mfma_f32_16x16x32_bf16 v[68:71], v[148:151], v[240:243], v[68:71]
	v_mfma_f32_16x16x32_bf16 v[64:67], v[156:159], v[240:243], v[64:67]
	s_barrier
	s_add_i32 s58, s34, s24
	v_lshl_add_u64 v[194:195], s[86:87], 0, v[168:169]
	s_mov_b32 m0, s58
	ds_read_b128 v[160:163], v216 offset:16384
	ds_read_b128 v[182:185], v216 offset:17408
	ds_read_b128 v[186:189], v216 offset:18432
	ds_read_b128 v[190:193], v216 offset:19456
	ds_read_b128 v[222:225], v216 offset:20480
	ds_read_b128 v[232:235], v216 offset:21504
	ds_read_b128 v[236:239], v216 offset:22528
	ds_read_b128 v[240:243], v216 offset:23552
	global_load_lds_dwordx4 v168, s[86:87]
	s_add_i32 m0, s58, 0x2000
	s_add_u32 s58, s86, 0x80000
	v_lshl_add_u64 v[230:231], s[86:87], 0, v[164:165]
	s_addc_u32 s59, s87, 0
	s_add_i32 s48, s35, s24
	global_load_lds_dwordx4 v164, s[86:87]
	s_mov_b32 m0, s48
	v_lshl_add_u64 v[246:247], s[88:89], 0, v[166:167]
	global_load_lds_dwordx4 v168, s[58:59]
	s_add_i32 m0, s48, 0x2000
	s_nop 0
	global_load_lds_dwordx4 v164, s[58:59]
	v_lshl_add_u64 v[244:245], s[88:89], 0, v[170:171]
	s_mov_b32 m0, s7
	s_nop 0
	global_load_lds_dwordx4 v170, s[88:89]
	s_mov_b32 m0, s8
	s_nop 0
	global_load_lds_dwordx4 v166, s[88:89]
	s_waitcnt vmcnt(8) lgkmcnt(0)
	s_barrier
; #define PG8_STAGE(bufoff, gbase, voff) do { _Pragma("unroll") for (int _i = 0; _i < 2; ++_i) \
;         __builtin_amdgcn_global_load_lds((const unsigned*)((const char*)(gbase) + (voff)[_i]), (PG8_LAS unsigned*)(lds + (bufoff) + ldsw + _i * 8192), 16, 0, 0); } while (0)
; #define PG8_LDA(dst, b, h) do { _Pragma("unroll") for (int m = 0; m < 4; ++m) _Pragma("unroll") for (int k = 0; k < 2; ++k) dst[m][k] = *(const PG8_LAS bf16x8*)(lds + PG8_SA(b, h) + aoff + m * 2048 + k * 1024); } while (0)
; #define PG8_LDB(dst, b, h) do { _Pragma("unroll") for (int n = 0; n < 2; ++n) _Pragma("unroll") for (int k = 0; k < 2; ++k) dst[n][k] = *(const PG8_LAS bf16x8*)(lds + PG8_SB(b, h) + boff + n * 2048 + k * 1024); } while (0)
; #define PG8_MMA(ai, bj, At, Bt) do { __builtin_amdgcn_s_setprio(1); _Pragma("unroll") for (int m = 0; m < 4; ++m) _Pragma("unroll") for (int n = 0; n < 2; ++n) _Pragma("unroll") for (int k = 0; k < 2; ++k) \
;         acc[ai][bj][m][n] = __builtin_amdgcn_mfma_f32_16x16x32_bf16(Bt[n][k], At[m][k], acc[ai][bj][m][n], 0, 0, 0); __builtin_amdgcn_s_setprio(0); } while (0)
; #define PG8_WAIT_V(n) asm volatile("s_waitcnt vmcnt(" #n ")" ::: "memory")
; #define PG8_WAIT_L(n) asm volatile("s_waitcnt lgkmcnt(" #n ")" ::: "memory")
; #define PG8_BAR __builtin_amdgcn_s_barrier()
; #define PG8_SCHED __builtin_amdgcn_sched_barrier(0)
; template <class Epi, class Sched, bool ALIGN_EPI = false, bool SP2 = false>
; __device__ __forceinline__ void gemm_phase(PG8_LAS unsigned char* lds, const Gemm g, const Sched& S, const Epi& E) {
;     ...
;             PG8_WAIT_V(8); PG8_WAIT_L(0); PG8_BAR; PG8_MMA(0, 0, At, B0); PG8_MMA(0, 1, At, B1); PG8_BAR; PG8_SCHED;
;             PG8_LDA(At, 0, 1); PG8_STAGE(PG8_SB(0, 0), b2, voffB); PG8_STAGE(PG8_SB(0, 1), b2 + hstep, voffB); PG8_STAGE(PG8_SA(0, 0), a2, voffA);
;             PG8_WAIT_V(8); PG8_WAIT_L(0); PG8_BAR; PG8_MMA(1, 0, At, B0); PG8_MMA(1, 1, At, B1); PG8_BAR; PG8_SCHED;
;             PG8_LDB(B0, 1, 0); PG8_LDB(B1, 1, 1); PG8_SCHED; PG8_LDA(At, 1, 0); PG8_STAGE(PG8_SA(0, 1), a2 + hstep, voffA);
;             PG8_WAIT_V(8); PG8_WAIT_L(0); PG8_BAR; PG8_MMA(0, 0, At, B0); PG8_MMA(0, 1, At, B1); PG8_BAR; PG8_SCHED;
	v_mfma_f32_16x16x32_bf16 v[60:63], v[128:131], v[160:163], 0
	v_mfma_f32_16x16x32_bf16 v[56:59], v[136:139], v[160:163], 0
	v_mfma_f32_16x16x32_bf16 v[52:55], v[128:131], v[186:189], 0
	v_mfma_f32_16x16x32_bf16 v[48:51], v[136:139], v[186:189], 0
	v_mfma_f32_16x16x32_bf16 v[36:39], v[128:131], v[222:225], 0
	v_mfma_f32_16x16x32_bf16 v[32:35], v[136:139], v[222:225], 0
	v_mfma_f32_16x16x32_bf16 v[20:23], v[128:131], v[236:239], 0
	v_mfma_f32_16x16x32_bf16 v[16:19], v[136:139], v[236:239], 0
	v_mfma_f32_16x16x32_bf16 v[60:63], v[132:135], v[182:185], v[60:63]
	v_mfma_f32_16x16x32_bf16 v[56:59], v[140:143], v[182:185], v[56:59]
	v_mfma_f32_16x16x32_bf16 v[52:55], v[132:135], v[190:193], v[52:55]
	v_mfma_f32_16x16x32_bf16 v[48:51], v[140:143], v[190:193], v[48:51]
	v_mfma_f32_16x16x32_bf16 v[36:39], v[132:135], v[232:235], v[36:39]
	v_mfma_f32_16x16x32_bf16 v[32:35], v[140:143], v[232:235], v[32:35]
	v_mfma_f32_16x16x32_bf16 v[20:23], v[132:135], v[240:243], v[20:23]
	v_mfma_f32_16x16x32_bf16 v[16:19], v[140:143], v[240:243], v[16:19]
	v_mfma_f32_16x16x32_bf16 v[44:47], v[144:147], v[160:163], 0
	v_mfma_f32_16x16x32_bf16 v[40:43], v[152:155], v[160:163], 0
	v_mfma_f32_16x16x32_bf16 v[28:31], v[144:147], v[186:189], 0
	v_mfma_f32_16x16x32_bf16 v[24:27], v[152:155], v[186:189], 0
	v_mfma_f32_16x16x32_bf16 v[12:15], v[144:147], v[222:225], 0
	v_mfma_f32_16x16x32_bf16 v[8:11], v[152:155], v[222:225], 0
	v_mfma_f32_16x16x32_bf16 v[4:7], v[144:147], v[236:239], 0
	v_mfma_f32_16x16x32_bf16 v[0:3], v[152:155], v[236:239], 0
	v_mfma_f32_16x16x32_bf16 v[44:47], v[148:151], v[182:185], v[44:47]
	v_mfma_f32_16x16x32_bf16 v[40:43], v[156:159], v[182:185], v[40:43]
	v_mfma_f32_16x16x32_bf16 v[28:31], v[148:151], v[190:193], v[28:31]
	v_mfma_f32_16x16x32_bf16 v[24:27], v[156:159], v[190:193], v[24:27]
	v_mfma_f32_16x16x32_bf16 v[12:15], v[148:151], v[232:235], v[12:15]
	v_mfma_f32_16x16x32_bf16 v[8:11], v[156:159], v[232:235], v[8:11]
	v_mfma_f32_16x16x32_bf16 v[4:7], v[148:151], v[240:243], v[4:7]
	v_mfma_f32_16x16x32_bf16 v[0:3], v[156:159], v[240:243], v[0:3]
	s_barrier
	s_add_i32 s48, 0, 0x18000
	s_add_i32 s60, 0, 0x1c000
	ds_read_b128 v[128:131], v248
	ds_read_b128 v[132:135], v248 offset:1024
	ds_read_b128 v[136:139], v248 offset:2048
	ds_read_b128 v[140:143], v248 offset:3072
	ds_read_b128 v[144:147], v249
	ds_read_b128 v[148:151], v249 offset:1024
	ds_read_b128 v[152:155], v249 offset:2048
	ds_read_b128 v[156:159], v249 offset:3072
	s_add_u32 s58, s88, 0x80000
	s_addc_u32 s59, s89, 0
	s_mov_b32 m0, s9
	ds_read_b128 v[160:163], v216 offset:32768
	ds_read_b128 v[182:185], v216 offset:33792
	ds_read_b128 v[186:189], v216 offset:34816
	ds_read_b128 v[190:193], v216 offset:35840
	ds_read_b128 v[222:225], v216 offset:36864
	ds_read_b128 v[232:235], v216 offset:37888
	ds_read_b128 v[236:239], v216 offset:38912
	ds_read_b128 v[240:243], v216 offset:39936
	global_load_lds_dwordx4 v170, s[58:59]
	s_mov_b32 m0, s26
	s_nop 0
	global_load_lds_dwordx4 v166, s[58:59]
	s_waitcnt vmcnt(8) lgkmcnt(0)
	s_barrier
	v_mfma_f32_16x16x32_bf16 v[124:127], v[128:131], v[160:163], v[124:127]
	v_mfma_f32_16x16x32_bf16 v[120:123], v[136:139], v[160:163], v[120:123]
	v_mfma_f32_16x16x32_bf16 v[116:119], v[128:131], v[186:189], v[116:119]
	v_mfma_f32_16x16x32_bf16 v[112:115], v[136:139], v[186:189], v[112:115]
	v_mfma_f32_16x16x32_bf16 v[100:103], v[128:131], v[222:225], v[100:103]
	v_mfma_f32_16x16x32_bf16 v[96:99], v[136:139], v[222:225], v[96:99]
	v_mfma_f32_16x16x32_bf16 v[84:87], v[128:131], v[236:239], v[84:87]
	v_mfma_f32_16x16x32_bf16 v[80:83], v[136:139], v[236:239], v[80:83]
	v_mfma_f32_16x16x32_bf16 v[124:127], v[132:135], v[182:185], v[124:127]
	v_mfma_f32_16x16x32_bf16 v[120:123], v[140:143], v[182:185], v[120:123]
	v_mfma_f32_16x16x32_bf16 v[116:119], v[132:135], v[190:193], v[116:119]
	v_mfma_f32_16x16x32_bf16 v[112:115], v[140:143], v[190:193], v[112:115]
	v_mfma_f32_16x16x32_bf16 v[100:103], v[132:135], v[232:235], v[100:103]
	v_mfma_f32_16x16x32_bf16 v[96:99], v[140:143], v[232:235], v[96:99]
	v_mfma_f32_16x16x32_bf16 v[84:87], v[132:135], v[240:243], v[84:87]
	v_mfma_f32_16x16x32_bf16 v[80:83], v[140:143], v[240:243], v[80:83]
	v_mfma_f32_16x16x32_bf16 v[108:111], v[144:147], v[160:163], v[108:111]
	v_mfma_f32_16x16x32_bf16 v[104:107], v[152:155], v[160:163], v[104:107]
	v_mfma_f32_16x16x32_bf16 v[92:95], v[144:147], v[186:189], v[92:95]
	v_mfma_f32_16x16x32_bf16 v[88:91], v[152:155], v[186:189], v[88:91]
	v_mfma_f32_16x16x32_bf16 v[76:79], v[144:147], v[222:225], v[76:79]
	v_mfma_f32_16x16x32_bf16 v[72:75], v[152:155], v[222:225], v[72:75]
	v_mfma_f32_16x16x32_bf16 v[68:71], v[144:147], v[236:239], v[68:71]
	v_mfma_f32_16x16x32_bf16 v[64:67], v[152:155], v[236:239], v[64:67]
	v_mfma_f32_16x16x32_bf16 v[108:111], v[148:151], v[182:185], v[108:111]
	v_mfma_f32_16x16x32_bf16 v[104:107], v[156:159], v[182:185], v[104:107]
	v_mfma_f32_16x16x32_bf16 v[92:95], v[148:151], v[190:193], v[92:95]
	v_mfma_f32_16x16x32_bf16 v[88:91], v[156:159], v[190:193], v[88:91]
	v_mfma_f32_16x16x32_bf16 v[76:79], v[148:151], v[232:235], v[76:79]
	v_mfma_f32_16x16x32_bf16 v[72:75], v[156:159], v[232:235], v[72:75]
	v_mfma_f32_16x16x32_bf16 v[68:71], v[148:151], v[240:243], v[68:71]
	v_mfma_f32_16x16x32_bf16 v[64:67], v[156:159], v[240:243], v[64:67]
	s_barrier
; #define PG8_STAGE(bufoff, gbase, voff) do { _Pragma("unroll") for (int _i = 0; _i < 2; ++_i) \
;         __builtin_amdgcn_global_load_lds((const unsigned*)((const char*)(gbase) + (voff)[_i]), (PG8_LAS unsigned*)(lds + (bufoff) + ldsw + _i * 8192), 16, 0, 0); } while (0)
; #define PG8_LDA(dst, b, h) do { _Pragma("unroll") for (int m = 0; m < 4; ++m) _Pragma("unroll") for (int k = 0; k < 2; ++k) dst[m][k] = *(const PG8_LAS bf16x8*)(lds + PG8_SA(b, h) + aoff + m * 2048 + k * 1024); } while (0)
; #define PG8_LDB(dst, b, h) do { _Pragma("unroll") for (int n = 0; n < 2; ++n) _Pragma("unroll") for (int k = 0; k < 2; ++k) dst[n][k] = *(const PG8_LAS bf16x8*)(lds + PG8_SB(b, h) + boff + n * 2048 + k * 1024); } while (0)
; #define PG8_MMA(ai, bj, At, Bt) do { __builtin_amdgcn_s_setprio(1); _Pragma("unroll") for (int m = 0; m < 4; ++m) _Pragma("unroll") for (int n = 0; n < 2; ++n) _Pragma("unroll") for (int k = 0; k < 2; ++k) \
;         acc[ai][bj][m][n] = __builtin_amdgcn_mfma_f32_16x16x32_bf16(Bt[n][k], At[m][k], acc[ai][bj][m][n], 0, 0, 0); __builtin_amdgcn_s_setprio(0); } while (0)
; #define PG8_WAIT_V(n) asm volatile("s_waitcnt vmcnt(" #n ")" ::: "memory")
; #define PG8_WAIT_L(n) asm volatile("s_waitcnt lgkmcnt(" #n ")" ::: "memory")
; #define PG8_BAR __builtin_amdgcn_s_barrier()
; #define PG8_SCHED __builtin_amdgcn_sched_barrier(0)
; template <class Epi, class Sched, bool ALIGN_EPI = false, bool SP2 = false>
; __device__ __forceinline__ void gemm_phase(PG8_LAS unsigned char* lds, const Gemm g, const Sched& S, const Epi& E) {
;     ...
;             PG8_LDB(B0, 0, 0); PG8_LDB(B1, 0, 1); PG8_SCHED; PG8_LDA(At, 0, 0); PG8_STAGE(PG8_SA(1, 1), a1 + hstep, voffA);
;     ...
;             PG8_LDA(At, 1, 1); PG8_STAGE(PG8_SB(1, 0), b3, voffB); PG8_STAGE(PG8_SB(1, 1), b3 + hstep, voffB); PG8_STAGE(PG8_SA(1, 0), a3, voffA);
;             PG8_WAIT_V(8); PG8_WAIT_L(0); PG8_BAR; PG8_MMA(1, 0, At, B0); PG8_MMA(1, 1, At, B1); PG8_BAR; PG8_SCHED;
	s_add_i32 s48, s48, s24
	v_lshl_add_u64 v[194:195], v[194:195], 0, s[54:55]
	s_mov_b32 m0, s48
	ds_read_b128 v[160:163], v216 offset:49152
	ds_read_b128 v[182:185], v216 offset:50176
	ds_read_b128 v[186:189], v216 offset:51200
	ds_read_b128 v[190:193], v216 offset:52224
	ds_read_b128 v[222:225], v216 offset:53248
	ds_read_b128 v[232:235], v216 offset:54272
	ds_read_b128 v[236:239], v216 offset:55296
	ds_read_b128 v[240:243], v216 offset:56320
	global_load_lds_dwordx4 v[194:195], off
	s_add_i32 m0, s48, 0x2000
	s_add_u32 s58, s86, 0x80080
	v_lshl_add_u64 v[194:195], v[230:231], 0, s[54:55]
	s_addc_u32 s59, s87, 0
	s_add_i32 s48, s60, s24
	global_load_lds_dwordx4 v[194:195], off
	s_mov_b32 m0, s48
	s_nop 0
	global_load_lds_dwordx4 v168, s[58:59]
	s_add_i32 m0, s48, 0x2000
	s_nop 0
	global_load_lds_dwordx4 v164, s[58:59]
	v_lshl_add_u64 v[194:195], v[244:245], 0, s[54:55]
	s_mov_b32 m0, s36
	s_nop 0
	global_load_lds_dwordx4 v[194:195], off
	v_lshl_add_u64 v[194:195], v[246:247], 0, s[54:55]
	s_mov_b32 m0, s37
	s_nop 0
	global_load_lds_dwordx4 v[194:195], off
	s_waitcnt vmcnt(8) lgkmcnt(0)
	s_barrier
	v_mfma_f32_16x16x32_bf16 v[60:63], v[128:131], v[160:163], v[60:63]
	v_mfma_f32_16x16x32_bf16 v[56:59], v[136:139], v[160:163], v[56:59]
	v_mfma_f32_16x16x32_bf16 v[52:55], v[128:131], v[186:189], v[52:55]
	v_mfma_f32_16x16x32_bf16 v[48:51], v[136:139], v[186:189], v[48:51]
	v_mfma_f32_16x16x32_bf16 v[36:39], v[128:131], v[222:225], v[36:39]
	v_mfma_f32_16x16x32_bf16 v[32:35], v[136:139], v[222:225], v[32:35]
	v_mfma_f32_16x16x32_bf16 v[20:23], v[128:131], v[236:239], v[20:23]
	v_mfma_f32_16x16x32_bf16 v[16:19], v[136:139], v[236:239], v[16:19]
	v_mfma_f32_16x16x32_bf16 v[60:63], v[132:135], v[182:185], v[60:63]
	v_mfma_f32_16x16x32_bf16 v[56:59], v[140:143], v[182:185], v[56:59]
	v_mfma_f32_16x16x32_bf16 v[52:55], v[132:135], v[190:193], v[52:55]
	v_mfma_f32_16x16x32_bf16 v[48:51], v[140:143], v[190:193], v[48:51]
	v_mfma_f32_16x16x32_bf16 v[36:39], v[132:135], v[232:235], v[36:39]
	v_mfma_f32_16x16x32_bf16 v[32:35], v[140:143], v[232:235], v[32:35]
	v_mfma_f32_16x16x32_bf16 v[20:23], v[132:135], v[240:243], v[20:23]
	v_mfma_f32_16x16x32_bf16 v[16:19], v[140:143], v[240:243], v[16:19]
	v_mfma_f32_16x16x32_bf16 v[44:47], v[144:147], v[160:163], v[44:47]
	v_mfma_f32_16x16x32_bf16 v[40:43], v[152:155], v[160:163], v[40:43]
	v_mfma_f32_16x16x32_bf16 v[28:31], v[144:147], v[186:189], v[28:31]
	v_mfma_f32_16x16x32_bf16 v[24:27], v[152:155], v[186:189], v[24:27]
	v_mfma_f32_16x16x32_bf16 v[12:15], v[144:147], v[222:225], v[12:15]
	v_mfma_f32_16x16x32_bf16 v[8:11], v[152:155], v[222:225], v[8:11]
	v_mfma_f32_16x16x32_bf16 v[4:7], v[144:147], v[236:239], v[4:7]
	v_mfma_f32_16x16x32_bf16 v[0:3], v[152:155], v[236:239], v[0:3]
	v_mfma_f32_16x16x32_bf16 v[44:47], v[148:151], v[182:185], v[44:47]
	v_mfma_f32_16x16x32_bf16 v[40:43], v[156:159], v[182:185], v[40:43]
	v_mfma_f32_16x16x32_bf16 v[28:31], v[148:151], v[190:193], v[28:31]
	v_mfma_f32_16x16x32_bf16 v[24:27], v[156:159], v[190:193], v[24:27]
	v_mfma_f32_16x16x32_bf16 v[12:15], v[148:151], v[232:235], v[12:15]
	v_mfma_f32_16x16x32_bf16 v[8:11], v[156:159], v[232:235], v[8:11]
	v_mfma_f32_16x16x32_bf16 v[4:7], v[148:151], v[240:243], v[4:7]
	v_mfma_f32_16x16x32_bf16 v[0:3], v[156:159], v[240:243], v[0:3]
	s_barrier
	s_add_i32 s39, s39, 2
	s_add_u32 s84, s84, 0x100
	s_addc_u32 s85, s85, 0
	s_add_u32 vcc_hi, vcc_hi, 0x100
	s_addc_u32 s38, s38, 0
	s_cmp_gt_u32 s39, 29
.LBB0_364:
	ds_read_b128 v[128:131], v214
	ds_read_b128 v[132:135], v214 offset:1024
	ds_read_b128 v[136:139], v214 offset:2048
	ds_read_b128 v[140:143], v214 offset:3072
	ds_read_b128 v[144:147], v215
	ds_read_b128 v[148:151], v215 offset:1024
	ds_read_b128 v[152:155], v215 offset:2048
	ds_read_b128 v[156:159], v215 offset:3072
	s_add_u32 s58, s84, 0xfff80080
	s_addc_u32 s59, s85, -1
	s_cmp_eq_u32 s39, 28
	s_cselect_b32 s89, s77, s59
	s_cselect_b32 s88, s83, s58
	s_cselect_b32 s87, s75, s38
	s_cselect_b32 s86, vcc_lo, vcc_hi
	s_add_i32 m0, s7, 0xc000
	ds_read_b128 v[160:163], v216
	ds_read_b128 v[182:185], v216 offset:1024
	ds_read_b128 v[186:189], v216 offset:2048
	ds_read_b128 v[190:193], v216 offset:3072
	ds_read_b128 v[222:225], v216 offset:4096
	ds_read_b128 v[232:235], v216 offset:5120
	ds_read_b128 v[236:239], v216 offset:6144
	ds_read_b128 v[240:243], v216 offset:7168
	global_load_lds_dwordx4 v174, s[84:85]
	s_add_i32 m0, s7, 0xe000
	s_nop 0
	global_load_lds_dwordx4 v176, s[84:85]
	s_waitcnt vmcnt(8) lgkmcnt(0)
	s_barrier
; #define PG8_STAGE(bufoff, gbase, voff) do { _Pragma("unroll") for (int _i = 0; _i < 2; ++_i) \
;         __builtin_amdgcn_global_load_lds((const unsigned*)((const char*)(gbase) + (voff)[_i]), (PG8_LAS unsigned*)(lds + (bufoff) + ldsw + _i * 8192), 16, 0, 0); } while (0)
; #define PG8_LDA(dst, b, h) do { _Pragma("unroll") for (int m = 0; m < 4; ++m) _Pragma("unroll") for (int k = 0; k < 2; ++k) dst[m][k] = *(const PG8_LAS bf16x8*)(lds + PG8_SA(b, h) + aoff + m * 2048 + k * 1024); } while (0)
; #define PG8_MMA(ai, bj, At, Bt) do { __builtin_amdgcn_s_setprio(1); _Pragma("unroll") for (int m = 0; m < 4; ++m) _Pragma("unroll") for (int n = 0; n < 2; ++n) _Pragma("unroll") for (int k = 0; k < 2; ++k) \
;         acc[ai][bj][m][n] = __builtin_amdgcn_mfma_f32_16x16x32_bf16(Bt[n][k], At[m][k], acc[ai][bj][m][n], 0, 0, 0); __builtin_amdgcn_s_setprio(0); } while (0)
; #define PG8_WAIT_V(n) asm volatile("s_waitcnt vmcnt(" #n ")" ::: "memory")
; #define PG8_WAIT_L(n) asm volatile("s_waitcnt lgkmcnt(" #n ")" ::: "memory")
; #define PG8_BAR __builtin_amdgcn_s_barrier()
; #define PG8_SCHED __builtin_amdgcn_sched_barrier(0)
; template <class Epi, class Sched, bool ALIGN_EPI = false, bool SP2 = false>
; __device__ __forceinline__ void gemm_phase(PG8_LAS unsigned char* lds, const Gemm g, const Sched& S, const Epi& E) {
;     ...
;             PG8_WAIT_V(8); PG8_WAIT_L(0); PG8_BAR; PG8_MMA(0, 0, At, B0); PG8_MMA(0, 1, At, B1); PG8_BAR; PG8_SCHED;
;             PG8_LDA(At, 0, 1); PG8_STAGE(PG8_SB(0, 0), b2, voffB); PG8_STAGE(PG8_SB(0, 1), b2 + hstep, voffB); PG8_STAGE(PG8_SA(0, 0), a2, voffA);
;             PG8_WAIT_V(8); PG8_WAIT_L(0); PG8_BAR; PG8_MMA(1, 0, At, B0); PG8_MMA(1, 1, At, B1); PG8_BAR; PG8_SCHED;
	v_mfma_f32_16x16x32_bf16 v[124:127], v[128:131], v[160:163], v[124:127]
	v_mfma_f32_16x16x32_bf16 v[120:123], v[136:139], v[160:163], v[120:123]
	v_mfma_f32_16x16x32_bf16 v[116:119], v[128:131], v[186:189], v[116:119]
	v_mfma_f32_16x16x32_bf16 v[112:115], v[136:139], v[186:189], v[112:115]
	v_mfma_f32_16x16x32_bf16 v[100:103], v[128:131], v[222:225], v[100:103]
	v_mfma_f32_16x16x32_bf16 v[96:99], v[136:139], v[222:225], v[96:99]
	v_mfma_f32_16x16x32_bf16 v[84:87], v[128:131], v[236:239], v[84:87]
	v_mfma_f32_16x16x32_bf16 v[80:83], v[136:139], v[236:239], v[80:83]
	v_mfma_f32_16x16x32_bf16 v[124:127], v[132:135], v[182:185], v[124:127]
	v_mfma_f32_16x16x32_bf16 v[120:123], v[140:143], v[182:185], v[120:123]
	v_mfma_f32_16x16x32_bf16 v[116:119], v[132:135], v[190:193], v[116:119]
	v_mfma_f32_16x16x32_bf16 v[112:115], v[140:143], v[190:193], v[112:115]
	v_mfma_f32_16x16x32_bf16 v[100:103], v[132:135], v[232:235], v[100:103]
	v_mfma_f32_16x16x32_bf16 v[96:99], v[140:143], v[232:235], v[96:99]
	v_mfma_f32_16x16x32_bf16 v[84:87], v[132:135], v[240:243], v[84:87]
	v_mfma_f32_16x16x32_bf16 v[80:83], v[140:143], v[240:243], v[80:83]
	v_mfma_f32_16x16x32_bf16 v[108:111], v[144:147], v[160:163], v[108:111]
	v_mfma_f32_16x16x32_bf16 v[104:107], v[152:155], v[160:163], v[104:107]
	v_mfma_f32_16x16x32_bf16 v[92:95], v[144:147], v[186:189], v[92:95]
	v_mfma_f32_16x16x32_bf16 v[88:91], v[152:155], v[186:189], v[88:91]
	v_mfma_f32_16x16x32_bf16 v[76:79], v[144:147], v[222:225], v[76:79]
	v_mfma_f32_16x16x32_bf16 v[72:75], v[152:155], v[222:225], v[72:75]
	v_mfma_f32_16x16x32_bf16 v[68:71], v[144:147], v[236:239], v[68:71]
	v_mfma_f32_16x16x32_bf16 v[64:67], v[152:155], v[236:239], v[64:67]
	v_mfma_f32_16x16x32_bf16 v[108:111], v[148:151], v[182:185], v[108:111]
	v_mfma_f32_16x16x32_bf16 v[104:107], v[156:159], v[182:185], v[104:107]
	v_mfma_f32_16x16x32_bf16 v[92:95], v[148:151], v[190:193], v[92:95]
	v_mfma_f32_16x16x32_bf16 v[88:91], v[156:159], v[190:193], v[88:91]
	v_mfma_f32_16x16x32_bf16 v[76:79], v[148:151], v[232:235], v[76:79]
	v_mfma_f32_16x16x32_bf16 v[72:75], v[156:159], v[232:235], v[72:75]
	v_mfma_f32_16x16x32_bf16 v[68:71], v[148:151], v[240:243], v[68:71]
	v_mfma_f32_16x16x32_bf16 v[64:67], v[156:159], v[240:243], v[64:67]
	s_barrier
	s_add_i32 s58, s34, s24
	v_lshl_add_u64 v[194:195], s[86:87], 0, v[168:169]
	s_mov_b32 m0, s58
	ds_read_b128 v[160:163], v216 offset:16384
	ds_read_b128 v[182:185], v216 offset:17408
	ds_read_b128 v[186:189], v216 offset:18432
	ds_read_b128 v[190:193], v216 offset:19456
	ds_read_b128 v[222:225], v216 offset:20480
	ds_read_b128 v[232:235], v216 offset:21504
	ds_read_b128 v[236:239], v216 offset:22528
	ds_read_b128 v[240:243], v216 offset:23552
	global_load_lds_dwordx4 v168, s[86:87]
	s_add_i32 m0, s58, 0x2000
	s_add_u32 s58, s86, 0x80000
	v_lshl_add_u64 v[230:231], s[86:87], 0, v[164:165]
	s_addc_u32 s59, s87, 0
	s_add_i32 s48, s35, s24
	global_load_lds_dwordx4 v164, s[86:87]
	s_mov_b32 m0, s48
	v_lshl_add_u64 v[246:247], s[88:89], 0, v[166:167]
	global_load_lds_dwordx4 v168, s[58:59]
	s_add_i32 m0, s48, 0x2000
	s_nop 0
	global_load_lds_dwordx4 v164, s[58:59]
	v_lshl_add_u64 v[244:245], s[88:89], 0, v[170:171]
	s_mov_b32 m0, s7
	s_nop 0
	global_load_lds_dwordx4 v170, s[88:89]
	s_mov_b32 m0, s8
	s_nop 0
	global_load_lds_dwordx4 v166, s[88:89]
	s_waitcnt vmcnt(8) lgkmcnt(0)
	s_barrier
	v_mfma_f32_16x16x32_bf16 v[60:63], v[128:131], v[160:163], v[60:63]
	v_mfma_f32_16x16x32_bf16 v[56:59], v[136:139], v[160:163], v[56:59]
	v_mfma_f32_16x16x32_bf16 v[52:55], v[128:131], v[186:189], v[52:55]
	v_mfma_f32_16x16x32_bf16 v[48:51], v[136:139], v[186:189], v[48:51]
	v_mfma_f32_16x16x32_bf16 v[36:39], v[128:131], v[222:225], v[36:39]
	v_mfma_f32_16x16x32_bf16 v[32:35], v[136:139], v[222:225], v[32:35]
	v_mfma_f32_16x16x32_bf16 v[20:23], v[128:131], v[236:239], v[20:23]
	v_mfma_f32_16x16x32_bf16 v[16:19], v[136:139], v[236:239], v[16:19]
	v_mfma_f32_16x16x32_bf16 v[60:63], v[132:135], v[182:185], v[60:63]
	v_mfma_f32_16x16x32_bf16 v[56:59], v[140:143], v[182:185], v[56:59]
	v_mfma_f32_16x16x32_bf16 v[52:55], v[132:135], v[190:193], v[52:55]
	v_mfma_f32_16x16x32_bf16 v[48:51], v[140:143], v[190:193], v[48:51]
	v_mfma_f32_16x16x32_bf16 v[36:39], v[132:135], v[232:235], v[36:39]
	v_mfma_f32_16x16x32_bf16 v[32:35], v[140:143], v[232:235], v[32:35]
	v_mfma_f32_16x16x32_bf16 v[20:23], v[132:135], v[240:243], v[20:23]
	v_mfma_f32_16x16x32_bf16 v[16:19], v[140:143], v[240:243], v[16:19]
	v_mfma_f32_16x16x32_bf16 v[44:47], v[144:147], v[160:163], v[44:47]
	v_mfma_f32_16x16x32_bf16 v[40:43], v[152:155], v[160:163], v[40:43]
	v_mfma_f32_16x16x32_bf16 v[28:31], v[144:147], v[186:189], v[28:31]
	v_mfma_f32_16x16x32_bf16 v[24:27], v[152:155], v[186:189], v[24:27]
	v_mfma_f32_16x16x32_bf16 v[12:15], v[144:147], v[222:225], v[12:15]
	v_mfma_f32_16x16x32_bf16 v[8:11], v[152:155], v[222:225], v[8:11]
	v_mfma_f32_16x16x32_bf16 v[4:7], v[144:147], v[236:239], v[4:7]
	v_mfma_f32_16x16x32_bf16 v[0:3], v[152:155], v[236:239], v[0:3]
	v_mfma_f32_16x16x32_bf16 v[44:47], v[148:151], v[182:185], v[44:47]
	v_mfma_f32_16x16x32_bf16 v[40:43], v[156:159], v[182:185], v[40:43]
	v_mfma_f32_16x16x32_bf16 v[28:31], v[148:151], v[190:193], v[28:31]
	v_mfma_f32_16x16x32_bf16 v[24:27], v[156:159], v[190:193], v[24:27]
	v_mfma_f32_16x16x32_bf16 v[12:15], v[148:151], v[232:235], v[12:15]
	v_mfma_f32_16x16x32_bf16 v[8:11], v[156:159], v[232:235], v[8:11]
	v_mfma_f32_16x16x32_bf16 v[4:7], v[148:151], v[240:243], v[4:7]
	v_mfma_f32_16x16x32_bf16 v[0:3], v[156:159], v[240:243], v[0:3]
	s_barrier
; #define PG8_STAGE(bufoff, gbase, voff) do { _Pragma("unroll") for (int _i = 0; _i < 2; ++_i) \
;         __builtin_amdgcn_global_load_lds((const unsigned*)((const char*)(gbase) + (voff)[_i]), (PG8_LAS unsigned*)(lds + (bufoff) + ldsw + _i * 8192), 16, 0, 0); } while (0)
; #define PG8_LDA(dst, b, h) do { _Pragma("unroll") for (int m = 0; m < 4; ++m) _Pragma("unroll") for (int k = 0; k < 2; ++k) dst[m][k] = *(const PG8_LAS bf16x8*)(lds + PG8_SA(b, h) + aoff + m * 2048 + k * 1024); } while (0)
; #define PG8_LDB(dst, b, h) do { _Pragma("unroll") for (int n = 0; n < 2; ++n) _Pragma("unroll") for (int k = 0; k < 2; ++k) dst[n][k] = *(const PG8_LAS bf16x8*)(lds + PG8_SB(b, h) + boff + n * 2048 + k * 1024); } while (0)
; #define PG8_MMA(ai, bj, At, Bt) do { __builtin_amdgcn_s_setprio(1); _Pragma("unroll") for (int m = 0; m < 4; ++m) _Pragma("unroll") for (int n = 0; n < 2; ++n) _Pragma("unroll") for (int k = 0; k < 2; ++k) \
;         acc[ai][bj][m][n] = __builtin_amdgcn_mfma_f32_16x16x32_bf16(Bt[n][k], At[m][k], acc[ai][bj][m][n], 0, 0, 0); __builtin_amdgcn_s_setprio(0); } while (0)
; #define PG8_WAIT_V(n) asm volatile("s_waitcnt vmcnt(" #n ")" ::: "memory")
; #define PG8_WAIT_L(n) asm volatile("s_waitcnt lgkmcnt(" #n ")" ::: "memory")
; #define PG8_BAR __builtin_amdgcn_s_barrier()
; #define PG8_SCHED __builtin_amdgcn_sched_barrier(0)
; template <class Epi, class Sched, bool ALIGN_EPI = false, bool SP2 = false>
; __device__ __forceinline__ void gemm_phase(PG8_LAS unsigned char* lds, const Gemm g, const Sched& S, const Epi& E) {
;     ...
;             PG8_LDB(B0, 1, 0); PG8_LDB(B1, 1, 1); PG8_SCHED; PG8_LDA(At, 1, 0); PG8_STAGE(PG8_SA(0, 1), a2 + hstep, voffA);
;             PG8_WAIT_V(8); PG8_WAIT_L(0); PG8_BAR; PG8_MMA(0, 0, At, B0); PG8_MMA(0, 1, At, B1); PG8_BAR; PG8_SCHED;
;             PG8_LDA(At, 1, 1); PG8_STAGE(PG8_SB(1, 0), b3, voffB); PG8_STAGE(PG8_SB(1, 1), b3 + hstep, voffB); PG8_STAGE(PG8_SA(1, 0), a3, voffA);
;             PG8_WAIT_V(8); PG8_WAIT_L(0); PG8_BAR; PG8_MMA(1, 0, At, B0); PG8_MMA(1, 1, At, B1); PG8_BAR; PG8_SCHED;
	s_add_i32 s48, 0, 0x18000
	s_add_i32 s60, 0, 0x1c000
	ds_read_b128 v[128:131], v248
	ds_read_b128 v[132:135], v248 offset:1024
	ds_read_b128 v[136:139], v248 offset:2048
	ds_read_b128 v[140:143], v248 offset:3072
	ds_read_b128 v[144:147], v249
	ds_read_b128 v[148:151], v249 offset:1024
	ds_read_b128 v[152:155], v249 offset:2048
	ds_read_b128 v[156:159], v249 offset:3072
	s_add_u32 s58, s88, 0x80000
	s_addc_u32 s59, s89, 0
	s_mov_b32 m0, s9
	ds_read_b128 v[160:163], v216 offset:32768
	ds_read_b128 v[182:185], v216 offset:33792
	ds_read_b128 v[186:189], v216 offset:34816
	ds_read_b128 v[190:193], v216 offset:35840
	ds_read_b128 v[222:225], v216 offset:36864
	ds_read_b128 v[232:235], v216 offset:37888
	ds_read_b128 v[236:239], v216 offset:38912
	ds_read_b128 v[240:243], v216 offset:39936
	global_load_lds_dwordx4 v170, s[58:59]
	s_mov_b32 m0, s26
	s_nop 0
	global_load_lds_dwordx4 v166, s[58:59]
	s_waitcnt vmcnt(8) lgkmcnt(0)
	s_barrier
	v_mfma_f32_16x16x32_bf16 v[124:127], v[128:131], v[160:163], v[124:127]
	v_mfma_f32_16x16x32_bf16 v[120:123], v[136:139], v[160:163], v[120:123]
	v_mfma_f32_16x16x32_bf16 v[116:119], v[128:131], v[186:189], v[116:119]
	v_mfma_f32_16x16x32_bf16 v[112:115], v[136:139], v[186:189], v[112:115]
	v_mfma_f32_16x16x32_bf16 v[100:103], v[128:131], v[222:225], v[100:103]
	v_mfma_f32_16x16x32_bf16 v[96:99], v[136:139], v[222:225], v[96:99]
	v_mfma_f32_16x16x32_bf16 v[84:87], v[128:131], v[236:239], v[84:87]
	v_mfma_f32_16x16x32_bf16 v[80:83], v[136:139], v[236:239], v[80:83]
	v_mfma_f32_16x16x32_bf16 v[124:127], v[132:135], v[182:185], v[124:127]
	v_mfma_f32_16x16x32_bf16 v[120:123], v[140:143], v[182:185], v[120:123]
	v_mfma_f32_16x16x32_bf16 v[116:119], v[132:135], v[190:193], v[116:119]
	v_mfma_f32_16x16x32_bf16 v[112:115], v[140:143], v[190:193], v[112:115]
	v_mfma_f32_16x16x32_bf16 v[100:103], v[132:135], v[232:235], v[100:103]
	v_mfma_f32_16x16x32_bf16 v[96:99], v[140:143], v[232:235], v[96:99]
	v_mfma_f32_16x16x32_bf16 v[84:87], v[132:135], v[240:243], v[84:87]
	v_mfma_f32_16x16x32_bf16 v[80:83], v[140:143], v[240:243], v[80:83]
	v_mfma_f32_16x16x32_bf16 v[108:111], v[144:147], v[160:163], v[108:111]
	v_mfma_f32_16x16x32_bf16 v[104:107], v[152:155], v[160:163], v[104:107]
	v_mfma_f32_16x16x32_bf16 v[92:95], v[144:147], v[186:189], v[92:95]
	v_mfma_f32_16x16x32_bf16 v[88:91], v[152:155], v[186:189], v[88:91]
	v_mfma_f32_16x16x32_bf16 v[76:79], v[144:147], v[222:225], v[76:79]
	v_mfma_f32_16x16x32_bf16 v[72:75], v[152:155], v[222:225], v[72:75]
	v_mfma_f32_16x16x32_bf16 v[68:71], v[144:147], v[236:239], v[68:71]
	v_mfma_f32_16x16x32_bf16 v[64:67], v[152:155], v[236:239], v[64:67]
	v_mfma_f32_16x16x32_bf16 v[108:111], v[148:151], v[182:185], v[108:111]
	v_mfma_f32_16x16x32_bf16 v[104:107], v[156:159], v[182:185], v[104:107]
	v_mfma_f32_16x16x32_bf16 v[92:95], v[148:151], v[190:193], v[92:95]
	v_mfma_f32_16x16x32_bf16 v[88:91], v[156:159], v[190:193], v[88:91]
	v_mfma_f32_16x16x32_bf16 v[76:79], v[148:151], v[232:235], v[76:79]
	v_mfma_f32_16x16x32_bf16 v[72:75], v[156:159], v[232:235], v[72:75]
	v_mfma_f32_16x16x32_bf16 v[68:71], v[148:151], v[240:243], v[68:71]
	v_mfma_f32_16x16x32_bf16 v[64:67], v[156:159], v[240:243], v[64:67]
	s_barrier
	s_add_i32 s48, s48, s24
	v_lshl_add_u64 v[194:195], v[194:195], 0, s[54:55]
	s_mov_b32 m0, s48
	ds_read_b128 v[160:163], v216 offset:49152
	ds_read_b128 v[182:185], v216 offset:50176
	ds_read_b128 v[186:189], v216 offset:51200
	ds_read_b128 v[190:193], v216 offset:52224
	ds_read_b128 v[222:225], v216 offset:53248
	ds_read_b128 v[232:235], v216 offset:54272
	ds_read_b128 v[236:239], v216 offset:55296
	ds_read_b128 v[240:243], v216 offset:56320
	global_load_lds_dwordx4 v[194:195], off
	s_add_i32 m0, s48, 0x2000
	s_add_u32 s58, s86, 0x80080
	v_lshl_add_u64 v[194:195], v[230:231], 0, s[54:55]
	s_addc_u32 s59, s87, 0
	s_add_i32 s48, s60, s24
	global_load_lds_dwordx4 v[194:195], off
	s_mov_b32 m0, s48
	s_nop 0
	global_load_lds_dwordx4 v168, s[58:59]
	s_add_i32 m0, s48, 0x2000
	s_nop 0
	global_load_lds_dwordx4 v164, s[58:59]
	v_lshl_add_u64 v[194:195], v[244:245], 0, s[54:55]
	s_mov_b32 m0, s36
	s_nop 0
	global_load_lds_dwordx4 v[194:195], off
	v_lshl_add_u64 v[194:195], v[246:247], 0, s[54:55]
	s_mov_b32 m0, s37
	s_nop 0
	global_load_lds_dwordx4 v[194:195], off
	s_waitcnt vmcnt(8) lgkmcnt(0)
	s_barrier
	v_mfma_f32_16x16x32_bf16 v[60:63], v[128:131], v[160:163], v[60:63]
	v_mfma_f32_16x16x32_bf16 v[56:59], v[136:139], v[160:163], v[56:59]
	v_mfma_f32_16x16x32_bf16 v[52:55], v[128:131], v[186:189], v[52:55]
	v_mfma_f32_16x16x32_bf16 v[48:51], v[136:139], v[186:189], v[48:51]
	v_mfma_f32_16x16x32_bf16 v[36:39], v[128:131], v[222:225], v[36:39]
	v_mfma_f32_16x16x32_bf16 v[32:35], v[136:139], v[222:225], v[32:35]
	v_mfma_f32_16x16x32_bf16 v[20:23], v[128:131], v[236:239], v[20:23]
	v_mfma_f32_16x16x32_bf16 v[16:19], v[136:139], v[236:239], v[16:19]
	v_mfma_f32_16x16x32_bf16 v[60:63], v[132:135], v[182:185], v[60:63]
	v_mfma_f32_16x16x32_bf16 v[56:59], v[140:143], v[182:185], v[56:59]
	v_mfma_f32_16x16x32_bf16 v[52:55], v[132:135], v[190:193], v[52:55]
	v_mfma_f32_16x16x32_bf16 v[48:51], v[140:143], v[190:193], v[48:51]
	v_mfma_f32_16x16x32_bf16 v[36:39], v[132:135], v[232:235], v[36:39]
	v_mfma_f32_16x16x32_bf16 v[32:35], v[140:143], v[232:235], v[32:35]
	v_mfma_f32_16x16x32_bf16 v[20:23], v[132:135], v[240:243], v[20:23]
	v_mfma_f32_16x16x32_bf16 v[16:19], v[140:143], v[240:243], v[16:19]
	v_mfma_f32_16x16x32_bf16 v[44:47], v[144:147], v[160:163], v[44:47]
	v_mfma_f32_16x16x32_bf16 v[40:43], v[152:155], v[160:163], v[40:43]
	v_mfma_f32_16x16x32_bf16 v[28:31], v[144:147], v[186:189], v[28:31]
	v_mfma_f32_16x16x32_bf16 v[24:27], v[152:155], v[186:189], v[24:27]
	v_mfma_f32_16x16x32_bf16 v[12:15], v[144:147], v[222:225], v[12:15]
	v_mfma_f32_16x16x32_bf16 v[8:11], v[152:155], v[222:225], v[8:11]
	v_mfma_f32_16x16x32_bf16 v[4:7], v[144:147], v[236:239], v[4:7]
	v_mfma_f32_16x16x32_bf16 v[0:3], v[152:155], v[236:239], v[0:3]
	v_mfma_f32_16x16x32_bf16 v[44:47], v[148:151], v[182:185], v[44:47]
	v_mfma_f32_16x16x32_bf16 v[40:43], v[156:159], v[182:185], v[40:43]
	v_mfma_f32_16x16x32_bf16 v[28:31], v[148:151], v[190:193], v[28:31]
	v_mfma_f32_16x16x32_bf16 v[24:27], v[156:159], v[190:193], v[24:27]
	v_mfma_f32_16x16x32_bf16 v[12:15], v[148:151], v[232:235], v[12:15]
	v_mfma_f32_16x16x32_bf16 v[8:11], v[156:159], v[232:235], v[8:11]
	v_mfma_f32_16x16x32_bf16 v[4:7], v[148:151], v[240:243], v[4:7]
	v_mfma_f32_16x16x32_bf16 v[0:3], v[156:159], v[240:243], v[0:3]
	s_barrier
; __device__ __forceinline__ float fsigmoid(float v) { return __builtin_amdgcn_rcpf(1.0f + __builtin_amdgcn_exp2f(-LOG2E * v)); }
; __device__ __forceinline__ float fsilu(float v) { return v * fsigmoid(v); }
; __device__ __forceinline__ u32x4 pack8(const f32x4 a, const f32x4 b) { u32x4 w; w.x = cvt_pk_bf16(a[0], a[1]); w.y = cvt_pk_bf16(a[2], a[3]); w.z = cvt_pk_bf16(b[0], b[1]); w.w = cvt_pk_bf16(b[2], b[3]); return w; }
;     template <int ACT> __device__ __forceinline__ void ew(const f32x4 (&acc)[2][2][4][2], bf16_t* D, int ld, int row0, int col0) const {
; #pragma unroll
;         for (int ai = 0; ai < 2; ++ai)
; #pragma unroll
;             for (int m = 0; m < 4; ++m) { bf16_t* rowp = D + (size_t)(row0 + ai * HALF + m * 16) * ld + col0;
; #pragma unroll
;                 for (int bj = 0; bj < 2; ++bj) { f32x4 v0 = acc[ai][bj][m][0], v1 = acc[ai][bj][m][1];
;                     if (ACT == 1) {
; #pragma unroll
;                         for (int j = 0; j < 4; ++j) { v0[j] = fsilu(v0[j]); v1[j] = fsilu(v1[j]); } }
;                     if (ACT == 2) {
; #pragma unroll
;                         for (int j = 0; j < 4; ++j) { v0[j] = fsigmoid(v0[j]); v1[j] = fsigmoid(v1[j]); } }
;                     *(u32x4*)(rowp + bj * HALF) = pack8(v0, v1); } }
;     __device__ __forceinline__ void operator()(const f32x4 (&acc)[2][2][4][2], const Unit& u, int wr, int wc, int fr, int fq) const {
;         const int pn = u.pn, row0 = u.pm * BM + wr * 64 + fr, cl = wc * 32 + 8 * fq;
;         if (pn < 4) ew<0>(acc, HQ, 1024, row0, pn * 256 + cl);
;     ...
;         else if (pn < 28) ew<0>(acc, DV, 1024, row0, (pn - 24) * 256 + cl);
;         else if (pn < 36) ew<2>(acc, SGA, 2048, row0, (pn - 28) * 256 + cl);
;         else ew<2>(acc, SGB, 2048, row0, (pn - 36) * 256 + cl);
	s_add_i32 s39, s39, 2
	s_add_u32 s84, s84, 0x100
	s_addc_u32 s85, s85, 0
	s_add_u32 vcc_hi, vcc_hi, 0x100
	s_addc_u32 s38, s38, 0
	s_cmp_gt_u32 s39, 29
	s_cbranch_scc0 .LBB0_364
	v_lshl_add_u32 v182, s82, 8, v196
	s_cmp_gt_i32 s23, 3
	s_mov_b64 s[82:83], -1
	s_cbranch_scc0 .LBB0_391
	s_cmp_gt_u32 s23, 7
	s_cbranch_scc0 .LBB0_388
	s_cmp_gt_u32 s23, 11
	s_cbranch_scc0 .LBB0_385
	s_cmp_gt_u32 s23, 15
	s_cbranch_scc0 .LBB0_382
	s_cmp_gt_u32 s23, 23
	s_cbranch_scc0 .LBB0_379
	s_lshl_b32 s75, s23, 8
	s_cmp_gt_u32 s23, 27
	s_cbranch_scc0 .LBB0_376
	v_mul_f32_e32 v129, 0xbfb8aa3b, v120
	v_exp_f32_e32 v129, v129
	v_mul_f32_e32 v130, 0xbfb8aa3b, v125
	v_mul_f32_e32 v131, 0xbfb8aa3b, v121
	v_exp_f32_e32 v130, v130
	v_exp_f32_e32 v131, v131
	v_add_f32_e32 v129, 1.0, v129
	v_mul_f32_e32 v128, 0xbfb8aa3b, v124
	v_rcp_f32_e32 v132, v129
	v_add_f32_e32 v129, 1.0, v130
	v_add_f32_e32 v130, 1.0, v131
	v_mul_f32_e32 v131, 0xbfb8aa3b, v126
	v_mul_f32_e32 v134, 0xbfb8aa3b, v127
	v_exp_f32_e32 v128, v128
	v_exp_f32_e32 v131, v131
	v_exp_f32_e32 v134, v134
	v_rcp_f32_e32 v129, v129
	v_add_f32_e32 v128, 1.0, v128
	v_add_f32_e32 v131, 1.0, v131
	v_add_f32_e32 v134, 1.0, v134
	v_rcp_f32_e32 v128, v128
	v_mul_f32_e32 v133, 0xbfb8aa3b, v122
	v_rcp_f32_e32 v131, v131
	v_mul_f32_e32 v135, 0xbfb8aa3b, v123
	v_rcp_f32_e32 v134, v134
	v_exp_f32_e32 v133, v133
	v_rcp_f32_e32 v130, v130
	v_exp_f32_e32 v135, v135
	v_cvt_pk_bf16_f32 v128, v128, v129
	v_cvt_pk_bf16_f32 v129, v131, v134
	v_mul_f32_e32 v131, 0xbfb8aa3b, v108
	v_add_f32_e32 v133, 1.0, v133
	v_add_f32_e32 v135, 1.0, v135
	v_cvt_pk_bf16_f32 v130, v132, v130
	v_exp_f32_e32 v132, v131
	v_mul_f32_e32 v131, 0xbfb8aa3b, v104
	v_rcp_f32_e32 v133, v133
	v_rcp_f32_e32 v135, v135
	v_exp_f32_e32 v134, v131
	v_mul_f32_e32 v137, 0xbfb8aa3b, v106
	v_mul_f32_e32 v138, 0xbfb8aa3b, v111
	v_cvt_pk_bf16_f32 v131, v133, v135
	v_add_f32_e32 v133, 1.0, v134
	v_mul_f32_e32 v134, 0xbfb8aa3b, v109
	v_mul_f32_e32 v135, 0xbfb8aa3b, v105
	v_exp_f32_e32 v134, v134
	v_exp_f32_e32 v135, v135
	v_rcp_f32_e32 v136, v133
	v_mul_f32_e32 v139, 0xbfb8aa3b, v107
	v_add_f32_e32 v133, 1.0, v134
	v_add_f32_e32 v134, 1.0, v135
	v_mul_f32_e32 v135, 0xbfb8aa3b, v110
	v_exp_f32_e32 v135, v135
	v_exp_f32_e32 v137, v137
	v_exp_f32_e32 v138, v138
	v_exp_f32_e32 v139, v139
	v_add_f32_e32 v132, 1.0, v132
	v_add_f32_e32 v135, 1.0, v135
	v_add_f32_e32 v137, 1.0, v137
	v_add_f32_e32 v138, 1.0, v138
	v_add_f32_e32 v139, 1.0, v139
	v_rcp_f32_e32 v132, v132
	v_rcp_f32_e32 v133, v133
	v_rcp_f32_e32 v135, v135
	v_rcp_f32_e32 v137, v137
	v_rcp_f32_e32 v138, v138
	v_rcp_f32_e32 v139, v139
	v_rcp_f32_e32 v134, v134
	v_cvt_pk_bf16_f32 v132, v132, v133
	v_cvt_pk_bf16_f32 v133, v135, v138
	v_cvt_pk_bf16_f32 v135, v137, v139
	v_mul_f32_e32 v138, 0xbfb8aa3b, v116
	v_mul_f32_e32 v139, 0xbfb8aa3b, v112
	v_exp_f32_e32 v138, v138
	v_exp_f32_e32 v139, v139
	v_cvt_pk_bf16_f32 v134, v136, v134
	v_or_b32_e32 v136, 16, v182
	v_ashrrev_i32_e32 v137, 31, v136
	v_lshlrev_b64 v[186:187], 12, v[136:137]
	v_add_f32_e32 v136, 1.0, v138
	v_add_f32_e32 v137, 1.0, v139
	v_mul_f32_e32 v138, 0xbfb8aa3b, v117
	v_mul_f32_e32 v139, 0xbfb8aa3b, v113
	v_exp_f32_e32 v138, v138
	v_exp_f32_e32 v139, v139
	v_rcp_f32_e32 v140, v137
	v_mul_f32_e32 v142, 0xbfb8aa3b, v119
	v_add_f32_e32 v137, 1.0, v138
	v_add_f32_e32 v138, 1.0, v139
	v_mul_f32_e32 v139, 0xbfb8aa3b, v118
	v_exp_f32_e32 v139, v139
	v_exp_f32_e32 v142, v142
	v_rcp_f32_e32 v136, v136
	v_rcp_f32_e32 v137, v137
	v_add_f32_e32 v139, 1.0, v139
	v_add_f32_e32 v142, 1.0, v142
	v_mul_f32_e32 v141, 0xbfb8aa3b, v114
	v_rcp_f32_e32 v139, v139
	v_mul_f32_e32 v143, 0xbfb8aa3b, v115
	v_rcp_f32_e32 v142, v142
	v_exp_f32_e32 v141, v141
	v_rcp_f32_e32 v138, v138
	v_exp_f32_e32 v143, v143
	v_cvt_pk_bf16_f32 v136, v136, v137
	v_cvt_pk_bf16_f32 v137, v139, v142
	v_mul_f32_e32 v139, 0xbfb8aa3b, v92
	v_add_f32_e32 v141, 1.0, v141
	v_add_f32_e32 v143, 1.0, v143
	v_cvt_pk_bf16_f32 v138, v140, v138
	v_exp_f32_e32 v140, v139
	v_mul_f32_e32 v139, 0xbfb8aa3b, v88
	v_rcp_f32_e32 v141, v141
	v_rcp_f32_e32 v143, v143
	v_exp_f32_e32 v142, v139
	v_mul_f32_e32 v145, 0xbfb8aa3b, v90
	v_mul_f32_e32 v146, 0xbfb8aa3b, v95
	v_cvt_pk_bf16_f32 v139, v141, v143
	v_add_f32_e32 v141, 1.0, v142
	v_mul_f32_e32 v142, 0xbfb8aa3b, v93
	v_mul_f32_e32 v143, 0xbfb8aa3b, v89
	v_exp_f32_e32 v142, v142
	v_exp_f32_e32 v143, v143
	v_rcp_f32_e32 v144, v141
	v_mul_f32_e32 v147, 0xbfb8aa3b, v91
	v_add_f32_e32 v141, 1.0, v142
	v_add_f32_e32 v142, 1.0, v143
	v_mul_f32_e32 v143, 0xbfb8aa3b, v94
	v_exp_f32_e32 v143, v143
	v_exp_f32_e32 v145, v145
	v_exp_f32_e32 v146, v146
	v_exp_f32_e32 v147, v147
	v_add_f32_e32 v140, 1.0, v140
	v_add_f32_e32 v143, 1.0, v143
	v_add_f32_e32 v145, 1.0, v145
	v_add_f32_e32 v146, 1.0, v146
	v_add_f32_e32 v147, 1.0, v147
	v_rcp_f32_e32 v140, v140
	v_rcp_f32_e32 v141, v141
	v_rcp_f32_e32 v143, v143
	v_rcp_f32_e32 v145, v145
	v_rcp_f32_e32 v146, v146
	v_rcp_f32_e32 v147, v147
	v_rcp_f32_e32 v142, v142
	v_cvt_pk_bf16_f32 v140, v140, v141
	v_cvt_pk_bf16_f32 v141, v143, v146
	v_cvt_pk_bf16_f32 v143, v145, v147
	v_mul_f32_e32 v146, 0xbfb8aa3b, v100
	v_mul_f32_e32 v147, 0xbfb8aa3b, v96
	v_exp_f32_e32 v146, v146
	v_exp_f32_e32 v147, v147
	v_cvt_pk_bf16_f32 v142, v144, v142
	v_or_b32_e32 v144, 32, v182
	v_ashrrev_i32_e32 v145, 31, v144
	v_lshlrev_b64 v[188:189], 12, v[144:145]
	v_add_f32_e32 v144, 1.0, v146
	v_add_f32_e32 v145, 1.0, v147
	v_mul_f32_e32 v146, 0xbfb8aa3b, v101
	v_mul_f32_e32 v147, 0xbfb8aa3b, v97
	v_exp_f32_e32 v146, v146
	v_exp_f32_e32 v147, v147
	v_rcp_f32_e32 v148, v145
	v_mul_f32_e32 v150, 0xbfb8aa3b, v103
	v_add_f32_e32 v145, 1.0, v146
	v_add_f32_e32 v146, 1.0, v147
; __device__ __forceinline__ float fsigmoid(float v) { return __builtin_amdgcn_rcpf(1.0f + __builtin_amdgcn_exp2f(-LOG2E * v)); }
; __device__ __forceinline__ float fsilu(float v) { return v * fsigmoid(v); }
; __device__ __forceinline__ u32x4 pack8(const f32x4 a, const f32x4 b) { u32x4 w; w.x = cvt_pk_bf16(a[0], a[1]); w.y = cvt_pk_bf16(a[2], a[3]); w.z = cvt_pk_bf16(b[0], b[1]); w.w = cvt_pk_bf16(b[2], b[3]); return w; }
;     template <int ACT> __device__ __forceinline__ void ew(const f32x4 (&acc)[2][2][4][2], bf16_t* D, int ld, int row0, int col0) const {
; #pragma unroll
;         for (int ai = 0; ai < 2; ++ai)
; #pragma unroll
;             for (int m = 0; m < 4; ++m) { bf16_t* rowp = D + (size_t)(row0 + ai * HALF + m * 16) * ld + col0;
; #pragma unroll
;                 for (int bj = 0; bj < 2; ++bj) { f32x4 v0 = acc[ai][bj][m][0], v1 = acc[ai][bj][m][1];
;                     if (ACT == 1) {
; #pragma unroll
;                         for (int j = 0; j < 4; ++j) { v0[j] = fsilu(v0[j]); v1[j] = fsilu(v1[j]); } }
;                     if (ACT == 2) {
; #pragma unroll
;                         for (int j = 0; j < 4; ++j) { v0[j] = fsigmoid(v0[j]); v1[j] = fsigmoid(v1[j]); } }
;                     *(u32x4*)(rowp + bj * HALF) = pack8(v0, v1); } }
	v_mul_f32_e32 v147, 0xbfb8aa3b, v102
	v_exp_f32_e32 v147, v147
	v_exp_f32_e32 v150, v150
	v_rcp_f32_e32 v144, v144
	v_rcp_f32_e32 v145, v145
	v_add_f32_e32 v147, 1.0, v147
	v_add_f32_e32 v150, 1.0, v150
	v_mul_f32_e32 v149, 0xbfb8aa3b, v98
	v_rcp_f32_e32 v147, v147
	v_mul_f32_e32 v151, 0xbfb8aa3b, v99
	v_rcp_f32_e32 v150, v150
	v_exp_f32_e32 v149, v149
	v_rcp_f32_e32 v146, v146
	v_exp_f32_e32 v151, v151
	v_cvt_pk_bf16_f32 v144, v144, v145
	v_cvt_pk_bf16_f32 v145, v147, v150
	v_mul_f32_e32 v147, 0xbfb8aa3b, v76
	v_add_f32_e32 v149, 1.0, v149
	v_add_f32_e32 v151, 1.0, v151
	v_cvt_pk_bf16_f32 v146, v148, v146
	v_exp_f32_e32 v148, v147
	v_mul_f32_e32 v147, 0xbfb8aa3b, v72
	v_rcp_f32_e32 v149, v149
	v_rcp_f32_e32 v151, v151
	v_exp_f32_e32 v150, v147
	v_mul_f32_e32 v153, 0xbfb8aa3b, v74
	v_mul_f32_e32 v154, 0xbfb8aa3b, v79
	v_cvt_pk_bf16_f32 v147, v149, v151
	v_add_f32_e32 v149, 1.0, v150
	v_mul_f32_e32 v150, 0xbfb8aa3b, v77
	v_mul_f32_e32 v151, 0xbfb8aa3b, v73
	v_exp_f32_e32 v150, v150
	v_exp_f32_e32 v151, v151
	v_rcp_f32_e32 v152, v149
	v_mul_f32_e32 v155, 0xbfb8aa3b, v75
	v_add_f32_e32 v149, 1.0, v150
	v_add_f32_e32 v150, 1.0, v151
	v_mul_f32_e32 v151, 0xbfb8aa3b, v78
	v_exp_f32_e32 v151, v151
	v_exp_f32_e32 v153, v153
	v_exp_f32_e32 v154, v154
	v_exp_f32_e32 v155, v155
	v_add_f32_e32 v148, 1.0, v148
	v_add_f32_e32 v151, 1.0, v151
	v_add_f32_e32 v153, 1.0, v153
	v_add_f32_e32 v154, 1.0, v154
	v_add_f32_e32 v155, 1.0, v155
	v_rcp_f32_e32 v148, v148
	v_rcp_f32_e32 v149, v149
	v_rcp_f32_e32 v151, v151
	v_rcp_f32_e32 v153, v153
	v_rcp_f32_e32 v154, v154
	v_rcp_f32_e32 v155, v155
	v_rcp_f32_e32 v150, v150
	v_cvt_pk_bf16_f32 v148, v148, v149
	v_cvt_pk_bf16_f32 v149, v151, v154
	v_cvt_pk_bf16_f32 v151, v153, v155
	v_mul_f32_e32 v154, 0xbfb8aa3b, v84
	v_mul_f32_e32 v155, 0xbfb8aa3b, v80
	v_exp_f32_e32 v154, v154
	v_exp_f32_e32 v155, v155
	v_cvt_pk_bf16_f32 v150, v152, v150
	v_or_b32_e32 v152, 48, v182
	v_ashrrev_i32_e32 v153, 31, v152
	v_lshlrev_b64 v[190:191], 12, v[152:153]
	v_add_f32_e32 v152, 1.0, v154
	v_add_f32_e32 v153, 1.0, v155
	v_mul_f32_e32 v154, 0xbfb8aa3b, v85
	v_mul_f32_e32 v155, 0xbfb8aa3b, v81
	v_exp_f32_e32 v154, v154
	v_exp_f32_e32 v155, v155
	v_rcp_f32_e32 v156, v153
	v_mul_f32_e32 v158, 0xbfb8aa3b, v87
	v_add_f32_e32 v153, 1.0, v154
	v_add_f32_e32 v154, 1.0, v155
	v_mul_f32_e32 v155, 0xbfb8aa3b, v86
	v_exp_f32_e32 v155, v155
	v_exp_f32_e32 v158, v158
	v_rcp_f32_e32 v152, v152
	v_rcp_f32_e32 v153, v153
	v_add_f32_e32 v155, 1.0, v155
	v_add_f32_e32 v158, 1.0, v158
	v_mul_f32_e32 v157, 0xbfb8aa3b, v82
	v_rcp_f32_e32 v155, v155
	v_mul_f32_e32 v159, 0xbfb8aa3b, v83
	v_rcp_f32_e32 v158, v158
	v_exp_f32_e32 v157, v157
	v_rcp_f32_e32 v154, v154
	v_exp_f32_e32 v159, v159
	v_cvt_pk_bf16_f32 v152, v152, v153
	v_cvt_pk_bf16_f32 v153, v155, v158
	v_mul_f32_e32 v155, 0xbfb8aa3b, v68
	v_add_f32_e32 v157, 1.0, v157
	v_add_f32_e32 v159, 1.0, v159
	v_cvt_pk_bf16_f32 v154, v156, v154
	v_exp_f32_e32 v156, v155
	v_mul_f32_e32 v155, 0xbfb8aa3b, v64
	v_rcp_f32_e32 v157, v157
	v_rcp_f32_e32 v159, v159
	v_exp_f32_e32 v158, v155
	v_mul_f32_e32 v161, 0xbfb8aa3b, v66
	v_mul_f32_e32 v162, 0xbfb8aa3b, v71
	v_cvt_pk_bf16_f32 v155, v157, v159
	v_add_f32_e32 v157, 1.0, v158
	v_mul_f32_e32 v158, 0xbfb8aa3b, v69
	v_mul_f32_e32 v159, 0xbfb8aa3b, v65
	v_exp_f32_e32 v158, v158
	v_exp_f32_e32 v159, v159
	v_rcp_f32_e32 v160, v157
	v_mul_f32_e32 v163, 0xbfb8aa3b, v67
	v_add_f32_e32 v157, 1.0, v158
	v_add_f32_e32 v158, 1.0, v159
	v_mul_f32_e32 v159, 0xbfb8aa3b, v70
	v_exp_f32_e32 v159, v159
	v_exp_f32_e32 v161, v161
	v_exp_f32_e32 v162, v162
	v_exp_f32_e32 v163, v163
	v_add_f32_e32 v156, 1.0, v156
	v_add_f32_e32 v159, 1.0, v159
	v_add_f32_e32 v161, 1.0, v161
	v_add_f32_e32 v162, 1.0, v162
	v_add_f32_e32 v163, 1.0, v163
	v_rcp_f32_e32 v156, v156
	v_rcp_f32_e32 v157, v157
	v_rcp_f32_e32 v159, v159
	v_rcp_f32_e32 v161, v161
	v_rcp_f32_e32 v162, v162
	v_rcp_f32_e32 v163, v163
	v_cvt_pk_bf16_f32 v156, v156, v157
	v_rcp_f32_e32 v158, v158
	v_cvt_pk_bf16_f32 v157, v159, v162
	v_cvt_pk_bf16_f32 v159, v161, v163
	v_mul_f32_e32 v161, 0xbfb8aa3b, v56
	v_exp_f32_e32 v161, v161
	v_mul_f32_e32 v162, 0xbfb8aa3b, v61
	v_mul_f32_e32 v163, 0xbfb8aa3b, v57
	v_exp_f32_e32 v162, v162
	v_exp_f32_e32 v163, v163
	v_add_f32_e32 v161, 1.0, v161
	v_cvt_pk_bf16_f32 v158, v160, v158
	v_mul_f32_e32 v160, 0xbfb8aa3b, v60
	v_rcp_f32_e32 v172, v161
	v_add_f32_e32 v161, 1.0, v162
	v_add_f32_e32 v162, 1.0, v163
	v_mul_f32_e32 v163, 0xbfb8aa3b, v62
	v_mul_f32_e32 v194, 0xbfb8aa3b, v58
	v_mul_f32_e32 v195, 0xbfb8aa3b, v63
	v_mul_f32_e32 v212, 0xbfb8aa3b, v59
	v_exp_f32_e32 v160, v160
	v_exp_f32_e32 v163, v163
	v_exp_f32_e32 v194, v194
	v_exp_f32_e32 v195, v195
	v_exp_f32_e32 v212, v212
	v_add_f32_e32 v160, 1.0, v160
	v_add_f32_e32 v163, 1.0, v163
	v_add_f32_e32 v194, 1.0, v194
	v_add_f32_e32 v195, 1.0, v195
	v_add_f32_e32 v212, 1.0, v212
	v_rcp_f32_e32 v160, v160
	v_rcp_f32_e32 v161, v161
	v_rcp_f32_e32 v162, v162
	v_rcp_f32_e32 v163, v163
	v_rcp_f32_e32 v194, v194
	v_rcp_f32_e32 v195, v195
	v_rcp_f32_e32 v212, v212
	v_ashrrev_i32_e32 v183, 31, v182
	v_lshlrev_b64 v[184:185], 12, v[182:183]
	s_mov_b64 s[38:39], 0x80000
	s_cmp_gt_u32 s23, 35
	v_lshl_add_u64 v[192:193], v[184:185], 0, s[38:39]
	v_cvt_pk_bf16_f32 v160, v160, v161
	v_cvt_pk_bf16_f32 v161, v163, v195
	v_cvt_pk_bf16_f32 v162, v172, v162
	v_cvt_pk_bf16_f32 v163, v194, v212
	s_cbranch_scc0 .LBB0_373
; __device__ __forceinline__ float fsigmoid(float v) { return __builtin_amdgcn_rcpf(1.0f + __builtin_amdgcn_exp2f(-LOG2E * v)); }
; __device__ __forceinline__ float fsilu(float v) { return v * fsigmoid(v); }
; __device__ __forceinline__ u32x4 pack8(const f32x4 a, const f32x4 b) { u32x4 w; w.x = cvt_pk_bf16(a[0], a[1]); w.y = cvt_pk_bf16(a[2], a[3]); w.z = cvt_pk_bf16(b[0], b[1]); w.w = cvt_pk_bf16(b[2], b[3]); return w; }
;     template <int ACT> __device__ __forceinline__ void ew(const f32x4 (&acc)[2][2][4][2], bf16_t* D, int ld, int row0, int col0) const {
; #pragma unroll
;         for (int ai = 0; ai < 2; ++ai)
; #pragma unroll
;             for (int m = 0; m < 4; ++m) { bf16_t* rowp = D + (size_t)(row0 + ai * HALF + m * 16) * ld + col0;
; #pragma unroll
;                 for (int bj = 0; bj < 2; ++bj) { f32x4 v0 = acc[ai][bj][m][0], v1 = acc[ai][bj][m][1];
;                     if (ACT == 1) {
; #pragma unroll
;                         for (int j = 0; j < 4; ++j) { v0[j] = fsilu(v0[j]); v1[j] = fsilu(v1[j]); } }
;                     if (ACT == 2) {
; #pragma unroll
;                         for (int j = 0; j < 4; ++j) { v0[j] = fsigmoid(v0[j]); v1[j] = fsigmoid(v1[j]); } }
;                     *(u32x4*)(rowp + bj * HALF) = pack8(v0, v1); } }
;     __device__ __forceinline__ void operator()(const f32x4 (&acc)[2][2][4][2], const Unit& u, int wr, int wc, int fr, int fq) const {
;     ...
;         else ew<2>(acc, SGB, 2048, row0, (pn - 36) * 256 + cl);
	v_readlane_b32 s38, v255, 23
	v_add_u32_e32 v172, s75, v199
	v_readlane_b32 s39, v255, 24
	v_mul_f32_e32 v212, 0xbfb8aa3b, v40
	v_mul_f32_e32 v220, 0xbfb8aa3b, v45
	v_lshl_add_u64 v[222:223], v[172:173], 1, s[38:39]
	v_lshl_add_u64 v[194:195], v[222:223], 0, v[184:185]
	v_lshl_add_u64 v[224:225], v[222:223], 0, v[186:187]
	global_store_dwordx4 v[194:195], v[128:131], off
	global_store_dwordx4 v[194:195], v[132:135], off offset:256
	global_store_dwordx4 v[224:225], v[136:139], off
	global_store_dwordx4 v[224:225], v[140:143], off offset:256
	v_lshl_add_u64 v[224:225], v[222:223], 0, v[188:189]
	global_store_dwordx4 v[224:225], v[144:147], off
	global_store_dwordx4 v[224:225], v[148:151], off offset:256
	v_lshl_add_u64 v[224:225], v[222:223], 0, v[190:191]
	v_lshl_add_u64 v[230:231], v[222:223], 0, v[192:193]
	v_mul_f32_e32 v222, 0xbfb8aa3b, v41
	v_exp_f32_e32 v222, v222
	v_mul_f32_e32 v223, 0xbfb8aa3b, v46
	global_store_dwordx4 v[224:225], v[152:155], off
	global_store_dwordx4 v[224:225], v[156:159], off offset:256
	v_exp_f32_e32 v223, v223
	v_mul_f32_e32 v224, 0xbfb8aa3b, v42
	v_exp_f32_e32 v224, v224
	v_add_f32_e32 v222, 1.0, v222
	v_rcp_f32_e32 v225, v222
	v_add_f32_e32 v222, 1.0, v223
	v_rcp_f32_e32 v223, v222
	v_add_f32_e32 v222, 1.0, v224
	v_mul_f32_e32 v224, 0xbfb8aa3b, v47
	v_mul_f32_e32 v172, 0xbfb8aa3b, v44
	v_exp_f32_e32 v224, v224
	v_mul_f32_e32 v232, 0xbfb8aa3b, v43
	v_exp_f32_e32 v172, v172
	v_exp_f32_e32 v212, v212
	v_exp_f32_e32 v220, v220
	v_exp_f32_e32 v232, v232
	v_rcp_f32_e32 v233, v222
	v_add_f32_e32 v222, 1.0, v224
	v_add_f32_e32 v172, 1.0, v172
	v_add_f32_e32 v212, 1.0, v212
	v_add_f32_e32 v220, 1.0, v220
	v_rcp_f32_e32 v224, v222
	v_add_f32_e32 v222, 1.0, v232
	v_rcp_f32_e32 v172, v172
	v_rcp_f32_e32 v212, v212
	v_rcp_f32_e32 v220, v220
	v_rcp_f32_e32 v232, v222
	v_cvt_pk_bf16_f32 v223, v223, v224
	v_cvt_pk_bf16_f32 v224, v212, v225
	v_cvt_pk_bf16_f32 v222, v172, v220
	v_cvt_pk_bf16_f32 v225, v233, v232
	global_store_dwordx4 v[230:231], v[222:225], off offset:256
	v_mul_f32_e32 v212, 0xbfb8aa3b, v48
	v_mul_f32_e32 v232, 0xbfb8aa3b, v51
	v_mul_f32_e32 v222, 0xbfb8aa3b, v49
	v_exp_f32_e32 v222, v222
	v_mul_f32_e32 v223, 0xbfb8aa3b, v54
	v_exp_f32_e32 v223, v223
	v_mul_f32_e32 v224, 0xbfb8aa3b, v50
	v_exp_f32_e32 v224, v224
	v_add_f32_e32 v222, 1.0, v222
	v_rcp_f32_e32 v225, v222
	v_add_f32_e32 v222, 1.0, v223
	v_rcp_f32_e32 v223, v222
	v_add_f32_e32 v222, 1.0, v224
	v_mul_f32_e32 v224, 0xbfb8aa3b, v55
	v_exp_f32_e32 v224, v224
	v_mul_f32_e32 v172, 0xbfb8aa3b, v52
	v_exp_f32_e32 v212, v212
	v_mul_f32_e32 v220, 0xbfb8aa3b, v53
	v_exp_f32_e32 v232, v232
	v_exp_f32_e32 v172, v172
	v_exp_f32_e32 v220, v220
	v_rcp_f32_e32 v233, v222
	v_add_f32_e32 v222, 1.0, v224
	v_add_f32_e32 v212, 1.0, v212
	v_rcp_f32_e32 v224, v222
	v_add_f32_e32 v222, 1.0, v232
	v_add_f32_e32 v172, 1.0, v172
	v_rcp_f32_e32 v212, v212
	v_add_f32_e32 v220, 1.0, v220
	v_rcp_f32_e32 v232, v222
	v_rcp_f32_e32 v172, v172
	v_rcp_f32_e32 v220, v220
	s_mov_b64 s[38:39], 0x90000
	global_store_dwordx4 v[230:231], v[160:163], off
	v_lshl_add_u64 v[230:231], v[194:195], 0, s[38:39]
	s_mov_b32 s38, 0x90000
	v_cvt_pk_bf16_f32 v223, v223, v224
	v_cvt_pk_bf16_f32 v224, v212, v225
	v_cvt_pk_bf16_f32 v225, v233, v232
	v_add_co_u32_e32 v232, vcc, s38, v194
	v_cvt_pk_bf16_f32 v222, v172, v220
	s_nop 0
	v_addc_co_u32_e32 v233, vcc, 0, v195, vcc
	global_store_dwordx4 v[232:233], v[222:225], off
	v_mul_f32_e32 v172, 0xbfb8aa3b, v28
	v_mul_f32_e32 v212, 0xbfb8aa3b, v24
	v_mul_f32_e32 v222, 0xbfb8aa3b, v25
	v_exp_f32_e32 v222, v222
	v_mul_f32_e32 v223, 0xbfb8aa3b, v30
	v_exp_f32_e32 v223, v223
	v_mul_f32_e32 v224, 0xbfb8aa3b, v26
	v_exp_f32_e32 v224, v224
	v_add_f32_e32 v222, 1.0, v222
	v_rcp_f32_e32 v225, v222
	v_add_f32_e32 v222, 1.0, v223
	v_rcp_f32_e32 v223, v222
	v_add_f32_e32 v222, 1.0, v224
	v_mul_f32_e32 v224, 0xbfb8aa3b, v31
	v_mul_f32_e32 v220, 0xbfb8aa3b, v29
	v_exp_f32_e32 v224, v224
	v_mul_f32_e32 v232, 0xbfb8aa3b, v27
	v_exp_f32_e32 v172, v172
	v_exp_f32_e32 v212, v212
	v_exp_f32_e32 v220, v220
	v_exp_f32_e32 v232, v232
	v_rcp_f32_e32 v233, v222
	v_add_f32_e32 v222, 1.0, v224
	v_add_f32_e32 v172, 1.0, v172
	v_add_f32_e32 v212, 1.0, v212
	v_add_f32_e32 v220, 1.0, v220
	v_rcp_f32_e32 v224, v222
	v_add_f32_e32 v222, 1.0, v232
	v_rcp_f32_e32 v172, v172
	v_rcp_f32_e32 v212, v212
	v_rcp_f32_e32 v220, v220
	v_rcp_f32_e32 v232, v222
	v_cvt_pk_bf16_f32 v223, v223, v224
	v_cvt_pk_bf16_f32 v224, v212, v225
	v_cvt_pk_bf16_f32 v222, v172, v220
	v_cvt_pk_bf16_f32 v225, v233, v232
	global_store_dwordx4 v[230:231], v[222:225], off offset:256
	v_mul_f32_e32 v212, 0xbfb8aa3b, v32
	v_mul_f32_e32 v232, 0xbfb8aa3b, v35
	v_mul_f32_e32 v222, 0xbfb8aa3b, v33
	v_exp_f32_e32 v222, v222
	v_mul_f32_e32 v223, 0xbfb8aa3b, v38
; __device__ __forceinline__ float fsigmoid(float v) { return __builtin_amdgcn_rcpf(1.0f + __builtin_amdgcn_exp2f(-LOG2E * v)); }
; __device__ __forceinline__ float fsilu(float v) { return v * fsigmoid(v); }
; __device__ __forceinline__ u32x4 pack8(const f32x4 a, const f32x4 b) { u32x4 w; w.x = cvt_pk_bf16(a[0], a[1]); w.y = cvt_pk_bf16(a[2], a[3]); w.z = cvt_pk_bf16(b[0], b[1]); w.w = cvt_pk_bf16(b[2], b[3]); return w; }
;     template <int ACT> __device__ __forceinline__ void ew(const f32x4 (&acc)[2][2][4][2], bf16_t* D, int ld, int row0, int col0) const {
; #pragma unroll
;         for (int ai = 0; ai < 2; ++ai)
; #pragma unroll
;             for (int m = 0; m < 4; ++m) { bf16_t* rowp = D + (size_t)(row0 + ai * HALF + m * 16) * ld + col0;
; #pragma unroll
;                 for (int bj = 0; bj < 2; ++bj) { f32x4 v0 = acc[ai][bj][m][0], v1 = acc[ai][bj][m][1];
;                     if (ACT == 1) {
; #pragma unroll
;                         for (int j = 0; j < 4; ++j) { v0[j] = fsilu(v0[j]); v1[j] = fsilu(v1[j]); } }
;                     if (ACT == 2) {
; #pragma unroll
;                         for (int j = 0; j < 4; ++j) { v0[j] = fsigmoid(v0[j]); v1[j] = fsigmoid(v1[j]); } }
;                     *(u32x4*)(rowp + bj * HALF) = pack8(v0, v1); } }
	v_exp_f32_e32 v223, v223
	v_mul_f32_e32 v224, 0xbfb8aa3b, v34
	v_exp_f32_e32 v224, v224
	v_add_f32_e32 v222, 1.0, v222
	v_rcp_f32_e32 v225, v222
	v_add_f32_e32 v222, 1.0, v223
	v_rcp_f32_e32 v223, v222
	v_add_f32_e32 v222, 1.0, v224
	v_mul_f32_e32 v224, 0xbfb8aa3b, v39
	v_exp_f32_e32 v224, v224
	v_mul_f32_e32 v172, 0xbfb8aa3b, v36
	v_exp_f32_e32 v212, v212
	v_mul_f32_e32 v220, 0xbfb8aa3b, v37
	v_exp_f32_e32 v232, v232
	v_exp_f32_e32 v172, v172
	v_exp_f32_e32 v220, v220
	v_rcp_f32_e32 v233, v222
	v_add_f32_e32 v222, 1.0, v224
	v_add_f32_e32 v212, 1.0, v212
	v_rcp_f32_e32 v224, v222
	v_add_f32_e32 v222, 1.0, v232
	v_add_f32_e32 v172, 1.0, v172
	v_rcp_f32_e32 v212, v212
	v_add_f32_e32 v220, 1.0, v220
	v_rcp_f32_e32 v232, v222
	v_rcp_f32_e32 v172, v172
	v_rcp_f32_e32 v220, v220
	v_cvt_pk_bf16_f32 v223, v223, v224
	v_cvt_pk_bf16_f32 v224, v212, v225
	v_cvt_pk_bf16_f32 v225, v233, v232
	v_add_co_u32_e32 v232, vcc, s49, v194
	v_cvt_pk_bf16_f32 v222, v172, v220
	s_nop 0
	v_addc_co_u32_e32 v233, vcc, 0, v195, vcc
	global_store_dwordx4 v[232:233], v[222:225], off
	v_mul_f32_e32 v172, 0xbfb8aa3b, v12
	v_mul_f32_e32 v212, 0xbfb8aa3b, v8
	v_mul_f32_e32 v222, 0xbfb8aa3b, v9
	v_exp_f32_e32 v222, v222
	v_mul_f32_e32 v223, 0xbfb8aa3b, v14
	v_exp_f32_e32 v223, v223
	v_mul_f32_e32 v224, 0xbfb8aa3b, v10
	v_exp_f32_e32 v224, v224
	v_add_f32_e32 v222, 1.0, v222
	v_rcp_f32_e32 v225, v222
	v_add_f32_e32 v222, 1.0, v223
	v_rcp_f32_e32 v223, v222
	v_add_f32_e32 v222, 1.0, v224
	v_mul_f32_e32 v224, 0xbfb8aa3b, v15
	v_mul_f32_e32 v220, 0xbfb8aa3b, v13
	v_exp_f32_e32 v224, v224
	v_mul_f32_e32 v232, 0xbfb8aa3b, v11
	v_exp_f32_e32 v172, v172
	v_exp_f32_e32 v212, v212
	v_exp_f32_e32 v220, v220
	v_exp_f32_e32 v232, v232
	v_rcp_f32_e32 v233, v222
	v_add_f32_e32 v222, 1.0, v224
	v_add_f32_e32 v172, 1.0, v172
	v_add_f32_e32 v212, 1.0, v212
	v_add_f32_e32 v220, 1.0, v220
	v_rcp_f32_e32 v224, v222
	v_add_f32_e32 v222, 1.0, v232
	v_rcp_f32_e32 v172, v172
	v_rcp_f32_e32 v212, v212
	v_rcp_f32_e32 v220, v220
	v_rcp_f32_e32 v232, v222
	s_mov_b64 s[38:39], 0xa0000
	v_lshl_add_u64 v[230:231], v[194:195], 0, s[38:39]
	v_cvt_pk_bf16_f32 v222, v172, v220
	v_cvt_pk_bf16_f32 v223, v223, v224
	v_cvt_pk_bf16_f32 v224, v212, v225
	v_cvt_pk_bf16_f32 v225, v233, v232
	global_store_dwordx4 v[230:231], v[222:225], off offset:256
	v_mul_f32_e32 v212, 0xbfb8aa3b, v16
	v_exp_f32_e32 v212, v212
	v_mul_f32_e32 v222, 0xbfb8aa3b, v17
	v_exp_f32_e32 v222, v222
	v_mul_f32_e32 v223, 0xbfb8aa3b, v22
	v_exp_f32_e32 v223, v223
	v_mul_f32_e32 v224, 0xbfb8aa3b, v18
	v_exp_f32_e32 v224, v224
	v_add_f32_e32 v222, 1.0, v222
	v_rcp_f32_e32 v225, v222
	v_add_f32_e32 v222, 1.0, v223
	v_rcp_f32_e32 v223, v222
	v_add_f32_e32 v222, 1.0, v224
	v_mul_f32_e32 v224, 0xbfb8aa3b, v23
	v_exp_f32_e32 v224, v224
	v_mul_f32_e32 v172, 0xbfb8aa3b, v20
	v_mul_f32_e32 v220, 0xbfb8aa3b, v21
	v_mul_f32_e32 v232, 0xbfb8aa3b, v19
	v_exp_f32_e32 v172, v172
	v_exp_f32_e32 v220, v220
	v_exp_f32_e32 v232, v232
	v_add_f32_e32 v212, 1.0, v212
	v_rcp_f32_e32 v233, v222
	v_add_f32_e32 v222, 1.0, v224
	v_rcp_f32_e32 v212, v212
	v_rcp_f32_e32 v224, v222
	v_add_f32_e32 v172, 1.0, v172
	v_add_f32_e32 v220, 1.0, v220
	v_add_f32_e32 v222, 1.0, v232
	v_rcp_f32_e32 v172, v172
	v_rcp_f32_e32 v220, v220
	v_rcp_f32_e32 v232, v222
	v_cvt_pk_bf16_f32 v223, v223, v224
	v_cvt_pk_bf16_f32 v224, v212, v225
	v_mul_f32_e32 v212, 0xbfb8aa3b, v0
	v_lshl_add_u64 v[230:231], v[194:195], 0, s[62:63]
	v_add_co_u32_e32 v194, vcc, s50, v194
	v_exp_f32_e32 v212, v212
	v_cvt_pk_bf16_f32 v222, v172, v220
	v_cvt_pk_bf16_f32 v225, v233, v232
	v_addc_co_u32_e32 v195, vcc, 0, v195, vcc
	global_store_dwordx4 v[194:195], v[222:225], off
	v_mul_f32_e32 v172, 0xbfb8aa3b, v4
	v_add_f32_e32 v194, 1.0, v212
	v_mul_f32_e32 v222, 0xbfb8aa3b, v2
	v_exp_f32_e32 v222, v222
	v_mul_f32_e32 v223, 0xbfb8aa3b, v7
	v_mul_f32_e32 v195, 0xbfb8aa3b, v5
	v_mul_f32_e32 v212, 0xbfb8aa3b, v1
	v_mul_f32_e32 v220, 0xbfb8aa3b, v6
	v_exp_f32_e32 v223, v223
	v_mul_f32_e32 v224, 0xbfb8aa3b, v3
	v_exp_f32_e32 v172, v172
	v_exp_f32_e32 v195, v195
	v_exp_f32_e32 v212, v212
	v_exp_f32_e32 v220, v220
	v_exp_f32_e32 v224, v224
	v_add_f32_e32 v222, 1.0, v222
	v_rcp_f32_e32 v225, v222
	v_add_f32_e32 v222, 1.0, v223
	v_add_f32_e32 v172, 1.0, v172
	v_add_f32_e32 v195, 1.0, v195
	v_add_f32_e32 v212, 1.0, v212
	v_add_f32_e32 v220, 1.0, v220
	v_rcp_f32_e32 v223, v222
	v_add_f32_e32 v222, 1.0, v224
	v_rcp_f32_e32 v172, v172
	v_rcp_f32_e32 v194, v194
	v_rcp_f32_e32 v195, v195
	v_rcp_f32_e32 v212, v212
	v_rcp_f32_e32 v220, v220
	v_rcp_f32_e32 v232, v222
	v_cvt_pk_bf16_f32 v222, v172, v195
	v_cvt_pk_bf16_f32 v224, v194, v212
	v_cvt_pk_bf16_f32 v223, v220, v223
	v_cvt_pk_bf16_f32 v225, v225, v232
	global_store_dwordx4 v[230:231], v[222:225], off offset:256
	s_mov_b64 s[82:83], 0

; #define PG8_STAGE(bufoff, gbase, voff) do { _Pragma("unroll") for (int _i = 0; _i < 2; ++_i) \
;         __builtin_amdgcn_global_load_lds((const unsigned*)((const char*)(gbase) + (voff)[_i]), (PG8_LAS unsigned*)(lds + (bufoff) + ldsw + _i * 8192), 16, 0, 0); } while (0)
; #define PG8_LDA(dst, b, h) do { _Pragma("unroll") for (int m = 0; m < 4; ++m) _Pragma("unroll") for (int k = 0; k < 2; ++k) dst[m][k] = *(const PG8_LAS bf16x8*)(lds + PG8_SA(b, h) + aoff + m * 2048 + k * 1024); } while (0)
; #define PG8_LDB(dst, b, h) do { _Pragma("unroll") for (int n = 0; n < 2; ++n) _Pragma("unroll") for (int k = 0; k < 2; ++k) dst[n][k] = *(const PG8_LAS bf16x8*)(lds + PG8_SB(b, h) + boff + n * 2048 + k * 1024); } while (0)
; #define PG8_WAIT_V(n) asm volatile("s_waitcnt vmcnt(" #n ")" ::: "memory")
; #define PG8_WAIT_L(n) asm volatile("s_waitcnt lgkmcnt(" #n ")" ::: "memory")
; #define PG8_BAR __builtin_amdgcn_s_barrier()
; #define PG8_SCHED __builtin_amdgcn_sched_barrier(0)
; template <class Epi, class Sched, bool ALIGN_EPI = false, bool SP2 = false>
; __device__ __forceinline__ void gemm_phase(PG8_LAS unsigned char* lds, const Gemm g, const Sched& S, const Epi& E) {
;     ...
;         const bool has_next = S.next(ui + 1, nxt);
;         const char* nA = has_next ? (const char*)g.A + (size_t)nxt.pm * tstep : cA; const char* nB = has_next ? (const char*)g.Bt + (size_t)nxt.pn * tstep : cB;
;         for (int t = 0; t < nt; t += 2) {
;             const bool last = (t == nt - 2);
;             const char* a1 = cA + (size_t)(t + 1) * kstep;
;             const char* a2 = last ? nA : cA + (size_t)(t + 2) * kstep; const char* b2 = last ? nB : cB + (size_t)(t + 2) * kstep;
;             const char* a3 = a2 + kstep; const char* b3 = b2 + kstep;
;             if (last && has_next) S.a_ready(nxt);
;             if constexpr (SP2) {
;             PG8_LDB(B0, 0, 0); PG8_LDB(B1, 0, 1); PG8_SCHED; PG8_LDA(At, 0, 0); PG8_STAGE(PG8_SA(1, 1), a1 + hstep, voffA);
;             PG8_WAIT_V(8); PG8_WAIT_L(0); PG8_BAR; PG8_MMA(0, 0, At, B0); PG8_MMA(0, 1, At, B1); PG8_BAR; PG8_SCHED;
;             PG8_LDA(At, 0, 1); PG8_STAGE(PG8_SB(0, 0), b2, voffB); PG8_STAGE(PG8_SB(0, 1), b2 + hstep, voffB); PG8_STAGE(PG8_SA(0, 0), a2, voffA);
;             PG8_WAIT_V(8); PG8_WAIT_L(0); PG8_BAR; PG8_MMA(1, 0, At, B0); PG8_MMA(1, 1, At, B1); PG8_BAR; PG8_SCHED;
.LBB0_734:
	s_ashr_i32 s39, s38, 31
	v_cmp_lt_i64_e32 vcc, s[40:41], v[140:141]
	s_lshl_b64 s[40:41], s[38:39], 19
	s_add_u32 s40, s9, s40
	s_addc_u32 s41, s22, s41
	s_and_b64 s[42:43], vcc, exec
	s_cselect_b32 s39, s41, s47
	s_cselect_b32 s65, s40, s46
	s_ashr_i32 s37, s36, 31
	s_lshl_b64 s[42:43], s[36:37], 19
	s_add_u32 s42, s23, s42
	s_addc_u32 s43, s52, s43
	s_and_b64 s[50:51], vcc, exec
	s_cselect_b32 s37, s43, s49
	s_cselect_b32 s66, s42, s48
	s_add_u32 s46, s46, 0x40080
	s_addc_u32 s47, s47, 0
	s_add_u32 s67, s48, 0x100
	s_addc_u32 s68, s49, 0
	s_mov_b32 s69, -2
	v_add_u32_e32 v210, 0x18000, v153
	v_add_u32_e32 v211, 0x1c000, v153
	ds_read_b128 v[144:147], v155
	ds_read_b128 v[148:151], v155 offset:1024
	ds_read_b128 v[158:161], v155 offset:2048
	ds_read_b128 v[162:165], v155 offset:3072
	ds_read_b128 v[166:169], v156
	ds_read_b128 v[170:173], v156 offset:1024
	ds_read_b128 v[174:177], v156 offset:2048
	ds_read_b128 v[178:181], v156 offset:3072
	s_add_u32 s48, s46, 0xfffc0080
	s_addc_u32 s49, s47, -1
	s_cmp_eq_u32 s69, 12
	s_cselect_b32 s51, s39, s49
	s_cselect_b32 s50, s65, s48
	s_cselect_b32 s49, s37, s68
	s_cselect_b32 s48, s66, s67
	s_add_i32 m0, s45, 0xc000
	ds_read_b128 v[182:185], v157
	ds_read_b128 v[186:189], v157 offset:1024
	ds_read_b128 v[190:193], v157 offset:2048
	ds_read_b128 v[194:197], v157 offset:3072
	ds_read_b128 v[198:201], v157 offset:4096
	ds_read_b128 v[202:205], v157 offset:5120
	ds_read_b128 v[206:209], v157 offset:6144
	ds_read_b128 v[214:217], v157 offset:7168
	global_load_lds_dwordx4 v136, s[46:47]
	s_add_i32 m0, s45, 0xe000
	s_nop 0
	global_load_lds_dwordx4 v138, s[46:47]
	s_waitcnt vmcnt(8) lgkmcnt(0)
	s_barrier
	v_mfma_f32_16x16x32_bf16 v[124:127], v[144:147], v[182:185], 0
	v_mfma_f32_16x16x32_bf16 v[120:123], v[158:161], v[182:185], 0
	v_mfma_f32_16x16x32_bf16 v[116:119], v[144:147], v[190:193], 0
	v_mfma_f32_16x16x32_bf16 v[112:115], v[158:161], v[190:193], 0
	v_mfma_f32_16x16x32_bf16 v[96:99], v[144:147], v[198:201], 0
	v_mfma_f32_16x16x32_bf16 v[88:91], v[158:161], v[198:201], 0
	v_mfma_f32_16x16x32_bf16 v[80:83], v[144:147], v[206:209], 0
	v_mfma_f32_16x16x32_bf16 v[72:75], v[158:161], v[206:209], 0
	v_mfma_f32_16x16x32_bf16 v[124:127], v[148:151], v[186:189], v[124:127]
	v_mfma_f32_16x16x32_bf16 v[120:123], v[162:165], v[186:189], v[120:123]
	v_mfma_f32_16x16x32_bf16 v[116:119], v[148:151], v[194:197], v[116:119]
	v_mfma_f32_16x16x32_bf16 v[112:115], v[162:165], v[194:197], v[112:115]
	v_mfma_f32_16x16x32_bf16 v[96:99], v[148:151], v[202:205], v[96:99]
	v_mfma_f32_16x16x32_bf16 v[88:91], v[162:165], v[202:205], v[88:91]
	v_mfma_f32_16x16x32_bf16 v[80:83], v[148:151], v[214:217], v[80:83]
	v_mfma_f32_16x16x32_bf16 v[72:75], v[162:165], v[214:217], v[72:75]
	v_mfma_f32_16x16x32_bf16 v[108:111], v[166:169], v[182:185], 0
	v_mfma_f32_16x16x32_bf16 v[104:107], v[174:177], v[182:185], 0
	v_mfma_f32_16x16x32_bf16 v[100:103], v[166:169], v[190:193], 0
	v_mfma_f32_16x16x32_bf16 v[92:95], v[174:177], v[190:193], 0
	v_mfma_f32_16x16x32_bf16 v[84:87], v[166:169], v[198:201], 0
	v_mfma_f32_16x16x32_bf16 v[76:79], v[174:177], v[198:201], 0
	v_mfma_f32_16x16x32_bf16 v[68:71], v[166:169], v[206:209], 0
	v_mfma_f32_16x16x32_bf16 v[64:67], v[174:177], v[206:209], 0
	v_mfma_f32_16x16x32_bf16 v[108:111], v[170:173], v[186:189], v[108:111]
	v_mfma_f32_16x16x32_bf16 v[104:107], v[178:181], v[186:189], v[104:107]
	v_mfma_f32_16x16x32_bf16 v[100:103], v[170:173], v[194:197], v[100:103]
	v_mfma_f32_16x16x32_bf16 v[92:95], v[178:181], v[194:197], v[92:95]
	v_mfma_f32_16x16x32_bf16 v[84:87], v[170:173], v[202:205], v[84:87]
	v_mfma_f32_16x16x32_bf16 v[76:79], v[178:181], v[202:205], v[76:79]
	v_mfma_f32_16x16x32_bf16 v[68:71], v[170:173], v[214:217], v[68:71]
	v_mfma_f32_16x16x32_bf16 v[64:67], v[178:181], v[214:217], v[64:67]
	s_barrier
	s_add_i32 s70, s62, s53
	s_mov_b32 m0, s70
	ds_read_b128 v[182:185], v157 offset:16384
	ds_read_b128 v[186:189], v157 offset:17408
	ds_read_b128 v[190:193], v157 offset:18432
	ds_read_b128 v[194:197], v157 offset:19456
	ds_read_b128 v[198:201], v157 offset:20480
	ds_read_b128 v[202:205], v157 offset:21504
	ds_read_b128 v[206:209], v157 offset:22528
	ds_read_b128 v[214:217], v157 offset:23552
	global_load_lds_dwordx4 v130, s[48:49]
	s_add_i32 m0, s70, 0x2000
	s_add_u32 s70, s48, 0x40000
	s_addc_u32 s71, s49, 0
	s_add_i32 s72, s63, s53
	global_load_lds_dwordx4 v134, s[48:49]
	s_mov_b32 m0, s72
	s_nop 0
	global_load_lds_dwordx4 v130, s[70:71]
	s_add_i32 m0, s72, 0x2000
	s_nop 0
	global_load_lds_dwordx4 v134, s[70:71]
	s_mov_b32 m0, s45
	s_nop 0
	global_load_lds_dwordx4 v128, s[50:51]
	s_mov_b32 m0, s54
	s_nop 0
	global_load_lds_dwordx4 v132, s[50:51]
	s_waitcnt vmcnt(8) lgkmcnt(0)
	s_barrier
; #define PG8_STAGE(bufoff, gbase, voff) do { _Pragma("unroll") for (int _i = 0; _i < 2; ++_i) \
;         __builtin_amdgcn_global_load_lds((const unsigned*)((const char*)(gbase) + (voff)[_i]), (PG8_LAS unsigned*)(lds + (bufoff) + ldsw + _i * 8192), 16, 0, 0); } while (0)
; #define PG8_LDA(dst, b, h) do { _Pragma("unroll") for (int m = 0; m < 4; ++m) _Pragma("unroll") for (int k = 0; k < 2; ++k) dst[m][k] = *(const PG8_LAS bf16x8*)(lds + PG8_SA(b, h) + aoff + m * 2048 + k * 1024); } while (0)
; #define PG8_LDB(dst, b, h) do { _Pragma("unroll") for (int n = 0; n < 2; ++n) _Pragma("unroll") for (int k = 0; k < 2; ++k) dst[n][k] = *(const PG8_LAS bf16x8*)(lds + PG8_SB(b, h) + boff + n * 2048 + k * 1024); } while (0)
; #define PG8_MMA(ai, bj, At, Bt) do { __builtin_amdgcn_s_setprio(1); _Pragma("unroll") for (int m = 0; m < 4; ++m) _Pragma("unroll") for (int n = 0; n < 2; ++n) _Pragma("unroll") for (int k = 0; k < 2; ++k) \
;         acc[ai][bj][m][n] = __builtin_amdgcn_mfma_f32_16x16x32_bf16(Bt[n][k], At[m][k], acc[ai][bj][m][n], 0, 0, 0); __builtin_amdgcn_s_setprio(0); } while (0)
; #define PG8_WAIT_V(n) asm volatile("s_waitcnt vmcnt(" #n ")" ::: "memory")
; #define PG8_WAIT_L(n) asm volatile("s_waitcnt lgkmcnt(" #n ")" ::: "memory")
; #define PG8_BAR __builtin_amdgcn_s_barrier()
; #define PG8_SCHED __builtin_amdgcn_sched_barrier(0)
; template <class Epi, class Sched, bool ALIGN_EPI = false, bool SP2 = false>
; __device__ __forceinline__ void gemm_phase(PG8_LAS unsigned char* lds, const Gemm g, const Sched& S, const Epi& E) {
;     ...
;             PG8_WAIT_V(8); PG8_WAIT_L(0); PG8_BAR; PG8_MMA(1, 0, At, B0); PG8_MMA(1, 1, At, B1); PG8_BAR; PG8_SCHED;
;             PG8_LDB(B0, 1, 0); PG8_LDB(B1, 1, 1); PG8_SCHED; PG8_LDA(At, 1, 0); PG8_STAGE(PG8_SA(0, 1), a2 + hstep, voffA);
;             PG8_WAIT_V(8); PG8_WAIT_L(0); PG8_BAR; PG8_MMA(0, 0, At, B0); PG8_MMA(0, 1, At, B1); PG8_BAR; PG8_SCHED;
	v_mfma_f32_16x16x32_bf16 v[60:63], v[144:147], v[182:185], 0
	v_mfma_f32_16x16x32_bf16 v[56:59], v[158:161], v[182:185], 0
	v_mfma_f32_16x16x32_bf16 v[48:51], v[144:147], v[190:193], 0
	v_mfma_f32_16x16x32_bf16 v[40:43], v[158:161], v[190:193], 0
	v_mfma_f32_16x16x32_bf16 v[32:35], v[144:147], v[198:201], 0
	v_mfma_f32_16x16x32_bf16 v[24:27], v[158:161], v[198:201], 0
	v_mfma_f32_16x16x32_bf16 v[16:19], v[144:147], v[206:209], 0
	v_mfma_f32_16x16x32_bf16 v[8:11], v[158:161], v[206:209], 0
	v_mfma_f32_16x16x32_bf16 v[60:63], v[148:151], v[186:189], v[60:63]
	v_mfma_f32_16x16x32_bf16 v[56:59], v[162:165], v[186:189], v[56:59]
	v_mfma_f32_16x16x32_bf16 v[48:51], v[148:151], v[194:197], v[48:51]
	v_mfma_f32_16x16x32_bf16 v[40:43], v[162:165], v[194:197], v[40:43]
	v_mfma_f32_16x16x32_bf16 v[32:35], v[148:151], v[202:205], v[32:35]
	v_mfma_f32_16x16x32_bf16 v[24:27], v[162:165], v[202:205], v[24:27]
	v_mfma_f32_16x16x32_bf16 v[16:19], v[148:151], v[214:217], v[16:19]
	v_mfma_f32_16x16x32_bf16 v[8:11], v[162:165], v[214:217], v[8:11]
	v_mfma_f32_16x16x32_bf16 v[52:55], v[166:169], v[182:185], 0
	v_mfma_f32_16x16x32_bf16 v[44:47], v[174:177], v[182:185], 0
	v_mfma_f32_16x16x32_bf16 v[36:39], v[166:169], v[190:193], 0
	v_mfma_f32_16x16x32_bf16 v[28:31], v[174:177], v[190:193], 0
	v_mfma_f32_16x16x32_bf16 v[20:23], v[166:169], v[198:201], 0
	v_mfma_f32_16x16x32_bf16 v[12:15], v[174:177], v[198:201], 0
	v_mfma_f32_16x16x32_bf16 v[4:7], v[166:169], v[206:209], 0
	v_mfma_f32_16x16x32_bf16 v[0:3], v[174:177], v[206:209], 0
	v_mfma_f32_16x16x32_bf16 v[52:55], v[170:173], v[186:189], v[52:55]
	v_mfma_f32_16x16x32_bf16 v[44:47], v[178:181], v[186:189], v[44:47]
	v_mfma_f32_16x16x32_bf16 v[36:39], v[170:173], v[194:197], v[36:39]
	v_mfma_f32_16x16x32_bf16 v[28:31], v[178:181], v[194:197], v[28:31]
	v_mfma_f32_16x16x32_bf16 v[20:23], v[170:173], v[202:205], v[20:23]
	v_mfma_f32_16x16x32_bf16 v[12:15], v[178:181], v[202:205], v[12:15]
	v_mfma_f32_16x16x32_bf16 v[4:7], v[170:173], v[214:217], v[4:7]
	v_mfma_f32_16x16x32_bf16 v[0:3], v[178:181], v[214:217], v[0:3]
	s_barrier
	s_add_i32 s70, 0, 0x18000
	s_add_i32 s71, 0, 0x1c000
	ds_read_b128 v[144:147], v210
	ds_read_b128 v[148:151], v210 offset:1024
	ds_read_b128 v[158:161], v210 offset:2048
	ds_read_b128 v[162:165], v210 offset:3072
	ds_read_b128 v[166:169], v211
	ds_read_b128 v[170:173], v211 offset:1024
	ds_read_b128 v[174:177], v211 offset:2048
	ds_read_b128 v[178:181], v211 offset:3072
	s_add_u32 s80, s50, 0x80
	s_addc_u32 s81, s51, 0
	s_add_u32 s50, s50, 0x40000
	s_addc_u32 s51, s51, 0
	s_mov_b32 m0, s55
	ds_read_b128 v[182:185], v157 offset:32768
	ds_read_b128 v[186:189], v157 offset:33792
	ds_read_b128 v[190:193], v157 offset:34816
	ds_read_b128 v[194:197], v157 offset:35840
	ds_read_b128 v[198:201], v157 offset:36864
	ds_read_b128 v[202:205], v157 offset:37888
	ds_read_b128 v[206:209], v157 offset:38912
	ds_read_b128 v[214:217], v157 offset:39936
	global_load_lds_dwordx4 v128, s[50:51]
	s_mov_b32 m0, s56
	s_nop 0
	global_load_lds_dwordx4 v132, s[50:51]
	s_waitcnt vmcnt(8) lgkmcnt(0)
	s_barrier
	v_mfma_f32_16x16x32_bf16 v[124:127], v[144:147], v[182:185], v[124:127]
	v_mfma_f32_16x16x32_bf16 v[120:123], v[158:161], v[182:185], v[120:123]
	v_mfma_f32_16x16x32_bf16 v[116:119], v[144:147], v[190:193], v[116:119]
	v_mfma_f32_16x16x32_bf16 v[112:115], v[158:161], v[190:193], v[112:115]
	v_mfma_f32_16x16x32_bf16 v[96:99], v[144:147], v[198:201], v[96:99]
	v_mfma_f32_16x16x32_bf16 v[88:91], v[158:161], v[198:201], v[88:91]
	v_mfma_f32_16x16x32_bf16 v[80:83], v[144:147], v[206:209], v[80:83]
	v_mfma_f32_16x16x32_bf16 v[72:75], v[158:161], v[206:209], v[72:75]
	v_mfma_f32_16x16x32_bf16 v[124:127], v[148:151], v[186:189], v[124:127]
	v_mfma_f32_16x16x32_bf16 v[120:123], v[162:165], v[186:189], v[120:123]
	v_mfma_f32_16x16x32_bf16 v[116:119], v[148:151], v[194:197], v[116:119]
	v_mfma_f32_16x16x32_bf16 v[112:115], v[162:165], v[194:197], v[112:115]
	v_mfma_f32_16x16x32_bf16 v[96:99], v[148:151], v[202:205], v[96:99]
	v_mfma_f32_16x16x32_bf16 v[88:91], v[162:165], v[202:205], v[88:91]
	v_mfma_f32_16x16x32_bf16 v[80:83], v[148:151], v[214:217], v[80:83]
	v_mfma_f32_16x16x32_bf16 v[72:75], v[162:165], v[214:217], v[72:75]
	v_mfma_f32_16x16x32_bf16 v[108:111], v[166:169], v[182:185], v[108:111]
	v_mfma_f32_16x16x32_bf16 v[104:107], v[174:177], v[182:185], v[104:107]
	v_mfma_f32_16x16x32_bf16 v[100:103], v[166:169], v[190:193], v[100:103]
	v_mfma_f32_16x16x32_bf16 v[92:95], v[174:177], v[190:193], v[92:95]
	v_mfma_f32_16x16x32_bf16 v[84:87], v[166:169], v[198:201], v[84:87]
	v_mfma_f32_16x16x32_bf16 v[76:79], v[174:177], v[198:201], v[76:79]
	v_mfma_f32_16x16x32_bf16 v[68:71], v[166:169], v[206:209], v[68:71]
	v_mfma_f32_16x16x32_bf16 v[64:67], v[174:177], v[206:209], v[64:67]
	v_mfma_f32_16x16x32_bf16 v[108:111], v[170:173], v[186:189], v[108:111]
	v_mfma_f32_16x16x32_bf16 v[104:107], v[178:181], v[186:189], v[104:107]
	v_mfma_f32_16x16x32_bf16 v[100:103], v[170:173], v[194:197], v[100:103]
	v_mfma_f32_16x16x32_bf16 v[92:95], v[178:181], v[194:197], v[92:95]
	v_mfma_f32_16x16x32_bf16 v[84:87], v[170:173], v[202:205], v[84:87]
	v_mfma_f32_16x16x32_bf16 v[76:79], v[178:181], v[202:205], v[76:79]
	v_mfma_f32_16x16x32_bf16 v[68:71], v[170:173], v[214:217], v[68:71]
	v_mfma_f32_16x16x32_bf16 v[64:67], v[178:181], v[214:217], v[64:67]
	s_barrier
; #define PG8_STAGE(bufoff, gbase, voff) do { _Pragma("unroll") for (int _i = 0; _i < 2; ++_i) \
;         __builtin_amdgcn_global_load_lds((const unsigned*)((const char*)(gbase) + (voff)[_i]), (PG8_LAS unsigned*)(lds + (bufoff) + ldsw + _i * 8192), 16, 0, 0); } while (0)
; #define PG8_LDA(dst, b, h) do { _Pragma("unroll") for (int m = 0; m < 4; ++m) _Pragma("unroll") for (int k = 0; k < 2; ++k) dst[m][k] = *(const PG8_LAS bf16x8*)(lds + PG8_SA(b, h) + aoff + m * 2048 + k * 1024); } while (0)
; #define PG8_LDB(dst, b, h) do { _Pragma("unroll") for (int n = 0; n < 2; ++n) _Pragma("unroll") for (int k = 0; k < 2; ++k) dst[n][k] = *(const PG8_LAS bf16x8*)(lds + PG8_SB(b, h) + boff + n * 2048 + k * 1024); } while (0)
; #define PG8_MMA(ai, bj, At, Bt) do { __builtin_amdgcn_s_setprio(1); _Pragma("unroll") for (int m = 0; m < 4; ++m) _Pragma("unroll") for (int n = 0; n < 2; ++n) _Pragma("unroll") for (int k = 0; k < 2; ++k) \
;         acc[ai][bj][m][n] = __builtin_amdgcn_mfma_f32_16x16x32_bf16(Bt[n][k], At[m][k], acc[ai][bj][m][n], 0, 0, 0); __builtin_amdgcn_s_setprio(0); } while (0)
; #define PG8_WAIT_V(n) asm volatile("s_waitcnt vmcnt(" #n ")" ::: "memory")
; #define PG8_BAR __builtin_amdgcn_s_barrier()
; template <class Epi, class Sched, bool ALIGN_EPI = false, bool SP2 = false>
; __device__ __forceinline__ void gemm_phase(PG8_LAS unsigned char* lds, const Gemm g, const Sched& S, const Epi& E) {
;     ...
;         for (int t = 0; t < nt; t += 2) {
;             const bool last = (t == nt - 2);
;             const char* a1 = cA + (size_t)(t + 1) * kstep;
;             const char* a2 = last ? nA : cA + (size_t)(t + 2) * kstep; const char* b2 = last ? nB : cB + (size_t)(t + 2) * kstep;
;             const char* a3 = a2 + kstep; const char* b3 = b2 + kstep;
;             if (last && has_next) S.a_ready(nxt);
;             if constexpr (SP2) {
;             PG8_LDB(B0, 0, 0); PG8_LDB(B1, 0, 1); PG8_SCHED; PG8_LDA(At, 0, 0); PG8_STAGE(PG8_SA(1, 1), a1 + hstep, voffA);
;             PG8_WAIT_V(8); PG8_WAIT_L(0); PG8_BAR; PG8_MMA(0, 0, At, B0); PG8_MMA(0, 1, At, B1); PG8_BAR; PG8_SCHED;
;     ...
;             PG8_LDA(At, 1, 1); PG8_STAGE(PG8_SB(1, 0), b3, voffB); PG8_STAGE(PG8_SB(1, 1), b3 + hstep, voffB); PG8_STAGE(PG8_SA(1, 0), a3, voffA);
;             PG8_WAIT_V(8); PG8_WAIT_L(0); PG8_BAR; PG8_MMA(1, 0, At, B0); PG8_MMA(1, 1, At, B1); PG8_BAR; PG8_SCHED;
	s_add_i32 s50, s70, s53
	s_add_u32 s82, s48, 0x80
	s_addc_u32 s83, s49, 0
	s_mov_b32 m0, s50
	ds_read_b128 v[182:185], v157 offset:49152
	ds_read_b128 v[186:189], v157 offset:50176
	ds_read_b128 v[190:193], v157 offset:51200
	ds_read_b128 v[194:197], v157 offset:52224
	ds_read_b128 v[198:201], v157 offset:53248
	ds_read_b128 v[202:205], v157 offset:54272
	ds_read_b128 v[206:209], v157 offset:55296
	ds_read_b128 v[214:217], v157 offset:56320
	global_load_lds_dwordx4 v130, s[82:83]
	s_add_i32 m0, s50, 0x2000
	s_add_u32 s48, s48, 0x40080
	s_addc_u32 s49, s49, 0
	s_add_i32 s50, s71, s53
	global_load_lds_dwordx4 v134, s[82:83]
	s_mov_b32 m0, s50
	s_nop 0
	global_load_lds_dwordx4 v130, s[48:49]
	s_add_i32 m0, s50, 0x2000
	s_nop 0
	global_load_lds_dwordx4 v134, s[48:49]
	s_mov_b32 m0, s58
	s_nop 0
	global_load_lds_dwordx4 v128, s[80:81]
	s_mov_b32 m0, s59
	s_nop 0
	global_load_lds_dwordx4 v132, s[80:81]
	s_waitcnt vmcnt(8) lgkmcnt(0)
	s_barrier
	v_mfma_f32_16x16x32_bf16 v[60:63], v[144:147], v[182:185], v[60:63]
	v_mfma_f32_16x16x32_bf16 v[56:59], v[158:161], v[182:185], v[56:59]
	v_mfma_f32_16x16x32_bf16 v[48:51], v[144:147], v[190:193], v[48:51]
	v_mfma_f32_16x16x32_bf16 v[40:43], v[158:161], v[190:193], v[40:43]
	v_mfma_f32_16x16x32_bf16 v[32:35], v[144:147], v[198:201], v[32:35]
	v_mfma_f32_16x16x32_bf16 v[24:27], v[158:161], v[198:201], v[24:27]
	v_mfma_f32_16x16x32_bf16 v[16:19], v[144:147], v[206:209], v[16:19]
	v_mfma_f32_16x16x32_bf16 v[8:11], v[158:161], v[206:209], v[8:11]
	v_mfma_f32_16x16x32_bf16 v[60:63], v[148:151], v[186:189], v[60:63]
	v_mfma_f32_16x16x32_bf16 v[56:59], v[162:165], v[186:189], v[56:59]
	v_mfma_f32_16x16x32_bf16 v[48:51], v[148:151], v[194:197], v[48:51]
	v_mfma_f32_16x16x32_bf16 v[40:43], v[162:165], v[194:197], v[40:43]
	v_mfma_f32_16x16x32_bf16 v[32:35], v[148:151], v[202:205], v[32:35]
	v_mfma_f32_16x16x32_bf16 v[24:27], v[162:165], v[202:205], v[24:27]
	v_mfma_f32_16x16x32_bf16 v[16:19], v[148:151], v[214:217], v[16:19]
	v_mfma_f32_16x16x32_bf16 v[8:11], v[162:165], v[214:217], v[8:11]
	v_mfma_f32_16x16x32_bf16 v[52:55], v[166:169], v[182:185], v[52:55]
	v_mfma_f32_16x16x32_bf16 v[44:47], v[174:177], v[182:185], v[44:47]
	v_mfma_f32_16x16x32_bf16 v[36:39], v[166:169], v[190:193], v[36:39]
	v_mfma_f32_16x16x32_bf16 v[28:31], v[174:177], v[190:193], v[28:31]
	v_mfma_f32_16x16x32_bf16 v[20:23], v[166:169], v[198:201], v[20:23]
	v_mfma_f32_16x16x32_bf16 v[12:15], v[174:177], v[198:201], v[12:15]
	v_mfma_f32_16x16x32_bf16 v[4:7], v[166:169], v[206:209], v[4:7]
	v_mfma_f32_16x16x32_bf16 v[0:3], v[174:177], v[206:209], v[0:3]
	v_mfma_f32_16x16x32_bf16 v[52:55], v[170:173], v[186:189], v[52:55]
	v_mfma_f32_16x16x32_bf16 v[44:47], v[178:181], v[186:189], v[44:47]
	v_mfma_f32_16x16x32_bf16 v[36:39], v[170:173], v[194:197], v[36:39]
	v_mfma_f32_16x16x32_bf16 v[28:31], v[178:181], v[194:197], v[28:31]
	v_mfma_f32_16x16x32_bf16 v[20:23], v[170:173], v[202:205], v[20:23]
	v_mfma_f32_16x16x32_bf16 v[12:15], v[178:181], v[202:205], v[12:15]
	v_mfma_f32_16x16x32_bf16 v[4:7], v[170:173], v[214:217], v[4:7]
	v_mfma_f32_16x16x32_bf16 v[0:3], v[178:181], v[214:217], v[0:3]
	s_barrier
	s_add_i32 s69, s69, 2
	s_add_u32 s46, s46, 0x100
	s_addc_u32 s47, s47, 0
	s_add_u32 s67, s67, 0x100
	s_addc_u32 s68, s68, 0
	s_cmp_gt_u32 s69, 13
.LBB0_735:
	ds_read_b128 v[144:147], v155
	ds_read_b128 v[148:151], v155 offset:1024
	ds_read_b128 v[158:161], v155 offset:2048
	ds_read_b128 v[162:165], v155 offset:3072
	ds_read_b128 v[166:169], v156
	ds_read_b128 v[170:173], v156 offset:1024
	ds_read_b128 v[174:177], v156 offset:2048
	ds_read_b128 v[178:181], v156 offset:3072
	s_add_u32 s48, s46, 0xfffc0080
	s_addc_u32 s49, s47, -1
	s_cmp_eq_u32 s69, 12
	s_cselect_b32 s51, s39, s49
	s_cselect_b32 s50, s65, s48
	s_cselect_b32 s49, s37, s68
	s_cselect_b32 s48, s66, s67
	s_add_i32 m0, s45, 0xc000
	ds_read_b128 v[182:185], v157
	ds_read_b128 v[186:189], v157 offset:1024
	ds_read_b128 v[190:193], v157 offset:2048
	ds_read_b128 v[194:197], v157 offset:3072
	ds_read_b128 v[198:201], v157 offset:4096
	ds_read_b128 v[202:205], v157 offset:5120
	ds_read_b128 v[206:209], v157 offset:6144
	ds_read_b128 v[214:217], v157 offset:7168
	global_load_lds_dwordx4 v136, s[46:47]
	s_add_i32 m0, s45, 0xe000
	s_nop 0
	global_load_lds_dwordx4 v138, s[46:47]
	s_waitcnt vmcnt(8) lgkmcnt(0)
	s_barrier
	v_mfma_f32_16x16x32_bf16 v[124:127], v[144:147], v[182:185], v[124:127]
	v_mfma_f32_16x16x32_bf16 v[120:123], v[158:161], v[182:185], v[120:123]
	v_mfma_f32_16x16x32_bf16 v[116:119], v[144:147], v[190:193], v[116:119]
	v_mfma_f32_16x16x32_bf16 v[112:115], v[158:161], v[190:193], v[112:115]
	v_mfma_f32_16x16x32_bf16 v[96:99], v[144:147], v[198:201], v[96:99]
	v_mfma_f32_16x16x32_bf16 v[88:91], v[158:161], v[198:201], v[88:91]
	v_mfma_f32_16x16x32_bf16 v[80:83], v[144:147], v[206:209], v[80:83]
	v_mfma_f32_16x16x32_bf16 v[72:75], v[158:161], v[206:209], v[72:75]
	v_mfma_f32_16x16x32_bf16 v[124:127], v[148:151], v[186:189], v[124:127]
	v_mfma_f32_16x16x32_bf16 v[120:123], v[162:165], v[186:189], v[120:123]
	v_mfma_f32_16x16x32_bf16 v[116:119], v[148:151], v[194:197], v[116:119]
	v_mfma_f32_16x16x32_bf16 v[112:115], v[162:165], v[194:197], v[112:115]
	v_mfma_f32_16x16x32_bf16 v[96:99], v[148:151], v[202:205], v[96:99]
	v_mfma_f32_16x16x32_bf16 v[88:91], v[162:165], v[202:205], v[88:91]
	v_mfma_f32_16x16x32_bf16 v[80:83], v[148:151], v[214:217], v[80:83]
	v_mfma_f32_16x16x32_bf16 v[72:75], v[162:165], v[214:217], v[72:75]
	v_mfma_f32_16x16x32_bf16 v[108:111], v[166:169], v[182:185], v[108:111]
	v_mfma_f32_16x16x32_bf16 v[104:107], v[174:177], v[182:185], v[104:107]
	v_mfma_f32_16x16x32_bf16 v[100:103], v[166:169], v[190:193], v[100:103]
	v_mfma_f32_16x16x32_bf16 v[92:95], v[174:177], v[190:193], v[92:95]
	v_mfma_f32_16x16x32_bf16 v[84:87], v[166:169], v[198:201], v[84:87]
	v_mfma_f32_16x16x32_bf16 v[76:79], v[174:177], v[198:201], v[76:79]
	v_mfma_f32_16x16x32_bf16 v[68:71], v[166:169], v[206:209], v[68:71]
	v_mfma_f32_16x16x32_bf16 v[64:67], v[174:177], v[206:209], v[64:67]
	v_mfma_f32_16x16x32_bf16 v[108:111], v[170:173], v[186:189], v[108:111]
	v_mfma_f32_16x16x32_bf16 v[104:107], v[178:181], v[186:189], v[104:107]
	v_mfma_f32_16x16x32_bf16 v[100:103], v[170:173], v[194:197], v[100:103]
	v_mfma_f32_16x16x32_bf16 v[92:95], v[178:181], v[194:197], v[92:95]
	v_mfma_f32_16x16x32_bf16 v[84:87], v[170:173], v[202:205], v[84:87]
	v_mfma_f32_16x16x32_bf16 v[76:79], v[178:181], v[202:205], v[76:79]
	v_mfma_f32_16x16x32_bf16 v[68:71], v[170:173], v[214:217], v[68:71]
	v_mfma_f32_16x16x32_bf16 v[64:67], v[178:181], v[214:217], v[64:67]
	s_barrier
; #define PG8_STAGE(bufoff, gbase, voff) do { _Pragma("unroll") for (int _i = 0; _i < 2; ++_i) \
;         __builtin_amdgcn_global_load_lds((const unsigned*)((const char*)(gbase) + (voff)[_i]), (PG8_LAS unsigned*)(lds + (bufoff) + ldsw + _i * 8192), 16, 0, 0); } while (0)
; #define PG8_LDA(dst, b, h) do { _Pragma("unroll") for (int m = 0; m < 4; ++m) _Pragma("unroll") for (int k = 0; k < 2; ++k) dst[m][k] = *(const PG8_LAS bf16x8*)(lds + PG8_SA(b, h) + aoff + m * 2048 + k * 1024); } while (0)
; #define PG8_LDB(dst, b, h) do { _Pragma("unroll") for (int n = 0; n < 2; ++n) _Pragma("unroll") for (int k = 0; k < 2; ++k) dst[n][k] = *(const PG8_LAS bf16x8*)(lds + PG8_SB(b, h) + boff + n * 2048 + k * 1024); } while (0)
; #define PG8_MMA(ai, bj, At, Bt) do { __builtin_amdgcn_s_setprio(1); _Pragma("unroll") for (int m = 0; m < 4; ++m) _Pragma("unroll") for (int n = 0; n < 2; ++n) _Pragma("unroll") for (int k = 0; k < 2; ++k) \
;         acc[ai][bj][m][n] = __builtin_amdgcn_mfma_f32_16x16x32_bf16(Bt[n][k], At[m][k], acc[ai][bj][m][n], 0, 0, 0); __builtin_amdgcn_s_setprio(0); } while (0)
; #define PG8_WAIT_V(n) asm volatile("s_waitcnt vmcnt(" #n ")" ::: "memory")
; #define PG8_WAIT_L(n) asm volatile("s_waitcnt lgkmcnt(" #n ")" ::: "memory")
; #define PG8_BAR __builtin_amdgcn_s_barrier()
; #define PG8_SCHED __builtin_amdgcn_sched_barrier(0)
; template <class Epi, class Sched, bool ALIGN_EPI = false, bool SP2 = false>
; __device__ __forceinline__ void gemm_phase(PG8_LAS unsigned char* lds, const Gemm g, const Sched& S, const Epi& E) {
;     ...
;             PG8_LDA(At, 0, 1); PG8_STAGE(PG8_SB(0, 0), b2, voffB); PG8_STAGE(PG8_SB(0, 1), b2 + hstep, voffB); PG8_STAGE(PG8_SA(0, 0), a2, voffA);
;             PG8_WAIT_V(8); PG8_WAIT_L(0); PG8_BAR; PG8_MMA(1, 0, At, B0); PG8_MMA(1, 1, At, B1); PG8_BAR; PG8_SCHED;
;             PG8_LDB(B0, 1, 0); PG8_LDB(B1, 1, 1); PG8_SCHED; PG8_LDA(At, 1, 0); PG8_STAGE(PG8_SA(0, 1), a2 + hstep, voffA);
;             PG8_WAIT_V(8); PG8_WAIT_L(0); PG8_BAR; PG8_MMA(0, 0, At, B0); PG8_MMA(0, 1, At, B1); PG8_BAR; PG8_SCHED;
	s_add_i32 s70, s62, s53
	s_mov_b32 m0, s70
	ds_read_b128 v[182:185], v157 offset:16384
	ds_read_b128 v[186:189], v157 offset:17408
	ds_read_b128 v[190:193], v157 offset:18432
	ds_read_b128 v[194:197], v157 offset:19456
	ds_read_b128 v[198:201], v157 offset:20480
	ds_read_b128 v[202:205], v157 offset:21504
	ds_read_b128 v[206:209], v157 offset:22528
	ds_read_b128 v[214:217], v157 offset:23552
	global_load_lds_dwordx4 v130, s[48:49]
	s_add_i32 m0, s70, 0x2000
	s_add_u32 s70, s48, 0x40000
	s_addc_u32 s71, s49, 0
	s_add_i32 s72, s63, s53
	global_load_lds_dwordx4 v134, s[48:49]
	s_mov_b32 m0, s72
	s_nop 0
	global_load_lds_dwordx4 v130, s[70:71]
	s_add_i32 m0, s72, 0x2000
	s_nop 0
	global_load_lds_dwordx4 v134, s[70:71]
	s_mov_b32 m0, s45
	s_nop 0
	global_load_lds_dwordx4 v128, s[50:51]
	s_mov_b32 m0, s54
	s_nop 0
	global_load_lds_dwordx4 v132, s[50:51]
	s_waitcnt vmcnt(8) lgkmcnt(0)
	s_barrier
	v_mfma_f32_16x16x32_bf16 v[60:63], v[144:147], v[182:185], v[60:63]
	v_mfma_f32_16x16x32_bf16 v[56:59], v[158:161], v[182:185], v[56:59]
	v_mfma_f32_16x16x32_bf16 v[48:51], v[144:147], v[190:193], v[48:51]
	v_mfma_f32_16x16x32_bf16 v[40:43], v[158:161], v[190:193], v[40:43]
	v_mfma_f32_16x16x32_bf16 v[32:35], v[144:147], v[198:201], v[32:35]
	v_mfma_f32_16x16x32_bf16 v[24:27], v[158:161], v[198:201], v[24:27]
	v_mfma_f32_16x16x32_bf16 v[16:19], v[144:147], v[206:209], v[16:19]
	v_mfma_f32_16x16x32_bf16 v[8:11], v[158:161], v[206:209], v[8:11]
	v_mfma_f32_16x16x32_bf16 v[60:63], v[148:151], v[186:189], v[60:63]
	v_mfma_f32_16x16x32_bf16 v[56:59], v[162:165], v[186:189], v[56:59]
	v_mfma_f32_16x16x32_bf16 v[48:51], v[148:151], v[194:197], v[48:51]
	v_mfma_f32_16x16x32_bf16 v[40:43], v[162:165], v[194:197], v[40:43]
	v_mfma_f32_16x16x32_bf16 v[32:35], v[148:151], v[202:205], v[32:35]
	v_mfma_f32_16x16x32_bf16 v[24:27], v[162:165], v[202:205], v[24:27]
	v_mfma_f32_16x16x32_bf16 v[16:19], v[148:151], v[214:217], v[16:19]
	v_mfma_f32_16x16x32_bf16 v[8:11], v[162:165], v[214:217], v[8:11]
	v_mfma_f32_16x16x32_bf16 v[52:55], v[166:169], v[182:185], v[52:55]
	v_mfma_f32_16x16x32_bf16 v[44:47], v[174:177], v[182:185], v[44:47]
	v_mfma_f32_16x16x32_bf16 v[36:39], v[166:169], v[190:193], v[36:39]
	v_mfma_f32_16x16x32_bf16 v[28:31], v[174:177], v[190:193], v[28:31]
	v_mfma_f32_16x16x32_bf16 v[20:23], v[166:169], v[198:201], v[20:23]
	v_mfma_f32_16x16x32_bf16 v[12:15], v[174:177], v[198:201], v[12:15]
	v_mfma_f32_16x16x32_bf16 v[4:7], v[166:169], v[206:209], v[4:7]
	v_mfma_f32_16x16x32_bf16 v[0:3], v[174:177], v[206:209], v[0:3]
	v_mfma_f32_16x16x32_bf16 v[52:55], v[170:173], v[186:189], v[52:55]
	v_mfma_f32_16x16x32_bf16 v[44:47], v[178:181], v[186:189], v[44:47]
	v_mfma_f32_16x16x32_bf16 v[36:39], v[170:173], v[194:197], v[36:39]
	v_mfma_f32_16x16x32_bf16 v[28:31], v[178:181], v[194:197], v[28:31]
	v_mfma_f32_16x16x32_bf16 v[20:23], v[170:173], v[202:205], v[20:23]
	v_mfma_f32_16x16x32_bf16 v[12:15], v[178:181], v[202:205], v[12:15]
	v_mfma_f32_16x16x32_bf16 v[4:7], v[170:173], v[214:217], v[4:7]
	v_mfma_f32_16x16x32_bf16 v[0:3], v[178:181], v[214:217], v[0:3]
	s_barrier
	s_add_i32 s70, 0, 0x18000
	s_add_i32 s71, 0, 0x1c000
	ds_read_b128 v[144:147], v210
	ds_read_b128 v[148:151], v210 offset:1024
	ds_read_b128 v[158:161], v210 offset:2048
	ds_read_b128 v[162:165], v210 offset:3072
	ds_read_b128 v[166:169], v211
	ds_read_b128 v[170:173], v211 offset:1024
	ds_read_b128 v[174:177], v211 offset:2048
	ds_read_b128 v[178:181], v211 offset:3072
	s_add_u32 s80, s50, 0x80
	s_addc_u32 s81, s51, 0
	s_add_u32 s50, s50, 0x40000
	s_addc_u32 s51, s51, 0
	s_mov_b32 m0, s55
	ds_read_b128 v[182:185], v157 offset:32768
	ds_read_b128 v[186:189], v157 offset:33792
	ds_read_b128 v[190:193], v157 offset:34816
	ds_read_b128 v[194:197], v157 offset:35840
	ds_read_b128 v[198:201], v157 offset:36864
	ds_read_b128 v[202:205], v157 offset:37888
	ds_read_b128 v[206:209], v157 offset:38912
	ds_read_b128 v[214:217], v157 offset:39936
	global_load_lds_dwordx4 v128, s[50:51]
	s_mov_b32 m0, s56
	s_nop 0
	global_load_lds_dwordx4 v132, s[50:51]
	s_waitcnt vmcnt(8) lgkmcnt(0)
	s_barrier
	v_mfma_f32_16x16x32_bf16 v[124:127], v[144:147], v[182:185], v[124:127]
	v_mfma_f32_16x16x32_bf16 v[120:123], v[158:161], v[182:185], v[120:123]
	v_mfma_f32_16x16x32_bf16 v[116:119], v[144:147], v[190:193], v[116:119]
	v_mfma_f32_16x16x32_bf16 v[112:115], v[158:161], v[190:193], v[112:115]
	v_mfma_f32_16x16x32_bf16 v[96:99], v[144:147], v[198:201], v[96:99]
	v_mfma_f32_16x16x32_bf16 v[88:91], v[158:161], v[198:201], v[88:91]
	v_mfma_f32_16x16x32_bf16 v[80:83], v[144:147], v[206:209], v[80:83]
	v_mfma_f32_16x16x32_bf16 v[72:75], v[158:161], v[206:209], v[72:75]
	v_mfma_f32_16x16x32_bf16 v[124:127], v[148:151], v[186:189], v[124:127]
	v_mfma_f32_16x16x32_bf16 v[120:123], v[162:165], v[186:189], v[120:123]
	v_mfma_f32_16x16x32_bf16 v[116:119], v[148:151], v[194:197], v[116:119]
	v_mfma_f32_16x16x32_bf16 v[112:115], v[162:165], v[194:197], v[112:115]
	v_mfma_f32_16x16x32_bf16 v[96:99], v[148:151], v[202:205], v[96:99]
	v_mfma_f32_16x16x32_bf16 v[88:91], v[162:165], v[202:205], v[88:91]
	v_mfma_f32_16x16x32_bf16 v[80:83], v[148:151], v[214:217], v[80:83]
	v_mfma_f32_16x16x32_bf16 v[72:75], v[162:165], v[214:217], v[72:75]
	v_mfma_f32_16x16x32_bf16 v[108:111], v[166:169], v[182:185], v[108:111]
	v_mfma_f32_16x16x32_bf16 v[104:107], v[174:177], v[182:185], v[104:107]
	v_mfma_f32_16x16x32_bf16 v[100:103], v[166:169], v[190:193], v[100:103]
	v_mfma_f32_16x16x32_bf16 v[92:95], v[174:177], v[190:193], v[92:95]
	v_mfma_f32_16x16x32_bf16 v[84:87], v[166:169], v[198:201], v[84:87]
	v_mfma_f32_16x16x32_bf16 v[76:79], v[174:177], v[198:201], v[76:79]
	v_mfma_f32_16x16x32_bf16 v[68:71], v[166:169], v[206:209], v[68:71]
	v_mfma_f32_16x16x32_bf16 v[64:67], v[174:177], v[206:209], v[64:67]
	v_mfma_f32_16x16x32_bf16 v[108:111], v[170:173], v[186:189], v[108:111]
	v_mfma_f32_16x16x32_bf16 v[104:107], v[178:181], v[186:189], v[104:107]
	v_mfma_f32_16x16x32_bf16 v[100:103], v[170:173], v[194:197], v[100:103]
	v_mfma_f32_16x16x32_bf16 v[92:95], v[178:181], v[194:197], v[92:95]
	v_mfma_f32_16x16x32_bf16 v[84:87], v[170:173], v[202:205], v[84:87]
	v_mfma_f32_16x16x32_bf16 v[76:79], v[178:181], v[202:205], v[76:79]
	v_mfma_f32_16x16x32_bf16 v[68:71], v[170:173], v[214:217], v[68:71]
	v_mfma_f32_16x16x32_bf16 v[64:67], v[178:181], v[214:217], v[64:67]
	s_barrier
; #define PG8_STAGE(bufoff, gbase, voff) do { _Pragma("unroll") for (int _i = 0; _i < 2; ++_i) \
;         __builtin_amdgcn_global_load_lds((const unsigned*)((const char*)(gbase) + (voff)[_i]), (PG8_LAS unsigned*)(lds + (bufoff) + ldsw + _i * 8192), 16, 0, 0); } while (0)
; #define PG8_LDA(dst, b, h) do { _Pragma("unroll") for (int m = 0; m < 4; ++m) _Pragma("unroll") for (int k = 0; k < 2; ++k) dst[m][k] = *(const PG8_LAS bf16x8*)(lds + PG8_SA(b, h) + aoff + m * 2048 + k * 1024); } while (0)
; #define PG8_WAIT_V(n) asm volatile("s_waitcnt vmcnt(" #n ")" ::: "memory")
; #define PG8_WAIT_L(n) asm volatile("s_waitcnt lgkmcnt(" #n ")" ::: "memory")
; #define PG8_BAR __builtin_amdgcn_s_barrier()
; #define PG8_SCHED __builtin_amdgcn_sched_barrier(0)
;     __device__ __forceinline__ void operator()(const f32x4 (&acc)[2][2][4][2], const Unit& u, int wr, int wc, int fr, int fq) const {
;         const int row0 = u.pm * BM + wr * 64 + fr, col0 = u.pn * BM + wc * 32 + 8 * fq;
; #pragma unroll
;         for (int ai = 0; ai < 2; ++ai) { u32x4 gw[4][2], pw[4][2];
; #pragma unroll
;             for (int m = 0; m < 4; ++m) { const size_t off = (size_t)(row0 + ai * HALF + m * 16) * 2048 + col0;
; #pragma unroll
;                 for (int bj = 0; bj < 2; ++bj) { gw[m][bj] = *(const u32x4*)(G + off + bj * HALF); if (PASS == 1) pw[m][bj] = *(const u32x4*)(MIX + off + bj * HALF); } }
; template <class Epi, class Sched, bool ALIGN_EPI = false, bool SP2 = false>
; __device__ __forceinline__ void gemm_phase(PG8_LAS unsigned char* lds, const Gemm g, const Sched& S, const Epi& E) {
;     ...
;             PG8_LDA(At, 1, 1); PG8_STAGE(PG8_SB(1, 0), b3, voffB); PG8_STAGE(PG8_SB(1, 1), b3 + hstep, voffB); PG8_STAGE(PG8_SA(1, 0), a3, voffA);
;             PG8_WAIT_V(8); PG8_WAIT_L(0); PG8_BAR; PG8_MMA(1, 0, At, B0); PG8_MMA(1, 1, At, B1); PG8_BAR; PG8_SCHED;
;     ...
;         if constexpr (ALIGN_EPI) { if (wr == 0) PG8_BAR; }
;         if constexpr (!Epi::AFTER_DRAIN) { E(acc, cur, wr, wc, fr, fq); S.done(cur); }
;         if (!has_next) break;
; #pragma unroll
;         for (int a = 0; a < 2; ++a)
; #pragma unroll
;             for (int b = 0; b < 2; ++b)
; #pragma unroll
;                 for (int m = 0; m < 4; ++m)
; #pragma unroll
;                     for (int n = 0; n < 2; ++n) acc[a][b][m][n] = (f32x4){0.f, 0.f, 0.f, 0.f};
;         cur = nxt; cA = nA; cB = nB; ++ui;
	s_add_i32 s50, s70, s53
	s_add_u32 s82, s48, 0x80
	s_addc_u32 s83, s49, 0
	s_mov_b32 m0, s50
	ds_read_b128 v[182:185], v157 offset:49152
	ds_read_b128 v[186:189], v157 offset:50176
	ds_read_b128 v[190:193], v157 offset:51200
	ds_read_b128 v[194:197], v157 offset:52224
	ds_read_b128 v[198:201], v157 offset:53248
	ds_read_b128 v[202:205], v157 offset:54272
	ds_read_b128 v[206:209], v157 offset:55296
	ds_read_b128 v[214:217], v157 offset:56320
	global_load_lds_dwordx4 v130, s[82:83]
	s_add_i32 m0, s50, 0x2000
	s_add_u32 s48, s48, 0x40080
	s_addc_u32 s49, s49, 0
	s_add_i32 s50, s71, s53
	global_load_lds_dwordx4 v134, s[82:83]
	s_mov_b32 m0, s50
	s_nop 0
	global_load_lds_dwordx4 v130, s[48:49]
	s_add_i32 m0, s50, 0x2000
	s_nop 0
	global_load_lds_dwordx4 v134, s[48:49]
	s_mov_b32 m0, s58
	s_nop 0
	global_load_lds_dwordx4 v128, s[80:81]
	s_mov_b32 m0, s59
	s_nop 0
	global_load_lds_dwordx4 v132, s[80:81]
	s_waitcnt vmcnt(8) lgkmcnt(0)
	s_barrier
	v_mfma_f32_16x16x32_bf16 v[60:63], v[144:147], v[182:185], v[60:63]
	v_mfma_f32_16x16x32_bf16 v[56:59], v[158:161], v[182:185], v[56:59]
	v_mfma_f32_16x16x32_bf16 v[48:51], v[144:147], v[190:193], v[48:51]
	v_mfma_f32_16x16x32_bf16 v[40:43], v[158:161], v[190:193], v[40:43]
	v_mfma_f32_16x16x32_bf16 v[32:35], v[144:147], v[198:201], v[32:35]
	v_mfma_f32_16x16x32_bf16 v[24:27], v[158:161], v[198:201], v[24:27]
	v_mfma_f32_16x16x32_bf16 v[16:19], v[144:147], v[206:209], v[16:19]
	v_mfma_f32_16x16x32_bf16 v[8:11], v[158:161], v[206:209], v[8:11]
	v_mfma_f32_16x16x32_bf16 v[60:63], v[148:151], v[186:189], v[60:63]
	v_mfma_f32_16x16x32_bf16 v[56:59], v[162:165], v[186:189], v[56:59]
	v_mfma_f32_16x16x32_bf16 v[48:51], v[148:151], v[194:197], v[48:51]
	v_mfma_f32_16x16x32_bf16 v[40:43], v[162:165], v[194:197], v[40:43]
	v_mfma_f32_16x16x32_bf16 v[32:35], v[148:151], v[202:205], v[32:35]
	v_mfma_f32_16x16x32_bf16 v[24:27], v[162:165], v[202:205], v[24:27]
	v_mfma_f32_16x16x32_bf16 v[16:19], v[148:151], v[214:217], v[16:19]
	v_mfma_f32_16x16x32_bf16 v[8:11], v[162:165], v[214:217], v[8:11]
	v_mfma_f32_16x16x32_bf16 v[52:55], v[166:169], v[182:185], v[52:55]
	v_mfma_f32_16x16x32_bf16 v[44:47], v[174:177], v[182:185], v[44:47]
	v_mfma_f32_16x16x32_bf16 v[36:39], v[166:169], v[190:193], v[36:39]
	v_mfma_f32_16x16x32_bf16 v[28:31], v[174:177], v[190:193], v[28:31]
	v_mfma_f32_16x16x32_bf16 v[20:23], v[166:169], v[198:201], v[20:23]
	v_mfma_f32_16x16x32_bf16 v[12:15], v[174:177], v[198:201], v[12:15]
	v_mfma_f32_16x16x32_bf16 v[4:7], v[166:169], v[206:209], v[4:7]
	v_mfma_f32_16x16x32_bf16 v[0:3], v[174:177], v[206:209], v[0:3]
	v_mfma_f32_16x16x32_bf16 v[52:55], v[170:173], v[186:189], v[52:55]
	v_mfma_f32_16x16x32_bf16 v[44:47], v[178:181], v[186:189], v[44:47]
	v_mfma_f32_16x16x32_bf16 v[36:39], v[170:173], v[194:197], v[36:39]
	v_mfma_f32_16x16x32_bf16 v[28:31], v[178:181], v[194:197], v[28:31]
	v_mfma_f32_16x16x32_bf16 v[20:23], v[170:173], v[202:205], v[20:23]
	v_mfma_f32_16x16x32_bf16 v[12:15], v[178:181], v[202:205], v[12:15]
	v_mfma_f32_16x16x32_bf16 v[4:7], v[170:173], v[214:217], v[4:7]
	v_mfma_f32_16x16x32_bf16 v[0:3], v[178:181], v[214:217], v[0:3]
	s_barrier
	s_add_i32 s69, s69, 2
	s_add_u32 s46, s46, 0x100
	s_addc_u32 s47, s47, 0
	s_add_u32 s67, s67, 0x100
	s_addc_u32 s68, s68, 0
	s_cmp_gt_u32 s69, 13
	s_cbranch_scc0 .LBB0_735
	v_lshl_add_u32 v150, s44, 8, v152
	v_lshl_or_b32 v144, s64, 8, v154
	v_ashrrev_i32_e32 v145, 31, v144
	v_or_b32_e32 v166, 16, v150
	v_lshlrev_b64 v[144:145], 1, v[144:145]
	v_ashrrev_i32_e32 v151, 31, v150
	v_ashrrev_i32_e32 v167, 31, v166
	v_lshl_add_u64 v[146:147], s[12:13], 0, v[144:145]
	v_lshlrev_b64 v[148:149], 12, v[150:151]
	v_lshlrev_b64 v[178:179], 12, v[166:167]
	v_lshl_add_u64 v[162:163], v[146:147], 0, v[148:149]
	v_lshl_add_u64 v[170:171], v[146:147], 0, v[178:179]
	global_load_dwordx4 v[158:161], v[162:163], off
	s_nop 0
	global_load_dwordx4 v[162:165], v[162:163], off offset:256
	s_nop 0
	global_load_dwordx4 v[166:169], v[170:171], off
	s_nop 0
	global_load_dwordx4 v[170:173], v[170:171], off offset:256
	v_or_b32_e32 v174, 32, v150
	v_ashrrev_i32_e32 v175, 31, v174
	v_lshlrev_b64 v[190:191], 12, v[174:175]
	v_lshl_add_u64 v[180:181], v[146:147], 0, v[190:191]
	global_load_dwordx4 v[174:177], v[180:181], off
	v_or_b32_e32 v150, 48, v150
	v_ashrrev_i32_e32 v151, 31, v150
	v_lshlrev_b64 v[150:151], 12, v[150:151]
	v_lshl_add_u64 v[182:183], s[14:15], 0, v[148:149]
	v_lshl_add_u64 v[186:187], v[146:147], 0, v[150:151]
	v_lshl_add_u64 v[192:193], v[182:183], 0, v[144:145]
	v_lshl_add_u64 v[194:195], s[14:15], 0, v[178:179]
	global_load_dwordx4 v[178:181], v[180:181], off offset:256
	s_nop 0
	global_load_dwordx4 v[182:185], v[186:187], off
	s_nop 0
	global_load_dwordx4 v[186:189], v[186:187], off offset:256
	v_lshl_add_u64 v[194:195], v[194:195], 0, v[144:145]
	s_and_b64 vcc, exec, s[10:11]
	s_mov_b32 s64, s36
	s_mov_b32 s44, s38
	s_mov_b64 s[48:49], s[42:43]
	s_mov_b64 s[46:47], s[40:41]
	s_waitcnt vmcnt(0)
; __device__ __forceinline__ float bf_lo(unsigned w) { return __uint_as_float(w << 16); }
; __device__ __forceinline__ float bf_hi(unsigned w) { return __uint_as_float(w & 0xffff0000u); }
; __device__ __forceinline__ u32x4 pack8(const f32x4 a, const f32x4 b) { u32x4 w; w.x = cvt_pk_bf16(a[0], a[1]); w.y = cvt_pk_bf16(a[2], a[3]); w.z = cvt_pk_bf16(b[0], b[1]); w.w = cvt_pk_bf16(b[2], b[3]); return w; }
;     __device__ __forceinline__ void operator()(const f32x4 (&acc)[2][2][4][2], const Unit& u, int wr, int wc, int fr, int fq) const {
;     ...
;             for (int m = 0; m < 4; ++m) { const size_t off = (size_t)(row0 + ai * HALF + m * 16) * 2048 + col0;
; #pragma unroll
;                 for (int bj = 0; bj < 2; ++bj) { gw[m][bj] = *(const u32x4*)(G + off + bj * HALF); if (PASS == 1) pw[m][bj] = *(const u32x4*)(MIX + off + bj * HALF); } }
;     ...
;             for (int m = 0; m < 4; ++m) { const size_t off = (size_t)(row0 + ai * HALF + m * 16) * 2048 + col0;
; #pragma unroll
;                 for (int bj = 0; bj < 2; ++bj) { const u32x4 g4 = gw[m][bj];
;                     f32x4 v0 = (f32x4){bf_lo(g4.x), bf_hi(g4.x), bf_lo(g4.y), bf_hi(g4.y)} * acc[ai][bj][m][0], v1 = (f32x4){bf_lo(g4.z), bf_hi(g4.z), bf_lo(g4.w), bf_hi(g4.w)} * acc[ai][bj][m][1];
;                     if (PASS == 1) { const u32x4 p4 = pw[m][bj]; v0 += (f32x4){bf_lo(p4.x), bf_hi(p4.x), bf_lo(p4.y), bf_hi(p4.y)}; v1 += (f32x4){bf_lo(p4.z), bf_hi(p4.z), bf_lo(p4.w), bf_hi(p4.w)}; }
;                     *(u32x4*)(MIX + off + bj * HALF) = pack8(v0, v1); } } }
	v_lshlrev_b32_e32 v196, 16, v158
	v_and_b32_e32 v197, 0xffff0000, v158
	v_lshlrev_b32_e32 v158, 16, v159
	v_and_b32_e32 v159, 0xffff0000, v159
	v_lshlrev_b32_e32 v198, 16, v160
	v_and_b32_e32 v199, 0xffff0000, v160
	v_lshlrev_b32_e32 v160, 16, v161
	v_and_b32_e32 v161, 0xffff0000, v161
	v_lshlrev_b32_e32 v200, 16, v162
	v_and_b32_e32 v201, 0xffff0000, v162
	v_lshlrev_b32_e32 v162, 16, v163
	v_and_b32_e32 v163, 0xffff0000, v163
	v_lshlrev_b32_e32 v202, 16, v164
	v_and_b32_e32 v203, 0xffff0000, v164
	v_lshlrev_b32_e32 v164, 16, v165
	v_and_b32_e32 v165, 0xffff0000, v165
	v_lshlrev_b32_e32 v204, 16, v166
	v_and_b32_e32 v205, 0xffff0000, v166
	v_lshlrev_b32_e32 v166, 16, v167
	v_and_b32_e32 v167, 0xffff0000, v167
	v_lshlrev_b32_e32 v206, 16, v168
	v_and_b32_e32 v207, 0xffff0000, v168
	v_lshlrev_b32_e32 v168, 16, v169
	v_and_b32_e32 v169, 0xffff0000, v169
	v_lshlrev_b32_e32 v208, 16, v170
	v_and_b32_e32 v209, 0xffff0000, v170
	v_lshlrev_b32_e32 v170, 16, v171
	v_and_b32_e32 v171, 0xffff0000, v171
	v_pk_mul_f32 v[126:127], v[126:127], v[158:159]
	v_pk_mul_f32 v[124:125], v[124:125], v[196:197]
	v_pk_mul_f32 v[122:123], v[122:123], v[160:161]
	v_pk_mul_f32 v[120:121], v[120:121], v[198:199]
	v_pk_mul_f32 v[110:111], v[110:111], v[162:163]
	v_pk_mul_f32 v[108:109], v[108:109], v[200:201]
	v_pk_mul_f32 v[158:159], v[106:107], v[164:165]
	v_pk_mul_f32 v[106:107], v[104:105], v[202:203]
	v_pk_mul_f32 v[118:119], v[118:119], v[166:167]
	v_pk_mul_f32 v[116:117], v[116:117], v[204:205]
	v_pk_mul_f32 v[114:115], v[114:115], v[168:169]
	v_pk_mul_f32 v[112:113], v[112:113], v[206:207]
	v_pk_mul_f32 v[160:161], v[102:103], v[170:171]
	v_pk_mul_f32 v[162:163], v[100:101], v[208:209]
	v_cvt_pk_bf16_f32 v100, v124, v125
	v_cvt_pk_bf16_f32 v101, v126, v127
	v_cvt_pk_bf16_f32 v102, v120, v121
	v_cvt_pk_bf16_f32 v103, v122, v123
	v_cvt_pk_bf16_f32 v104, v108, v109
	v_cvt_pk_bf16_f32 v105, v110, v111
	v_cvt_pk_bf16_f32 v106, v106, v107
	v_cvt_pk_bf16_f32 v107, v158, v159
	v_cvt_pk_bf16_f32 v108, v116, v117
	v_cvt_pk_bf16_f32 v109, v118, v119
	v_cvt_pk_bf16_f32 v110, v112, v113
	v_cvt_pk_bf16_f32 v111, v114, v115
	global_store_dwordx4 v[192:193], v[100:103], off
	global_store_dwordx4 v[192:193], v[104:107], off offset:256
	global_store_dwordx4 v[194:195], v[108:111], off
	v_lshlrev_b32_e32 v100, 16, v172
	v_and_b32_e32 v101, 0xffff0000, v172
	v_lshlrev_b32_e32 v102, 16, v173
	v_and_b32_e32 v103, 0xffff0000, v173
	v_pk_mul_f32 v[102:103], v[94:95], v[102:103]
	v_pk_mul_f32 v[94:95], v[92:93], v[100:101]
	v_cvt_pk_bf16_f32 v92, v162, v163
	v_cvt_pk_bf16_f32 v93, v160, v161
	v_cvt_pk_bf16_f32 v94, v94, v95
	v_cvt_pk_bf16_f32 v95, v102, v103
	global_store_dwordx4 v[194:195], v[92:95], off offset:256
	v_lshl_add_u64 v[100:101], v[148:149], 0, s[30:31]
	v_lshl_add_u64 v[102:103], v[148:149], 0, s[34:35]
	v_lshlrev_b32_e32 v92, 16, v174
	v_and_b32_e32 v93, 0xffff0000, v174
	v_lshlrev_b32_e32 v94, 16, v175
	v_and_b32_e32 v95, 0xffff0000, v175
	v_pk_mul_f32 v[94:95], v[98:99], v[94:95]
	v_pk_mul_f32 v[92:93], v[96:97], v[92:93]
	v_lshlrev_b32_e32 v96, 16, v176
	v_and_b32_e32 v97, 0xffff0000, v176
	v_lshlrev_b32_e32 v98, 16, v177
	v_and_b32_e32 v99, 0xffff0000, v177
	v_pk_mul_f32 v[98:99], v[90:91], v[98:99]
	v_pk_mul_f32 v[90:91], v[88:89], v[96:97]
	v_cvt_pk_bf16_f32 v88, v92, v93
	v_lshl_add_u64 v[92:93], s[14:15], 0, v[190:191]
	v_cvt_pk_bf16_f32 v89, v94, v95
	v_cvt_pk_bf16_f32 v90, v90, v91
	v_cvt_pk_bf16_f32 v91, v98, v99
	v_lshl_add_u64 v[92:93], v[92:93], 0, v[144:145]
	global_store_dwordx4 v[92:93], v[88:91], off
	v_lshl_add_u64 v[96:97], v[148:149], 0, s[26:27]
	v_lshl_add_u64 v[98:99], v[148:149], 0, s[28:29]
	v_lshlrev_b32_e32 v88, 16, v178
	v_and_b32_e32 v89, 0xffff0000, v178
	v_lshlrev_b32_e32 v90, 16, v179
	v_and_b32_e32 v91, 0xffff0000, v179
	v_pk_mul_f32 v[86:87], v[86:87], v[90:91]
	v_pk_mul_f32 v[84:85], v[84:85], v[88:89]
	v_lshlrev_b32_e32 v88, 16, v180
	v_and_b32_e32 v89, 0xffff0000, v180
	v_lshlrev_b32_e32 v90, 16, v181
	v_and_b32_e32 v91, 0xffff0000, v181
	v_pk_mul_f32 v[90:91], v[78:79], v[90:91]
	v_pk_mul_f32 v[78:79], v[76:77], v[88:89]
	v_cvt_pk_bf16_f32 v76, v84, v85
	v_cvt_pk_bf16_f32 v77, v86, v87
	v_cvt_pk_bf16_f32 v78, v78, v79
	v_cvt_pk_bf16_f32 v79, v90, v91
	global_store_dwordx4 v[92:93], v[76:79], off offset:256
	s_nop 1
	v_lshlrev_b32_e32 v76, 16, v182
	v_and_b32_e32 v77, 0xffff0000, v182
	v_lshlrev_b32_e32 v78, 16, v183
	v_and_b32_e32 v79, 0xffff0000, v183
	v_pk_mul_f32 v[78:79], v[82:83], v[78:79]
	v_pk_mul_f32 v[76:77], v[80:81], v[76:77]
	v_lshlrev_b32_e32 v80, 16, v184
	v_and_b32_e32 v81, 0xffff0000, v184
	v_lshlrev_b32_e32 v82, 16, v185
	v_and_b32_e32 v83, 0xffff0000, v185
	v_pk_mul_f32 v[82:83], v[74:75], v[82:83]
	v_pk_mul_f32 v[74:75], v[72:73], v[80:81]
	v_cvt_pk_bf16_f32 v72, v76, v77
	v_lshl_add_u64 v[76:77], s[14:15], 0, v[150:151]
	v_cvt_pk_bf16_f32 v73, v78, v79
	v_cvt_pk_bf16_f32 v74, v74, v75
	v_cvt_pk_bf16_f32 v75, v82, v83
	v_lshl_add_u64 v[76:77], v[76:77], 0, v[144:145]
	global_store_dwordx4 v[76:77], v[72:75], off
	s_nop 1
	v_lshlrev_b32_e32 v72, 16, v186
	v_and_b32_e32 v73, 0xffff0000, v186
	v_lshlrev_b32_e32 v74, 16, v187
	v_and_b32_e32 v75, 0xffff0000, v187
	v_pk_mul_f32 v[70:71], v[70:71], v[74:75]
	v_pk_mul_f32 v[68:69], v[68:69], v[72:73]
	v_lshlrev_b32_e32 v72, 16, v188
	v_and_b32_e32 v73, 0xffff0000, v188
	v_lshlrev_b32_e32 v74, 16, v189
	v_and_b32_e32 v75, 0xffff0000, v189
	v_pk_mul_f32 v[74:75], v[66:67], v[74:75]
	v_pk_mul_f32 v[66:67], v[64:65], v[72:73]
	v_cvt_pk_bf16_f32 v64, v68, v69
	v_cvt_pk_bf16_f32 v65, v70, v71
	v_cvt_pk_bf16_f32 v66, v66, v67
	v_cvt_pk_bf16_f32 v67, v74, v75
	global_store_dwordx4 v[76:77], v[64:67], off offset:256
	s_nop 1
	v_lshl_add_u64 v[64:65], v[146:147], 0, v[96:97]
	global_load_dwordx4 v[68:71], v[64:65], off
	global_load_dwordx4 v[72:75], v[64:65], off offset:256
	v_lshl_add_u64 v[64:65], v[146:147], 0, v[98:99]
	global_load_dwordx4 v[76:79], v[64:65], off
	global_load_dwordx4 v[80:83], v[64:65], off offset:256
	v_lshl_add_u64 v[64:65], v[146:147], 0, v[100:101]
	global_load_dwordx4 v[84:87], v[64:65], off
	global_load_dwordx4 v[88:91], v[64:65], off offset:256
	v_lshl_add_u64 v[64:65], v[146:147], 0, v[102:103]
	global_load_dwordx4 v[92:95], v[64:65], off
	s_nop 0
	global_load_dwordx4 v[64:67], v[64:65], off offset:256
	s_waitcnt vmcnt(7)
; __device__ __forceinline__ float bf_lo(unsigned w) { return __uint_as_float(w << 16); }
; __device__ __forceinline__ float bf_hi(unsigned w) { return __uint_as_float(w & 0xffff0000u); }
; __device__ __forceinline__ u32x4 pack8(const f32x4 a, const f32x4 b) { u32x4 w; w.x = cvt_pk_bf16(a[0], a[1]); w.y = cvt_pk_bf16(a[2], a[3]); w.z = cvt_pk_bf16(b[0], b[1]); w.w = cvt_pk_bf16(b[2], b[3]); return w; }
; #define PG8_WAIT_V(n) asm volatile("s_waitcnt vmcnt(" #n ")" ::: "memory")
; #define PG8_BAR __builtin_amdgcn_s_barrier()
;     __device__ __forceinline__ void operator()(const f32x4 (&acc)[2][2][4][2], const Unit& u, int wr, int wc, int fr, int fq) const {
;     ...
;             for (int m = 0; m < 4; ++m) { const size_t off = (size_t)(row0 + ai * HALF + m * 16) * 2048 + col0;
; #pragma unroll
;                 for (int bj = 0; bj < 2; ++bj) { const u32x4 g4 = gw[m][bj];
;                     f32x4 v0 = (f32x4){bf_lo(g4.x), bf_hi(g4.x), bf_lo(g4.y), bf_hi(g4.y)} * acc[ai][bj][m][0], v1 = (f32x4){bf_lo(g4.z), bf_hi(g4.z), bf_lo(g4.w), bf_hi(g4.w)} * acc[ai][bj][m][1];
;                     if (PASS == 1) { const u32x4 p4 = pw[m][bj]; v0 += (f32x4){bf_lo(p4.x), bf_hi(p4.x), bf_lo(p4.y), bf_hi(p4.y)}; v1 += (f32x4){bf_lo(p4.z), bf_hi(p4.z), bf_lo(p4.w), bf_hi(p4.w)}; }
;                     *(u32x4*)(MIX + off + bj * HALF) = pack8(v0, v1); } } }
; template <class Epi, class Sched, bool ALIGN_EPI = false, bool SP2 = false>
; __device__ __forceinline__ void gemm_phase(PG8_LAS unsigned char* lds, const Gemm g, const Sched& S, const Epi& E) {
;     ...
;     PG8_WAIT_V(0);
;     if constexpr (!ALIGN_EPI) { if (wr == 0) PG8_BAR; }
;     PG8_BAR;
	v_lshlrev_b32_e32 v104, 16, v68
	v_and_b32_e32 v105, 0xffff0000, v68
	v_lshlrev_b32_e32 v68, 16, v69
	v_and_b32_e32 v69, 0xffff0000, v69
	v_pk_mul_f32 v[62:63], v[62:63], v[68:69]
	v_pk_mul_f32 v[60:61], v[60:61], v[104:105]
	v_lshlrev_b32_e32 v68, 16, v70
	v_and_b32_e32 v69, 0xffff0000, v70
	v_lshlrev_b32_e32 v70, 16, v71
	v_and_b32_e32 v71, 0xffff0000, v71
	v_pk_mul_f32 v[70:71], v[58:59], v[70:71]
	v_pk_mul_f32 v[58:59], v[56:57], v[68:69]
	v_cvt_pk_bf16_f32 v56, v60, v61
	v_lshl_add_u64 v[60:61], s[14:15], 0, v[96:97]
	v_cvt_pk_bf16_f32 v57, v62, v63
	v_cvt_pk_bf16_f32 v58, v58, v59
	v_cvt_pk_bf16_f32 v59, v70, v71
	v_lshl_add_u64 v[60:61], v[60:61], 0, v[144:145]
	global_store_dwordx4 v[60:61], v[56:59], off
	s_waitcnt vmcnt(7)
	s_nop 0
	v_lshlrev_b32_e32 v56, 16, v72
	v_and_b32_e32 v57, 0xffff0000, v72
	v_lshlrev_b32_e32 v58, 16, v73
	v_and_b32_e32 v59, 0xffff0000, v73
	v_pk_mul_f32 v[54:55], v[54:55], v[58:59]
	v_pk_mul_f32 v[52:53], v[52:53], v[56:57]
	v_lshlrev_b32_e32 v56, 16, v74
	v_and_b32_e32 v57, 0xffff0000, v74
	v_lshlrev_b32_e32 v58, 16, v75
	v_and_b32_e32 v59, 0xffff0000, v75
	v_pk_mul_f32 v[58:59], v[46:47], v[58:59]
	v_pk_mul_f32 v[46:47], v[44:45], v[56:57]
	v_cvt_pk_bf16_f32 v44, v52, v53
	v_cvt_pk_bf16_f32 v45, v54, v55
	v_cvt_pk_bf16_f32 v46, v46, v47
	v_cvt_pk_bf16_f32 v47, v58, v59
	global_store_dwordx4 v[60:61], v[44:47], off offset:256
	s_waitcnt vmcnt(7)
	s_nop 0
	v_lshlrev_b32_e32 v44, 16, v76
	v_and_b32_e32 v45, 0xffff0000, v76
	v_lshlrev_b32_e32 v46, 16, v77
	v_and_b32_e32 v47, 0xffff0000, v77
	v_pk_mul_f32 v[46:47], v[50:51], v[46:47]
	v_pk_mul_f32 v[44:45], v[48:49], v[44:45]
	v_lshlrev_b32_e32 v48, 16, v78
	v_and_b32_e32 v49, 0xffff0000, v78
	v_lshlrev_b32_e32 v50, 16, v79
	v_and_b32_e32 v51, 0xffff0000, v79
	v_pk_mul_f32 v[50:51], v[42:43], v[50:51]
	v_pk_mul_f32 v[42:43], v[40:41], v[48:49]
	v_cvt_pk_bf16_f32 v40, v44, v45
	v_lshl_add_u64 v[44:45], s[14:15], 0, v[98:99]
	v_cvt_pk_bf16_f32 v41, v46, v47
	v_cvt_pk_bf16_f32 v42, v42, v43
	v_cvt_pk_bf16_f32 v43, v50, v51
	v_lshl_add_u64 v[44:45], v[44:45], 0, v[144:145]
	global_store_dwordx4 v[44:45], v[40:43], off
	s_waitcnt vmcnt(7)
	s_nop 0
	v_lshlrev_b32_e32 v40, 16, v80
	v_and_b32_e32 v41, 0xffff0000, v80
	v_lshlrev_b32_e32 v42, 16, v81
	v_and_b32_e32 v43, 0xffff0000, v81
	v_pk_mul_f32 v[38:39], v[38:39], v[42:43]
	v_pk_mul_f32 v[36:37], v[36:37], v[40:41]
	v_lshlrev_b32_e32 v40, 16, v82
	v_and_b32_e32 v41, 0xffff0000, v82
	v_lshlrev_b32_e32 v42, 16, v83
	v_and_b32_e32 v43, 0xffff0000, v83
	v_pk_mul_f32 v[42:43], v[30:31], v[42:43]
	v_pk_mul_f32 v[30:31], v[28:29], v[40:41]
	v_cvt_pk_bf16_f32 v28, v36, v37
	v_cvt_pk_bf16_f32 v29, v38, v39
	v_cvt_pk_bf16_f32 v30, v30, v31
	v_cvt_pk_bf16_f32 v31, v42, v43
	global_store_dwordx4 v[44:45], v[28:31], off offset:256
	s_waitcnt vmcnt(7)
	s_nop 0
	v_lshlrev_b32_e32 v28, 16, v84
	v_and_b32_e32 v29, 0xffff0000, v84
	v_lshlrev_b32_e32 v30, 16, v85
	v_and_b32_e32 v31, 0xffff0000, v85
	v_pk_mul_f32 v[30:31], v[34:35], v[30:31]
	v_pk_mul_f32 v[28:29], v[32:33], v[28:29]
	v_lshlrev_b32_e32 v32, 16, v86
	v_and_b32_e32 v33, 0xffff0000, v86
	v_lshlrev_b32_e32 v34, 16, v87
	v_and_b32_e32 v35, 0xffff0000, v87
	v_pk_mul_f32 v[34:35], v[26:27], v[34:35]
	v_pk_mul_f32 v[26:27], v[24:25], v[32:33]
	v_cvt_pk_bf16_f32 v24, v28, v29
	v_lshl_add_u64 v[28:29], s[14:15], 0, v[100:101]
	v_cvt_pk_bf16_f32 v25, v30, v31
	v_cvt_pk_bf16_f32 v26, v26, v27
	v_cvt_pk_bf16_f32 v27, v34, v35
	v_lshl_add_u64 v[28:29], v[28:29], 0, v[144:145]
	global_store_dwordx4 v[28:29], v[24:27], off
	s_waitcnt vmcnt(7)
	s_nop 0
	v_lshlrev_b32_e32 v24, 16, v88
	v_and_b32_e32 v25, 0xffff0000, v88
	v_lshlrev_b32_e32 v26, 16, v89
	v_and_b32_e32 v27, 0xffff0000, v89
	v_pk_mul_f32 v[22:23], v[22:23], v[26:27]
	v_pk_mul_f32 v[20:21], v[20:21], v[24:25]
	v_lshlrev_b32_e32 v24, 16, v90
	v_and_b32_e32 v25, 0xffff0000, v90
	v_lshlrev_b32_e32 v26, 16, v91
	v_and_b32_e32 v27, 0xffff0000, v91
	v_pk_mul_f32 v[26:27], v[14:15], v[26:27]
	v_pk_mul_f32 v[14:15], v[12:13], v[24:25]
	v_cvt_pk_bf16_f32 v12, v20, v21
	v_cvt_pk_bf16_f32 v13, v22, v23
	v_cvt_pk_bf16_f32 v14, v14, v15
	v_cvt_pk_bf16_f32 v15, v26, v27
	global_store_dwordx4 v[28:29], v[12:15], off offset:256
	s_waitcnt vmcnt(7)
	s_nop 0
	v_lshlrev_b32_e32 v12, 16, v92
	v_and_b32_e32 v13, 0xffff0000, v92
	v_lshlrev_b32_e32 v14, 16, v93
	v_and_b32_e32 v15, 0xffff0000, v93
	v_pk_mul_f32 v[14:15], v[18:19], v[14:15]
	v_pk_mul_f32 v[12:13], v[16:17], v[12:13]
	v_lshlrev_b32_e32 v16, 16, v94
	v_and_b32_e32 v17, 0xffff0000, v94
	v_lshlrev_b32_e32 v18, 16, v95
	v_and_b32_e32 v19, 0xffff0000, v95
	v_pk_mul_f32 v[18:19], v[10:11], v[18:19]
	v_pk_mul_f32 v[10:11], v[8:9], v[16:17]
	v_cvt_pk_bf16_f32 v8, v12, v13
	v_lshl_add_u64 v[12:13], s[14:15], 0, v[102:103]
	v_cvt_pk_bf16_f32 v9, v14, v15
	v_cvt_pk_bf16_f32 v10, v10, v11
	v_cvt_pk_bf16_f32 v11, v18, v19
	v_lshl_add_u64 v[12:13], v[12:13], 0, v[144:145]
	global_store_dwordx4 v[12:13], v[8:11], off
	s_waitcnt vmcnt(7)
	s_nop 0
	v_lshlrev_b32_e32 v8, 16, v64
	v_and_b32_e32 v9, 0xffff0000, v64
	v_lshlrev_b32_e32 v10, 16, v65
	v_and_b32_e32 v11, 0xffff0000, v65
	v_pk_mul_f32 v[6:7], v[6:7], v[10:11]
	v_pk_mul_f32 v[4:5], v[4:5], v[8:9]
	v_lshlrev_b32_e32 v8, 16, v66
	v_and_b32_e32 v9, 0xffff0000, v66
	v_lshlrev_b32_e32 v10, 16, v67
	v_and_b32_e32 v11, 0xffff0000, v67
	v_pk_mul_f32 v[10:11], v[2:3], v[10:11]
	v_pk_mul_f32 v[2:3], v[0:1], v[8:9]
	v_cvt_pk_bf16_f32 v0, v4, v5
	v_cvt_pk_bf16_f32 v1, v6, v7
	v_cvt_pk_bf16_f32 v2, v2, v3
	v_cvt_pk_bf16_f32 v3, v10, v11
	global_store_dwordx4 v[12:13], v[0:3], off offset:256
	s_cbranch_vccz .LBB0_728
	s_waitcnt vmcnt(0)
	s_cmpk_gt_u32 s3, 0xff
	s_cbranch_scc1 .LBB0_739
	s_barrier

; #define PG8_STAGE(bufoff, gbase, voff) do { _Pragma("unroll") for (int _i = 0; _i < 2; ++_i) \
;         __builtin_amdgcn_global_load_lds((const unsigned*)((const char*)(gbase) + (voff)[_i]), (PG8_LAS unsigned*)(lds + (bufoff) + ldsw + _i * 8192), 16, 0, 0); } while (0)
; #define PG8_LDA(dst, b, h) do { _Pragma("unroll") for (int m = 0; m < 4; ++m) _Pragma("unroll") for (int k = 0; k < 2; ++k) dst[m][k] = *(const PG8_LAS bf16x8*)(lds + PG8_SA(b, h) + aoff + m * 2048 + k * 1024); } while (0)
; #define PG8_LDB(dst, b, h) do { _Pragma("unroll") for (int n = 0; n < 2; ++n) _Pragma("unroll") for (int k = 0; k < 2; ++k) dst[n][k] = *(const PG8_LAS bf16x8*)(lds + PG8_SB(b, h) + boff + n * 2048 + k * 1024); } while (0)
; #define PG8_MMA(ai, bj, At, Bt) do { __builtin_amdgcn_s_setprio(1); _Pragma("unroll") for (int m = 0; m < 4; ++m) _Pragma("unroll") for (int n = 0; n < 2; ++n) _Pragma("unroll") for (int k = 0; k < 2; ++k) \
;         acc[ai][bj][m][n] = __builtin_amdgcn_mfma_f32_16x16x32_bf16(Bt[n][k], At[m][k], acc[ai][bj][m][n], 0, 0, 0); __builtin_amdgcn_s_setprio(0); } while (0)
; #define PG8_BAR __builtin_amdgcn_s_barrier()
; template <class Epi, class Sched, bool ALIGN_EPI = false, bool SP2 = false>
; __device__ __forceinline__ void gemm_phase(PG8_LAS unsigned char* lds, const Gemm g, const Sched& S, const Epi& E) {
;     ...
;         const bool has_next = S.next(ui + 1, nxt);
;         const char* nA = has_next ? (const char*)g.A + (size_t)nxt.pm * tstep : cA; const char* nB = has_next ? (const char*)g.Bt + (size_t)nxt.pn * tstep : cB;
;         for (int t = 0; t < nt; t += 2) {
;             const bool last = (t == nt - 2);
;             const char* a1 = cA + (size_t)(t + 1) * kstep;
;             const char* a2 = last ? nA : cA + (size_t)(t + 2) * kstep; const char* b2 = last ? nB : cB + (size_t)(t + 2) * kstep;
;             const char* a3 = a2 + kstep; const char* b3 = b2 + kstep;
;             if (last && has_next) S.a_ready(nxt);
;             if constexpr (SP2) {
;             PG8_LDB(B0, 0, 0); PG8_LDB(B1, 0, 1); PG8_SCHED; PG8_LDA(At, 0, 0); PG8_STAGE(PG8_SA(1, 1), a1 + hstep, voffA);
;             PG8_WAIT_V(8); PG8_WAIT_L(0); PG8_BAR; PG8_MMA(0, 0, At, B0); PG8_MMA(0, 1, At, B1); PG8_BAR; PG8_SCHED;
;             PG8_LDA(At, 0, 1); PG8_STAGE(PG8_SB(0, 0), b2, voffB); PG8_STAGE(PG8_SB(0, 1), b2 + hstep, voffB); PG8_STAGE(PG8_SA(0, 0), a2, voffA);
.LBB0_754:
	s_ashr_i32 s29, s28, 31
	v_cmp_lt_i64_e32 vcc, s[30:31], v[160:161]
	s_lshl_b64 s[30:31], s[28:29], 19
	s_add_u32 s30, s9, s30
	s_addc_u32 s31, s22, s31
	s_and_b64 s[34:35], vcc, exec
	s_cselect_b32 s29, s31, s39
	s_cselect_b32 s57, s30, s38
	s_ashr_i32 s27, s26, 31
	s_lshl_b64 s[34:35], s[26:27], 19
	s_add_u32 s34, s23, s34
	s_addc_u32 s35, s44, s35
	s_and_b64 s[42:43], vcc, exec
	s_cselect_b32 s27, s35, s41
	s_cselect_b32 s58, s34, s40
	s_add_u32 s38, s38, 0x40080
	s_addc_u32 s39, s39, 0
	s_add_u32 s59, s40, 0x100
	s_addc_u32 s60, s41, 0
	s_mov_b32 s61, -2
	v_add_u32_e32 v172, 0x18000, v175
	v_add_u32_e32 v173, 0x1c000, v175
	ds_read_b128 v[128:131], v177
	ds_read_b128 v[132:135], v177 offset:1024
	ds_read_b128 v[136:139], v177 offset:2048
	ds_read_b128 v[140:143], v177 offset:3072
	ds_read_b128 v[144:147], v178
	ds_read_b128 v[164:167], v178 offset:1024
	ds_read_b128 v[168:171], v178 offset:2048
	ds_read_b128 v[180:183], v178 offset:3072
	s_add_u32 s40, s38, 0xfffc0080
	s_addc_u32 s41, s39, -1
	s_cmp_eq_u32 s61, 12
	s_cselect_b32 s43, s29, s41
	s_cselect_b32 s42, s57, s40
	s_cselect_b32 s41, s27, s60
	s_cselect_b32 s40, s58, s59
	s_add_i32 m0, s37, 0xc000
	ds_read_b128 v[184:187], v179
	ds_read_b128 v[188:191], v179 offset:1024
	ds_read_b128 v[192:195], v179 offset:2048
	ds_read_b128 v[196:199], v179 offset:3072
	ds_read_b128 v[200:203], v179 offset:4096
	ds_read_b128 v[204:207], v179 offset:5120
	ds_read_b128 v[208:211], v179 offset:6144
	ds_read_b128 v[214:217], v179 offset:7168
	global_load_lds_dwordx4 v156, s[38:39]
	s_add_i32 m0, s37, 0xe000
	s_nop 0
	global_load_lds_dwordx4 v158, s[38:39]
	s_waitcnt vmcnt(8) lgkmcnt(0)
	s_barrier
	v_mfma_f32_16x16x32_bf16 v[124:127], v[128:131], v[184:187], 0
	v_mfma_f32_16x16x32_bf16 v[120:123], v[136:139], v[184:187], 0
	v_mfma_f32_16x16x32_bf16 v[108:111], v[128:131], v[192:195], 0
	v_mfma_f32_16x16x32_bf16 v[104:107], v[136:139], v[192:195], 0
	v_mfma_f32_16x16x32_bf16 v[92:95], v[128:131], v[200:203], 0
	v_mfma_f32_16x16x32_bf16 v[88:91], v[136:139], v[200:203], 0
	v_mfma_f32_16x16x32_bf16 v[76:79], v[128:131], v[208:211], 0
	v_mfma_f32_16x16x32_bf16 v[72:75], v[136:139], v[208:211], 0
	v_mfma_f32_16x16x32_bf16 v[124:127], v[132:135], v[188:191], v[124:127]
	v_mfma_f32_16x16x32_bf16 v[120:123], v[140:143], v[188:191], v[120:123]
	v_mfma_f32_16x16x32_bf16 v[108:111], v[132:135], v[196:199], v[108:111]
	v_mfma_f32_16x16x32_bf16 v[104:107], v[140:143], v[196:199], v[104:107]
	v_mfma_f32_16x16x32_bf16 v[92:95], v[132:135], v[204:207], v[92:95]
	v_mfma_f32_16x16x32_bf16 v[88:91], v[140:143], v[204:207], v[88:91]
	v_mfma_f32_16x16x32_bf16 v[76:79], v[132:135], v[214:217], v[76:79]
	v_mfma_f32_16x16x32_bf16 v[72:75], v[140:143], v[214:217], v[72:75]
	v_mfma_f32_16x16x32_bf16 v[116:119], v[144:147], v[184:187], 0
	v_mfma_f32_16x16x32_bf16 v[112:115], v[168:171], v[184:187], 0
	v_mfma_f32_16x16x32_bf16 v[100:103], v[144:147], v[192:195], 0
	v_mfma_f32_16x16x32_bf16 v[96:99], v[168:171], v[192:195], 0
	v_mfma_f32_16x16x32_bf16 v[84:87], v[144:147], v[200:203], 0
	v_mfma_f32_16x16x32_bf16 v[80:83], v[168:171], v[200:203], 0
	v_mfma_f32_16x16x32_bf16 v[68:71], v[144:147], v[208:211], 0
	v_mfma_f32_16x16x32_bf16 v[64:67], v[168:171], v[208:211], 0
	v_mfma_f32_16x16x32_bf16 v[116:119], v[164:167], v[188:191], v[116:119]
	v_mfma_f32_16x16x32_bf16 v[112:115], v[180:183], v[188:191], v[112:115]
	v_mfma_f32_16x16x32_bf16 v[100:103], v[164:167], v[196:199], v[100:103]
	v_mfma_f32_16x16x32_bf16 v[96:99], v[180:183], v[196:199], v[96:99]
	v_mfma_f32_16x16x32_bf16 v[84:87], v[164:167], v[204:207], v[84:87]
	v_mfma_f32_16x16x32_bf16 v[80:83], v[180:183], v[204:207], v[80:83]
	v_mfma_f32_16x16x32_bf16 v[68:71], v[164:167], v[214:217], v[68:71]
	v_mfma_f32_16x16x32_bf16 v[64:67], v[180:183], v[214:217], v[64:67]
	s_barrier
	s_add_i32 s62, s54, s45
	s_mov_b32 m0, s62
	ds_read_b128 v[184:187], v179 offset:16384
	ds_read_b128 v[188:191], v179 offset:17408
	ds_read_b128 v[192:195], v179 offset:18432
	ds_read_b128 v[196:199], v179 offset:19456
	ds_read_b128 v[200:203], v179 offset:20480
	ds_read_b128 v[204:207], v179 offset:21504
	ds_read_b128 v[208:211], v179 offset:22528
	ds_read_b128 v[214:217], v179 offset:23552
	global_load_lds_dwordx4 v150, s[40:41]
	s_add_i32 m0, s62, 0x2000
	s_add_u32 s62, s40, 0x40000
	s_addc_u32 s63, s41, 0
	s_add_i32 s64, s55, s45
	global_load_lds_dwordx4 v154, s[40:41]
	s_mov_b32 m0, s64
	s_nop 0
	global_load_lds_dwordx4 v150, s[62:63]
	s_add_i32 m0, s64, 0x2000
	s_nop 0
	global_load_lds_dwordx4 v154, s[62:63]
	s_mov_b32 m0, s37
	s_nop 0
	global_load_lds_dwordx4 v148, s[42:43]
	s_mov_b32 m0, s46
	s_nop 0
	global_load_lds_dwordx4 v152, s[42:43]
	s_waitcnt vmcnt(8) lgkmcnt(0)
	s_barrier
; #define PG8_STAGE(bufoff, gbase, voff) do { _Pragma("unroll") for (int _i = 0; _i < 2; ++_i) \
;         __builtin_amdgcn_global_load_lds((const unsigned*)((const char*)(gbase) + (voff)[_i]), (PG8_LAS unsigned*)(lds + (bufoff) + ldsw + _i * 8192), 16, 0, 0); } while (0)
; #define PG8_LDA(dst, b, h) do { _Pragma("unroll") for (int m = 0; m < 4; ++m) _Pragma("unroll") for (int k = 0; k < 2; ++k) dst[m][k] = *(const PG8_LAS bf16x8*)(lds + PG8_SA(b, h) + aoff + m * 2048 + k * 1024); } while (0)
; #define PG8_LDB(dst, b, h) do { _Pragma("unroll") for (int n = 0; n < 2; ++n) _Pragma("unroll") for (int k = 0; k < 2; ++k) dst[n][k] = *(const PG8_LAS bf16x8*)(lds + PG8_SB(b, h) + boff + n * 2048 + k * 1024); } while (0)
; #define PG8_MMA(ai, bj, At, Bt) do { __builtin_amdgcn_s_setprio(1); _Pragma("unroll") for (int m = 0; m < 4; ++m) _Pragma("unroll") for (int n = 0; n < 2; ++n) _Pragma("unroll") for (int k = 0; k < 2; ++k) \
;         acc[ai][bj][m][n] = __builtin_amdgcn_mfma_f32_16x16x32_bf16(Bt[n][k], At[m][k], acc[ai][bj][m][n], 0, 0, 0); __builtin_amdgcn_s_setprio(0); } while (0)
; #define PG8_WAIT_V(n) asm volatile("s_waitcnt vmcnt(" #n ")" ::: "memory")
; #define PG8_WAIT_L(n) asm volatile("s_waitcnt lgkmcnt(" #n ")" ::: "memory")
; #define PG8_BAR __builtin_amdgcn_s_barrier()
; #define PG8_SCHED __builtin_amdgcn_sched_barrier(0)
; template <class Epi, class Sched, bool ALIGN_EPI = false, bool SP2 = false>
; __device__ __forceinline__ void gemm_phase(PG8_LAS unsigned char* lds, const Gemm g, const Sched& S, const Epi& E) {
;     ...
;             PG8_WAIT_V(8); PG8_WAIT_L(0); PG8_BAR; PG8_MMA(1, 0, At, B0); PG8_MMA(1, 1, At, B1); PG8_BAR; PG8_SCHED;
;             PG8_LDB(B0, 1, 0); PG8_LDB(B1, 1, 1); PG8_SCHED; PG8_LDA(At, 1, 0); PG8_STAGE(PG8_SA(0, 1), a2 + hstep, voffA);
;             PG8_WAIT_V(8); PG8_WAIT_L(0); PG8_BAR; PG8_MMA(0, 0, At, B0); PG8_MMA(0, 1, At, B1); PG8_BAR; PG8_SCHED;
	v_mfma_f32_16x16x32_bf16 v[60:63], v[128:131], v[184:187], 0
	v_mfma_f32_16x16x32_bf16 v[56:59], v[136:139], v[184:187], 0
	v_mfma_f32_16x16x32_bf16 v[44:47], v[128:131], v[192:195], 0
	v_mfma_f32_16x16x32_bf16 v[40:43], v[136:139], v[192:195], 0
	v_mfma_f32_16x16x32_bf16 v[28:31], v[128:131], v[200:203], 0
	v_mfma_f32_16x16x32_bf16 v[24:27], v[136:139], v[200:203], 0
	v_mfma_f32_16x16x32_bf16 v[12:15], v[128:131], v[208:211], 0
	v_mfma_f32_16x16x32_bf16 v[8:11], v[136:139], v[208:211], 0
	v_mfma_f32_16x16x32_bf16 v[60:63], v[132:135], v[188:191], v[60:63]
	v_mfma_f32_16x16x32_bf16 v[56:59], v[140:143], v[188:191], v[56:59]
	v_mfma_f32_16x16x32_bf16 v[44:47], v[132:135], v[196:199], v[44:47]
	v_mfma_f32_16x16x32_bf16 v[40:43], v[140:143], v[196:199], v[40:43]
	v_mfma_f32_16x16x32_bf16 v[28:31], v[132:135], v[204:207], v[28:31]
	v_mfma_f32_16x16x32_bf16 v[24:27], v[140:143], v[204:207], v[24:27]
	v_mfma_f32_16x16x32_bf16 v[12:15], v[132:135], v[214:217], v[12:15]
	v_mfma_f32_16x16x32_bf16 v[8:11], v[140:143], v[214:217], v[8:11]
	v_mfma_f32_16x16x32_bf16 v[52:55], v[144:147], v[184:187], 0
	v_mfma_f32_16x16x32_bf16 v[48:51], v[168:171], v[184:187], 0
	v_mfma_f32_16x16x32_bf16 v[36:39], v[144:147], v[192:195], 0
	v_mfma_f32_16x16x32_bf16 v[32:35], v[168:171], v[192:195], 0
	v_mfma_f32_16x16x32_bf16 v[20:23], v[144:147], v[200:203], 0
	v_mfma_f32_16x16x32_bf16 v[16:19], v[168:171], v[200:203], 0
	v_mfma_f32_16x16x32_bf16 v[4:7], v[144:147], v[208:211], 0
	v_mfma_f32_16x16x32_bf16 v[0:3], v[168:171], v[208:211], 0
	v_mfma_f32_16x16x32_bf16 v[52:55], v[164:167], v[188:191], v[52:55]
	v_mfma_f32_16x16x32_bf16 v[48:51], v[180:183], v[188:191], v[48:51]
	v_mfma_f32_16x16x32_bf16 v[36:39], v[164:167], v[196:199], v[36:39]
	v_mfma_f32_16x16x32_bf16 v[32:35], v[180:183], v[196:199], v[32:35]
	v_mfma_f32_16x16x32_bf16 v[20:23], v[164:167], v[204:207], v[20:23]
	v_mfma_f32_16x16x32_bf16 v[16:19], v[180:183], v[204:207], v[16:19]
	v_mfma_f32_16x16x32_bf16 v[4:7], v[164:167], v[214:217], v[4:7]
	v_mfma_f32_16x16x32_bf16 v[0:3], v[180:183], v[214:217], v[0:3]
	s_barrier
	s_add_i32 s62, 0, 0x18000
	s_add_i32 s63, 0, 0x1c000
	ds_read_b128 v[128:131], v172
	ds_read_b128 v[132:135], v172 offset:1024
	ds_read_b128 v[136:139], v172 offset:2048
	ds_read_b128 v[140:143], v172 offset:3072
	ds_read_b128 v[144:147], v173
	ds_read_b128 v[164:167], v173 offset:1024
	ds_read_b128 v[168:171], v173 offset:2048
	ds_read_b128 v[180:183], v173 offset:3072
	s_add_u32 s84, s42, 0x80
	s_addc_u32 s85, s43, 0
	s_add_u32 s42, s42, 0x40000
	s_addc_u32 s43, s43, 0
	s_mov_b32 m0, s47
	ds_read_b128 v[184:187], v179 offset:32768
	ds_read_b128 v[188:191], v179 offset:33792
	ds_read_b128 v[192:195], v179 offset:34816
	ds_read_b128 v[196:199], v179 offset:35840
	ds_read_b128 v[200:203], v179 offset:36864
	ds_read_b128 v[204:207], v179 offset:37888
	ds_read_b128 v[208:211], v179 offset:38912
	ds_read_b128 v[214:217], v179 offset:39936
	global_load_lds_dwordx4 v148, s[42:43]
	s_mov_b32 m0, s48
	s_nop 0
	global_load_lds_dwordx4 v152, s[42:43]
	s_waitcnt vmcnt(8) lgkmcnt(0)
	s_barrier
	v_mfma_f32_16x16x32_bf16 v[124:127], v[128:131], v[184:187], v[124:127]
	v_mfma_f32_16x16x32_bf16 v[120:123], v[136:139], v[184:187], v[120:123]
	v_mfma_f32_16x16x32_bf16 v[108:111], v[128:131], v[192:195], v[108:111]
	v_mfma_f32_16x16x32_bf16 v[104:107], v[136:139], v[192:195], v[104:107]
	v_mfma_f32_16x16x32_bf16 v[92:95], v[128:131], v[200:203], v[92:95]
	v_mfma_f32_16x16x32_bf16 v[88:91], v[136:139], v[200:203], v[88:91]
	v_mfma_f32_16x16x32_bf16 v[76:79], v[128:131], v[208:211], v[76:79]
	v_mfma_f32_16x16x32_bf16 v[72:75], v[136:139], v[208:211], v[72:75]
	v_mfma_f32_16x16x32_bf16 v[124:127], v[132:135], v[188:191], v[124:127]
	v_mfma_f32_16x16x32_bf16 v[120:123], v[140:143], v[188:191], v[120:123]
	v_mfma_f32_16x16x32_bf16 v[108:111], v[132:135], v[196:199], v[108:111]
	v_mfma_f32_16x16x32_bf16 v[104:107], v[140:143], v[196:199], v[104:107]
	v_mfma_f32_16x16x32_bf16 v[92:95], v[132:135], v[204:207], v[92:95]
	v_mfma_f32_16x16x32_bf16 v[88:91], v[140:143], v[204:207], v[88:91]
	v_mfma_f32_16x16x32_bf16 v[76:79], v[132:135], v[214:217], v[76:79]
	v_mfma_f32_16x16x32_bf16 v[72:75], v[140:143], v[214:217], v[72:75]
	v_mfma_f32_16x16x32_bf16 v[116:119], v[144:147], v[184:187], v[116:119]
	v_mfma_f32_16x16x32_bf16 v[112:115], v[168:171], v[184:187], v[112:115]
	v_mfma_f32_16x16x32_bf16 v[100:103], v[144:147], v[192:195], v[100:103]
	v_mfma_f32_16x16x32_bf16 v[96:99], v[168:171], v[192:195], v[96:99]
	v_mfma_f32_16x16x32_bf16 v[84:87], v[144:147], v[200:203], v[84:87]
	v_mfma_f32_16x16x32_bf16 v[80:83], v[168:171], v[200:203], v[80:83]
	v_mfma_f32_16x16x32_bf16 v[68:71], v[144:147], v[208:211], v[68:71]
	v_mfma_f32_16x16x32_bf16 v[64:67], v[168:171], v[208:211], v[64:67]
	v_mfma_f32_16x16x32_bf16 v[116:119], v[164:167], v[188:191], v[116:119]
	v_mfma_f32_16x16x32_bf16 v[112:115], v[180:183], v[188:191], v[112:115]
	v_mfma_f32_16x16x32_bf16 v[100:103], v[164:167], v[196:199], v[100:103]
	v_mfma_f32_16x16x32_bf16 v[96:99], v[180:183], v[196:199], v[96:99]
	v_mfma_f32_16x16x32_bf16 v[84:87], v[164:167], v[204:207], v[84:87]
	v_mfma_f32_16x16x32_bf16 v[80:83], v[180:183], v[204:207], v[80:83]
	v_mfma_f32_16x16x32_bf16 v[68:71], v[164:167], v[214:217], v[68:71]
	v_mfma_f32_16x16x32_bf16 v[64:67], v[180:183], v[214:217], v[64:67]
	s_barrier
; #define PG8_STAGE(bufoff, gbase, voff) do { _Pragma("unroll") for (int _i = 0; _i < 2; ++_i) \
;         __builtin_amdgcn_global_load_lds((const unsigned*)((const char*)(gbase) + (voff)[_i]), (PG8_LAS unsigned*)(lds + (bufoff) + ldsw + _i * 8192), 16, 0, 0); } while (0)
; #define PG8_LDA(dst, b, h) do { _Pragma("unroll") for (int m = 0; m < 4; ++m) _Pragma("unroll") for (int k = 0; k < 2; ++k) dst[m][k] = *(const PG8_LAS bf16x8*)(lds + PG8_SA(b, h) + aoff + m * 2048 + k * 1024); } while (0)
; #define PG8_LDB(dst, b, h) do { _Pragma("unroll") for (int n = 0; n < 2; ++n) _Pragma("unroll") for (int k = 0; k < 2; ++k) dst[n][k] = *(const PG8_LAS bf16x8*)(lds + PG8_SB(b, h) + boff + n * 2048 + k * 1024); } while (0)
; #define PG8_MMA(ai, bj, At, Bt) do { __builtin_amdgcn_s_setprio(1); _Pragma("unroll") for (int m = 0; m < 4; ++m) _Pragma("unroll") for (int n = 0; n < 2; ++n) _Pragma("unroll") for (int k = 0; k < 2; ++k) \
;         acc[ai][bj][m][n] = __builtin_amdgcn_mfma_f32_16x16x32_bf16(Bt[n][k], At[m][k], acc[ai][bj][m][n], 0, 0, 0); __builtin_amdgcn_s_setprio(0); } while (0)
; #define PG8_WAIT_V(n) asm volatile("s_waitcnt vmcnt(" #n ")" ::: "memory")
; #define PG8_BAR __builtin_amdgcn_s_barrier()
; template <class Epi, class Sched, bool ALIGN_EPI = false, bool SP2 = false>
; __device__ __forceinline__ void gemm_phase(PG8_LAS unsigned char* lds, const Gemm g, const Sched& S, const Epi& E) {
;     ...
;         for (int t = 0; t < nt; t += 2) {
;             const bool last = (t == nt - 2);
;             const char* a1 = cA + (size_t)(t + 1) * kstep;
;             const char* a2 = last ? nA : cA + (size_t)(t + 2) * kstep; const char* b2 = last ? nB : cB + (size_t)(t + 2) * kstep;
;             const char* a3 = a2 + kstep; const char* b3 = b2 + kstep;
;             if (last && has_next) S.a_ready(nxt);
;             if constexpr (SP2) {
;             PG8_LDB(B0, 0, 0); PG8_LDB(B1, 0, 1); PG8_SCHED; PG8_LDA(At, 0, 0); PG8_STAGE(PG8_SA(1, 1), a1 + hstep, voffA);
;             PG8_WAIT_V(8); PG8_WAIT_L(0); PG8_BAR; PG8_MMA(0, 0, At, B0); PG8_MMA(0, 1, At, B1); PG8_BAR; PG8_SCHED;
;     ...
;             PG8_LDA(At, 1, 1); PG8_STAGE(PG8_SB(1, 0), b3, voffB); PG8_STAGE(PG8_SB(1, 1), b3 + hstep, voffB); PG8_STAGE(PG8_SA(1, 0), a3, voffA);
;             PG8_WAIT_V(8); PG8_WAIT_L(0); PG8_BAR; PG8_MMA(1, 0, At, B0); PG8_MMA(1, 1, At, B1); PG8_BAR; PG8_SCHED;
	s_add_i32 s42, s62, s45
	s_add_u32 s86, s40, 0x80
	s_addc_u32 s87, s41, 0
	s_mov_b32 m0, s42
	ds_read_b128 v[184:187], v179 offset:49152
	ds_read_b128 v[188:191], v179 offset:50176
	ds_read_b128 v[192:195], v179 offset:51200
	ds_read_b128 v[196:199], v179 offset:52224
	ds_read_b128 v[200:203], v179 offset:53248
	ds_read_b128 v[204:207], v179 offset:54272
	ds_read_b128 v[208:211], v179 offset:55296
	ds_read_b128 v[214:217], v179 offset:56320
	global_load_lds_dwordx4 v150, s[86:87]
	s_add_i32 m0, s42, 0x2000
	s_add_u32 s40, s40, 0x40080
	s_addc_u32 s41, s41, 0
	s_add_i32 s42, s63, s45
	global_load_lds_dwordx4 v154, s[86:87]
	s_mov_b32 m0, s42
	s_nop 0
	global_load_lds_dwordx4 v150, s[40:41]
	s_add_i32 m0, s42, 0x2000
	s_nop 0
	global_load_lds_dwordx4 v154, s[40:41]
	s_mov_b32 m0, s50
	s_nop 0
	global_load_lds_dwordx4 v148, s[84:85]
	s_mov_b32 m0, s51
	s_nop 0
	global_load_lds_dwordx4 v152, s[84:85]
	s_waitcnt vmcnt(8) lgkmcnt(0)
	s_barrier
	v_mfma_f32_16x16x32_bf16 v[60:63], v[128:131], v[184:187], v[60:63]
	v_mfma_f32_16x16x32_bf16 v[56:59], v[136:139], v[184:187], v[56:59]
	v_mfma_f32_16x16x32_bf16 v[44:47], v[128:131], v[192:195], v[44:47]
	v_mfma_f32_16x16x32_bf16 v[40:43], v[136:139], v[192:195], v[40:43]
	v_mfma_f32_16x16x32_bf16 v[28:31], v[128:131], v[200:203], v[28:31]
	v_mfma_f32_16x16x32_bf16 v[24:27], v[136:139], v[200:203], v[24:27]
	v_mfma_f32_16x16x32_bf16 v[12:15], v[128:131], v[208:211], v[12:15]
	v_mfma_f32_16x16x32_bf16 v[8:11], v[136:139], v[208:211], v[8:11]
	v_mfma_f32_16x16x32_bf16 v[60:63], v[132:135], v[188:191], v[60:63]
	v_mfma_f32_16x16x32_bf16 v[56:59], v[140:143], v[188:191], v[56:59]
	v_mfma_f32_16x16x32_bf16 v[44:47], v[132:135], v[196:199], v[44:47]
	v_mfma_f32_16x16x32_bf16 v[40:43], v[140:143], v[196:199], v[40:43]
	v_mfma_f32_16x16x32_bf16 v[28:31], v[132:135], v[204:207], v[28:31]
	v_mfma_f32_16x16x32_bf16 v[24:27], v[140:143], v[204:207], v[24:27]
	v_mfma_f32_16x16x32_bf16 v[12:15], v[132:135], v[214:217], v[12:15]
	v_mfma_f32_16x16x32_bf16 v[8:11], v[140:143], v[214:217], v[8:11]
	v_mfma_f32_16x16x32_bf16 v[52:55], v[144:147], v[184:187], v[52:55]
	v_mfma_f32_16x16x32_bf16 v[48:51], v[168:171], v[184:187], v[48:51]
	v_mfma_f32_16x16x32_bf16 v[36:39], v[144:147], v[192:195], v[36:39]
	v_mfma_f32_16x16x32_bf16 v[32:35], v[168:171], v[192:195], v[32:35]
	v_mfma_f32_16x16x32_bf16 v[20:23], v[144:147], v[200:203], v[20:23]
	v_mfma_f32_16x16x32_bf16 v[16:19], v[168:171], v[200:203], v[16:19]
	v_mfma_f32_16x16x32_bf16 v[4:7], v[144:147], v[208:211], v[4:7]
	v_mfma_f32_16x16x32_bf16 v[0:3], v[168:171], v[208:211], v[0:3]
	v_mfma_f32_16x16x32_bf16 v[52:55], v[164:167], v[188:191], v[52:55]
	v_mfma_f32_16x16x32_bf16 v[48:51], v[180:183], v[188:191], v[48:51]
	v_mfma_f32_16x16x32_bf16 v[36:39], v[164:167], v[196:199], v[36:39]
	v_mfma_f32_16x16x32_bf16 v[32:35], v[180:183], v[196:199], v[32:35]
	v_mfma_f32_16x16x32_bf16 v[20:23], v[164:167], v[204:207], v[20:23]
	v_mfma_f32_16x16x32_bf16 v[16:19], v[180:183], v[204:207], v[16:19]
	v_mfma_f32_16x16x32_bf16 v[4:7], v[164:167], v[214:217], v[4:7]
	v_mfma_f32_16x16x32_bf16 v[0:3], v[180:183], v[214:217], v[0:3]
	s_barrier
	s_add_i32 s61, s61, 2
	s_add_u32 s38, s38, 0x100
	s_addc_u32 s39, s39, 0
	s_add_u32 s59, s59, 0x100
	s_addc_u32 s60, s60, 0
	s_cmp_gt_u32 s61, 13
.LBB0_755:
	ds_read_b128 v[128:131], v177
	ds_read_b128 v[132:135], v177 offset:1024
	ds_read_b128 v[136:139], v177 offset:2048
	ds_read_b128 v[140:143], v177 offset:3072
	ds_read_b128 v[144:147], v178
	ds_read_b128 v[164:167], v178 offset:1024
	ds_read_b128 v[168:171], v178 offset:2048
	ds_read_b128 v[180:183], v178 offset:3072
	s_add_u32 s40, s38, 0xfffc0080
	s_addc_u32 s41, s39, -1
	s_cmp_eq_u32 s61, 12
	s_cselect_b32 s43, s29, s41
	s_cselect_b32 s42, s57, s40
	s_cselect_b32 s41, s27, s60
	s_cselect_b32 s40, s58, s59
	s_add_i32 m0, s37, 0xc000
	ds_read_b128 v[184:187], v179
	ds_read_b128 v[188:191], v179 offset:1024
	ds_read_b128 v[192:195], v179 offset:2048
	ds_read_b128 v[196:199], v179 offset:3072
	ds_read_b128 v[200:203], v179 offset:4096
	ds_read_b128 v[204:207], v179 offset:5120
	ds_read_b128 v[208:211], v179 offset:6144
	ds_read_b128 v[214:217], v179 offset:7168
	global_load_lds_dwordx4 v156, s[38:39]
	s_add_i32 m0, s37, 0xe000
	s_nop 0
	global_load_lds_dwordx4 v158, s[38:39]
	s_waitcnt vmcnt(8) lgkmcnt(0)
	s_barrier
	v_mfma_f32_16x16x32_bf16 v[124:127], v[128:131], v[184:187], v[124:127]
	v_mfma_f32_16x16x32_bf16 v[120:123], v[136:139], v[184:187], v[120:123]
	v_mfma_f32_16x16x32_bf16 v[108:111], v[128:131], v[192:195], v[108:111]
	v_mfma_f32_16x16x32_bf16 v[104:107], v[136:139], v[192:195], v[104:107]
	v_mfma_f32_16x16x32_bf16 v[92:95], v[128:131], v[200:203], v[92:95]
	v_mfma_f32_16x16x32_bf16 v[88:91], v[136:139], v[200:203], v[88:91]
	v_mfma_f32_16x16x32_bf16 v[76:79], v[128:131], v[208:211], v[76:79]
	v_mfma_f32_16x16x32_bf16 v[72:75], v[136:139], v[208:211], v[72:75]
	v_mfma_f32_16x16x32_bf16 v[124:127], v[132:135], v[188:191], v[124:127]
	v_mfma_f32_16x16x32_bf16 v[120:123], v[140:143], v[188:191], v[120:123]
	v_mfma_f32_16x16x32_bf16 v[108:111], v[132:135], v[196:199], v[108:111]
	v_mfma_f32_16x16x32_bf16 v[104:107], v[140:143], v[196:199], v[104:107]
	v_mfma_f32_16x16x32_bf16 v[92:95], v[132:135], v[204:207], v[92:95]
	v_mfma_f32_16x16x32_bf16 v[88:91], v[140:143], v[204:207], v[88:91]
	v_mfma_f32_16x16x32_bf16 v[76:79], v[132:135], v[214:217], v[76:79]
	v_mfma_f32_16x16x32_bf16 v[72:75], v[140:143], v[214:217], v[72:75]
	v_mfma_f32_16x16x32_bf16 v[116:119], v[144:147], v[184:187], v[116:119]
	v_mfma_f32_16x16x32_bf16 v[112:115], v[168:171], v[184:187], v[112:115]
	v_mfma_f32_16x16x32_bf16 v[100:103], v[144:147], v[192:195], v[100:103]
	v_mfma_f32_16x16x32_bf16 v[96:99], v[168:171], v[192:195], v[96:99]
	v_mfma_f32_16x16x32_bf16 v[84:87], v[144:147], v[200:203], v[84:87]
	v_mfma_f32_16x16x32_bf16 v[80:83], v[168:171], v[200:203], v[80:83]
	v_mfma_f32_16x16x32_bf16 v[68:71], v[144:147], v[208:211], v[68:71]
	v_mfma_f32_16x16x32_bf16 v[64:67], v[168:171], v[208:211], v[64:67]
	v_mfma_f32_16x16x32_bf16 v[116:119], v[164:167], v[188:191], v[116:119]
	v_mfma_f32_16x16x32_bf16 v[112:115], v[180:183], v[188:191], v[112:115]
	v_mfma_f32_16x16x32_bf16 v[100:103], v[164:167], v[196:199], v[100:103]
	v_mfma_f32_16x16x32_bf16 v[96:99], v[180:183], v[196:199], v[96:99]
	v_mfma_f32_16x16x32_bf16 v[84:87], v[164:167], v[204:207], v[84:87]
	v_mfma_f32_16x16x32_bf16 v[80:83], v[180:183], v[204:207], v[80:83]
	v_mfma_f32_16x16x32_bf16 v[68:71], v[164:167], v[214:217], v[68:71]
	v_mfma_f32_16x16x32_bf16 v[64:67], v[180:183], v[214:217], v[64:67]
	s_barrier
; #define PG8_STAGE(bufoff, gbase, voff) do { _Pragma("unroll") for (int _i = 0; _i < 2; ++_i) \
;         __builtin_amdgcn_global_load_lds((const unsigned*)((const char*)(gbase) + (voff)[_i]), (PG8_LAS unsigned*)(lds + (bufoff) + ldsw + _i * 8192), 16, 0, 0); } while (0)
; #define PG8_LDA(dst, b, h) do { _Pragma("unroll") for (int m = 0; m < 4; ++m) _Pragma("unroll") for (int k = 0; k < 2; ++k) dst[m][k] = *(const PG8_LAS bf16x8*)(lds + PG8_SA(b, h) + aoff + m * 2048 + k * 1024); } while (0)
; #define PG8_LDB(dst, b, h) do { _Pragma("unroll") for (int n = 0; n < 2; ++n) _Pragma("unroll") for (int k = 0; k < 2; ++k) dst[n][k] = *(const PG8_LAS bf16x8*)(lds + PG8_SB(b, h) + boff + n * 2048 + k * 1024); } while (0)
; #define PG8_MMA(ai, bj, At, Bt) do { __builtin_amdgcn_s_setprio(1); _Pragma("unroll") for (int m = 0; m < 4; ++m) _Pragma("unroll") for (int n = 0; n < 2; ++n) _Pragma("unroll") for (int k = 0; k < 2; ++k) \
;         acc[ai][bj][m][n] = __builtin_amdgcn_mfma_f32_16x16x32_bf16(Bt[n][k], At[m][k], acc[ai][bj][m][n], 0, 0, 0); __builtin_amdgcn_s_setprio(0); } while (0)
; #define PG8_WAIT_V(n) asm volatile("s_waitcnt vmcnt(" #n ")" ::: "memory")
; #define PG8_WAIT_L(n) asm volatile("s_waitcnt lgkmcnt(" #n ")" ::: "memory")
; #define PG8_BAR __builtin_amdgcn_s_barrier()
; #define PG8_SCHED __builtin_amdgcn_sched_barrier(0)
; template <class Epi, class Sched, bool ALIGN_EPI = false, bool SP2 = false>
; __device__ __forceinline__ void gemm_phase(PG8_LAS unsigned char* lds, const Gemm g, const Sched& S, const Epi& E) {
;     ...
;             PG8_LDA(At, 0, 1); PG8_STAGE(PG8_SB(0, 0), b2, voffB); PG8_STAGE(PG8_SB(0, 1), b2 + hstep, voffB); PG8_STAGE(PG8_SA(0, 0), a2, voffA);
;             PG8_WAIT_V(8); PG8_WAIT_L(0); PG8_BAR; PG8_MMA(1, 0, At, B0); PG8_MMA(1, 1, At, B1); PG8_BAR; PG8_SCHED;
;             PG8_LDB(B0, 1, 0); PG8_LDB(B1, 1, 1); PG8_SCHED; PG8_LDA(At, 1, 0); PG8_STAGE(PG8_SA(0, 1), a2 + hstep, voffA);
;             PG8_WAIT_V(8); PG8_WAIT_L(0); PG8_BAR; PG8_MMA(0, 0, At, B0); PG8_MMA(0, 1, At, B1); PG8_BAR; PG8_SCHED;
	s_add_i32 s62, s54, s45
	s_mov_b32 m0, s62
	ds_read_b128 v[184:187], v179 offset:16384
	ds_read_b128 v[188:191], v179 offset:17408
	ds_read_b128 v[192:195], v179 offset:18432
	ds_read_b128 v[196:199], v179 offset:19456
	ds_read_b128 v[200:203], v179 offset:20480
	ds_read_b128 v[204:207], v179 offset:21504
	ds_read_b128 v[208:211], v179 offset:22528
	ds_read_b128 v[214:217], v179 offset:23552
	global_load_lds_dwordx4 v150, s[40:41]
	s_add_i32 m0, s62, 0x2000
	s_add_u32 s62, s40, 0x40000
	s_addc_u32 s63, s41, 0
	s_add_i32 s64, s55, s45
	global_load_lds_dwordx4 v154, s[40:41]
	s_mov_b32 m0, s64
	s_nop 0
	global_load_lds_dwordx4 v150, s[62:63]
	s_add_i32 m0, s64, 0x2000
	s_nop 0
	global_load_lds_dwordx4 v154, s[62:63]
	s_mov_b32 m0, s37
	s_nop 0
	global_load_lds_dwordx4 v148, s[42:43]
	s_mov_b32 m0, s46
	s_nop 0
	global_load_lds_dwordx4 v152, s[42:43]
	s_waitcnt vmcnt(8) lgkmcnt(0)
	s_barrier
	v_mfma_f32_16x16x32_bf16 v[60:63], v[128:131], v[184:187], v[60:63]
	v_mfma_f32_16x16x32_bf16 v[56:59], v[136:139], v[184:187], v[56:59]
	v_mfma_f32_16x16x32_bf16 v[44:47], v[128:131], v[192:195], v[44:47]
	v_mfma_f32_16x16x32_bf16 v[40:43], v[136:139], v[192:195], v[40:43]
	v_mfma_f32_16x16x32_bf16 v[28:31], v[128:131], v[200:203], v[28:31]
	v_mfma_f32_16x16x32_bf16 v[24:27], v[136:139], v[200:203], v[24:27]
	v_mfma_f32_16x16x32_bf16 v[12:15], v[128:131], v[208:211], v[12:15]
	v_mfma_f32_16x16x32_bf16 v[8:11], v[136:139], v[208:211], v[8:11]
	v_mfma_f32_16x16x32_bf16 v[60:63], v[132:135], v[188:191], v[60:63]
	v_mfma_f32_16x16x32_bf16 v[56:59], v[140:143], v[188:191], v[56:59]
	v_mfma_f32_16x16x32_bf16 v[44:47], v[132:135], v[196:199], v[44:47]
	v_mfma_f32_16x16x32_bf16 v[40:43], v[140:143], v[196:199], v[40:43]
	v_mfma_f32_16x16x32_bf16 v[28:31], v[132:135], v[204:207], v[28:31]
	v_mfma_f32_16x16x32_bf16 v[24:27], v[140:143], v[204:207], v[24:27]
	v_mfma_f32_16x16x32_bf16 v[12:15], v[132:135], v[214:217], v[12:15]
	v_mfma_f32_16x16x32_bf16 v[8:11], v[140:143], v[214:217], v[8:11]
	v_mfma_f32_16x16x32_bf16 v[52:55], v[144:147], v[184:187], v[52:55]
	v_mfma_f32_16x16x32_bf16 v[48:51], v[168:171], v[184:187], v[48:51]
	v_mfma_f32_16x16x32_bf16 v[36:39], v[144:147], v[192:195], v[36:39]
	v_mfma_f32_16x16x32_bf16 v[32:35], v[168:171], v[192:195], v[32:35]
	v_mfma_f32_16x16x32_bf16 v[20:23], v[144:147], v[200:203], v[20:23]
	v_mfma_f32_16x16x32_bf16 v[16:19], v[168:171], v[200:203], v[16:19]
	v_mfma_f32_16x16x32_bf16 v[4:7], v[144:147], v[208:211], v[4:7]
	v_mfma_f32_16x16x32_bf16 v[0:3], v[168:171], v[208:211], v[0:3]
	v_mfma_f32_16x16x32_bf16 v[52:55], v[164:167], v[188:191], v[52:55]
	v_mfma_f32_16x16x32_bf16 v[48:51], v[180:183], v[188:191], v[48:51]
	v_mfma_f32_16x16x32_bf16 v[36:39], v[164:167], v[196:199], v[36:39]
	v_mfma_f32_16x16x32_bf16 v[32:35], v[180:183], v[196:199], v[32:35]
	v_mfma_f32_16x16x32_bf16 v[20:23], v[164:167], v[204:207], v[20:23]
	v_mfma_f32_16x16x32_bf16 v[16:19], v[180:183], v[204:207], v[16:19]
	v_mfma_f32_16x16x32_bf16 v[4:7], v[164:167], v[214:217], v[4:7]
	v_mfma_f32_16x16x32_bf16 v[0:3], v[180:183], v[214:217], v[0:3]
	s_barrier
	s_add_i32 s62, 0, 0x18000
	s_add_i32 s63, 0, 0x1c000
	ds_read_b128 v[128:131], v172
	ds_read_b128 v[132:135], v172 offset:1024
	ds_read_b128 v[136:139], v172 offset:2048
	ds_read_b128 v[140:143], v172 offset:3072
	ds_read_b128 v[144:147], v173
	ds_read_b128 v[164:167], v173 offset:1024
	ds_read_b128 v[168:171], v173 offset:2048
	ds_read_b128 v[180:183], v173 offset:3072
	s_add_u32 s84, s42, 0x80
	s_addc_u32 s85, s43, 0
	s_add_u32 s42, s42, 0x40000
	s_addc_u32 s43, s43, 0
	s_mov_b32 m0, s47
	ds_read_b128 v[184:187], v179 offset:32768
	ds_read_b128 v[188:191], v179 offset:33792
	ds_read_b128 v[192:195], v179 offset:34816
	ds_read_b128 v[196:199], v179 offset:35840
	ds_read_b128 v[200:203], v179 offset:36864
	ds_read_b128 v[204:207], v179 offset:37888
	ds_read_b128 v[208:211], v179 offset:38912
	ds_read_b128 v[214:217], v179 offset:39936
	global_load_lds_dwordx4 v148, s[42:43]
	s_mov_b32 m0, s48
	s_nop 0
	global_load_lds_dwordx4 v152, s[42:43]
	s_waitcnt vmcnt(8) lgkmcnt(0)
	s_barrier
	v_mfma_f32_16x16x32_bf16 v[124:127], v[128:131], v[184:187], v[124:127]
	v_mfma_f32_16x16x32_bf16 v[120:123], v[136:139], v[184:187], v[120:123]
	v_mfma_f32_16x16x32_bf16 v[108:111], v[128:131], v[192:195], v[108:111]
	v_mfma_f32_16x16x32_bf16 v[104:107], v[136:139], v[192:195], v[104:107]
	v_mfma_f32_16x16x32_bf16 v[92:95], v[128:131], v[200:203], v[92:95]
	v_mfma_f32_16x16x32_bf16 v[88:91], v[136:139], v[200:203], v[88:91]
	v_mfma_f32_16x16x32_bf16 v[76:79], v[128:131], v[208:211], v[76:79]
	v_mfma_f32_16x16x32_bf16 v[72:75], v[136:139], v[208:211], v[72:75]
	v_mfma_f32_16x16x32_bf16 v[124:127], v[132:135], v[188:191], v[124:127]
	v_mfma_f32_16x16x32_bf16 v[120:123], v[140:143], v[188:191], v[120:123]
	v_mfma_f32_16x16x32_bf16 v[108:111], v[132:135], v[196:199], v[108:111]
	v_mfma_f32_16x16x32_bf16 v[104:107], v[140:143], v[196:199], v[104:107]
	v_mfma_f32_16x16x32_bf16 v[92:95], v[132:135], v[204:207], v[92:95]
	v_mfma_f32_16x16x32_bf16 v[88:91], v[140:143], v[204:207], v[88:91]
	v_mfma_f32_16x16x32_bf16 v[76:79], v[132:135], v[214:217], v[76:79]
	v_mfma_f32_16x16x32_bf16 v[72:75], v[140:143], v[214:217], v[72:75]
	v_mfma_f32_16x16x32_bf16 v[116:119], v[144:147], v[184:187], v[116:119]
	v_mfma_f32_16x16x32_bf16 v[112:115], v[168:171], v[184:187], v[112:115]
	v_mfma_f32_16x16x32_bf16 v[100:103], v[144:147], v[192:195], v[100:103]
	v_mfma_f32_16x16x32_bf16 v[96:99], v[168:171], v[192:195], v[96:99]
	v_mfma_f32_16x16x32_bf16 v[84:87], v[144:147], v[200:203], v[84:87]
	v_mfma_f32_16x16x32_bf16 v[80:83], v[168:171], v[200:203], v[80:83]
	v_mfma_f32_16x16x32_bf16 v[68:71], v[144:147], v[208:211], v[68:71]
	v_mfma_f32_16x16x32_bf16 v[64:67], v[168:171], v[208:211], v[64:67]
	v_mfma_f32_16x16x32_bf16 v[116:119], v[164:167], v[188:191], v[116:119]
	v_mfma_f32_16x16x32_bf16 v[112:115], v[180:183], v[188:191], v[112:115]
	v_mfma_f32_16x16x32_bf16 v[100:103], v[164:167], v[196:199], v[100:103]
	v_mfma_f32_16x16x32_bf16 v[96:99], v[180:183], v[196:199], v[96:99]
	v_mfma_f32_16x16x32_bf16 v[84:87], v[164:167], v[204:207], v[84:87]
	v_mfma_f32_16x16x32_bf16 v[80:83], v[180:183], v[204:207], v[80:83]
	v_mfma_f32_16x16x32_bf16 v[68:71], v[164:167], v[214:217], v[68:71]
	v_mfma_f32_16x16x32_bf16 v[64:67], v[180:183], v[214:217], v[64:67]
	s_barrier
; #define PG8_STAGE(bufoff, gbase, voff) do { _Pragma("unroll") for (int _i = 0; _i < 2; ++_i) \
;         __builtin_amdgcn_global_load_lds((const unsigned*)((const char*)(gbase) + (voff)[_i]), (PG8_LAS unsigned*)(lds + (bufoff) + ldsw + _i * 8192), 16, 0, 0); } while (0)
; #define PG8_LDA(dst, b, h) do { _Pragma("unroll") for (int m = 0; m < 4; ++m) _Pragma("unroll") for (int k = 0; k < 2; ++k) dst[m][k] = *(const PG8_LAS bf16x8*)(lds + PG8_SA(b, h) + aoff + m * 2048 + k * 1024); } while (0)
; #define PG8_WAIT_V(n) asm volatile("s_waitcnt vmcnt(" #n ")" ::: "memory")
; #define PG8_WAIT_L(n) asm volatile("s_waitcnt lgkmcnt(" #n ")" ::: "memory")
; #define PG8_BAR __builtin_amdgcn_s_barrier()
; #define PG8_SCHED __builtin_amdgcn_sched_barrier(0)
;     __device__ __forceinline__ void operator()(const f32x4 (&acc)[2][2][4][2], const Unit& u, int wr, int wc, int fr, int fq) const {
;         const int row0 = u.pm * BM + wr * 64 + fr, col0 = u.pn * BM + wc * 32 + 8 * fq;
; #pragma unroll
;         for (int ai = 0; ai < 2; ++ai) { u32x4 gw[4][2], pw[4][2];
; #pragma unroll
;             for (int m = 0; m < 4; ++m) { const size_t off = (size_t)(row0 + ai * HALF + m * 16) * 2048 + col0;
; #pragma unroll
;                 for (int bj = 0; bj < 2; ++bj) { gw[m][bj] = *(const u32x4*)(G + off + bj * HALF); if (PASS == 1) pw[m][bj] = *(const u32x4*)(MIX + off + bj * HALF); } }
; template <class Epi, class Sched, bool ALIGN_EPI = false, bool SP2 = false>
; __device__ __forceinline__ void gemm_phase(PG8_LAS unsigned char* lds, const Gemm g, const Sched& S, const Epi& E) {
;     ...
;             PG8_LDA(At, 1, 1); PG8_STAGE(PG8_SB(1, 0), b3, voffB); PG8_STAGE(PG8_SB(1, 1), b3 + hstep, voffB); PG8_STAGE(PG8_SA(1, 0), a3, voffA);
;             PG8_WAIT_V(8); PG8_WAIT_L(0); PG8_BAR; PG8_MMA(1, 0, At, B0); PG8_MMA(1, 1, At, B1); PG8_BAR; PG8_SCHED;
;     ...
;         if constexpr (ALIGN_EPI) { if (wr == 0) PG8_BAR; }
;         if constexpr (!Epi::AFTER_DRAIN) { E(acc, cur, wr, wc, fr, fq); S.done(cur); }
;         if (!has_next) break;
; #pragma unroll
;         for (int a = 0; a < 2; ++a)
; #pragma unroll
;             for (int b = 0; b < 2; ++b)
; #pragma unroll
;                 for (int m = 0; m < 4; ++m)
; #pragma unroll
;                     for (int n = 0; n < 2; ++n) acc[a][b][m][n] = (f32x4){0.f, 0.f, 0.f, 0.f};
;         cur = nxt; cA = nA; cB = nB; ++ui;
	s_add_i32 s42, s62, s45
	s_add_u32 s86, s40, 0x80
	s_addc_u32 s87, s41, 0
	s_mov_b32 m0, s42
	ds_read_b128 v[184:187], v179 offset:49152
	ds_read_b128 v[188:191], v179 offset:50176
	ds_read_b128 v[192:195], v179 offset:51200
	ds_read_b128 v[196:199], v179 offset:52224
	ds_read_b128 v[200:203], v179 offset:53248
	ds_read_b128 v[204:207], v179 offset:54272
	ds_read_b128 v[208:211], v179 offset:55296
	ds_read_b128 v[214:217], v179 offset:56320
	global_load_lds_dwordx4 v150, s[86:87]
	s_add_i32 m0, s42, 0x2000
	s_add_u32 s40, s40, 0x40080
	s_addc_u32 s41, s41, 0
	s_add_i32 s42, s63, s45
	global_load_lds_dwordx4 v154, s[86:87]
	s_mov_b32 m0, s42
	s_nop 0
	global_load_lds_dwordx4 v150, s[40:41]
	s_add_i32 m0, s42, 0x2000
	s_nop 0
	global_load_lds_dwordx4 v154, s[40:41]
	s_mov_b32 m0, s50
	s_nop 0
	global_load_lds_dwordx4 v148, s[84:85]
	s_mov_b32 m0, s51
	s_nop 0
	global_load_lds_dwordx4 v152, s[84:85]
	s_waitcnt vmcnt(8) lgkmcnt(0)
	s_barrier
	v_mfma_f32_16x16x32_bf16 v[60:63], v[128:131], v[184:187], v[60:63]
	v_mfma_f32_16x16x32_bf16 v[56:59], v[136:139], v[184:187], v[56:59]
	v_mfma_f32_16x16x32_bf16 v[44:47], v[128:131], v[192:195], v[44:47]
	v_mfma_f32_16x16x32_bf16 v[40:43], v[136:139], v[192:195], v[40:43]
	v_mfma_f32_16x16x32_bf16 v[28:31], v[128:131], v[200:203], v[28:31]
	v_mfma_f32_16x16x32_bf16 v[24:27], v[136:139], v[200:203], v[24:27]
	v_mfma_f32_16x16x32_bf16 v[12:15], v[128:131], v[208:211], v[12:15]
	v_mfma_f32_16x16x32_bf16 v[8:11], v[136:139], v[208:211], v[8:11]
	v_mfma_f32_16x16x32_bf16 v[60:63], v[132:135], v[188:191], v[60:63]
	v_mfma_f32_16x16x32_bf16 v[56:59], v[140:143], v[188:191], v[56:59]
	v_mfma_f32_16x16x32_bf16 v[44:47], v[132:135], v[196:199], v[44:47]
	v_mfma_f32_16x16x32_bf16 v[40:43], v[140:143], v[196:199], v[40:43]
	v_mfma_f32_16x16x32_bf16 v[28:31], v[132:135], v[204:207], v[28:31]
	v_mfma_f32_16x16x32_bf16 v[24:27], v[140:143], v[204:207], v[24:27]
	v_mfma_f32_16x16x32_bf16 v[12:15], v[132:135], v[214:217], v[12:15]
	v_mfma_f32_16x16x32_bf16 v[8:11], v[140:143], v[214:217], v[8:11]
	v_mfma_f32_16x16x32_bf16 v[52:55], v[144:147], v[184:187], v[52:55]
	v_mfma_f32_16x16x32_bf16 v[48:51], v[168:171], v[184:187], v[48:51]
	v_mfma_f32_16x16x32_bf16 v[36:39], v[144:147], v[192:195], v[36:39]
	v_mfma_f32_16x16x32_bf16 v[32:35], v[168:171], v[192:195], v[32:35]
	v_mfma_f32_16x16x32_bf16 v[20:23], v[144:147], v[200:203], v[20:23]
	v_mfma_f32_16x16x32_bf16 v[16:19], v[168:171], v[200:203], v[16:19]
	v_mfma_f32_16x16x32_bf16 v[4:7], v[144:147], v[208:211], v[4:7]
	v_mfma_f32_16x16x32_bf16 v[0:3], v[168:171], v[208:211], v[0:3]
	v_mfma_f32_16x16x32_bf16 v[52:55], v[164:167], v[188:191], v[52:55]
	v_mfma_f32_16x16x32_bf16 v[48:51], v[180:183], v[188:191], v[48:51]
	v_mfma_f32_16x16x32_bf16 v[36:39], v[164:167], v[196:199], v[36:39]
	v_mfma_f32_16x16x32_bf16 v[32:35], v[180:183], v[196:199], v[32:35]
	v_mfma_f32_16x16x32_bf16 v[20:23], v[164:167], v[204:207], v[20:23]
	v_mfma_f32_16x16x32_bf16 v[16:19], v[180:183], v[204:207], v[16:19]
	v_mfma_f32_16x16x32_bf16 v[4:7], v[164:167], v[214:217], v[4:7]
	v_mfma_f32_16x16x32_bf16 v[0:3], v[180:183], v[214:217], v[0:3]
	s_barrier
	s_add_i32 s61, s61, 2
	s_add_u32 s38, s38, 0x100
	s_addc_u32 s39, s39, 0
	s_add_u32 s59, s59, 0x100
	s_addc_u32 s60, s60, 0
	s_cmp_gt_u32 s61, 13
	s_cbranch_scc0 .LBB0_755
	v_lshl_add_u32 v168, s36, 8, v174
	v_lshl_or_b32 v166, s56, 8, v176
	v_ashrrev_i32_e32 v169, 31, v168
	v_ashrrev_i32_e32 v167, 31, v166
	v_lshlrev_b64 v[128:129], 11, v[168:169]
	v_lshl_add_u64 v[128:129], v[128:129], 0, v[166:167]
	v_lshlrev_b64 v[128:129], 1, v[128:129]
	v_lshl_add_u64 v[130:131], s[12:13], 0, v[128:129]
	global_load_dwordx4 v[180:183], v[130:131], off
	v_lshl_add_u64 v[128:129], s[14:15], 0, v[128:129]
	v_or_b32_e32 v212, 16, v168
	global_load_dwordx4 v[184:187], v[128:129], off
	global_load_dwordx4 v[188:191], v[130:131], off offset:256
	global_load_dwordx4 v[192:195], v[128:129], off offset:256
	v_ashrrev_i32_e32 v213, 31, v212
	v_lshlrev_b64 v[128:129], 11, v[212:213]
	v_lshl_add_u64 v[128:129], v[128:129], 0, v[166:167]
	v_lshlrev_b64 v[128:129], 1, v[128:129]
	v_lshl_add_u64 v[130:131], s[12:13], 0, v[128:129]
	v_lshl_add_u64 v[128:129], s[14:15], 0, v[128:129]
	global_load_dwordx4 v[196:199], v[130:131], off
	global_load_dwordx4 v[200:203], v[128:129], off
	v_or_b32_e32 v172, 32, v168
	v_or_b32_e32 v170, 48, v168
	v_ashrrev_i32_e32 v173, 31, v172
	v_ashrrev_i32_e32 v171, 31, v170
	v_lshlrev_b64 v[132:133], 12, v[168:169]
	v_lshlrev_b64 v[134:135], 11, v[172:173]
	v_lshlrev_b64 v[136:137], 11, v[170:171]
	v_lshlrev_b64 v[164:165], 1, v[166:167]
	v_lshl_add_u64 v[132:133], s[14:15], 0, v[132:133]
	v_lshl_add_u64 v[134:135], v[134:135], 0, v[166:167]
	v_lshl_add_u64 v[136:137], v[136:137], 0, v[166:167]
	v_lshl_add_u64 v[218:219], v[132:133], 0, v[164:165]
	v_lshlrev_b64 v[132:133], 1, v[134:135]
	v_lshlrev_b64 v[134:135], 1, v[136:137]
	v_lshl_add_u64 v[136:137], s[12:13], 0, v[132:133]
	v_lshl_add_u64 v[132:133], s[14:15], 0, v[132:133]
	v_lshl_add_u64 v[138:139], s[12:13], 0, v[134:135]
	v_lshl_add_u64 v[230:231], s[14:15], 0, v[134:135]
	global_load_dwordx4 v[204:207], v[130:131], off offset:256
	global_load_dwordx4 v[208:211], v[128:129], off offset:256
	global_load_dwordx4 v[214:217], v[136:137], off
	global_load_dwordx4 v[222:225], v[136:137], off offset:256
	global_load_dwordx4 v[232:235], v[132:133], off
	global_load_dwordx4 v[144:147], v[132:133], off offset:256
	global_load_dwordx4 v[140:143], v[138:139], off
	s_nop 0
	global_load_dwordx4 v[132:135], v[138:139], off offset:256
	s_nop 0
	global_load_dwordx4 v[136:139], v[230:231], off
	global_load_dwordx4 v[128:131], v[230:231], off offset:256
	s_and_b64 vcc, exec, s[10:11]
	s_mov_b32 s56, s26
	s_mov_b32 s36, s28
	s_mov_b64 s[40:41], s[34:35]
	s_mov_b64 s[38:39], s[30:31]
	s_waitcnt vmcnt(0)
; __device__ __forceinline__ float bf_lo(unsigned w) { return __uint_as_float(w << 16); }
; __device__ __forceinline__ float bf_hi(unsigned w) { return __uint_as_float(w & 0xffff0000u); }
; __device__ __forceinline__ u32x4 pack8(const f32x4 a, const f32x4 b) { u32x4 w; w.x = cvt_pk_bf16(a[0], a[1]); w.y = cvt_pk_bf16(a[2], a[3]); w.z = cvt_pk_bf16(b[0], b[1]); w.w = cvt_pk_bf16(b[2], b[3]); return w; }
;     __device__ __forceinline__ void operator()(const f32x4 (&acc)[2][2][4][2], const Unit& u, int wr, int wc, int fr, int fq) const {
;     ...
;             for (int m = 0; m < 4; ++m) { const size_t off = (size_t)(row0 + ai * HALF + m * 16) * 2048 + col0;
; #pragma unroll
;                 for (int bj = 0; bj < 2; ++bj) { const u32x4 g4 = gw[m][bj];
;                     f32x4 v0 = (f32x4){bf_lo(g4.x), bf_hi(g4.x), bf_lo(g4.y), bf_hi(g4.y)} * acc[ai][bj][m][0], v1 = (f32x4){bf_lo(g4.z), bf_hi(g4.z), bf_lo(g4.w), bf_hi(g4.w)} * acc[ai][bj][m][1];
;                     if (PASS == 1) { const u32x4 p4 = pw[m][bj]; v0 += (f32x4){bf_lo(p4.x), bf_hi(p4.x), bf_lo(p4.y), bf_hi(p4.y)}; v1 += (f32x4){bf_lo(p4.z), bf_hi(p4.z), bf_lo(p4.w), bf_hi(p4.w)}; }
;                     *(u32x4*)(MIX + off + bj * HALF) = pack8(v0, v1); } } }
	v_lshlrev_b32_e32 v230, 16, v180
	v_and_b32_e32 v231, 0xffff0000, v180
	v_lshlrev_b32_e32 v180, 16, v181
	v_and_b32_e32 v181, 0xffff0000, v181
	v_lshlrev_b32_e32 v236, 16, v182
	v_and_b32_e32 v237, 0xffff0000, v182
	v_lshlrev_b32_e32 v182, 16, v183
	v_and_b32_e32 v183, 0xffff0000, v183
	v_lshlrev_b32_e32 v238, 16, v184
	v_and_b32_e32 v239, 0xffff0000, v184
	v_lshlrev_b32_e32 v184, 16, v185
	v_and_b32_e32 v185, 0xffff0000, v185
	v_lshlrev_b32_e32 v240, 16, v186
	v_and_b32_e32 v241, 0xffff0000, v186
	v_lshlrev_b32_e32 v186, 16, v187
	v_and_b32_e32 v187, 0xffff0000, v187
	v_lshlrev_b32_e32 v242, 16, v188
	v_and_b32_e32 v243, 0xffff0000, v188
	v_lshlrev_b32_e32 v188, 16, v189
	v_and_b32_e32 v189, 0xffff0000, v189
	v_lshlrev_b32_e32 v246, 16, v192
	v_and_b32_e32 v247, 0xffff0000, v192
	v_lshlrev_b32_e32 v192, 16, v193
	v_and_b32_e32 v193, 0xffff0000, v193
	v_pk_fma_f32 v[126:127], v[126:127], v[180:181], v[184:185]
	v_pk_fma_f32 v[124:125], v[124:125], v[230:231], v[238:239]
	v_pk_fma_f32 v[122:123], v[122:123], v[182:183], v[186:187]
	v_pk_fma_f32 v[120:121], v[120:121], v[236:237], v[240:241]
	v_pk_fma_f32 v[180:181], v[118:119], v[188:189], v[192:193]
	v_pk_fma_f32 v[182:183], v[116:117], v[242:243], v[246:247]
	v_cvt_pk_bf16_f32 v116, v124, v125
	v_cvt_pk_bf16_f32 v117, v126, v127
	v_cvt_pk_bf16_f32 v118, v120, v121
	v_cvt_pk_bf16_f32 v119, v122, v123
	v_lshlrev_b32_e32 v244, 16, v190
	v_and_b32_e32 v245, 0xffff0000, v190
	v_lshlrev_b32_e32 v190, 16, v191
	v_and_b32_e32 v191, 0xffff0000, v191
	v_lshlrev_b32_e32 v248, 16, v194
	global_store_dwordx4 v[218:219], v[116:119], off
	v_and_b32_e32 v249, 0xffff0000, v194
	v_lshlrev_b32_e32 v122, 16, v200
	v_lshlrev_b32_e32 v116, 16, v195
	v_and_b32_e32 v117, 0xffff0000, v195
	v_pk_fma_f32 v[116:117], v[114:115], v[190:191], v[116:117]
	v_pk_fma_f32 v[114:115], v[112:113], v[244:245], v[248:249]
	v_cvt_pk_bf16_f32 v112, v182, v183
	v_cvt_pk_bf16_f32 v113, v180, v181
	v_cvt_pk_bf16_f32 v114, v114, v115
	v_cvt_pk_bf16_f32 v115, v116, v117
	global_store_dwordx4 v[218:219], v[112:115], off offset:256
	v_lshlrev_b32_e32 v116, 16, v197
	v_and_b32_e32 v117, 0xffff0000, v197
	v_lshlrev_b32_e32 v114, 16, v196
	v_and_b32_e32 v115, 0xffff0000, v196
	v_and_b32_e32 v123, 0xffff0000, v200
	v_lshlrev_b32_e32 v124, 16, v201
	v_and_b32_e32 v125, 0xffff0000, v201
	v_lshlrev_b64 v[112:113], 12, v[212:213]
	v_lshlrev_b32_e32 v118, 16, v198
	v_and_b32_e32 v119, 0xffff0000, v198
	v_lshlrev_b32_e32 v120, 16, v199
	v_and_b32_e32 v121, 0xffff0000, v199
	v_pk_fma_f32 v[110:111], v[110:111], v[116:117], v[124:125]
	v_pk_fma_f32 v[108:109], v[108:109], v[114:115], v[122:123]
	v_lshlrev_b32_e32 v114, 16, v202
	v_and_b32_e32 v115, 0xffff0000, v202
	v_lshlrev_b32_e32 v116, 16, v203
	v_and_b32_e32 v117, 0xffff0000, v203
	v_pk_fma_f32 v[116:117], v[106:107], v[120:121], v[116:117]
	v_pk_fma_f32 v[106:107], v[104:105], v[118:119], v[114:115]
	v_cvt_pk_bf16_f32 v104, v108, v109
	v_lshl_add_u64 v[108:109], s[14:15], 0, v[112:113]
	v_cvt_pk_bf16_f32 v105, v110, v111
	v_cvt_pk_bf16_f32 v106, v106, v107
	v_cvt_pk_bf16_f32 v107, v116, v117
	v_lshl_add_u64 v[108:109], v[108:109], 0, v[164:165]
	global_store_dwordx4 v[108:109], v[104:107], off
	v_lshlrev_b32_e32 v114, 16, v208
	v_and_b32_e32 v115, 0xffff0000, v208
	v_lshlrev_b32_e32 v104, 16, v204
	v_and_b32_e32 v105, 0xffff0000, v204
	v_lshlrev_b32_e32 v106, 16, v205
	v_and_b32_e32 v107, 0xffff0000, v205
	v_lshlrev_b32_e32 v116, 16, v209
	v_and_b32_e32 v117, 0xffff0000, v209
	v_lshlrev_b32_e32 v110, 16, v206
	v_and_b32_e32 v111, 0xffff0000, v206
	v_lshlrev_b32_e32 v112, 16, v207
	v_and_b32_e32 v113, 0xffff0000, v207
	v_pk_fma_f32 v[102:103], v[102:103], v[106:107], v[116:117]
	v_pk_fma_f32 v[100:101], v[100:101], v[104:105], v[114:115]
	v_lshlrev_b32_e32 v104, 16, v210
	v_and_b32_e32 v105, 0xffff0000, v210
	v_lshlrev_b32_e32 v106, 16, v211
	v_and_b32_e32 v107, 0xffff0000, v211
	v_pk_fma_f32 v[106:107], v[98:99], v[112:113], v[106:107]
	v_pk_fma_f32 v[98:99], v[96:97], v[110:111], v[104:105]
	v_cvt_pk_bf16_f32 v96, v100, v101
	v_cvt_pk_bf16_f32 v97, v102, v103
	v_cvt_pk_bf16_f32 v98, v98, v99
	v_cvt_pk_bf16_f32 v99, v106, v107
	global_store_dwordx4 v[108:109], v[96:99], off offset:256
	v_lshlrev_b32_e32 v100, 16, v215
	v_and_b32_e32 v101, 0xffff0000, v215
	v_lshlrev_b32_e32 v98, 16, v214
	v_and_b32_e32 v99, 0xffff0000, v214
	v_lshlrev_b32_e32 v106, 16, v232
	v_and_b32_e32 v107, 0xffff0000, v232
	v_lshlrev_b32_e32 v108, 16, v233
	v_and_b32_e32 v109, 0xffff0000, v233
	v_lshlrev_b64 v[96:97], 12, v[172:173]
	v_lshlrev_b32_e32 v102, 16, v216
	v_and_b32_e32 v103, 0xffff0000, v216
	v_lshlrev_b32_e32 v104, 16, v217
	v_and_b32_e32 v105, 0xffff0000, v217
	v_pk_fma_f32 v[94:95], v[94:95], v[100:101], v[108:109]
	v_pk_fma_f32 v[92:93], v[92:93], v[98:99], v[106:107]
	v_lshlrev_b32_e32 v98, 16, v234
	v_and_b32_e32 v99, 0xffff0000, v234
	v_lshlrev_b32_e32 v100, 16, v235
	v_and_b32_e32 v101, 0xffff0000, v235
	v_pk_fma_f32 v[100:101], v[90:91], v[104:105], v[100:101]
	v_pk_fma_f32 v[90:91], v[88:89], v[102:103], v[98:99]
	v_cvt_pk_bf16_f32 v88, v92, v93
	v_lshl_add_u64 v[92:93], s[14:15], 0, v[96:97]
	v_cvt_pk_bf16_f32 v89, v94, v95
	v_cvt_pk_bf16_f32 v90, v90, v91
	v_cvt_pk_bf16_f32 v91, v100, v101
	v_lshl_add_u64 v[92:93], v[92:93], 0, v[164:165]
	global_store_dwordx4 v[92:93], v[88:91], off
	v_lshlrev_b32_e32 v98, 16, v144
	v_and_b32_e32 v99, 0xffff0000, v144
	v_lshlrev_b32_e32 v88, 16, v222
	v_and_b32_e32 v89, 0xffff0000, v222
	v_lshlrev_b32_e32 v90, 16, v223
	v_and_b32_e32 v91, 0xffff0000, v223
	v_lshlrev_b32_e32 v100, 16, v145
	v_and_b32_e32 v101, 0xffff0000, v145
	v_lshlrev_b32_e32 v94, 16, v224
; __device__ __forceinline__ float bf_lo(unsigned w) { return __uint_as_float(w << 16); }
; __device__ __forceinline__ float bf_hi(unsigned w) { return __uint_as_float(w & 0xffff0000u); }
; __device__ __forceinline__ u32x4 pack8(const f32x4 a, const f32x4 b) { u32x4 w; w.x = cvt_pk_bf16(a[0], a[1]); w.y = cvt_pk_bf16(a[2], a[3]); w.z = cvt_pk_bf16(b[0], b[1]); w.w = cvt_pk_bf16(b[2], b[3]); return w; }
;     __device__ __forceinline__ void operator()(const f32x4 (&acc)[2][2][4][2], const Unit& u, int wr, int wc, int fr, int fq) const {
;     ...
;             for (int m = 0; m < 4; ++m) { const size_t off = (size_t)(row0 + ai * HALF + m * 16) * 2048 + col0;
; #pragma unroll
;                 for (int bj = 0; bj < 2; ++bj) { gw[m][bj] = *(const u32x4*)(G + off + bj * HALF); if (PASS == 1) pw[m][bj] = *(const u32x4*)(MIX + off + bj * HALF); } }
;     ...
;             for (int m = 0; m < 4; ++m) { const size_t off = (size_t)(row0 + ai * HALF + m * 16) * 2048 + col0;
; #pragma unroll
;                 for (int bj = 0; bj < 2; ++bj) { const u32x4 g4 = gw[m][bj];
;                     f32x4 v0 = (f32x4){bf_lo(g4.x), bf_hi(g4.x), bf_lo(g4.y), bf_hi(g4.y)} * acc[ai][bj][m][0], v1 = (f32x4){bf_lo(g4.z), bf_hi(g4.z), bf_lo(g4.w), bf_hi(g4.w)} * acc[ai][bj][m][1];
;                     if (PASS == 1) { const u32x4 p4 = pw[m][bj]; v0 += (f32x4){bf_lo(p4.x), bf_hi(p4.x), bf_lo(p4.y), bf_hi(p4.y)}; v1 += (f32x4){bf_lo(p4.z), bf_hi(p4.z), bf_lo(p4.w), bf_hi(p4.w)}; }
;                     *(u32x4*)(MIX + off + bj * HALF) = pack8(v0, v1); } } }
	v_and_b32_e32 v95, 0xffff0000, v224
	v_lshlrev_b32_e32 v96, 16, v225
	v_and_b32_e32 v97, 0xffff0000, v225
	v_pk_fma_f32 v[86:87], v[86:87], v[90:91], v[100:101]
	v_pk_fma_f32 v[84:85], v[84:85], v[88:89], v[98:99]
	v_lshlrev_b32_e32 v88, 16, v146
	v_and_b32_e32 v89, 0xffff0000, v146
	v_lshlrev_b32_e32 v90, 16, v147
	v_and_b32_e32 v91, 0xffff0000, v147
	v_pk_fma_f32 v[90:91], v[82:83], v[96:97], v[90:91]
	v_pk_fma_f32 v[82:83], v[80:81], v[94:95], v[88:89]
	v_cvt_pk_bf16_f32 v80, v84, v85
	v_cvt_pk_bf16_f32 v81, v86, v87
	v_cvt_pk_bf16_f32 v82, v82, v83
	v_cvt_pk_bf16_f32 v83, v90, v91
	global_store_dwordx4 v[92:93], v[80:83], off offset:256
	v_lshlrev_b32_e32 v84, 16, v141
	v_and_b32_e32 v85, 0xffff0000, v141
	v_lshlrev_b32_e32 v82, 16, v140
	v_and_b32_e32 v83, 0xffff0000, v140
	v_lshlrev_b32_e32 v90, 16, v136
	v_and_b32_e32 v91, 0xffff0000, v136
	v_lshlrev_b32_e32 v92, 16, v137
	v_and_b32_e32 v93, 0xffff0000, v137
	v_lshlrev_b64 v[80:81], 12, v[170:171]
	v_lshlrev_b32_e32 v86, 16, v142
	v_and_b32_e32 v87, 0xffff0000, v142
	v_lshlrev_b32_e32 v88, 16, v143
	v_and_b32_e32 v89, 0xffff0000, v143
	v_pk_fma_f32 v[78:79], v[78:79], v[84:85], v[92:93]
	v_pk_fma_f32 v[76:77], v[76:77], v[82:83], v[90:91]
	v_lshlrev_b32_e32 v82, 16, v138
	v_and_b32_e32 v83, 0xffff0000, v138
	v_lshlrev_b32_e32 v84, 16, v139
	v_and_b32_e32 v85, 0xffff0000, v139
	v_pk_fma_f32 v[84:85], v[74:75], v[88:89], v[84:85]
	v_pk_fma_f32 v[74:75], v[72:73], v[86:87], v[82:83]
	v_cvt_pk_bf16_f32 v72, v76, v77
	v_lshl_add_u64 v[76:77], s[14:15], 0, v[80:81]
	v_cvt_pk_bf16_f32 v73, v78, v79
	v_cvt_pk_bf16_f32 v74, v74, v75
	v_cvt_pk_bf16_f32 v75, v84, v85
	v_lshl_add_u64 v[76:77], v[76:77], 0, v[164:165]
	global_store_dwordx4 v[76:77], v[72:75], off
	v_lshlrev_b32_e32 v82, 16, v128
	v_and_b32_e32 v83, 0xffff0000, v128
	v_lshlrev_b32_e32 v72, 16, v132
	v_and_b32_e32 v73, 0xffff0000, v132
	v_lshlrev_b32_e32 v74, 16, v133
	v_and_b32_e32 v75, 0xffff0000, v133
	v_lshlrev_b32_e32 v84, 16, v129
	v_and_b32_e32 v85, 0xffff0000, v129
	v_lshlrev_b32_e32 v78, 16, v134
	v_and_b32_e32 v79, 0xffff0000, v134
	v_lshlrev_b32_e32 v80, 16, v135
	v_and_b32_e32 v81, 0xffff0000, v135
	v_pk_fma_f32 v[70:71], v[70:71], v[74:75], v[84:85]
	v_pk_fma_f32 v[68:69], v[68:69], v[72:73], v[82:83]
	v_lshlrev_b32_e32 v72, 16, v130
	v_and_b32_e32 v73, 0xffff0000, v130
	v_lshlrev_b32_e32 v74, 16, v131
	v_and_b32_e32 v75, 0xffff0000, v131
	v_pk_fma_f32 v[74:75], v[66:67], v[80:81], v[74:75]
	v_pk_fma_f32 v[66:67], v[64:65], v[78:79], v[72:73]
	v_add_u32_e32 v130, 0x80, v168
	v_cvt_pk_bf16_f32 v64, v68, v69
	v_cvt_pk_bf16_f32 v65, v70, v71
	v_cvt_pk_bf16_f32 v66, v66, v67
	v_cvt_pk_bf16_f32 v67, v74, v75
	v_ashrrev_i32_e32 v131, 31, v130
	global_store_dwordx4 v[76:77], v[64:67], off offset:256
	v_add_u32_e32 v132, 0x90, v168
	v_ashrrev_i32_e32 v133, 31, v132
	v_lshlrev_b64 v[64:65], 11, v[130:131]
	v_lshl_add_u64 v[64:65], v[64:65], 0, v[166:167]
	v_lshlrev_b64 v[64:65], 1, v[64:65]
	v_lshl_add_u64 v[66:67], s[12:13], 0, v[64:65]
	global_load_dwordx4 v[90:93], v[66:67], off
	v_lshl_add_u64 v[64:65], s[14:15], 0, v[64:65]
	global_load_dwordx4 v[94:97], v[64:65], off
	global_load_dwordx4 v[98:101], v[66:67], off offset:256
	global_load_dwordx4 v[102:105], v[64:65], off offset:256
	v_lshlrev_b64 v[64:65], 11, v[132:133]
	v_lshl_add_u64 v[64:65], v[64:65], 0, v[166:167]
	v_lshlrev_b64 v[64:65], 1, v[64:65]
	v_lshl_add_u64 v[66:67], s[12:13], 0, v[64:65]
	v_lshl_add_u64 v[64:65], s[14:15], 0, v[64:65]
	global_load_dwordx4 v[106:109], v[66:67], off
	global_load_dwordx4 v[110:113], v[66:67], off offset:256
	global_load_dwordx4 v[114:117], v[64:65], off
	global_load_dwordx4 v[118:121], v[64:65], off offset:256
	v_add_u32_e32 v134, 0xa0, v168
	v_ashrrev_i32_e32 v135, 31, v134
	v_lshlrev_b64 v[64:65], 11, v[134:135]
	v_lshl_add_u64 v[64:65], v[64:65], 0, v[166:167]
	v_lshlrev_b64 v[64:65], 1, v[64:65]
	v_lshl_add_u64 v[66:67], s[12:13], 0, v[64:65]
	v_lshl_add_u64 v[64:65], s[14:15], 0, v[64:65]
	global_load_dwordx4 v[122:125], v[66:67], off
	global_load_dwordx4 v[84:87], v[66:67], off offset:256
	global_load_dwordx4 v[126:129], v[64:65], off
	global_load_dwordx4 v[80:83], v[64:65], off offset:256
	v_add_u32_e32 v88, 0xb0, v168
	v_ashrrev_i32_e32 v89, 31, v88
	v_lshlrev_b64 v[64:65], 11, v[88:89]
	v_lshl_add_u64 v[64:65], v[64:65], 0, v[166:167]
	v_lshlrev_b64 v[64:65], 1, v[64:65]
	v_lshl_add_u64 v[66:67], s[12:13], 0, v[64:65]
	v_lshl_add_u64 v[64:65], s[14:15], 0, v[64:65]
	global_load_dwordx4 v[76:79], v[66:67], off
	global_load_dwordx4 v[68:71], v[66:67], off offset:256
	global_load_dwordx4 v[72:75], v[64:65], off
	s_nop 0
	global_load_dwordx4 v[64:67], v[64:65], off offset:256
	v_lshlrev_b64 v[130:131], 12, v[130:131]
	s_waitcnt vmcnt(15)
	v_lshlrev_b32_e32 v136, 16, v90
	v_and_b32_e32 v137, 0xffff0000, v90
	v_lshlrev_b32_e32 v90, 16, v91
	v_and_b32_e32 v91, 0xffff0000, v91
	s_waitcnt vmcnt(14)
	v_lshlrev_b32_e32 v140, 16, v94
	v_and_b32_e32 v141, 0xffff0000, v94
	v_lshlrev_b32_e32 v94, 16, v95
	v_and_b32_e32 v95, 0xffff0000, v95
	v_lshlrev_b32_e32 v138, 16, v92
	v_and_b32_e32 v139, 0xffff0000, v92
	v_lshlrev_b32_e32 v92, 16, v93
	v_and_b32_e32 v93, 0xffff0000, v93
	v_pk_fma_f32 v[62:63], v[62:63], v[90:91], v[94:95]
	v_pk_fma_f32 v[60:61], v[60:61], v[136:137], v[140:141]
	v_lshlrev_b32_e32 v90, 16, v96
	v_and_b32_e32 v91, 0xffff0000, v96
	v_lshlrev_b32_e32 v94, 16, v97
	v_and_b32_e32 v95, 0xffff0000, v97
	v_pk_fma_f32 v[92:93], v[58:59], v[92:93], v[94:95]
	v_pk_fma_f32 v[58:59], v[56:57], v[138:139], v[90:91]
	v_cvt_pk_bf16_f32 v56, v60, v61
	v_lshl_add_u64 v[60:61], s[14:15], 0, v[130:131]
	v_cvt_pk_bf16_f32 v57, v62, v63
	v_cvt_pk_bf16_f32 v58, v58, v59
	v_cvt_pk_bf16_f32 v59, v92, v93
	v_lshl_add_u64 v[60:61], v[60:61], 0, v[164:165]
	global_store_dwordx4 v[60:61], v[56:59], off
	s_waitcnt vmcnt(13)
; __device__ __forceinline__ float bf_lo(unsigned w) { return __uint_as_float(w << 16); }
; __device__ __forceinline__ float bf_hi(unsigned w) { return __uint_as_float(w & 0xffff0000u); }
; __device__ __forceinline__ u32x4 pack8(const f32x4 a, const f32x4 b) { u32x4 w; w.x = cvt_pk_bf16(a[0], a[1]); w.y = cvt_pk_bf16(a[2], a[3]); w.z = cvt_pk_bf16(b[0], b[1]); w.w = cvt_pk_bf16(b[2], b[3]); return w; }
;     __device__ __forceinline__ void operator()(const f32x4 (&acc)[2][2][4][2], const Unit& u, int wr, int wc, int fr, int fq) const {
;     ...
;             for (int m = 0; m < 4; ++m) { const size_t off = (size_t)(row0 + ai * HALF + m * 16) * 2048 + col0;
; #pragma unroll
;                 for (int bj = 0; bj < 2; ++bj) { const u32x4 g4 = gw[m][bj];
;                     f32x4 v0 = (f32x4){bf_lo(g4.x), bf_hi(g4.x), bf_lo(g4.y), bf_hi(g4.y)} * acc[ai][bj][m][0], v1 = (f32x4){bf_lo(g4.z), bf_hi(g4.z), bf_lo(g4.w), bf_hi(g4.w)} * acc[ai][bj][m][1];
;                     if (PASS == 1) { const u32x4 p4 = pw[m][bj]; v0 += (f32x4){bf_lo(p4.x), bf_hi(p4.x), bf_lo(p4.y), bf_hi(p4.y)}; v1 += (f32x4){bf_lo(p4.z), bf_hi(p4.z), bf_lo(p4.w), bf_hi(p4.w)}; }
;                     *(u32x4*)(MIX + off + bj * HALF) = pack8(v0, v1); } } }
	v_lshlrev_b32_e32 v92, 16, v102
	v_and_b32_e32 v93, 0xffff0000, v102
	v_lshlrev_b32_e32 v56, 16, v98
	v_and_b32_e32 v57, 0xffff0000, v98
	v_lshlrev_b32_e32 v58, 16, v99
	v_and_b32_e32 v59, 0xffff0000, v99
	v_lshlrev_b32_e32 v94, 16, v103
	v_and_b32_e32 v95, 0xffff0000, v103
	v_lshlrev_b32_e32 v62, 16, v100
	v_and_b32_e32 v63, 0xffff0000, v100
	v_lshlrev_b32_e32 v90, 16, v101
	v_and_b32_e32 v91, 0xffff0000, v101
	v_pk_fma_f32 v[54:55], v[54:55], v[58:59], v[94:95]
	v_pk_fma_f32 v[52:53], v[52:53], v[56:57], v[92:93]
	v_lshlrev_b32_e32 v56, 16, v104
	v_and_b32_e32 v57, 0xffff0000, v104
	v_lshlrev_b32_e32 v58, 16, v105
	v_and_b32_e32 v59, 0xffff0000, v105
	v_pk_fma_f32 v[58:59], v[50:51], v[90:91], v[58:59]
	v_pk_fma_f32 v[50:51], v[48:49], v[62:63], v[56:57]
	v_cvt_pk_bf16_f32 v48, v52, v53
	v_cvt_pk_bf16_f32 v49, v54, v55
	v_cvt_pk_bf16_f32 v50, v50, v51
	v_cvt_pk_bf16_f32 v51, v58, v59
	global_store_dwordx4 v[60:61], v[48:51], off offset:256
	s_waitcnt vmcnt(13)
	v_lshlrev_b32_e32 v52, 16, v107
	v_and_b32_e32 v53, 0xffff0000, v107
	v_lshlrev_b32_e32 v50, 16, v106
	v_and_b32_e32 v51, 0xffff0000, v106
	s_waitcnt vmcnt(11)
	v_lshlrev_b32_e32 v58, 16, v114
	v_and_b32_e32 v59, 0xffff0000, v114
	v_lshlrev_b32_e32 v60, 16, v115
	v_and_b32_e32 v61, 0xffff0000, v115
	v_lshlrev_b64 v[48:49], 12, v[132:133]
	v_lshlrev_b32_e32 v54, 16, v108
	v_and_b32_e32 v55, 0xffff0000, v108
	v_lshlrev_b32_e32 v56, 16, v109
	v_and_b32_e32 v57, 0xffff0000, v109
	v_pk_fma_f32 v[46:47], v[46:47], v[52:53], v[60:61]
	v_pk_fma_f32 v[44:45], v[44:45], v[50:51], v[58:59]
	v_lshlrev_b32_e32 v50, 16, v116
	v_and_b32_e32 v51, 0xffff0000, v116
	v_lshlrev_b32_e32 v52, 16, v117
	v_and_b32_e32 v53, 0xffff0000, v117
	v_pk_fma_f32 v[52:53], v[42:43], v[56:57], v[52:53]
	v_pk_fma_f32 v[42:43], v[40:41], v[54:55], v[50:51]
	v_cvt_pk_bf16_f32 v40, v44, v45
	v_lshl_add_u64 v[44:45], s[14:15], 0, v[48:49]
	v_cvt_pk_bf16_f32 v41, v46, v47
	v_cvt_pk_bf16_f32 v42, v42, v43
	v_cvt_pk_bf16_f32 v43, v52, v53
	v_lshl_add_u64 v[44:45], v[44:45], 0, v[164:165]
	global_store_dwordx4 v[44:45], v[40:43], off
	s_waitcnt vmcnt(11)
	v_lshlrev_b32_e32 v50, 16, v118
	v_and_b32_e32 v51, 0xffff0000, v118
	v_lshlrev_b32_e32 v40, 16, v110
	v_and_b32_e32 v41, 0xffff0000, v110
	v_lshlrev_b32_e32 v42, 16, v111
	v_and_b32_e32 v43, 0xffff0000, v111
	v_lshlrev_b32_e32 v52, 16, v119
	v_and_b32_e32 v53, 0xffff0000, v119
	v_lshlrev_b32_e32 v46, 16, v112
	v_and_b32_e32 v47, 0xffff0000, v112
	v_lshlrev_b32_e32 v48, 16, v113
	v_and_b32_e32 v49, 0xffff0000, v113
	v_pk_fma_f32 v[38:39], v[38:39], v[42:43], v[52:53]
	v_pk_fma_f32 v[36:37], v[36:37], v[40:41], v[50:51]
	v_lshlrev_b32_e32 v40, 16, v120
	v_and_b32_e32 v41, 0xffff0000, v120
	v_lshlrev_b32_e32 v42, 16, v121
	v_and_b32_e32 v43, 0xffff0000, v121
	v_pk_fma_f32 v[42:43], v[34:35], v[48:49], v[42:43]
	v_pk_fma_f32 v[34:35], v[32:33], v[46:47], v[40:41]
	v_cvt_pk_bf16_f32 v32, v36, v37
	v_cvt_pk_bf16_f32 v33, v38, v39
	v_cvt_pk_bf16_f32 v34, v34, v35
	v_cvt_pk_bf16_f32 v35, v42, v43
	global_store_dwordx4 v[44:45], v[32:35], off offset:256
	s_waitcnt vmcnt(11)
	v_lshlrev_b32_e32 v36, 16, v123
	v_and_b32_e32 v37, 0xffff0000, v123
	v_lshlrev_b32_e32 v34, 16, v122
	v_and_b32_e32 v35, 0xffff0000, v122
	s_waitcnt vmcnt(9)
; __device__ __forceinline__ float bf_lo(unsigned w) { return __uint_as_float(w << 16); }
; __device__ __forceinline__ float bf_hi(unsigned w) { return __uint_as_float(w & 0xffff0000u); }
; __device__ __forceinline__ u32x4 pack8(const f32x4 a, const f32x4 b) { u32x4 w; w.x = cvt_pk_bf16(a[0], a[1]); w.y = cvt_pk_bf16(a[2], a[3]); w.z = cvt_pk_bf16(b[0], b[1]); w.w = cvt_pk_bf16(b[2], b[3]); return w; }
; #define PG8_WAIT_V(n) asm volatile("s_waitcnt vmcnt(" #n ")" ::: "memory")
; #define PG8_BAR __builtin_amdgcn_s_barrier()
;     __device__ __forceinline__ void operator()(const f32x4 (&acc)[2][2][4][2], const Unit& u, int wr, int wc, int fr, int fq) const {
;     ...
;             for (int m = 0; m < 4; ++m) { const size_t off = (size_t)(row0 + ai * HALF + m * 16) * 2048 + col0;
; #pragma unroll
;                 for (int bj = 0; bj < 2; ++bj) { const u32x4 g4 = gw[m][bj];
;                     f32x4 v0 = (f32x4){bf_lo(g4.x), bf_hi(g4.x), bf_lo(g4.y), bf_hi(g4.y)} * acc[ai][bj][m][0], v1 = (f32x4){bf_lo(g4.z), bf_hi(g4.z), bf_lo(g4.w), bf_hi(g4.w)} * acc[ai][bj][m][1];
;                     if (PASS == 1) { const u32x4 p4 = pw[m][bj]; v0 += (f32x4){bf_lo(p4.x), bf_hi(p4.x), bf_lo(p4.y), bf_hi(p4.y)}; v1 += (f32x4){bf_lo(p4.z), bf_hi(p4.z), bf_lo(p4.w), bf_hi(p4.w)}; }
;                     *(u32x4*)(MIX + off + bj * HALF) = pack8(v0, v1); } } }
; template <class Epi, class Sched, bool ALIGN_EPI = false, bool SP2 = false>
; __device__ __forceinline__ void gemm_phase(PG8_LAS unsigned char* lds, const Gemm g, const Sched& S, const Epi& E) {
;     ...
;     PG8_WAIT_V(0);
;     if constexpr (!ALIGN_EPI) { if (wr == 0) PG8_BAR; }
;     PG8_BAR;
	v_lshlrev_b32_e32 v42, 16, v126
	v_and_b32_e32 v43, 0xffff0000, v126
	v_lshlrev_b32_e32 v44, 16, v127
	v_and_b32_e32 v45, 0xffff0000, v127
	v_lshlrev_b64 v[32:33], 12, v[134:135]
	v_lshlrev_b32_e32 v38, 16, v124
	v_and_b32_e32 v39, 0xffff0000, v124
	v_lshlrev_b32_e32 v40, 16, v125
	v_and_b32_e32 v41, 0xffff0000, v125
	v_pk_fma_f32 v[30:31], v[30:31], v[36:37], v[44:45]
	v_pk_fma_f32 v[28:29], v[28:29], v[34:35], v[42:43]
	v_lshlrev_b32_e32 v34, 16, v128
	v_and_b32_e32 v35, 0xffff0000, v128
	v_lshlrev_b32_e32 v36, 16, v129
	v_and_b32_e32 v37, 0xffff0000, v129
	v_pk_fma_f32 v[36:37], v[26:27], v[40:41], v[36:37]
	v_pk_fma_f32 v[26:27], v[24:25], v[38:39], v[34:35]
	v_cvt_pk_bf16_f32 v24, v28, v29
	v_lshl_add_u64 v[28:29], s[14:15], 0, v[32:33]
	v_cvt_pk_bf16_f32 v25, v30, v31
	v_cvt_pk_bf16_f32 v26, v26, v27
	v_cvt_pk_bf16_f32 v27, v36, v37
	v_lshl_add_u64 v[28:29], v[28:29], 0, v[164:165]
	global_store_dwordx4 v[28:29], v[24:27], off
	s_waitcnt vmcnt(9)
	v_lshlrev_b32_e32 v34, 16, v80
	v_and_b32_e32 v35, 0xffff0000, v80
	v_lshlrev_b32_e32 v24, 16, v84
	v_and_b32_e32 v25, 0xffff0000, v84
	v_lshlrev_b32_e32 v26, 16, v85
	v_and_b32_e32 v27, 0xffff0000, v85
	v_lshlrev_b32_e32 v36, 16, v81
	v_and_b32_e32 v37, 0xffff0000, v81
	v_lshlrev_b32_e32 v30, 16, v86
	v_and_b32_e32 v31, 0xffff0000, v86
	v_lshlrev_b32_e32 v32, 16, v87
	v_and_b32_e32 v33, 0xffff0000, v87
	v_pk_fma_f32 v[22:23], v[22:23], v[26:27], v[36:37]
	v_pk_fma_f32 v[20:21], v[20:21], v[24:25], v[34:35]
	v_lshlrev_b32_e32 v24, 16, v82
	v_and_b32_e32 v25, 0xffff0000, v82
	v_lshlrev_b32_e32 v26, 16, v83
	v_and_b32_e32 v27, 0xffff0000, v83
	v_pk_fma_f32 v[26:27], v[18:19], v[32:33], v[26:27]
	v_pk_fma_f32 v[18:19], v[16:17], v[30:31], v[24:25]
	v_cvt_pk_bf16_f32 v16, v20, v21
	v_cvt_pk_bf16_f32 v17, v22, v23
	v_cvt_pk_bf16_f32 v18, v18, v19
	v_cvt_pk_bf16_f32 v19, v26, v27
	global_store_dwordx4 v[28:29], v[16:19], off offset:256
	s_waitcnt vmcnt(9)
	v_lshlrev_b32_e32 v20, 16, v77
	v_and_b32_e32 v21, 0xffff0000, v77
	v_lshlrev_b32_e32 v18, 16, v76
	v_and_b32_e32 v19, 0xffff0000, v76
	s_waitcnt vmcnt(7)
	v_lshlrev_b32_e32 v26, 16, v72
	v_and_b32_e32 v27, 0xffff0000, v72
	v_lshlrev_b32_e32 v28, 16, v73
	v_and_b32_e32 v29, 0xffff0000, v73
	v_lshlrev_b64 v[16:17], 12, v[88:89]
	v_lshlrev_b32_e32 v22, 16, v78
	v_and_b32_e32 v23, 0xffff0000, v78
	v_lshlrev_b32_e32 v24, 16, v79
	v_and_b32_e32 v25, 0xffff0000, v79
	v_pk_fma_f32 v[14:15], v[14:15], v[20:21], v[28:29]
	v_pk_fma_f32 v[12:13], v[12:13], v[18:19], v[26:27]
	v_lshlrev_b32_e32 v18, 16, v74
	v_and_b32_e32 v19, 0xffff0000, v74
	v_lshlrev_b32_e32 v20, 16, v75
	v_and_b32_e32 v21, 0xffff0000, v75
	v_pk_fma_f32 v[20:21], v[10:11], v[24:25], v[20:21]
	v_pk_fma_f32 v[10:11], v[8:9], v[22:23], v[18:19]
	v_cvt_pk_bf16_f32 v8, v12, v13
	v_lshl_add_u64 v[12:13], s[14:15], 0, v[16:17]
	v_cvt_pk_bf16_f32 v9, v14, v15
	v_cvt_pk_bf16_f32 v10, v10, v11
	v_cvt_pk_bf16_f32 v11, v20, v21
	v_lshl_add_u64 v[12:13], v[12:13], 0, v[164:165]
	global_store_dwordx4 v[12:13], v[8:11], off
	s_waitcnt vmcnt(7)
	v_lshlrev_b32_e32 v18, 16, v64
	v_and_b32_e32 v19, 0xffff0000, v64
	v_lshlrev_b32_e32 v8, 16, v68
	v_and_b32_e32 v9, 0xffff0000, v68
	v_lshlrev_b32_e32 v10, 16, v69
	v_and_b32_e32 v11, 0xffff0000, v69
	v_lshlrev_b32_e32 v20, 16, v65
	v_and_b32_e32 v21, 0xffff0000, v65
	v_lshlrev_b32_e32 v14, 16, v70
	v_and_b32_e32 v15, 0xffff0000, v70
	v_lshlrev_b32_e32 v16, 16, v71
	v_and_b32_e32 v17, 0xffff0000, v71
	v_pk_fma_f32 v[6:7], v[6:7], v[10:11], v[20:21]
	v_pk_fma_f32 v[4:5], v[4:5], v[8:9], v[18:19]
	v_lshlrev_b32_e32 v8, 16, v66
	v_and_b32_e32 v9, 0xffff0000, v66
	v_lshlrev_b32_e32 v10, 16, v67
	v_and_b32_e32 v11, 0xffff0000, v67
	v_pk_fma_f32 v[10:11], v[2:3], v[16:17], v[10:11]
	v_pk_fma_f32 v[2:3], v[0:1], v[14:15], v[8:9]
	v_cvt_pk_bf16_f32 v0, v4, v5
	v_cvt_pk_bf16_f32 v1, v6, v7
	v_cvt_pk_bf16_f32 v2, v2, v3
	v_cvt_pk_bf16_f32 v3, v10, v11
	global_store_dwordx4 v[12:13], v[0:3], off offset:256
	s_cbranch_vccz .LBB0_748
	s_waitcnt vmcnt(0)
	s_cmpk_gt_u32 s3, 0xff
	s_cbranch_scc1 .LBB0_759
	s_barrier

; #define PG8_STAGE(bufoff, gbase, voff) do { _Pragma("unroll") for (int _i = 0; _i < 2; ++_i) \
;         __builtin_amdgcn_global_load_lds((const unsigned*)((const char*)(gbase) + (voff)[_i]), (PG8_LAS unsigned*)(lds + (bufoff) + ldsw + _i * 8192), 16, 0, 0); } while (0)
; #define PG8_LDA(dst, b, h) do { _Pragma("unroll") for (int m = 0; m < 4; ++m) _Pragma("unroll") for (int k = 0; k < 2; ++k) dst[m][k] = *(const PG8_LAS bf16x8*)(lds + PG8_SA(b, h) + aoff + m * 2048 + k * 1024); } while (0)
; #define PG8_LDB(dst, b, h) do { _Pragma("unroll") for (int n = 0; n < 2; ++n) _Pragma("unroll") for (int k = 0; k < 2; ++k) dst[n][k] = *(const PG8_LAS bf16x8*)(lds + PG8_SB(b, h) + boff + n * 2048 + k * 1024); } while (0)
; #define PG8_MMA(ai, bj, At, Bt) do { __builtin_amdgcn_s_setprio(1); _Pragma("unroll") for (int m = 0; m < 4; ++m) _Pragma("unroll") for (int n = 0; n < 2; ++n) _Pragma("unroll") for (int k = 0; k < 2; ++k) \
;         acc[ai][bj][m][n] = __builtin_amdgcn_mfma_f32_16x16x32_bf16(Bt[n][k], At[m][k], acc[ai][bj][m][n], 0, 0, 0); __builtin_amdgcn_s_setprio(0); } while (0)
; #define PG8_BAR __builtin_amdgcn_s_barrier()
; template <class Epi, class Sched, bool ALIGN_EPI = false, bool SP2 = false>
; __device__ __forceinline__ void gemm_phase(PG8_LAS unsigned char* lds, const Gemm g, const Sched& S, const Epi& E) {
;     ...
;         const bool has_next = S.next(ui + 1, nxt);
;         const char* nA = has_next ? (const char*)g.A + (size_t)nxt.pm * tstep : cA; const char* nB = has_next ? (const char*)g.Bt + (size_t)nxt.pn * tstep : cB;
;         for (int t = 0; t < nt; t += 2) {
;             const bool last = (t == nt - 2);
;             const char* a1 = cA + (size_t)(t + 1) * kstep;
;             const char* a2 = last ? nA : cA + (size_t)(t + 2) * kstep; const char* b2 = last ? nB : cB + (size_t)(t + 2) * kstep;
;             const char* a3 = a2 + kstep; const char* b3 = b2 + kstep;
;             if (last && has_next) S.a_ready(nxt);
;             if constexpr (SP2) {
;             PG8_LDB(B0, 0, 0); PG8_LDB(B1, 0, 1); PG8_SCHED; PG8_LDA(At, 0, 0); PG8_STAGE(PG8_SA(1, 1), a1 + hstep, voffA);
;             PG8_WAIT_V(8); PG8_WAIT_L(0); PG8_BAR; PG8_MMA(0, 0, At, B0); PG8_MMA(0, 1, At, B1); PG8_BAR; PG8_SCHED;
;             PG8_LDA(At, 0, 1); PG8_STAGE(PG8_SB(0, 0), b2, voffB); PG8_STAGE(PG8_SB(0, 1), b2 + hstep, voffB); PG8_STAGE(PG8_SA(0, 0), a2, voffA);
.LBB0_826:
	s_ashr_i32 s39, s38, 31
	v_cmp_lt_i64_e32 vcc, s[40:41], v[156:157]
	s_lshl_b64 s[40:41], s[38:39], 20
	s_add_u32 s40, s9, s40
	s_addc_u32 s41, s22, s41
	s_and_b64 s[42:43], vcc, exec
	s_cselect_b32 s39, s41, s47
	s_cselect_b32 s67, s40, s46
	s_ashr_i32 s37, s36, 31
	s_lshl_b64 s[42:43], s[36:37], 20
	s_add_u32 s42, s23, s42
	s_addc_u32 s43, s52, s43
	s_and_b64 s[50:51], vcc, exec
	s_cselect_b32 s37, s43, s49
	s_cselect_b32 s68, s42, s48
	s_add_u32 s46, s46, 0x80080
	s_addc_u32 s47, s47, 0
	s_add_u32 s69, s48, 0x100
	s_addc_u32 s70, s49, 0
	s_mov_b32 s71, -2
	v_add_u32_e32 v164, 0x18000, v167
	v_add_u32_e32 v165, 0x1c000, v167
	ds_read_b128 v[128:131], v169
	ds_read_b128 v[132:135], v169 offset:1024
	ds_read_b128 v[136:139], v169 offset:2048
	ds_read_b128 v[140:143], v169 offset:3072
	ds_read_b128 v[160:163], v170
	ds_read_b128 v[172:175], v170 offset:1024
	ds_read_b128 v[176:179], v170 offset:2048
	ds_read_b128 v[180:183], v170 offset:3072
	s_add_u32 s48, s46, 0xfff80080
	s_addc_u32 s49, s47, -1
	s_cmp_eq_u32 s71, 28
	s_cselect_b32 s51, s39, s49
	s_cselect_b32 s50, s67, s48
	s_cselect_b32 s49, s37, s70
	s_cselect_b32 s48, s68, s69
	s_add_i32 m0, s45, 0xc000
	ds_read_b128 v[184:187], v171
	ds_read_b128 v[188:191], v171 offset:1024
	ds_read_b128 v[192:195], v171 offset:2048
	ds_read_b128 v[196:199], v171 offset:3072
	ds_read_b128 v[200:203], v171 offset:4096
	ds_read_b128 v[204:207], v171 offset:5120
	ds_read_b128 v[208:211], v171 offset:6144
	ds_read_b128 v[214:217], v171 offset:7168
	global_load_lds_dwordx4 v152, s[46:47]
	s_add_i32 m0, s45, 0xe000
	s_nop 0
	global_load_lds_dwordx4 v154, s[46:47]
	s_waitcnt vmcnt(8) lgkmcnt(0)
	s_barrier
	v_mfma_f32_16x16x32_bf16 v[124:127], v[128:131], v[184:187], 0
	v_mfma_f32_16x16x32_bf16 v[120:123], v[136:139], v[184:187], 0
	v_mfma_f32_16x16x32_bf16 v[116:119], v[128:131], v[192:195], 0
	v_mfma_f32_16x16x32_bf16 v[112:115], v[136:139], v[192:195], 0
	v_mfma_f32_16x16x32_bf16 v[108:111], v[128:131], v[200:203], 0
	v_mfma_f32_16x16x32_bf16 v[96:99], v[136:139], v[200:203], 0
	v_mfma_f32_16x16x32_bf16 v[80:83], v[128:131], v[208:211], 0
	v_mfma_f32_16x16x32_bf16 v[72:75], v[136:139], v[208:211], 0
	v_mfma_f32_16x16x32_bf16 v[124:127], v[132:135], v[188:191], v[124:127]
	v_mfma_f32_16x16x32_bf16 v[120:123], v[140:143], v[188:191], v[120:123]
	v_mfma_f32_16x16x32_bf16 v[116:119], v[132:135], v[196:199], v[116:119]
	v_mfma_f32_16x16x32_bf16 v[112:115], v[140:143], v[196:199], v[112:115]
	v_mfma_f32_16x16x32_bf16 v[108:111], v[132:135], v[204:207], v[108:111]
	v_mfma_f32_16x16x32_bf16 v[96:99], v[140:143], v[204:207], v[96:99]
	v_mfma_f32_16x16x32_bf16 v[80:83], v[132:135], v[214:217], v[80:83]
	v_mfma_f32_16x16x32_bf16 v[72:75], v[140:143], v[214:217], v[72:75]
	v_mfma_f32_16x16x32_bf16 v[104:107], v[160:163], v[184:187], 0
	v_mfma_f32_16x16x32_bf16 v[100:103], v[176:179], v[184:187], 0
	v_mfma_f32_16x16x32_bf16 v[92:95], v[160:163], v[192:195], 0
	v_mfma_f32_16x16x32_bf16 v[88:91], v[176:179], v[192:195], 0
	v_mfma_f32_16x16x32_bf16 v[84:87], v[160:163], v[200:203], 0
	v_mfma_f32_16x16x32_bf16 v[76:79], v[176:179], v[200:203], 0
	v_mfma_f32_16x16x32_bf16 v[68:71], v[160:163], v[208:211], 0
	v_mfma_f32_16x16x32_bf16 v[64:67], v[176:179], v[208:211], 0
	v_mfma_f32_16x16x32_bf16 v[104:107], v[172:175], v[188:191], v[104:107]
	v_mfma_f32_16x16x32_bf16 v[100:103], v[180:183], v[188:191], v[100:103]
	v_mfma_f32_16x16x32_bf16 v[92:95], v[172:175], v[196:199], v[92:95]
	v_mfma_f32_16x16x32_bf16 v[88:91], v[180:183], v[196:199], v[88:91]
	v_mfma_f32_16x16x32_bf16 v[84:87], v[172:175], v[204:207], v[84:87]
	v_mfma_f32_16x16x32_bf16 v[76:79], v[180:183], v[204:207], v[76:79]
	v_mfma_f32_16x16x32_bf16 v[68:71], v[172:175], v[214:217], v[68:71]
	v_mfma_f32_16x16x32_bf16 v[64:67], v[180:183], v[214:217], v[64:67]
	s_barrier
	s_add_i32 s72, s64, s53
	s_mov_b32 m0, s72
	ds_read_b128 v[184:187], v171 offset:16384
	ds_read_b128 v[188:191], v171 offset:17408
	ds_read_b128 v[192:195], v171 offset:18432
	ds_read_b128 v[196:199], v171 offset:19456
	ds_read_b128 v[200:203], v171 offset:20480
	ds_read_b128 v[204:207], v171 offset:21504
	ds_read_b128 v[208:211], v171 offset:22528
	ds_read_b128 v[214:217], v171 offset:23552
	global_load_lds_dwordx4 v146, s[48:49]
	s_add_i32 m0, s72, 0x2000
	s_add_u32 s72, s48, 0x80000
	s_addc_u32 s73, s49, 0
	s_add_i32 s74, s65, s53
	global_load_lds_dwordx4 v150, s[48:49]
	s_mov_b32 m0, s74
	s_nop 0
	global_load_lds_dwordx4 v146, s[72:73]
	s_add_i32 m0, s74, 0x2000
	s_nop 0
	global_load_lds_dwordx4 v150, s[72:73]
	s_mov_b32 m0, s45
	s_nop 0
	global_load_lds_dwordx4 v144, s[50:51]
	s_mov_b32 m0, s54
	s_nop 0
	global_load_lds_dwordx4 v148, s[50:51]
	s_waitcnt vmcnt(8) lgkmcnt(0)
	s_barrier
; #define PG8_STAGE(bufoff, gbase, voff) do { _Pragma("unroll") for (int _i = 0; _i < 2; ++_i) \
;         __builtin_amdgcn_global_load_lds((const unsigned*)((const char*)(gbase) + (voff)[_i]), (PG8_LAS unsigned*)(lds + (bufoff) + ldsw + _i * 8192), 16, 0, 0); } while (0)
; #define PG8_LDA(dst, b, h) do { _Pragma("unroll") for (int m = 0; m < 4; ++m) _Pragma("unroll") for (int k = 0; k < 2; ++k) dst[m][k] = *(const PG8_LAS bf16x8*)(lds + PG8_SA(b, h) + aoff + m * 2048 + k * 1024); } while (0)
; #define PG8_LDB(dst, b, h) do { _Pragma("unroll") for (int n = 0; n < 2; ++n) _Pragma("unroll") for (int k = 0; k < 2; ++k) dst[n][k] = *(const PG8_LAS bf16x8*)(lds + PG8_SB(b, h) + boff + n * 2048 + k * 1024); } while (0)
; #define PG8_MMA(ai, bj, At, Bt) do { __builtin_amdgcn_s_setprio(1); _Pragma("unroll") for (int m = 0; m < 4; ++m) _Pragma("unroll") for (int n = 0; n < 2; ++n) _Pragma("unroll") for (int k = 0; k < 2; ++k) \
;         acc[ai][bj][m][n] = __builtin_amdgcn_mfma_f32_16x16x32_bf16(Bt[n][k], At[m][k], acc[ai][bj][m][n], 0, 0, 0); __builtin_amdgcn_s_setprio(0); } while (0)
; #define PG8_WAIT_V(n) asm volatile("s_waitcnt vmcnt(" #n ")" ::: "memory")
; #define PG8_WAIT_L(n) asm volatile("s_waitcnt lgkmcnt(" #n ")" ::: "memory")
; #define PG8_BAR __builtin_amdgcn_s_barrier()
; #define PG8_SCHED __builtin_amdgcn_sched_barrier(0)
; template <class Epi, class Sched, bool ALIGN_EPI = false, bool SP2 = false>
; __device__ __forceinline__ void gemm_phase(PG8_LAS unsigned char* lds, const Gemm g, const Sched& S, const Epi& E) {
;     ...
;             PG8_WAIT_V(8); PG8_WAIT_L(0); PG8_BAR; PG8_MMA(1, 0, At, B0); PG8_MMA(1, 1, At, B1); PG8_BAR; PG8_SCHED;
;             PG8_LDB(B0, 1, 0); PG8_LDB(B1, 1, 1); PG8_SCHED; PG8_LDA(At, 1, 0); PG8_STAGE(PG8_SA(0, 1), a2 + hstep, voffA);
;             PG8_WAIT_V(8); PG8_WAIT_L(0); PG8_BAR; PG8_MMA(0, 0, At, B0); PG8_MMA(0, 1, At, B1); PG8_BAR; PG8_SCHED;
	v_mfma_f32_16x16x32_bf16 v[60:63], v[128:131], v[184:187], 0
	v_mfma_f32_16x16x32_bf16 v[56:59], v[136:139], v[184:187], 0
	v_mfma_f32_16x16x32_bf16 v[52:55], v[128:131], v[192:195], 0
	v_mfma_f32_16x16x32_bf16 v[48:51], v[136:139], v[192:195], 0
	v_mfma_f32_16x16x32_bf16 v[44:47], v[128:131], v[200:203], 0
	v_mfma_f32_16x16x32_bf16 v[32:35], v[136:139], v[200:203], 0
	v_mfma_f32_16x16x32_bf16 v[20:23], v[128:131], v[208:211], 0
	v_mfma_f32_16x16x32_bf16 v[8:11], v[136:139], v[208:211], 0
	v_mfma_f32_16x16x32_bf16 v[60:63], v[132:135], v[188:191], v[60:63]
	v_mfma_f32_16x16x32_bf16 v[56:59], v[140:143], v[188:191], v[56:59]
	v_mfma_f32_16x16x32_bf16 v[52:55], v[132:135], v[196:199], v[52:55]
	v_mfma_f32_16x16x32_bf16 v[48:51], v[140:143], v[196:199], v[48:51]
	v_mfma_f32_16x16x32_bf16 v[44:47], v[132:135], v[204:207], v[44:47]
	v_mfma_f32_16x16x32_bf16 v[32:35], v[140:143], v[204:207], v[32:35]
	v_mfma_f32_16x16x32_bf16 v[20:23], v[132:135], v[214:217], v[20:23]
	v_mfma_f32_16x16x32_bf16 v[8:11], v[140:143], v[214:217], v[8:11]
	v_mfma_f32_16x16x32_bf16 v[40:43], v[160:163], v[184:187], 0
	v_mfma_f32_16x16x32_bf16 v[36:39], v[176:179], v[184:187], 0
	v_mfma_f32_16x16x32_bf16 v[28:31], v[160:163], v[192:195], 0
	v_mfma_f32_16x16x32_bf16 v[24:27], v[176:179], v[192:195], 0
	v_mfma_f32_16x16x32_bf16 v[16:19], v[160:163], v[200:203], 0
	v_mfma_f32_16x16x32_bf16 v[12:15], v[176:179], v[200:203], 0
	v_mfma_f32_16x16x32_bf16 v[4:7], v[160:163], v[208:211], 0
	v_mfma_f32_16x16x32_bf16 v[0:3], v[176:179], v[208:211], 0
	v_mfma_f32_16x16x32_bf16 v[40:43], v[172:175], v[188:191], v[40:43]
	v_mfma_f32_16x16x32_bf16 v[36:39], v[180:183], v[188:191], v[36:39]
	v_mfma_f32_16x16x32_bf16 v[28:31], v[172:175], v[196:199], v[28:31]
	v_mfma_f32_16x16x32_bf16 v[24:27], v[180:183], v[196:199], v[24:27]
	v_mfma_f32_16x16x32_bf16 v[16:19], v[172:175], v[204:207], v[16:19]
	v_mfma_f32_16x16x32_bf16 v[12:15], v[180:183], v[204:207], v[12:15]
	v_mfma_f32_16x16x32_bf16 v[4:7], v[172:175], v[214:217], v[4:7]
	v_mfma_f32_16x16x32_bf16 v[0:3], v[180:183], v[214:217], v[0:3]
	s_barrier
	s_add_i32 s72, 0, 0x18000
	s_add_i32 s73, 0, 0x1c000
	ds_read_b128 v[128:131], v164
	ds_read_b128 v[132:135], v164 offset:1024
	ds_read_b128 v[136:139], v164 offset:2048
	ds_read_b128 v[140:143], v164 offset:3072
	ds_read_b128 v[160:163], v165
	ds_read_b128 v[172:175], v165 offset:1024
	ds_read_b128 v[176:179], v165 offset:2048
	ds_read_b128 v[180:183], v165 offset:3072
	s_add_u32 s84, s50, 0x80
	s_addc_u32 s85, s51, 0
	s_add_u32 s50, s50, 0x80000
	s_addc_u32 s51, s51, 0
	s_mov_b32 m0, s55
	ds_read_b128 v[184:187], v171 offset:32768
	ds_read_b128 v[188:191], v171 offset:33792
	ds_read_b128 v[192:195], v171 offset:34816
	ds_read_b128 v[196:199], v171 offset:35840
	ds_read_b128 v[200:203], v171 offset:36864
	ds_read_b128 v[204:207], v171 offset:37888
	ds_read_b128 v[208:211], v171 offset:38912
	ds_read_b128 v[214:217], v171 offset:39936
	global_load_lds_dwordx4 v144, s[50:51]
	s_mov_b32 m0, s56
	s_nop 0
	global_load_lds_dwordx4 v148, s[50:51]
	s_waitcnt vmcnt(8) lgkmcnt(0)
	s_barrier
	v_mfma_f32_16x16x32_bf16 v[124:127], v[128:131], v[184:187], v[124:127]
	v_mfma_f32_16x16x32_bf16 v[120:123], v[136:139], v[184:187], v[120:123]
	v_mfma_f32_16x16x32_bf16 v[116:119], v[128:131], v[192:195], v[116:119]
	v_mfma_f32_16x16x32_bf16 v[112:115], v[136:139], v[192:195], v[112:115]
	v_mfma_f32_16x16x32_bf16 v[108:111], v[128:131], v[200:203], v[108:111]
	v_mfma_f32_16x16x32_bf16 v[96:99], v[136:139], v[200:203], v[96:99]
	v_mfma_f32_16x16x32_bf16 v[80:83], v[128:131], v[208:211], v[80:83]
	v_mfma_f32_16x16x32_bf16 v[72:75], v[136:139], v[208:211], v[72:75]
	v_mfma_f32_16x16x32_bf16 v[124:127], v[132:135], v[188:191], v[124:127]
	v_mfma_f32_16x16x32_bf16 v[120:123], v[140:143], v[188:191], v[120:123]
	v_mfma_f32_16x16x32_bf16 v[116:119], v[132:135], v[196:199], v[116:119]
	v_mfma_f32_16x16x32_bf16 v[112:115], v[140:143], v[196:199], v[112:115]
	v_mfma_f32_16x16x32_bf16 v[108:111], v[132:135], v[204:207], v[108:111]
	v_mfma_f32_16x16x32_bf16 v[96:99], v[140:143], v[204:207], v[96:99]
	v_mfma_f32_16x16x32_bf16 v[80:83], v[132:135], v[214:217], v[80:83]
	v_mfma_f32_16x16x32_bf16 v[72:75], v[140:143], v[214:217], v[72:75]
	v_mfma_f32_16x16x32_bf16 v[104:107], v[160:163], v[184:187], v[104:107]
	v_mfma_f32_16x16x32_bf16 v[100:103], v[176:179], v[184:187], v[100:103]
	v_mfma_f32_16x16x32_bf16 v[92:95], v[160:163], v[192:195], v[92:95]
	v_mfma_f32_16x16x32_bf16 v[88:91], v[176:179], v[192:195], v[88:91]
	v_mfma_f32_16x16x32_bf16 v[84:87], v[160:163], v[200:203], v[84:87]
	v_mfma_f32_16x16x32_bf16 v[76:79], v[176:179], v[200:203], v[76:79]
	v_mfma_f32_16x16x32_bf16 v[68:71], v[160:163], v[208:211], v[68:71]
	v_mfma_f32_16x16x32_bf16 v[64:67], v[176:179], v[208:211], v[64:67]
	v_mfma_f32_16x16x32_bf16 v[104:107], v[172:175], v[188:191], v[104:107]
	v_mfma_f32_16x16x32_bf16 v[100:103], v[180:183], v[188:191], v[100:103]
	v_mfma_f32_16x16x32_bf16 v[92:95], v[172:175], v[196:199], v[92:95]
	v_mfma_f32_16x16x32_bf16 v[88:91], v[180:183], v[196:199], v[88:91]
	v_mfma_f32_16x16x32_bf16 v[84:87], v[172:175], v[204:207], v[84:87]
	v_mfma_f32_16x16x32_bf16 v[76:79], v[180:183], v[204:207], v[76:79]
	v_mfma_f32_16x16x32_bf16 v[68:71], v[172:175], v[214:217], v[68:71]
	v_mfma_f32_16x16x32_bf16 v[64:67], v[180:183], v[214:217], v[64:67]
	s_barrier
; #define PG8_STAGE(bufoff, gbase, voff) do { _Pragma("unroll") for (int _i = 0; _i < 2; ++_i) \
;         __builtin_amdgcn_global_load_lds((const unsigned*)((const char*)(gbase) + (voff)[_i]), (PG8_LAS unsigned*)(lds + (bufoff) + ldsw + _i * 8192), 16, 0, 0); } while (0)
; #define PG8_LDA(dst, b, h) do { _Pragma("unroll") for (int m = 0; m < 4; ++m) _Pragma("unroll") for (int k = 0; k < 2; ++k) dst[m][k] = *(const PG8_LAS bf16x8*)(lds + PG8_SA(b, h) + aoff + m * 2048 + k * 1024); } while (0)
; #define PG8_LDB(dst, b, h) do { _Pragma("unroll") for (int n = 0; n < 2; ++n) _Pragma("unroll") for (int k = 0; k < 2; ++k) dst[n][k] = *(const PG8_LAS bf16x8*)(lds + PG8_SB(b, h) + boff + n * 2048 + k * 1024); } while (0)
; #define PG8_MMA(ai, bj, At, Bt) do { __builtin_amdgcn_s_setprio(1); _Pragma("unroll") for (int m = 0; m < 4; ++m) _Pragma("unroll") for (int n = 0; n < 2; ++n) _Pragma("unroll") for (int k = 0; k < 2; ++k) \
;         acc[ai][bj][m][n] = __builtin_amdgcn_mfma_f32_16x16x32_bf16(Bt[n][k], At[m][k], acc[ai][bj][m][n], 0, 0, 0); __builtin_amdgcn_s_setprio(0); } while (0)
; #define PG8_WAIT_V(n) asm volatile("s_waitcnt vmcnt(" #n ")" ::: "memory")
; #define PG8_BAR __builtin_amdgcn_s_barrier()
; template <class Epi, class Sched, bool ALIGN_EPI = false, bool SP2 = false>
; __device__ __forceinline__ void gemm_phase(PG8_LAS unsigned char* lds, const Gemm g, const Sched& S, const Epi& E) {
;     ...
;         for (int t = 0; t < nt; t += 2) {
;             const bool last = (t == nt - 2);
;             const char* a1 = cA + (size_t)(t + 1) * kstep;
;             const char* a2 = last ? nA : cA + (size_t)(t + 2) * kstep; const char* b2 = last ? nB : cB + (size_t)(t + 2) * kstep;
;             const char* a3 = a2 + kstep; const char* b3 = b2 + kstep;
;             if (last && has_next) S.a_ready(nxt);
;             if constexpr (SP2) {
;             PG8_LDB(B0, 0, 0); PG8_LDB(B1, 0, 1); PG8_SCHED; PG8_LDA(At, 0, 0); PG8_STAGE(PG8_SA(1, 1), a1 + hstep, voffA);
;             PG8_WAIT_V(8); PG8_WAIT_L(0); PG8_BAR; PG8_MMA(0, 0, At, B0); PG8_MMA(0, 1, At, B1); PG8_BAR; PG8_SCHED;
;     ...
;             PG8_LDA(At, 1, 1); PG8_STAGE(PG8_SB(1, 0), b3, voffB); PG8_STAGE(PG8_SB(1, 1), b3 + hstep, voffB); PG8_STAGE(PG8_SA(1, 0), a3, voffA);
;             PG8_WAIT_V(8); PG8_WAIT_L(0); PG8_BAR; PG8_MMA(1, 0, At, B0); PG8_MMA(1, 1, At, B1); PG8_BAR; PG8_SCHED;
	s_add_i32 s50, s72, s53
	s_add_u32 s86, s48, 0x80
	s_addc_u32 s87, s49, 0
	s_mov_b32 m0, s50
	ds_read_b128 v[184:187], v171 offset:49152
	ds_read_b128 v[188:191], v171 offset:50176
	ds_read_b128 v[192:195], v171 offset:51200
	ds_read_b128 v[196:199], v171 offset:52224
	ds_read_b128 v[200:203], v171 offset:53248
	ds_read_b128 v[204:207], v171 offset:54272
	ds_read_b128 v[208:211], v171 offset:55296
	ds_read_b128 v[214:217], v171 offset:56320
	global_load_lds_dwordx4 v146, s[86:87]
	s_add_i32 m0, s50, 0x2000
	s_add_u32 s48, s48, 0x80080
	s_addc_u32 s49, s49, 0
	s_add_i32 s50, s73, s53
	global_load_lds_dwordx4 v150, s[86:87]
	s_mov_b32 m0, s50
	s_nop 0
	global_load_lds_dwordx4 v146, s[48:49]
	s_add_i32 m0, s50, 0x2000
	s_nop 0
	global_load_lds_dwordx4 v150, s[48:49]
	s_mov_b32 m0, s60
	s_nop 0
	global_load_lds_dwordx4 v144, s[84:85]
	s_mov_b32 m0, s61
	s_nop 0
	global_load_lds_dwordx4 v148, s[84:85]
	s_waitcnt vmcnt(8) lgkmcnt(0)
	s_barrier
	v_mfma_f32_16x16x32_bf16 v[60:63], v[128:131], v[184:187], v[60:63]
	v_mfma_f32_16x16x32_bf16 v[56:59], v[136:139], v[184:187], v[56:59]
	v_mfma_f32_16x16x32_bf16 v[52:55], v[128:131], v[192:195], v[52:55]
	v_mfma_f32_16x16x32_bf16 v[48:51], v[136:139], v[192:195], v[48:51]
	v_mfma_f32_16x16x32_bf16 v[44:47], v[128:131], v[200:203], v[44:47]
	v_mfma_f32_16x16x32_bf16 v[32:35], v[136:139], v[200:203], v[32:35]
	v_mfma_f32_16x16x32_bf16 v[20:23], v[128:131], v[208:211], v[20:23]
	v_mfma_f32_16x16x32_bf16 v[8:11], v[136:139], v[208:211], v[8:11]
	v_mfma_f32_16x16x32_bf16 v[60:63], v[132:135], v[188:191], v[60:63]
	v_mfma_f32_16x16x32_bf16 v[56:59], v[140:143], v[188:191], v[56:59]
	v_mfma_f32_16x16x32_bf16 v[52:55], v[132:135], v[196:199], v[52:55]
	v_mfma_f32_16x16x32_bf16 v[48:51], v[140:143], v[196:199], v[48:51]
	v_mfma_f32_16x16x32_bf16 v[44:47], v[132:135], v[204:207], v[44:47]
	v_mfma_f32_16x16x32_bf16 v[32:35], v[140:143], v[204:207], v[32:35]
	v_mfma_f32_16x16x32_bf16 v[20:23], v[132:135], v[214:217], v[20:23]
	v_mfma_f32_16x16x32_bf16 v[8:11], v[140:143], v[214:217], v[8:11]
	v_mfma_f32_16x16x32_bf16 v[40:43], v[160:163], v[184:187], v[40:43]
	v_mfma_f32_16x16x32_bf16 v[36:39], v[176:179], v[184:187], v[36:39]
	v_mfma_f32_16x16x32_bf16 v[28:31], v[160:163], v[192:195], v[28:31]
	v_mfma_f32_16x16x32_bf16 v[24:27], v[176:179], v[192:195], v[24:27]
	v_mfma_f32_16x16x32_bf16 v[16:19], v[160:163], v[200:203], v[16:19]
	v_mfma_f32_16x16x32_bf16 v[12:15], v[176:179], v[200:203], v[12:15]
	v_mfma_f32_16x16x32_bf16 v[4:7], v[160:163], v[208:211], v[4:7]
	v_mfma_f32_16x16x32_bf16 v[0:3], v[176:179], v[208:211], v[0:3]
	v_mfma_f32_16x16x32_bf16 v[40:43], v[172:175], v[188:191], v[40:43]
	v_mfma_f32_16x16x32_bf16 v[36:39], v[180:183], v[188:191], v[36:39]
	v_mfma_f32_16x16x32_bf16 v[28:31], v[172:175], v[196:199], v[28:31]
	v_mfma_f32_16x16x32_bf16 v[24:27], v[180:183], v[196:199], v[24:27]
	v_mfma_f32_16x16x32_bf16 v[16:19], v[172:175], v[204:207], v[16:19]
	v_mfma_f32_16x16x32_bf16 v[12:15], v[180:183], v[204:207], v[12:15]
	v_mfma_f32_16x16x32_bf16 v[4:7], v[172:175], v[214:217], v[4:7]
	v_mfma_f32_16x16x32_bf16 v[0:3], v[180:183], v[214:217], v[0:3]
	s_barrier
	s_add_i32 s71, s71, 2
	s_add_u32 s46, s46, 0x100
	s_addc_u32 s47, s47, 0
	s_add_u32 s69, s69, 0x100
	s_addc_u32 s70, s70, 0
	s_cmp_gt_u32 s71, 29
.LBB0_827:
	ds_read_b128 v[128:131], v169
	ds_read_b128 v[132:135], v169 offset:1024
	ds_read_b128 v[136:139], v169 offset:2048
	ds_read_b128 v[140:143], v169 offset:3072
	ds_read_b128 v[160:163], v170
	ds_read_b128 v[172:175], v170 offset:1024
	ds_read_b128 v[176:179], v170 offset:2048
	ds_read_b128 v[180:183], v170 offset:3072
	s_add_u32 s48, s46, 0xfff80080
	s_addc_u32 s49, s47, -1
	s_cmp_eq_u32 s71, 28
	s_cselect_b32 s51, s39, s49
	s_cselect_b32 s50, s67, s48
	s_cselect_b32 s49, s37, s70
	s_cselect_b32 s48, s68, s69
	s_add_i32 m0, s45, 0xc000
	ds_read_b128 v[184:187], v171
	ds_read_b128 v[188:191], v171 offset:1024
	ds_read_b128 v[192:195], v171 offset:2048
	ds_read_b128 v[196:199], v171 offset:3072
	ds_read_b128 v[200:203], v171 offset:4096
	ds_read_b128 v[204:207], v171 offset:5120
	ds_read_b128 v[208:211], v171 offset:6144
	ds_read_b128 v[214:217], v171 offset:7168
	global_load_lds_dwordx4 v152, s[46:47]
	s_add_i32 m0, s45, 0xe000
	s_nop 0
	global_load_lds_dwordx4 v154, s[46:47]
	s_waitcnt vmcnt(8) lgkmcnt(0)
	s_barrier
	v_mfma_f32_16x16x32_bf16 v[124:127], v[128:131], v[184:187], v[124:127]
	v_mfma_f32_16x16x32_bf16 v[120:123], v[136:139], v[184:187], v[120:123]
	v_mfma_f32_16x16x32_bf16 v[116:119], v[128:131], v[192:195], v[116:119]
	v_mfma_f32_16x16x32_bf16 v[112:115], v[136:139], v[192:195], v[112:115]
	v_mfma_f32_16x16x32_bf16 v[108:111], v[128:131], v[200:203], v[108:111]
	v_mfma_f32_16x16x32_bf16 v[96:99], v[136:139], v[200:203], v[96:99]
	v_mfma_f32_16x16x32_bf16 v[80:83], v[128:131], v[208:211], v[80:83]
	v_mfma_f32_16x16x32_bf16 v[72:75], v[136:139], v[208:211], v[72:75]
	v_mfma_f32_16x16x32_bf16 v[124:127], v[132:135], v[188:191], v[124:127]
	v_mfma_f32_16x16x32_bf16 v[120:123], v[140:143], v[188:191], v[120:123]
	v_mfma_f32_16x16x32_bf16 v[116:119], v[132:135], v[196:199], v[116:119]
	v_mfma_f32_16x16x32_bf16 v[112:115], v[140:143], v[196:199], v[112:115]
	v_mfma_f32_16x16x32_bf16 v[108:111], v[132:135], v[204:207], v[108:111]
	v_mfma_f32_16x16x32_bf16 v[96:99], v[140:143], v[204:207], v[96:99]
	v_mfma_f32_16x16x32_bf16 v[80:83], v[132:135], v[214:217], v[80:83]
	v_mfma_f32_16x16x32_bf16 v[72:75], v[140:143], v[214:217], v[72:75]
	v_mfma_f32_16x16x32_bf16 v[104:107], v[160:163], v[184:187], v[104:107]
	v_mfma_f32_16x16x32_bf16 v[100:103], v[176:179], v[184:187], v[100:103]
	v_mfma_f32_16x16x32_bf16 v[92:95], v[160:163], v[192:195], v[92:95]
	v_mfma_f32_16x16x32_bf16 v[88:91], v[176:179], v[192:195], v[88:91]
	v_mfma_f32_16x16x32_bf16 v[84:87], v[160:163], v[200:203], v[84:87]
	v_mfma_f32_16x16x32_bf16 v[76:79], v[176:179], v[200:203], v[76:79]
	v_mfma_f32_16x16x32_bf16 v[68:71], v[160:163], v[208:211], v[68:71]
	v_mfma_f32_16x16x32_bf16 v[64:67], v[176:179], v[208:211], v[64:67]
	v_mfma_f32_16x16x32_bf16 v[104:107], v[172:175], v[188:191], v[104:107]
	v_mfma_f32_16x16x32_bf16 v[100:103], v[180:183], v[188:191], v[100:103]
	v_mfma_f32_16x16x32_bf16 v[92:95], v[172:175], v[196:199], v[92:95]
	v_mfma_f32_16x16x32_bf16 v[88:91], v[180:183], v[196:199], v[88:91]
	v_mfma_f32_16x16x32_bf16 v[84:87], v[172:175], v[204:207], v[84:87]
	v_mfma_f32_16x16x32_bf16 v[76:79], v[180:183], v[204:207], v[76:79]
	v_mfma_f32_16x16x32_bf16 v[68:71], v[172:175], v[214:217], v[68:71]
	v_mfma_f32_16x16x32_bf16 v[64:67], v[180:183], v[214:217], v[64:67]
	s_barrier
; #define PG8_STAGE(bufoff, gbase, voff) do { _Pragma("unroll") for (int _i = 0; _i < 2; ++_i) \
;         __builtin_amdgcn_global_load_lds((const unsigned*)((const char*)(gbase) + (voff)[_i]), (PG8_LAS unsigned*)(lds + (bufoff) + ldsw + _i * 8192), 16, 0, 0); } while (0)
; #define PG8_LDA(dst, b, h) do { _Pragma("unroll") for (int m = 0; m < 4; ++m) _Pragma("unroll") for (int k = 0; k < 2; ++k) dst[m][k] = *(const PG8_LAS bf16x8*)(lds + PG8_SA(b, h) + aoff + m * 2048 + k * 1024); } while (0)
; #define PG8_LDB(dst, b, h) do { _Pragma("unroll") for (int n = 0; n < 2; ++n) _Pragma("unroll") for (int k = 0; k < 2; ++k) dst[n][k] = *(const PG8_LAS bf16x8*)(lds + PG8_SB(b, h) + boff + n * 2048 + k * 1024); } while (0)
; #define PG8_MMA(ai, bj, At, Bt) do { __builtin_amdgcn_s_setprio(1); _Pragma("unroll") for (int m = 0; m < 4; ++m) _Pragma("unroll") for (int n = 0; n < 2; ++n) _Pragma("unroll") for (int k = 0; k < 2; ++k) \
;         acc[ai][bj][m][n] = __builtin_amdgcn_mfma_f32_16x16x32_bf16(Bt[n][k], At[m][k], acc[ai][bj][m][n], 0, 0, 0); __builtin_amdgcn_s_setprio(0); } while (0)
; #define PG8_WAIT_V(n) asm volatile("s_waitcnt vmcnt(" #n ")" ::: "memory")
; #define PG8_WAIT_L(n) asm volatile("s_waitcnt lgkmcnt(" #n ")" ::: "memory")
; #define PG8_BAR __builtin_amdgcn_s_barrier()
; #define PG8_SCHED __builtin_amdgcn_sched_barrier(0)
; template <class Epi, class Sched, bool ALIGN_EPI = false, bool SP2 = false>
; __device__ __forceinline__ void gemm_phase(PG8_LAS unsigned char* lds, const Gemm g, const Sched& S, const Epi& E) {
;     ...
;             PG8_LDA(At, 0, 1); PG8_STAGE(PG8_SB(0, 0), b2, voffB); PG8_STAGE(PG8_SB(0, 1), b2 + hstep, voffB); PG8_STAGE(PG8_SA(0, 0), a2, voffA);
;             PG8_WAIT_V(8); PG8_WAIT_L(0); PG8_BAR; PG8_MMA(1, 0, At, B0); PG8_MMA(1, 1, At, B1); PG8_BAR; PG8_SCHED;
;             PG8_LDB(B0, 1, 0); PG8_LDB(B1, 1, 1); PG8_SCHED; PG8_LDA(At, 1, 0); PG8_STAGE(PG8_SA(0, 1), a2 + hstep, voffA);
;             PG8_WAIT_V(8); PG8_WAIT_L(0); PG8_BAR; PG8_MMA(0, 0, At, B0); PG8_MMA(0, 1, At, B1); PG8_BAR; PG8_SCHED;
	s_add_i32 s72, s64, s53
	s_mov_b32 m0, s72
	ds_read_b128 v[184:187], v171 offset:16384
	ds_read_b128 v[188:191], v171 offset:17408
	ds_read_b128 v[192:195], v171 offset:18432
	ds_read_b128 v[196:199], v171 offset:19456
	ds_read_b128 v[200:203], v171 offset:20480
	ds_read_b128 v[204:207], v171 offset:21504
	ds_read_b128 v[208:211], v171 offset:22528
	ds_read_b128 v[214:217], v171 offset:23552
	global_load_lds_dwordx4 v146, s[48:49]
	s_add_i32 m0, s72, 0x2000
	s_add_u32 s72, s48, 0x80000
	s_addc_u32 s73, s49, 0
	s_add_i32 s74, s65, s53
	global_load_lds_dwordx4 v150, s[48:49]
	s_mov_b32 m0, s74
	s_nop 0
	global_load_lds_dwordx4 v146, s[72:73]
	s_add_i32 m0, s74, 0x2000
	s_nop 0
	global_load_lds_dwordx4 v150, s[72:73]
	s_mov_b32 m0, s45
	s_nop 0
	global_load_lds_dwordx4 v144, s[50:51]
	s_mov_b32 m0, s54
	s_nop 0
	global_load_lds_dwordx4 v148, s[50:51]
	s_waitcnt vmcnt(8) lgkmcnt(0)
	s_barrier
	v_mfma_f32_16x16x32_bf16 v[60:63], v[128:131], v[184:187], v[60:63]
	v_mfma_f32_16x16x32_bf16 v[56:59], v[136:139], v[184:187], v[56:59]
	v_mfma_f32_16x16x32_bf16 v[52:55], v[128:131], v[192:195], v[52:55]
	v_mfma_f32_16x16x32_bf16 v[48:51], v[136:139], v[192:195], v[48:51]
	v_mfma_f32_16x16x32_bf16 v[44:47], v[128:131], v[200:203], v[44:47]
	v_mfma_f32_16x16x32_bf16 v[32:35], v[136:139], v[200:203], v[32:35]
	v_mfma_f32_16x16x32_bf16 v[20:23], v[128:131], v[208:211], v[20:23]
	v_mfma_f32_16x16x32_bf16 v[8:11], v[136:139], v[208:211], v[8:11]
	v_mfma_f32_16x16x32_bf16 v[60:63], v[132:135], v[188:191], v[60:63]
	v_mfma_f32_16x16x32_bf16 v[56:59], v[140:143], v[188:191], v[56:59]
	v_mfma_f32_16x16x32_bf16 v[52:55], v[132:135], v[196:199], v[52:55]
	v_mfma_f32_16x16x32_bf16 v[48:51], v[140:143], v[196:199], v[48:51]
	v_mfma_f32_16x16x32_bf16 v[44:47], v[132:135], v[204:207], v[44:47]
	v_mfma_f32_16x16x32_bf16 v[32:35], v[140:143], v[204:207], v[32:35]
	v_mfma_f32_16x16x32_bf16 v[20:23], v[132:135], v[214:217], v[20:23]
	v_mfma_f32_16x16x32_bf16 v[8:11], v[140:143], v[214:217], v[8:11]
	v_mfma_f32_16x16x32_bf16 v[40:43], v[160:163], v[184:187], v[40:43]
	v_mfma_f32_16x16x32_bf16 v[36:39], v[176:179], v[184:187], v[36:39]
	v_mfma_f32_16x16x32_bf16 v[28:31], v[160:163], v[192:195], v[28:31]
	v_mfma_f32_16x16x32_bf16 v[24:27], v[176:179], v[192:195], v[24:27]
	v_mfma_f32_16x16x32_bf16 v[16:19], v[160:163], v[200:203], v[16:19]
	v_mfma_f32_16x16x32_bf16 v[12:15], v[176:179], v[200:203], v[12:15]
	v_mfma_f32_16x16x32_bf16 v[4:7], v[160:163], v[208:211], v[4:7]
	v_mfma_f32_16x16x32_bf16 v[0:3], v[176:179], v[208:211], v[0:3]
	v_mfma_f32_16x16x32_bf16 v[40:43], v[172:175], v[188:191], v[40:43]
	v_mfma_f32_16x16x32_bf16 v[36:39], v[180:183], v[188:191], v[36:39]
	v_mfma_f32_16x16x32_bf16 v[28:31], v[172:175], v[196:199], v[28:31]
	v_mfma_f32_16x16x32_bf16 v[24:27], v[180:183], v[196:199], v[24:27]
	v_mfma_f32_16x16x32_bf16 v[16:19], v[172:175], v[204:207], v[16:19]
	v_mfma_f32_16x16x32_bf16 v[12:15], v[180:183], v[204:207], v[12:15]
	v_mfma_f32_16x16x32_bf16 v[4:7], v[172:175], v[214:217], v[4:7]
	v_mfma_f32_16x16x32_bf16 v[0:3], v[180:183], v[214:217], v[0:3]
	s_barrier
	s_add_i32 s72, 0, 0x18000
	s_add_i32 s73, 0, 0x1c000
	ds_read_b128 v[128:131], v164
	ds_read_b128 v[132:135], v164 offset:1024
	ds_read_b128 v[136:139], v164 offset:2048
	ds_read_b128 v[140:143], v164 offset:3072
	ds_read_b128 v[160:163], v165
	ds_read_b128 v[172:175], v165 offset:1024
	ds_read_b128 v[176:179], v165 offset:2048
	ds_read_b128 v[180:183], v165 offset:3072
	s_add_u32 s84, s50, 0x80
	s_addc_u32 s85, s51, 0
	s_add_u32 s50, s50, 0x80000
	s_addc_u32 s51, s51, 0
	s_mov_b32 m0, s55
	ds_read_b128 v[184:187], v171 offset:32768
	ds_read_b128 v[188:191], v171 offset:33792
	ds_read_b128 v[192:195], v171 offset:34816
	ds_read_b128 v[196:199], v171 offset:35840
	ds_read_b128 v[200:203], v171 offset:36864
	ds_read_b128 v[204:207], v171 offset:37888
	ds_read_b128 v[208:211], v171 offset:38912
	ds_read_b128 v[214:217], v171 offset:39936
	global_load_lds_dwordx4 v144, s[50:51]
	s_mov_b32 m0, s56
	s_nop 0
	global_load_lds_dwordx4 v148, s[50:51]
	s_waitcnt vmcnt(8) lgkmcnt(0)
	s_barrier
	v_mfma_f32_16x16x32_bf16 v[124:127], v[128:131], v[184:187], v[124:127]
	v_mfma_f32_16x16x32_bf16 v[120:123], v[136:139], v[184:187], v[120:123]
	v_mfma_f32_16x16x32_bf16 v[116:119], v[128:131], v[192:195], v[116:119]
	v_mfma_f32_16x16x32_bf16 v[112:115], v[136:139], v[192:195], v[112:115]
	v_mfma_f32_16x16x32_bf16 v[108:111], v[128:131], v[200:203], v[108:111]
	v_mfma_f32_16x16x32_bf16 v[96:99], v[136:139], v[200:203], v[96:99]
	v_mfma_f32_16x16x32_bf16 v[80:83], v[128:131], v[208:211], v[80:83]
	v_mfma_f32_16x16x32_bf16 v[72:75], v[136:139], v[208:211], v[72:75]
	v_mfma_f32_16x16x32_bf16 v[124:127], v[132:135], v[188:191], v[124:127]
	v_mfma_f32_16x16x32_bf16 v[120:123], v[140:143], v[188:191], v[120:123]
	v_mfma_f32_16x16x32_bf16 v[116:119], v[132:135], v[196:199], v[116:119]
	v_mfma_f32_16x16x32_bf16 v[112:115], v[140:143], v[196:199], v[112:115]
	v_mfma_f32_16x16x32_bf16 v[108:111], v[132:135], v[204:207], v[108:111]
	v_mfma_f32_16x16x32_bf16 v[96:99], v[140:143], v[204:207], v[96:99]
	v_mfma_f32_16x16x32_bf16 v[80:83], v[132:135], v[214:217], v[80:83]
	v_mfma_f32_16x16x32_bf16 v[72:75], v[140:143], v[214:217], v[72:75]
	v_mfma_f32_16x16x32_bf16 v[104:107], v[160:163], v[184:187], v[104:107]
	v_mfma_f32_16x16x32_bf16 v[100:103], v[176:179], v[184:187], v[100:103]
	v_mfma_f32_16x16x32_bf16 v[92:95], v[160:163], v[192:195], v[92:95]
	v_mfma_f32_16x16x32_bf16 v[88:91], v[176:179], v[192:195], v[88:91]
	v_mfma_f32_16x16x32_bf16 v[84:87], v[160:163], v[200:203], v[84:87]
	v_mfma_f32_16x16x32_bf16 v[76:79], v[176:179], v[200:203], v[76:79]
	v_mfma_f32_16x16x32_bf16 v[68:71], v[160:163], v[208:211], v[68:71]
	v_mfma_f32_16x16x32_bf16 v[64:67], v[176:179], v[208:211], v[64:67]
	v_mfma_f32_16x16x32_bf16 v[104:107], v[172:175], v[188:191], v[104:107]
	v_mfma_f32_16x16x32_bf16 v[100:103], v[180:183], v[188:191], v[100:103]
	v_mfma_f32_16x16x32_bf16 v[92:95], v[172:175], v[196:199], v[92:95]
	v_mfma_f32_16x16x32_bf16 v[88:91], v[180:183], v[196:199], v[88:91]
	v_mfma_f32_16x16x32_bf16 v[84:87], v[172:175], v[204:207], v[84:87]
	v_mfma_f32_16x16x32_bf16 v[76:79], v[180:183], v[204:207], v[76:79]
	v_mfma_f32_16x16x32_bf16 v[68:71], v[172:175], v[214:217], v[68:71]
	v_mfma_f32_16x16x32_bf16 v[64:67], v[180:183], v[214:217], v[64:67]
	s_barrier
; #define PG8_STAGE(bufoff, gbase, voff) do { _Pragma("unroll") for (int _i = 0; _i < 2; ++_i) \
;         __builtin_amdgcn_global_load_lds((const unsigned*)((const char*)(gbase) + (voff)[_i]), (PG8_LAS unsigned*)(lds + (bufoff) + ldsw + _i * 8192), 16, 0, 0); } while (0)
; #define PG8_LDA(dst, b, h) do { _Pragma("unroll") for (int m = 0; m < 4; ++m) _Pragma("unroll") for (int k = 0; k < 2; ++k) dst[m][k] = *(const PG8_LAS bf16x8*)(lds + PG8_SA(b, h) + aoff + m * 2048 + k * 1024); } while (0)
;     __device__ __forceinline__ void operator()(const f32x4 (&acc)[2][2][4][2], const Unit& u, int wr, int wc, int fr, int fq) const {
;         const int row0 = u.pm * BM + wr * 64 + fr, col0 = u.pn * BM + wc * 32 + 8 * fq;
;         const float* gp = gate + (u.pm >> 5) * 18432 + col0;
;         f32x4 gv[2][2];
; #pragma unroll
;         for (int bj = 0; bj < 2; ++bj)
; #pragma unroll
;             for (int n = 0; n < 2; ++n) gv[bj][n] = *(const f32x4*)(gp + bj * HALF + 4 * n) * scale;
; #pragma unroll
;         for (int ai = 0; ai < 2; ++ai) { f32x4 r[4][2][2];
; #pragma unroll
;             for (int m = 0; m < 4; ++m) { const size_t off = (size_t)(row0 + ai * HALF + m * 16) * 2048 + col0;
; #pragma unroll
;                 for (int bj = 0; bj < 2; ++bj)
; #pragma unroll
;                     for (int n = 0; n < 2; ++n) r[m][bj][n] = *(const f32x4*)(res + off + bj * HALF + 4 * n); }
; template <class Epi, class Sched, bool ALIGN_EPI = false, bool SP2 = false>
; __device__ __forceinline__ void gemm_phase(PG8_LAS unsigned char* lds, const Gemm g, const Sched& S, const Epi& E) {
;     ...
;             PG8_LDA(At, 1, 1); PG8_STAGE(PG8_SB(1, 0), b3, voffB); PG8_STAGE(PG8_SB(1, 1), b3 + hstep, voffB); PG8_STAGE(PG8_SA(1, 0), a3, voffA);
;             PG8_WAIT_V(8); PG8_WAIT_L(0); PG8_BAR; PG8_MMA(1, 0, At, B0); PG8_MMA(1, 1, At, B1); PG8_BAR; PG8_SCHED;
;     ...
;         if constexpr (ALIGN_EPI) { if (wr == 0) PG8_BAR; }
;         if constexpr (!Epi::AFTER_DRAIN) { E(acc, cur, wr, wc, fr, fq); S.done(cur); }
;         if (!has_next) break;
; #pragma unroll
;         for (int a = 0; a < 2; ++a)
; #pragma unroll
;             for (int b = 0; b < 2; ++b)
; #pragma unroll
;                 for (int m = 0; m < 4; ++m)
; #pragma unroll
;                     for (int n = 0; n < 2; ++n) acc[a][b][m][n] = (f32x4){0.f, 0.f, 0.f, 0.f};
;         cur = nxt; cA = nA; cB = nB; ++ui;
	s_add_i32 s50, s72, s53
	s_add_u32 s86, s48, 0x80
	s_addc_u32 s87, s49, 0
	s_mov_b32 m0, s50
	ds_read_b128 v[184:187], v171 offset:49152
	ds_read_b128 v[188:191], v171 offset:50176
	ds_read_b128 v[192:195], v171 offset:51200
	ds_read_b128 v[196:199], v171 offset:52224
	ds_read_b128 v[200:203], v171 offset:53248
	ds_read_b128 v[204:207], v171 offset:54272
	ds_read_b128 v[208:211], v171 offset:55296
	ds_read_b128 v[214:217], v171 offset:56320
	global_load_lds_dwordx4 v146, s[86:87]
	s_add_i32 m0, s50, 0x2000
	s_add_u32 s48, s48, 0x80080
	s_addc_u32 s49, s49, 0
	s_add_i32 s50, s73, s53
	global_load_lds_dwordx4 v150, s[86:87]
	s_mov_b32 m0, s50
	s_nop 0
	global_load_lds_dwordx4 v146, s[48:49]
	s_add_i32 m0, s50, 0x2000
	s_nop 0
	global_load_lds_dwordx4 v150, s[48:49]
	s_mov_b32 m0, s60
	s_nop 0
	global_load_lds_dwordx4 v144, s[84:85]
	s_mov_b32 m0, s61
	s_nop 0
	global_load_lds_dwordx4 v148, s[84:85]
	s_waitcnt vmcnt(8) lgkmcnt(0)
	s_barrier
	v_mfma_f32_16x16x32_bf16 v[60:63], v[128:131], v[184:187], v[60:63]
	v_mfma_f32_16x16x32_bf16 v[56:59], v[136:139], v[184:187], v[56:59]
	v_mfma_f32_16x16x32_bf16 v[52:55], v[128:131], v[192:195], v[52:55]
	v_mfma_f32_16x16x32_bf16 v[48:51], v[136:139], v[192:195], v[48:51]
	v_mfma_f32_16x16x32_bf16 v[44:47], v[128:131], v[200:203], v[44:47]
	v_mfma_f32_16x16x32_bf16 v[32:35], v[136:139], v[200:203], v[32:35]
	v_mfma_f32_16x16x32_bf16 v[20:23], v[128:131], v[208:211], v[20:23]
	v_mfma_f32_16x16x32_bf16 v[8:11], v[136:139], v[208:211], v[8:11]
	v_mfma_f32_16x16x32_bf16 v[60:63], v[132:135], v[188:191], v[60:63]
	v_mfma_f32_16x16x32_bf16 v[56:59], v[140:143], v[188:191], v[56:59]
	v_mfma_f32_16x16x32_bf16 v[52:55], v[132:135], v[196:199], v[52:55]
	v_mfma_f32_16x16x32_bf16 v[48:51], v[140:143], v[196:199], v[48:51]
	v_mfma_f32_16x16x32_bf16 v[44:47], v[132:135], v[204:207], v[44:47]
	v_mfma_f32_16x16x32_bf16 v[32:35], v[140:143], v[204:207], v[32:35]
	v_mfma_f32_16x16x32_bf16 v[20:23], v[132:135], v[214:217], v[20:23]
	v_mfma_f32_16x16x32_bf16 v[8:11], v[140:143], v[214:217], v[8:11]
	v_mfma_f32_16x16x32_bf16 v[40:43], v[160:163], v[184:187], v[40:43]
	v_mfma_f32_16x16x32_bf16 v[36:39], v[176:179], v[184:187], v[36:39]
	v_mfma_f32_16x16x32_bf16 v[28:31], v[160:163], v[192:195], v[28:31]
	v_mfma_f32_16x16x32_bf16 v[24:27], v[176:179], v[192:195], v[24:27]
	v_mfma_f32_16x16x32_bf16 v[16:19], v[160:163], v[200:203], v[16:19]
	v_mfma_f32_16x16x32_bf16 v[12:15], v[176:179], v[200:203], v[12:15]
	v_mfma_f32_16x16x32_bf16 v[4:7], v[160:163], v[208:211], v[4:7]
	v_mfma_f32_16x16x32_bf16 v[0:3], v[176:179], v[208:211], v[0:3]
	v_mfma_f32_16x16x32_bf16 v[40:43], v[172:175], v[188:191], v[40:43]
	v_mfma_f32_16x16x32_bf16 v[36:39], v[180:183], v[188:191], v[36:39]
	v_mfma_f32_16x16x32_bf16 v[28:31], v[172:175], v[196:199], v[28:31]
	v_mfma_f32_16x16x32_bf16 v[24:27], v[180:183], v[196:199], v[24:27]
	v_mfma_f32_16x16x32_bf16 v[16:19], v[172:175], v[204:207], v[16:19]
	v_mfma_f32_16x16x32_bf16 v[12:15], v[180:183], v[204:207], v[12:15]
	v_mfma_f32_16x16x32_bf16 v[4:7], v[172:175], v[214:217], v[4:7]
	v_mfma_f32_16x16x32_bf16 v[0:3], v[180:183], v[214:217], v[0:3]
	s_barrier
	s_add_i32 s71, s71, 2
	s_add_u32 s46, s46, 0x100
	s_addc_u32 s47, s47, 0
	s_add_u32 s69, s69, 0x100
	s_addc_u32 s70, s70, 0
	s_cmp_gt_u32 s71, 29
	s_cbranch_scc0 .LBB0_827
	s_lshr_b32 s37, s44, 5
	s_mul_i32 s46, s37, 0x4800
	v_lshl_or_b32 v128, s66, 8, v168
	s_ashr_i32 s47, s46, 31
	v_lshl_add_u32 v212, s44, 8, v166
	s_lshl_b64 s[46:47], s[46:47], 2
	v_ashrrev_i32_e32 v129, 31, v128
	v_or_b32_e32 v188, 16, v212
	v_or_b32_e32 v204, 32, v212
	s_add_u32 s46, s58, s46
	v_lshlrev_b64 v[160:161], 2, v[128:129]
	v_ashrrev_i32_e32 v213, 31, v212
	v_ashrrev_i32_e32 v189, 31, v188
	v_ashrrev_i32_e32 v205, 31, v204
	s_addc_u32 s47, s59, s47
	v_lshl_add_u64 v[162:163], s[12:13], 0, v[160:161]
	v_lshlrev_b64 v[164:165], 13, v[212:213]
	v_lshlrev_b64 v[218:219], 13, v[188:189]
	v_lshlrev_b64 v[230:231], 13, v[204:205]
	v_or_b32_e32 v212, 48, v212
	v_lshl_add_u64 v[136:137], s[46:47], 0, v[160:161]
	v_lshl_add_u64 v[184:185], v[162:163], 0, v[164:165]
	v_lshl_add_u64 v[200:201], v[162:163], 0, v[218:219]
	v_lshl_add_u64 v[222:223], v[162:163], 0, v[230:231]
	v_ashrrev_i32_e32 v213, 31, v212
	global_load_dwordx4 v[132:135], v[136:137], off offset:16
	global_load_dwordx4 v[140:143], v[136:137], off
	global_load_dwordx4 v[172:175], v[184:185], off offset:16
	global_load_dwordx4 v[176:179], v[184:185], off
	global_load_dwordx4 v[128:131], v[136:137], off offset:528
	s_nop 0
	global_load_dwordx4 v[136:139], v[136:137], off offset:512
	s_nop 0
	global_load_dwordx4 v[180:183], v[184:185], off offset:528
	s_nop 0
	global_load_dwordx4 v[184:187], v[184:185], off offset:512
	s_nop 0
	global_load_dwordx4 v[188:191], v[200:201], off
	global_load_dwordx4 v[192:195], v[200:201], off offset:16
	global_load_dwordx4 v[196:199], v[200:201], off offset:528
	s_nop 0
	global_load_dwordx4 v[200:203], v[200:201], off offset:512
	s_nop 0
	global_load_dwordx4 v[204:207], v[222:223], off
	global_load_dwordx4 v[208:211], v[222:223], off offset:16
	global_load_dwordx4 v[214:217], v[222:223], off offset:512
	s_nop 0
	global_load_dwordx4 v[222:225], v[222:223], off offset:528
	v_lshlrev_b64 v[212:213], 13, v[212:213]
	v_lshl_add_u64 v[244:245], v[162:163], 0, v[212:213]
	global_load_dwordx4 v[232:235], v[244:245], off
	global_load_dwordx4 v[236:239], v[244:245], off offset:16
	global_load_dwordx4 v[240:243], v[244:245], off offset:512
	s_nop 0
	global_load_dwordx4 v[244:247], v[244:245], off offset:528
	v_lshl_add_u64 v[248:249], s[14:15], 0, v[164:165]
	v_lshl_add_u64 v[248:249], v[248:249], 0, v[160:161]
	v_lshl_add_u64 v[218:219], s[14:15], 0, v[218:219]
	v_lshl_add_u64 v[230:231], s[14:15], 0, v[230:231]
	v_lshl_add_u64 v[218:219], v[218:219], 0, v[160:161]
	v_lshl_add_u64 v[230:231], v[230:231], 0, v[160:161]
	s_and_b64 vcc, exec, s[10:11]
	s_mov_b32 s66, s36
	s_mov_b32 s44, s38
	s_mov_b64 s[48:49], s[42:43]
	s_mov_b64 s[46:47], s[40:41]
	s_waitcnt vmcnt(0)
;     __device__ __forceinline__ void operator()(const f32x4 (&acc)[2][2][4][2], const Unit& u, int wr, int wc, int fr, int fq) const {
;     ...
;             for (int m = 0; m < 4; ++m) { const size_t off = (size_t)(row0 + ai * HALF + m * 16) * 2048 + col0;
; #pragma unroll
;                 for (int bj = 0; bj < 2; ++bj)
; #pragma unroll
;                     for (int n = 0; n < 2; ++n) r[m][bj][n] = *(const f32x4*)(res + off + bj * HALF + 4 * n); }
;     ...
;             for (int m = 0; m < 4; ++m) { const size_t off = (size_t)(row0 + ai * HALF + m * 16) * 2048 + col0;
; #pragma unroll
;                 for (int bj = 0; bj < 2; ++bj)
; #pragma unroll
;                     for (int n = 0; n < 2; ++n) *(f32x4*)(out + off + bj * HALF + 4 * n) = r[m][bj][n] + gv[bj][n] * acc[ai][bj][m][n]; } }
	v_pk_fma_f32 v[122:123], v[122:123], v[134:135], v[174:175]
	v_pk_fma_f32 v[126:127], v[126:127], v[142:143], v[178:179]
	v_pk_fma_f32 v[124:125], v[124:125], v[140:141], v[176:177]
	v_pk_fma_f32 v[120:121], v[120:121], v[132:133], v[172:173]
	v_pk_fma_f32 v[76:77], v[76:77], v[128:129], v[222:223]
	v_pk_fma_f32 v[106:107], v[106:107], v[138:139], v[186:187]
	v_pk_fma_f32 v[104:105], v[104:105], v[136:137], v[184:185]
	v_pk_fma_f32 v[102:103], v[102:103], v[130:131], v[182:183]
	v_pk_fma_f32 v[100:101], v[100:101], v[128:129], v[180:181]
	v_pk_fma_f32 v[118:119], v[118:119], v[142:143], v[190:191]
	v_pk_fma_f32 v[116:117], v[116:117], v[140:141], v[188:189]
	v_pk_fma_f32 v[114:115], v[114:115], v[134:135], v[194:195]
	v_pk_fma_f32 v[112:113], v[112:113], v[132:133], v[192:193]
	v_pk_fma_f32 v[94:95], v[94:95], v[138:139], v[202:203]
	v_pk_fma_f32 v[92:93], v[92:93], v[136:137], v[200:201]
	v_pk_fma_f32 v[90:91], v[90:91], v[130:131], v[198:199]
	v_pk_fma_f32 v[88:89], v[88:89], v[128:129], v[196:197]
	v_pk_fma_f32 v[110:111], v[110:111], v[142:143], v[206:207]
	v_pk_fma_f32 v[108:109], v[108:109], v[140:141], v[204:205]
	v_pk_fma_f32 v[98:99], v[98:99], v[134:135], v[210:211]
	v_pk_fma_f32 v[96:97], v[96:97], v[132:133], v[208:209]
	v_pk_fma_f32 v[86:87], v[86:87], v[138:139], v[216:217]
	v_pk_fma_f32 v[84:85], v[84:85], v[136:137], v[214:215]
	v_pk_fma_f32 v[78:79], v[78:79], v[130:131], v[224:225]
	global_store_dwordx4 v[248:249], v[124:127], off
	global_store_dwordx4 v[248:249], v[120:123], off offset:16
	global_store_dwordx4 v[248:249], v[104:107], off offset:512
	global_store_dwordx4 v[248:249], v[100:103], off offset:528
	global_store_dwordx4 v[218:219], v[116:119], off
	global_store_dwordx4 v[218:219], v[112:115], off offset:16
	global_store_dwordx4 v[218:219], v[92:95], off offset:512
	global_store_dwordx4 v[218:219], v[88:91], off offset:528
	global_store_dwordx4 v[230:231], v[108:111], off
	global_store_dwordx4 v[230:231], v[96:99], off offset:16
	global_store_dwordx4 v[230:231], v[84:87], off offset:512
	global_store_dwordx4 v[230:231], v[76:79], off offset:528
	v_pk_fma_f32 v[74:75], v[74:75], v[134:135], v[238:239]
	v_pk_fma_f32 v[72:73], v[72:73], v[132:133], v[236:237]
	v_pk_fma_f32 v[76:77], v[80:81], v[140:141], v[232:233]
	v_lshl_add_u64 v[80:81], s[14:15], 0, v[212:213]
	v_pk_fma_f32 v[78:79], v[82:83], v[142:143], v[234:235]
	v_lshl_add_u64 v[80:81], v[80:81], 0, v[160:161]
	v_pk_fma_f32 v[70:71], v[70:71], v[138:139], v[242:243]
	v_pk_fma_f32 v[68:69], v[68:69], v[136:137], v[240:241]
	v_pk_fma_f32 v[66:67], v[66:67], v[130:131], v[246:247]
	v_pk_fma_f32 v[64:65], v[64:65], v[128:129], v[244:245]
	v_lshl_add_u64 v[172:173], v[164:165], 0, s[26:27]
	v_lshl_add_u64 v[174:175], v[164:165], 0, s[28:29]
	v_lshl_add_u64 v[176:177], v[164:165], 0, s[30:31]
	global_store_dwordx4 v[80:81], v[76:79], off
	global_store_dwordx4 v[80:81], v[72:75], off offset:16
	global_store_dwordx4 v[80:81], v[68:71], off offset:512
	global_store_dwordx4 v[80:81], v[64:67], off offset:528
	v_lshl_add_u64 v[76:77], v[162:163], 0, v[172:173]
	v_lshl_add_u64 v[92:93], v[162:163], 0, v[174:175]
	v_lshl_add_u64 v[108:109], v[162:163], 0, v[176:177]
	global_load_dwordx4 v[64:67], v[76:77], off
	global_load_dwordx4 v[68:71], v[76:77], off offset:16
	global_load_dwordx4 v[72:75], v[76:77], off offset:512
	s_nop 0
	global_load_dwordx4 v[76:79], v[76:77], off offset:528
	s_nop 0
	global_load_dwordx4 v[80:83], v[92:93], off
	global_load_dwordx4 v[84:87], v[92:93], off offset:16
	global_load_dwordx4 v[88:91], v[92:93], off offset:512
	s_nop 0
	global_load_dwordx4 v[92:95], v[92:93], off offset:528
	s_nop 0
	global_load_dwordx4 v[96:99], v[108:109], off
	global_load_dwordx4 v[100:103], v[108:109], off offset:16
	global_load_dwordx4 v[104:107], v[108:109], off offset:512
	s_nop 0
	global_load_dwordx4 v[108:111], v[108:109], off offset:528
	v_lshl_add_u64 v[164:165], v[164:165], 0, s[34:35]
	v_lshl_add_u64 v[124:125], v[162:163], 0, v[164:165]
	global_load_dwordx4 v[112:115], v[124:125], off
	global_load_dwordx4 v[116:119], v[124:125], off offset:16
	global_load_dwordx4 v[120:123], v[124:125], off offset:512
	s_nop 0
	global_load_dwordx4 v[124:127], v[124:125], off offset:528
	v_lshl_add_u64 v[162:163], s[14:15], 0, v[172:173]
	v_lshl_add_u64 v[172:173], s[14:15], 0, v[174:175]
	v_lshl_add_u64 v[174:175], s[14:15], 0, v[176:177]
	v_lshl_add_u64 v[162:163], v[162:163], 0, v[160:161]
	v_lshl_add_u64 v[172:173], v[172:173], 0, v[160:161]
	v_lshl_add_u64 v[174:175], v[174:175], 0, v[160:161]
	s_waitcnt vmcnt(15)
; #define PG8_WAIT_V(n) asm volatile("s_waitcnt vmcnt(" #n ")" ::: "memory")
; #define PG8_BAR __builtin_amdgcn_s_barrier()
;     __device__ __forceinline__ void operator()(const f32x4 (&acc)[2][2][4][2], const Unit& u, int wr, int wc, int fr, int fq) const {
;     ...
;             for (int m = 0; m < 4; ++m) { const size_t off = (size_t)(row0 + ai * HALF + m * 16) * 2048 + col0;
; #pragma unroll
;                 for (int bj = 0; bj < 2; ++bj)
; #pragma unroll
;                     for (int n = 0; n < 2; ++n) *(f32x4*)(out + off + bj * HALF + 4 * n) = r[m][bj][n] + gv[bj][n] * acc[ai][bj][m][n]; } }
; template <class Epi, class Sched, bool ALIGN_EPI = false, bool SP2 = false>
; __device__ __forceinline__ void gemm_phase(PG8_LAS unsigned char* lds, const Gemm g, const Sched& S, const Epi& E) {
;     ...
;     PG8_WAIT_V(0);
;     if constexpr (!ALIGN_EPI) { if (wr == 0) PG8_BAR; }
;     PG8_BAR;
	v_pk_fma_f32 v[62:63], v[62:63], v[142:143], v[66:67]
	v_pk_fma_f32 v[60:61], v[60:61], v[140:141], v[64:65]
	s_waitcnt vmcnt(14)
	v_pk_fma_f32 v[58:59], v[58:59], v[134:135], v[70:71]
	v_pk_fma_f32 v[56:57], v[56:57], v[132:133], v[68:69]
	s_waitcnt vmcnt(13)
	v_pk_fma_f32 v[42:43], v[42:43], v[138:139], v[74:75]
	s_waitcnt vmcnt(4)
	v_pk_fma_f32 v[12:13], v[12:13], v[128:129], v[108:109]
	v_pk_fma_f32 v[40:41], v[40:41], v[136:137], v[72:73]
	v_pk_fma_f32 v[38:39], v[38:39], v[130:131], v[78:79]
	v_pk_fma_f32 v[36:37], v[36:37], v[128:129], v[76:77]
	v_pk_fma_f32 v[54:55], v[54:55], v[142:143], v[82:83]
	v_pk_fma_f32 v[52:53], v[52:53], v[140:141], v[80:81]
	v_pk_fma_f32 v[50:51], v[50:51], v[134:135], v[86:87]
	v_pk_fma_f32 v[48:49], v[48:49], v[132:133], v[84:85]
	v_pk_fma_f32 v[30:31], v[30:31], v[138:139], v[90:91]
	v_pk_fma_f32 v[28:29], v[28:29], v[136:137], v[88:89]
	v_pk_fma_f32 v[26:27], v[26:27], v[130:131], v[94:95]
	v_pk_fma_f32 v[24:25], v[24:25], v[128:129], v[92:93]
	v_pk_fma_f32 v[46:47], v[46:47], v[142:143], v[98:99]
	v_pk_fma_f32 v[44:45], v[44:45], v[140:141], v[96:97]
	v_pk_fma_f32 v[34:35], v[34:35], v[134:135], v[102:103]
	v_pk_fma_f32 v[32:33], v[32:33], v[132:133], v[100:101]
	v_pk_fma_f32 v[18:19], v[18:19], v[138:139], v[106:107]
	v_pk_fma_f32 v[16:17], v[16:17], v[136:137], v[104:105]
	v_pk_fma_f32 v[14:15], v[14:15], v[130:131], v[110:111]
	global_store_dwordx4 v[162:163], v[60:63], off
	global_store_dwordx4 v[162:163], v[56:59], off offset:16
	global_store_dwordx4 v[162:163], v[40:43], off offset:512
	global_store_dwordx4 v[162:163], v[36:39], off offset:528
	global_store_dwordx4 v[172:173], v[52:55], off
	global_store_dwordx4 v[172:173], v[48:51], off offset:16
	global_store_dwordx4 v[172:173], v[28:31], off offset:512
	global_store_dwordx4 v[172:173], v[24:27], off offset:528
	global_store_dwordx4 v[174:175], v[44:47], off
	global_store_dwordx4 v[174:175], v[32:35], off offset:16
	global_store_dwordx4 v[174:175], v[16:19], off offset:512
	global_store_dwordx4 v[174:175], v[12:15], off offset:528
	s_waitcnt vmcnt(15)
	v_pk_fma_f32 v[22:23], v[22:23], v[142:143], v[114:115]
	v_pk_fma_f32 v[20:21], v[20:21], v[140:141], v[112:113]
	v_lshl_add_u64 v[12:13], s[14:15], 0, v[164:165]
	v_lshl_add_u64 v[12:13], v[12:13], 0, v[160:161]
	s_waitcnt vmcnt(14)
	v_pk_fma_f32 v[10:11], v[10:11], v[134:135], v[118:119]
	v_pk_fma_f32 v[8:9], v[8:9], v[132:133], v[116:117]
	s_waitcnt vmcnt(13)
	v_pk_fma_f32 v[6:7], v[6:7], v[138:139], v[122:123]
	v_pk_fma_f32 v[4:5], v[4:5], v[136:137], v[120:121]
	s_waitcnt vmcnt(12)
	v_pk_fma_f32 v[2:3], v[2:3], v[130:131], v[126:127]
	v_pk_fma_f32 v[0:1], v[0:1], v[128:129], v[124:125]
	global_store_dwordx4 v[12:13], v[20:23], off
	global_store_dwordx4 v[12:13], v[8:11], off offset:16
	global_store_dwordx4 v[12:13], v[4:7], off offset:512
	global_store_dwordx4 v[12:13], v[0:3], off offset:528
	s_cbranch_vccz .LBB0_820
	s_waitcnt vmcnt(0)
	s_cmpk_gt_u32 s3, 0xff
	s_cbranch_scc1 .LBB0_831
	s_barrier

; #define PG8_STAGE(bufoff, gbase, voff) do { _Pragma("unroll") for (int _i = 0; _i < 2; ++_i) \
;         __builtin_amdgcn_global_load_lds((const unsigned*)((const char*)(gbase) + (voff)[_i]), (PG8_LAS unsigned*)(lds + (bufoff) + ldsw + _i * 8192), 16, 0, 0); } while (0)
; #define PG8_LDA(dst, b, h) do { _Pragma("unroll") for (int m = 0; m < 4; ++m) _Pragma("unroll") for (int k = 0; k < 2; ++k) dst[m][k] = *(const PG8_LAS bf16x8*)(lds + PG8_SA(b, h) + aoff + m * 2048 + k * 1024); } while (0)
; #define PG8_LDB(dst, b, h) do { _Pragma("unroll") for (int n = 0; n < 2; ++n) _Pragma("unroll") for (int k = 0; k < 2; ++k) dst[n][k] = *(const PG8_LAS bf16x8*)(lds + PG8_SB(b, h) + boff + n * 2048 + k * 1024); } while (0)
; #define PG8_WAIT_V(n) asm volatile("s_waitcnt vmcnt(" #n ")" ::: "memory")
; #define PG8_WAIT_L(n) asm volatile("s_waitcnt lgkmcnt(" #n ")" ::: "memory")
; #define PG8_BAR __builtin_amdgcn_s_barrier()
; #define PG8_SCHED __builtin_amdgcn_sched_barrier(0)
; template <class Epi, class Sched, bool ALIGN_EPI = false, bool SP2 = false>
; __device__ __forceinline__ void gemm_phase(PG8_LAS unsigned char* lds, const Gemm g, const Sched& S, const Epi& E) {
;     ...
;         const bool has_next = S.next(ui + 1, nxt);
;         const char* nA = has_next ? (const char*)g.A + (size_t)nxt.pm * tstep : cA; const char* nB = has_next ? (const char*)g.Bt + (size_t)nxt.pn * tstep : cB;
;         for (int t = 0; t < nt; t += 2) {
;             const bool last = (t == nt - 2);
;             const char* a1 = cA + (size_t)(t + 1) * kstep;
;             const char* a2 = last ? nA : cA + (size_t)(t + 2) * kstep; const char* b2 = last ? nB : cB + (size_t)(t + 2) * kstep;
;             const char* a3 = a2 + kstep; const char* b3 = b2 + kstep;
;             if (last && has_next) S.a_ready(nxt);
;             if constexpr (SP2) {
;             PG8_LDB(B0, 0, 0); PG8_LDB(B1, 0, 1); PG8_SCHED; PG8_LDA(At, 0, 0); PG8_STAGE(PG8_SA(1, 1), a1 + hstep, voffA);
;             PG8_WAIT_V(8); PG8_WAIT_L(0); PG8_BAR; PG8_MMA(0, 0, At, B0); PG8_MMA(0, 1, At, B1); PG8_BAR; PG8_SCHED;
;             PG8_LDA(At, 0, 1); PG8_STAGE(PG8_SB(0, 0), b2, voffB); PG8_STAGE(PG8_SB(0, 1), b2 + hstep, voffB); PG8_STAGE(PG8_SA(0, 0), a2, voffA);
;             PG8_WAIT_V(8); PG8_WAIT_L(0); PG8_BAR; PG8_MMA(1, 0, At, B0); PG8_MMA(1, 1, At, B1); PG8_BAR; PG8_SCHED;
.LBB0_944:
	s_ashr_i32 s23, s22, 31
	v_cmp_lt_i64_e32 vcc, s[24:25], v[140:141]
	s_lshl_b64 s[24:25], s[22:23], 20
	s_add_u32 s24, s38, s24
	s_addc_u32 s25, s39, s25
	s_and_b64 s[26:27], vcc, exec
	s_cselect_b32 s23, s25, s31
	s_cselect_b32 s57, s24, s30
	s_ashr_i32 s15, s14, 31
	s_lshl_b64 s[26:27], s[14:15], 20
	s_add_u32 s26, s40, s26
	s_addc_u32 s27, s41, s27
	s_and_b64 s[36:37], vcc, exec
	s_cselect_b32 s15, s27, s35
	s_cselect_b32 s58, s26, s34
	s_add_u32 s30, s30, 0x80080
	s_addc_u32 s31, s31, 0
	s_add_u32 s59, s34, 0x100
	s_addc_u32 s60, s35, 0
	s_mov_b32 s61, -2
	v_add_u32_e32 v144, 0x18000, v147
	v_add_u32_e32 v145, 0x1c000, v147
	ds_read_b128 v[152:155], v149
	ds_read_b128 v[156:159], v149 offset:1024
	ds_read_b128 v[160:163], v149 offset:2048
	ds_read_b128 v[164:167], v149 offset:3072
	ds_read_b128 v[168:171], v150
	ds_read_b128 v[172:175], v150 offset:1024
	ds_read_b128 v[176:179], v150 offset:2048
	ds_read_b128 v[180:183], v150 offset:3072
	s_add_u32 s34, s30, 0xfff80080
	s_addc_u32 s35, s31, -1
	s_cmp_eq_u32 s61, 28
	s_cselect_b32 s37, s23, s35
	s_cselect_b32 s36, s57, s34
	s_cselect_b32 s35, s15, s60
	s_cselect_b32 s34, s58, s59
	s_add_i32 m0, s29, 0xc000
	ds_read_b128 v[184:187], v151
	ds_read_b128 v[188:191], v151 offset:1024
	ds_read_b128 v[192:195], v151 offset:2048
	ds_read_b128 v[196:199], v151 offset:3072
	ds_read_b128 v[200:203], v151 offset:4096
	ds_read_b128 v[204:207], v151 offset:5120
	ds_read_b128 v[208:211], v151 offset:6144
	ds_read_b128 v[212:215], v151 offset:7168
	global_load_lds_dwordx4 v136, s[30:31]
	s_add_i32 m0, s29, 0xe000
	s_nop 0
	global_load_lds_dwordx4 v138, s[30:31]
	s_waitcnt vmcnt(8) lgkmcnt(0)
	s_barrier
	v_mfma_f32_16x16x32_bf16 v[124:127], v[152:155], v[184:187], 0
	v_mfma_f32_16x16x32_bf16 v[120:123], v[160:163], v[184:187], 0
	v_mfma_f32_16x16x32_bf16 v[108:111], v[152:155], v[192:195], 0
	v_mfma_f32_16x16x32_bf16 v[104:107], v[160:163], v[192:195], 0
	v_mfma_f32_16x16x32_bf16 v[92:95], v[152:155], v[200:203], 0
	v_mfma_f32_16x16x32_bf16 v[88:91], v[160:163], v[200:203], 0
	v_mfma_f32_16x16x32_bf16 v[76:79], v[152:155], v[208:211], 0
	v_mfma_f32_16x16x32_bf16 v[72:75], v[160:163], v[208:211], 0
	v_mfma_f32_16x16x32_bf16 v[124:127], v[156:159], v[188:191], v[124:127]
	v_mfma_f32_16x16x32_bf16 v[120:123], v[164:167], v[188:191], v[120:123]
	v_mfma_f32_16x16x32_bf16 v[108:111], v[156:159], v[196:199], v[108:111]
	v_mfma_f32_16x16x32_bf16 v[104:107], v[164:167], v[196:199], v[104:107]
	v_mfma_f32_16x16x32_bf16 v[92:95], v[156:159], v[204:207], v[92:95]
	v_mfma_f32_16x16x32_bf16 v[88:91], v[164:167], v[204:207], v[88:91]
	v_mfma_f32_16x16x32_bf16 v[76:79], v[156:159], v[212:215], v[76:79]
	v_mfma_f32_16x16x32_bf16 v[72:75], v[164:167], v[212:215], v[72:75]
	v_mfma_f32_16x16x32_bf16 v[116:119], v[168:171], v[184:187], 0
	v_mfma_f32_16x16x32_bf16 v[112:115], v[176:179], v[184:187], 0
	v_mfma_f32_16x16x32_bf16 v[100:103], v[168:171], v[192:195], 0
	v_mfma_f32_16x16x32_bf16 v[96:99], v[176:179], v[192:195], 0
	v_mfma_f32_16x16x32_bf16 v[84:87], v[168:171], v[200:203], 0
	v_mfma_f32_16x16x32_bf16 v[80:83], v[176:179], v[200:203], 0
	v_mfma_f32_16x16x32_bf16 v[68:71], v[168:171], v[208:211], 0
	v_mfma_f32_16x16x32_bf16 v[64:67], v[176:179], v[208:211], 0
	v_mfma_f32_16x16x32_bf16 v[116:119], v[172:175], v[188:191], v[116:119]
	v_mfma_f32_16x16x32_bf16 v[112:115], v[180:183], v[188:191], v[112:115]
	v_mfma_f32_16x16x32_bf16 v[100:103], v[172:175], v[196:199], v[100:103]
	v_mfma_f32_16x16x32_bf16 v[96:99], v[180:183], v[196:199], v[96:99]
	v_mfma_f32_16x16x32_bf16 v[84:87], v[172:175], v[204:207], v[84:87]
	v_mfma_f32_16x16x32_bf16 v[80:83], v[180:183], v[204:207], v[80:83]
	v_mfma_f32_16x16x32_bf16 v[68:71], v[172:175], v[212:215], v[68:71]
	v_mfma_f32_16x16x32_bf16 v[64:67], v[180:183], v[212:215], v[64:67]
	s_barrier
	s_add_i32 s62, s53, s42
	s_mov_b32 m0, s62
	ds_read_b128 v[184:187], v151 offset:16384
	ds_read_b128 v[188:191], v151 offset:17408
	ds_read_b128 v[192:195], v151 offset:18432
	ds_read_b128 v[196:199], v151 offset:19456
	ds_read_b128 v[200:203], v151 offset:20480
	ds_read_b128 v[204:207], v151 offset:21504
	ds_read_b128 v[208:211], v151 offset:22528
	ds_read_b128 v[212:215], v151 offset:23552
	global_load_lds_dwordx4 v132, s[34:35]
	s_add_i32 m0, s62, 0x2000
	s_add_u32 s62, s34, 0x80000
	s_addc_u32 s63, s35, 0
	s_add_i32 s64, s54, s42
	global_load_lds_dwordx4 v128, s[34:35]
	s_mov_b32 m0, s64
	s_nop 0
	global_load_lds_dwordx4 v132, s[62:63]
	s_add_i32 m0, s64, 0x2000
	s_nop 0
	global_load_lds_dwordx4 v128, s[62:63]
	s_mov_b32 m0, s29
	s_nop 0
	global_load_lds_dwordx4 v134, s[36:37]
	s_mov_b32 m0, s45
	s_nop 0
	global_load_lds_dwordx4 v130, s[36:37]
	s_waitcnt vmcnt(8) lgkmcnt(0)
	s_barrier
; #define PG8_STAGE(bufoff, gbase, voff) do { _Pragma("unroll") for (int _i = 0; _i < 2; ++_i) \
;         __builtin_amdgcn_global_load_lds((const unsigned*)((const char*)(gbase) + (voff)[_i]), (PG8_LAS unsigned*)(lds + (bufoff) + ldsw + _i * 8192), 16, 0, 0); } while (0)
; #define PG8_LDA(dst, b, h) do { _Pragma("unroll") for (int m = 0; m < 4; ++m) _Pragma("unroll") for (int k = 0; k < 2; ++k) dst[m][k] = *(const PG8_LAS bf16x8*)(lds + PG8_SA(b, h) + aoff + m * 2048 + k * 1024); } while (0)
; #define PG8_LDB(dst, b, h) do { _Pragma("unroll") for (int n = 0; n < 2; ++n) _Pragma("unroll") for (int k = 0; k < 2; ++k) dst[n][k] = *(const PG8_LAS bf16x8*)(lds + PG8_SB(b, h) + boff + n * 2048 + k * 1024); } while (0)
; #define PG8_MMA(ai, bj, At, Bt) do { __builtin_amdgcn_s_setprio(1); _Pragma("unroll") for (int m = 0; m < 4; ++m) _Pragma("unroll") for (int n = 0; n < 2; ++n) _Pragma("unroll") for (int k = 0; k < 2; ++k) \
;         acc[ai][bj][m][n] = __builtin_amdgcn_mfma_f32_16x16x32_bf16(Bt[n][k], At[m][k], acc[ai][bj][m][n], 0, 0, 0); __builtin_amdgcn_s_setprio(0); } while (0)
; #define PG8_WAIT_V(n) asm volatile("s_waitcnt vmcnt(" #n ")" ::: "memory")
; #define PG8_WAIT_L(n) asm volatile("s_waitcnt lgkmcnt(" #n ")" ::: "memory")
; #define PG8_BAR __builtin_amdgcn_s_barrier()
; #define PG8_SCHED __builtin_amdgcn_sched_barrier(0)
; template <class Epi, class Sched, bool ALIGN_EPI = false, bool SP2 = false>
; __device__ __forceinline__ void gemm_phase(PG8_LAS unsigned char* lds, const Gemm g, const Sched& S, const Epi& E) {
;     ...
;             PG8_WAIT_V(8); PG8_WAIT_L(0); PG8_BAR; PG8_MMA(1, 0, At, B0); PG8_MMA(1, 1, At, B1); PG8_BAR; PG8_SCHED;
;             PG8_LDB(B0, 1, 0); PG8_LDB(B1, 1, 1); PG8_SCHED; PG8_LDA(At, 1, 0); PG8_STAGE(PG8_SA(0, 1), a2 + hstep, voffA);
;             PG8_WAIT_V(8); PG8_WAIT_L(0); PG8_BAR; PG8_MMA(0, 0, At, B0); PG8_MMA(0, 1, At, B1); PG8_BAR; PG8_SCHED;
	v_mfma_f32_16x16x32_bf16 v[60:63], v[152:155], v[184:187], 0
	v_mfma_f32_16x16x32_bf16 v[56:59], v[160:163], v[184:187], 0
	v_mfma_f32_16x16x32_bf16 v[44:47], v[152:155], v[192:195], 0
	v_mfma_f32_16x16x32_bf16 v[40:43], v[160:163], v[192:195], 0
	v_mfma_f32_16x16x32_bf16 v[28:31], v[152:155], v[200:203], 0
	v_mfma_f32_16x16x32_bf16 v[24:27], v[160:163], v[200:203], 0
	v_mfma_f32_16x16x32_bf16 v[12:15], v[152:155], v[208:211], 0
	v_mfma_f32_16x16x32_bf16 v[8:11], v[160:163], v[208:211], 0
	v_mfma_f32_16x16x32_bf16 v[60:63], v[156:159], v[188:191], v[60:63]
	v_mfma_f32_16x16x32_bf16 v[56:59], v[164:167], v[188:191], v[56:59]
	v_mfma_f32_16x16x32_bf16 v[44:47], v[156:159], v[196:199], v[44:47]
	v_mfma_f32_16x16x32_bf16 v[40:43], v[164:167], v[196:199], v[40:43]
	v_mfma_f32_16x16x32_bf16 v[28:31], v[156:159], v[204:207], v[28:31]
	v_mfma_f32_16x16x32_bf16 v[24:27], v[164:167], v[204:207], v[24:27]
	v_mfma_f32_16x16x32_bf16 v[12:15], v[156:159], v[212:215], v[12:15]
	v_mfma_f32_16x16x32_bf16 v[8:11], v[164:167], v[212:215], v[8:11]
	v_mfma_f32_16x16x32_bf16 v[52:55], v[168:171], v[184:187], 0
	v_mfma_f32_16x16x32_bf16 v[48:51], v[176:179], v[184:187], 0
	v_mfma_f32_16x16x32_bf16 v[36:39], v[168:171], v[192:195], 0
	v_mfma_f32_16x16x32_bf16 v[32:35], v[176:179], v[192:195], 0
	v_mfma_f32_16x16x32_bf16 v[20:23], v[168:171], v[200:203], 0
	v_mfma_f32_16x16x32_bf16 v[16:19], v[176:179], v[200:203], 0
	v_mfma_f32_16x16x32_bf16 v[4:7], v[168:171], v[208:211], 0
	v_mfma_f32_16x16x32_bf16 v[0:3], v[176:179], v[208:211], 0
	v_mfma_f32_16x16x32_bf16 v[52:55], v[172:175], v[188:191], v[52:55]
	v_mfma_f32_16x16x32_bf16 v[48:51], v[180:183], v[188:191], v[48:51]
	v_mfma_f32_16x16x32_bf16 v[36:39], v[172:175], v[196:199], v[36:39]
	v_mfma_f32_16x16x32_bf16 v[32:35], v[180:183], v[196:199], v[32:35]
	v_mfma_f32_16x16x32_bf16 v[20:23], v[172:175], v[204:207], v[20:23]
	v_mfma_f32_16x16x32_bf16 v[16:19], v[180:183], v[204:207], v[16:19]
	v_mfma_f32_16x16x32_bf16 v[4:7], v[172:175], v[212:215], v[4:7]
	v_mfma_f32_16x16x32_bf16 v[0:3], v[180:183], v[212:215], v[0:3]
	s_barrier
	s_add_i32 s62, 0, 0x18000
	s_add_i32 s63, 0, 0x1c000
	ds_read_b128 v[152:155], v144
	ds_read_b128 v[156:159], v144 offset:1024
	ds_read_b128 v[160:163], v144 offset:2048
	ds_read_b128 v[164:167], v144 offset:3072
	ds_read_b128 v[168:171], v145
	ds_read_b128 v[172:175], v145 offset:1024
	ds_read_b128 v[176:179], v145 offset:2048
	ds_read_b128 v[180:183], v145 offset:3072
	s_add_u32 s84, s36, 0x80
	s_addc_u32 s85, s37, 0
	s_add_u32 s36, s36, 0x80000
	s_addc_u32 s37, s37, 0
	s_mov_b32 m0, s46
	ds_read_b128 v[184:187], v151 offset:32768
	ds_read_b128 v[188:191], v151 offset:33792
	ds_read_b128 v[192:195], v151 offset:34816
	ds_read_b128 v[196:199], v151 offset:35840
	ds_read_b128 v[200:203], v151 offset:36864
	ds_read_b128 v[204:207], v151 offset:37888
	ds_read_b128 v[208:211], v151 offset:38912
	ds_read_b128 v[212:215], v151 offset:39936
	global_load_lds_dwordx4 v134, s[36:37]
	s_mov_b32 m0, s47
	s_nop 0
	global_load_lds_dwordx4 v130, s[36:37]
	s_waitcnt vmcnt(8) lgkmcnt(0)
	s_barrier
	v_mfma_f32_16x16x32_bf16 v[124:127], v[152:155], v[184:187], v[124:127]
	v_mfma_f32_16x16x32_bf16 v[120:123], v[160:163], v[184:187], v[120:123]
	v_mfma_f32_16x16x32_bf16 v[108:111], v[152:155], v[192:195], v[108:111]
	v_mfma_f32_16x16x32_bf16 v[104:107], v[160:163], v[192:195], v[104:107]
	v_mfma_f32_16x16x32_bf16 v[92:95], v[152:155], v[200:203], v[92:95]
	v_mfma_f32_16x16x32_bf16 v[88:91], v[160:163], v[200:203], v[88:91]
	v_mfma_f32_16x16x32_bf16 v[76:79], v[152:155], v[208:211], v[76:79]
	v_mfma_f32_16x16x32_bf16 v[72:75], v[160:163], v[208:211], v[72:75]
	v_mfma_f32_16x16x32_bf16 v[124:127], v[156:159], v[188:191], v[124:127]
	v_mfma_f32_16x16x32_bf16 v[120:123], v[164:167], v[188:191], v[120:123]
	v_mfma_f32_16x16x32_bf16 v[108:111], v[156:159], v[196:199], v[108:111]
	v_mfma_f32_16x16x32_bf16 v[104:107], v[164:167], v[196:199], v[104:107]
	v_mfma_f32_16x16x32_bf16 v[92:95], v[156:159], v[204:207], v[92:95]
	v_mfma_f32_16x16x32_bf16 v[88:91], v[164:167], v[204:207], v[88:91]
	v_mfma_f32_16x16x32_bf16 v[76:79], v[156:159], v[212:215], v[76:79]
	v_mfma_f32_16x16x32_bf16 v[72:75], v[164:167], v[212:215], v[72:75]
	v_mfma_f32_16x16x32_bf16 v[116:119], v[168:171], v[184:187], v[116:119]
	v_mfma_f32_16x16x32_bf16 v[112:115], v[176:179], v[184:187], v[112:115]
	v_mfma_f32_16x16x32_bf16 v[100:103], v[168:171], v[192:195], v[100:103]
	v_mfma_f32_16x16x32_bf16 v[96:99], v[176:179], v[192:195], v[96:99]
	v_mfma_f32_16x16x32_bf16 v[84:87], v[168:171], v[200:203], v[84:87]
	v_mfma_f32_16x16x32_bf16 v[80:83], v[176:179], v[200:203], v[80:83]
	v_mfma_f32_16x16x32_bf16 v[68:71], v[168:171], v[208:211], v[68:71]
	v_mfma_f32_16x16x32_bf16 v[64:67], v[176:179], v[208:211], v[64:67]
	v_mfma_f32_16x16x32_bf16 v[116:119], v[172:175], v[188:191], v[116:119]
	v_mfma_f32_16x16x32_bf16 v[112:115], v[180:183], v[188:191], v[112:115]
	v_mfma_f32_16x16x32_bf16 v[100:103], v[172:175], v[196:199], v[100:103]
	v_mfma_f32_16x16x32_bf16 v[96:99], v[180:183], v[196:199], v[96:99]
	v_mfma_f32_16x16x32_bf16 v[84:87], v[172:175], v[204:207], v[84:87]
	v_mfma_f32_16x16x32_bf16 v[80:83], v[180:183], v[204:207], v[80:83]
	v_mfma_f32_16x16x32_bf16 v[68:71], v[172:175], v[212:215], v[68:71]
	v_mfma_f32_16x16x32_bf16 v[64:67], v[180:183], v[212:215], v[64:67]
	s_barrier
; #define PG8_STAGE(bufoff, gbase, voff) do { _Pragma("unroll") for (int _i = 0; _i < 2; ++_i) \
;         __builtin_amdgcn_global_load_lds((const unsigned*)((const char*)(gbase) + (voff)[_i]), (PG8_LAS unsigned*)(lds + (bufoff) + ldsw + _i * 8192), 16, 0, 0); } while (0)
; #define PG8_LDA(dst, b, h) do { _Pragma("unroll") for (int m = 0; m < 4; ++m) _Pragma("unroll") for (int k = 0; k < 2; ++k) dst[m][k] = *(const PG8_LAS bf16x8*)(lds + PG8_SA(b, h) + aoff + m * 2048 + k * 1024); } while (0)
; #define PG8_LDB(dst, b, h) do { _Pragma("unroll") for (int n = 0; n < 2; ++n) _Pragma("unroll") for (int k = 0; k < 2; ++k) dst[n][k] = *(const PG8_LAS bf16x8*)(lds + PG8_SB(b, h) + boff + n * 2048 + k * 1024); } while (0)
; #define PG8_MMA(ai, bj, At, Bt) do { __builtin_amdgcn_s_setprio(1); _Pragma("unroll") for (int m = 0; m < 4; ++m) _Pragma("unroll") for (int n = 0; n < 2; ++n) _Pragma("unroll") for (int k = 0; k < 2; ++k) \
;         acc[ai][bj][m][n] = __builtin_amdgcn_mfma_f32_16x16x32_bf16(Bt[n][k], At[m][k], acc[ai][bj][m][n], 0, 0, 0); __builtin_amdgcn_s_setprio(0); } while (0)
; #define PG8_WAIT_V(n) asm volatile("s_waitcnt vmcnt(" #n ")" ::: "memory")
; #define PG8_WAIT_L(n) asm volatile("s_waitcnt lgkmcnt(" #n ")" ::: "memory")
; #define PG8_BAR __builtin_amdgcn_s_barrier()
; #define PG8_SCHED __builtin_amdgcn_sched_barrier(0)
; template <class Epi, class Sched, bool ALIGN_EPI = false, bool SP2 = false>
; __device__ __forceinline__ void gemm_phase(PG8_LAS unsigned char* lds, const Gemm g, const Sched& S, const Epi& E) {
;     ...
;             PG8_LDB(B0, 0, 0); PG8_LDB(B1, 0, 1); PG8_SCHED; PG8_LDA(At, 0, 0); PG8_STAGE(PG8_SA(1, 1), a1 + hstep, voffA);
;             PG8_WAIT_V(8); PG8_WAIT_L(0); PG8_BAR; PG8_MMA(0, 0, At, B0); PG8_MMA(0, 1, At, B1); PG8_BAR; PG8_SCHED;
;     ...
;             PG8_LDA(At, 1, 1); PG8_STAGE(PG8_SB(1, 0), b3, voffB); PG8_STAGE(PG8_SB(1, 1), b3 + hstep, voffB); PG8_STAGE(PG8_SA(1, 0), a3, voffA);
;             PG8_WAIT_V(8); PG8_WAIT_L(0); PG8_BAR; PG8_MMA(1, 0, At, B0); PG8_MMA(1, 1, At, B1); PG8_BAR; PG8_SCHED;
	s_add_i32 s36, s62, s42
	s_add_u32 s86, s34, 0x80
	s_addc_u32 s87, s35, 0
	s_mov_b32 m0, s36
	ds_read_b128 v[184:187], v151 offset:49152
	ds_read_b128 v[188:191], v151 offset:50176
	ds_read_b128 v[192:195], v151 offset:51200
	ds_read_b128 v[196:199], v151 offset:52224
	ds_read_b128 v[200:203], v151 offset:53248
	ds_read_b128 v[204:207], v151 offset:54272
	ds_read_b128 v[208:211], v151 offset:55296
	ds_read_b128 v[212:215], v151 offset:56320
	global_load_lds_dwordx4 v132, s[86:87]
	s_add_i32 m0, s36, 0x2000
	s_add_u32 s34, s34, 0x80080
	s_addc_u32 s35, s35, 0
	s_add_i32 s36, s63, s42
	global_load_lds_dwordx4 v128, s[86:87]
	s_mov_b32 m0, s36
	s_nop 0
	global_load_lds_dwordx4 v132, s[34:35]
	s_add_i32 m0, s36, 0x2000
	s_nop 0
	global_load_lds_dwordx4 v128, s[34:35]
	s_mov_b32 m0, s49
	s_nop 0
	global_load_lds_dwordx4 v134, s[84:85]
	s_mov_b32 m0, s50
	s_nop 0
	global_load_lds_dwordx4 v130, s[84:85]
	s_waitcnt vmcnt(8) lgkmcnt(0)
	s_barrier
	v_mfma_f32_16x16x32_bf16 v[60:63], v[152:155], v[184:187], v[60:63]
	v_mfma_f32_16x16x32_bf16 v[56:59], v[160:163], v[184:187], v[56:59]
	v_mfma_f32_16x16x32_bf16 v[44:47], v[152:155], v[192:195], v[44:47]
	v_mfma_f32_16x16x32_bf16 v[40:43], v[160:163], v[192:195], v[40:43]
	v_mfma_f32_16x16x32_bf16 v[28:31], v[152:155], v[200:203], v[28:31]
	v_mfma_f32_16x16x32_bf16 v[24:27], v[160:163], v[200:203], v[24:27]
	v_mfma_f32_16x16x32_bf16 v[12:15], v[152:155], v[208:211], v[12:15]
	v_mfma_f32_16x16x32_bf16 v[8:11], v[160:163], v[208:211], v[8:11]
	v_mfma_f32_16x16x32_bf16 v[60:63], v[156:159], v[188:191], v[60:63]
	v_mfma_f32_16x16x32_bf16 v[56:59], v[164:167], v[188:191], v[56:59]
	v_mfma_f32_16x16x32_bf16 v[44:47], v[156:159], v[196:199], v[44:47]
	v_mfma_f32_16x16x32_bf16 v[40:43], v[164:167], v[196:199], v[40:43]
	v_mfma_f32_16x16x32_bf16 v[28:31], v[156:159], v[204:207], v[28:31]
	v_mfma_f32_16x16x32_bf16 v[24:27], v[164:167], v[204:207], v[24:27]
	v_mfma_f32_16x16x32_bf16 v[12:15], v[156:159], v[212:215], v[12:15]
	v_mfma_f32_16x16x32_bf16 v[8:11], v[164:167], v[212:215], v[8:11]
	v_mfma_f32_16x16x32_bf16 v[52:55], v[168:171], v[184:187], v[52:55]
	v_mfma_f32_16x16x32_bf16 v[48:51], v[176:179], v[184:187], v[48:51]
	v_mfma_f32_16x16x32_bf16 v[36:39], v[168:171], v[192:195], v[36:39]
	v_mfma_f32_16x16x32_bf16 v[32:35], v[176:179], v[192:195], v[32:35]
	v_mfma_f32_16x16x32_bf16 v[20:23], v[168:171], v[200:203], v[20:23]
	v_mfma_f32_16x16x32_bf16 v[16:19], v[176:179], v[200:203], v[16:19]
	v_mfma_f32_16x16x32_bf16 v[4:7], v[168:171], v[208:211], v[4:7]
	v_mfma_f32_16x16x32_bf16 v[0:3], v[176:179], v[208:211], v[0:3]
	v_mfma_f32_16x16x32_bf16 v[52:55], v[172:175], v[188:191], v[52:55]
	v_mfma_f32_16x16x32_bf16 v[48:51], v[180:183], v[188:191], v[48:51]
	v_mfma_f32_16x16x32_bf16 v[36:39], v[172:175], v[196:199], v[36:39]
	v_mfma_f32_16x16x32_bf16 v[32:35], v[180:183], v[196:199], v[32:35]
	v_mfma_f32_16x16x32_bf16 v[20:23], v[172:175], v[204:207], v[20:23]
	v_mfma_f32_16x16x32_bf16 v[16:19], v[180:183], v[204:207], v[16:19]
	v_mfma_f32_16x16x32_bf16 v[4:7], v[172:175], v[212:215], v[4:7]
	v_mfma_f32_16x16x32_bf16 v[0:3], v[180:183], v[212:215], v[0:3]
	s_barrier
	s_add_i32 s61, s61, 2
	s_add_u32 s30, s30, 0x100
	s_addc_u32 s31, s31, 0
	s_add_u32 s59, s59, 0x100
	s_addc_u32 s60, s60, 0
	s_cmp_gt_u32 s61, 29
.LBB0_945:
	ds_read_b128 v[152:155], v149
	ds_read_b128 v[156:159], v149 offset:1024
	ds_read_b128 v[160:163], v149 offset:2048
	ds_read_b128 v[164:167], v149 offset:3072
	ds_read_b128 v[168:171], v150
	ds_read_b128 v[172:175], v150 offset:1024
	ds_read_b128 v[176:179], v150 offset:2048
	ds_read_b128 v[180:183], v150 offset:3072
	s_add_u32 s34, s30, 0xfff80080
	s_addc_u32 s35, s31, -1
	s_cmp_eq_u32 s61, 28
	s_cselect_b32 s37, s23, s35
	s_cselect_b32 s36, s57, s34
	s_cselect_b32 s35, s15, s60
	s_cselect_b32 s34, s58, s59
	s_add_i32 m0, s29, 0xc000
	ds_read_b128 v[184:187], v151
	ds_read_b128 v[188:191], v151 offset:1024
	ds_read_b128 v[192:195], v151 offset:2048
	ds_read_b128 v[196:199], v151 offset:3072
	ds_read_b128 v[200:203], v151 offset:4096
	ds_read_b128 v[204:207], v151 offset:5120
	ds_read_b128 v[208:211], v151 offset:6144
	ds_read_b128 v[212:215], v151 offset:7168
	global_load_lds_dwordx4 v136, s[30:31]
	s_add_i32 m0, s29, 0xe000
	s_nop 0
	global_load_lds_dwordx4 v138, s[30:31]
	s_waitcnt vmcnt(8) lgkmcnt(0)
	s_barrier
	v_mfma_f32_16x16x32_bf16 v[124:127], v[152:155], v[184:187], v[124:127]
	v_mfma_f32_16x16x32_bf16 v[120:123], v[160:163], v[184:187], v[120:123]
	v_mfma_f32_16x16x32_bf16 v[108:111], v[152:155], v[192:195], v[108:111]
	v_mfma_f32_16x16x32_bf16 v[104:107], v[160:163], v[192:195], v[104:107]
	v_mfma_f32_16x16x32_bf16 v[92:95], v[152:155], v[200:203], v[92:95]
	v_mfma_f32_16x16x32_bf16 v[88:91], v[160:163], v[200:203], v[88:91]
	v_mfma_f32_16x16x32_bf16 v[76:79], v[152:155], v[208:211], v[76:79]
	v_mfma_f32_16x16x32_bf16 v[72:75], v[160:163], v[208:211], v[72:75]
	v_mfma_f32_16x16x32_bf16 v[124:127], v[156:159], v[188:191], v[124:127]
	v_mfma_f32_16x16x32_bf16 v[120:123], v[164:167], v[188:191], v[120:123]
	v_mfma_f32_16x16x32_bf16 v[108:111], v[156:159], v[196:199], v[108:111]
	v_mfma_f32_16x16x32_bf16 v[104:107], v[164:167], v[196:199], v[104:107]
	v_mfma_f32_16x16x32_bf16 v[92:95], v[156:159], v[204:207], v[92:95]
	v_mfma_f32_16x16x32_bf16 v[88:91], v[164:167], v[204:207], v[88:91]
	v_mfma_f32_16x16x32_bf16 v[76:79], v[156:159], v[212:215], v[76:79]
	v_mfma_f32_16x16x32_bf16 v[72:75], v[164:167], v[212:215], v[72:75]
	v_mfma_f32_16x16x32_bf16 v[116:119], v[168:171], v[184:187], v[116:119]
	v_mfma_f32_16x16x32_bf16 v[112:115], v[176:179], v[184:187], v[112:115]
	v_mfma_f32_16x16x32_bf16 v[100:103], v[168:171], v[192:195], v[100:103]
	v_mfma_f32_16x16x32_bf16 v[96:99], v[176:179], v[192:195], v[96:99]
	v_mfma_f32_16x16x32_bf16 v[84:87], v[168:171], v[200:203], v[84:87]
	v_mfma_f32_16x16x32_bf16 v[80:83], v[176:179], v[200:203], v[80:83]
	v_mfma_f32_16x16x32_bf16 v[68:71], v[168:171], v[208:211], v[68:71]
	v_mfma_f32_16x16x32_bf16 v[64:67], v[176:179], v[208:211], v[64:67]
	v_mfma_f32_16x16x32_bf16 v[116:119], v[172:175], v[188:191], v[116:119]
	v_mfma_f32_16x16x32_bf16 v[112:115], v[180:183], v[188:191], v[112:115]
	v_mfma_f32_16x16x32_bf16 v[100:103], v[172:175], v[196:199], v[100:103]
	v_mfma_f32_16x16x32_bf16 v[96:99], v[180:183], v[196:199], v[96:99]
	v_mfma_f32_16x16x32_bf16 v[84:87], v[172:175], v[204:207], v[84:87]
	v_mfma_f32_16x16x32_bf16 v[80:83], v[180:183], v[204:207], v[80:83]
	v_mfma_f32_16x16x32_bf16 v[68:71], v[172:175], v[212:215], v[68:71]
	v_mfma_f32_16x16x32_bf16 v[64:67], v[180:183], v[212:215], v[64:67]
	s_barrier
; #define PG8_STAGE(bufoff, gbase, voff) do { _Pragma("unroll") for (int _i = 0; _i < 2; ++_i) \
;         __builtin_amdgcn_global_load_lds((const unsigned*)((const char*)(gbase) + (voff)[_i]), (PG8_LAS unsigned*)(lds + (bufoff) + ldsw + _i * 8192), 16, 0, 0); } while (0)
; #define PG8_LDA(dst, b, h) do { _Pragma("unroll") for (int m = 0; m < 4; ++m) _Pragma("unroll") for (int k = 0; k < 2; ++k) dst[m][k] = *(const PG8_LAS bf16x8*)(lds + PG8_SA(b, h) + aoff + m * 2048 + k * 1024); } while (0)
; #define PG8_LDB(dst, b, h) do { _Pragma("unroll") for (int n = 0; n < 2; ++n) _Pragma("unroll") for (int k = 0; k < 2; ++k) dst[n][k] = *(const PG8_LAS bf16x8*)(lds + PG8_SB(b, h) + boff + n * 2048 + k * 1024); } while (0)
; #define PG8_MMA(ai, bj, At, Bt) do { __builtin_amdgcn_s_setprio(1); _Pragma("unroll") for (int m = 0; m < 4; ++m) _Pragma("unroll") for (int n = 0; n < 2; ++n) _Pragma("unroll") for (int k = 0; k < 2; ++k) \
;         acc[ai][bj][m][n] = __builtin_amdgcn_mfma_f32_16x16x32_bf16(Bt[n][k], At[m][k], acc[ai][bj][m][n], 0, 0, 0); __builtin_amdgcn_s_setprio(0); } while (0)
; #define PG8_WAIT_V(n) asm volatile("s_waitcnt vmcnt(" #n ")" ::: "memory")
; #define PG8_WAIT_L(n) asm volatile("s_waitcnt lgkmcnt(" #n ")" ::: "memory")
; #define PG8_BAR __builtin_amdgcn_s_barrier()
; #define PG8_SCHED __builtin_amdgcn_sched_barrier(0)
; template <class Epi, class Sched, bool ALIGN_EPI = false, bool SP2 = false>
; __device__ __forceinline__ void gemm_phase(PG8_LAS unsigned char* lds, const Gemm g, const Sched& S, const Epi& E) {
;     ...
;             PG8_LDA(At, 0, 1); PG8_STAGE(PG8_SB(0, 0), b2, voffB); PG8_STAGE(PG8_SB(0, 1), b2 + hstep, voffB); PG8_STAGE(PG8_SA(0, 0), a2, voffA);
;             PG8_WAIT_V(8); PG8_WAIT_L(0); PG8_BAR; PG8_MMA(1, 0, At, B0); PG8_MMA(1, 1, At, B1); PG8_BAR; PG8_SCHED;
;             PG8_LDB(B0, 1, 0); PG8_LDB(B1, 1, 1); PG8_SCHED; PG8_LDA(At, 1, 0); PG8_STAGE(PG8_SA(0, 1), a2 + hstep, voffA);
;             PG8_WAIT_V(8); PG8_WAIT_L(0); PG8_BAR; PG8_MMA(0, 0, At, B0); PG8_MMA(0, 1, At, B1); PG8_BAR; PG8_SCHED;
	s_add_i32 s62, s53, s42
	s_mov_b32 m0, s62
	ds_read_b128 v[184:187], v151 offset:16384
	ds_read_b128 v[188:191], v151 offset:17408
	ds_read_b128 v[192:195], v151 offset:18432
	ds_read_b128 v[196:199], v151 offset:19456
	ds_read_b128 v[200:203], v151 offset:20480
	ds_read_b128 v[204:207], v151 offset:21504
	ds_read_b128 v[208:211], v151 offset:22528
	ds_read_b128 v[212:215], v151 offset:23552
	global_load_lds_dwordx4 v132, s[34:35]
	s_add_i32 m0, s62, 0x2000
	s_add_u32 s62, s34, 0x80000
	s_addc_u32 s63, s35, 0
	s_add_i32 s64, s54, s42
	global_load_lds_dwordx4 v128, s[34:35]
	s_mov_b32 m0, s64
	s_nop 0
	global_load_lds_dwordx4 v132, s[62:63]
	s_add_i32 m0, s64, 0x2000
	s_nop 0
	global_load_lds_dwordx4 v128, s[62:63]
	s_mov_b32 m0, s29
	s_nop 0
	global_load_lds_dwordx4 v134, s[36:37]
	s_mov_b32 m0, s45
	s_nop 0
	global_load_lds_dwordx4 v130, s[36:37]
	s_waitcnt vmcnt(8) lgkmcnt(0)
	s_barrier
	v_mfma_f32_16x16x32_bf16 v[60:63], v[152:155], v[184:187], v[60:63]
	v_mfma_f32_16x16x32_bf16 v[56:59], v[160:163], v[184:187], v[56:59]
	v_mfma_f32_16x16x32_bf16 v[44:47], v[152:155], v[192:195], v[44:47]
	v_mfma_f32_16x16x32_bf16 v[40:43], v[160:163], v[192:195], v[40:43]
	v_mfma_f32_16x16x32_bf16 v[28:31], v[152:155], v[200:203], v[28:31]
	v_mfma_f32_16x16x32_bf16 v[24:27], v[160:163], v[200:203], v[24:27]
	v_mfma_f32_16x16x32_bf16 v[12:15], v[152:155], v[208:211], v[12:15]
	v_mfma_f32_16x16x32_bf16 v[8:11], v[160:163], v[208:211], v[8:11]
	v_mfma_f32_16x16x32_bf16 v[60:63], v[156:159], v[188:191], v[60:63]
	v_mfma_f32_16x16x32_bf16 v[56:59], v[164:167], v[188:191], v[56:59]
	v_mfma_f32_16x16x32_bf16 v[44:47], v[156:159], v[196:199], v[44:47]
	v_mfma_f32_16x16x32_bf16 v[40:43], v[164:167], v[196:199], v[40:43]
	v_mfma_f32_16x16x32_bf16 v[28:31], v[156:159], v[204:207], v[28:31]
	v_mfma_f32_16x16x32_bf16 v[24:27], v[164:167], v[204:207], v[24:27]
	v_mfma_f32_16x16x32_bf16 v[12:15], v[156:159], v[212:215], v[12:15]
	v_mfma_f32_16x16x32_bf16 v[8:11], v[164:167], v[212:215], v[8:11]
	v_mfma_f32_16x16x32_bf16 v[52:55], v[168:171], v[184:187], v[52:55]
	v_mfma_f32_16x16x32_bf16 v[48:51], v[176:179], v[184:187], v[48:51]
	v_mfma_f32_16x16x32_bf16 v[36:39], v[168:171], v[192:195], v[36:39]
	v_mfma_f32_16x16x32_bf16 v[32:35], v[176:179], v[192:195], v[32:35]
	v_mfma_f32_16x16x32_bf16 v[20:23], v[168:171], v[200:203], v[20:23]
	v_mfma_f32_16x16x32_bf16 v[16:19], v[176:179], v[200:203], v[16:19]
	v_mfma_f32_16x16x32_bf16 v[4:7], v[168:171], v[208:211], v[4:7]
	v_mfma_f32_16x16x32_bf16 v[0:3], v[176:179], v[208:211], v[0:3]
	v_mfma_f32_16x16x32_bf16 v[52:55], v[172:175], v[188:191], v[52:55]
	v_mfma_f32_16x16x32_bf16 v[48:51], v[180:183], v[188:191], v[48:51]
	v_mfma_f32_16x16x32_bf16 v[36:39], v[172:175], v[196:199], v[36:39]
	v_mfma_f32_16x16x32_bf16 v[32:35], v[180:183], v[196:199], v[32:35]
	v_mfma_f32_16x16x32_bf16 v[20:23], v[172:175], v[204:207], v[20:23]
	v_mfma_f32_16x16x32_bf16 v[16:19], v[180:183], v[204:207], v[16:19]
	v_mfma_f32_16x16x32_bf16 v[4:7], v[172:175], v[212:215], v[4:7]
	v_mfma_f32_16x16x32_bf16 v[0:3], v[180:183], v[212:215], v[0:3]
	s_barrier
	s_add_i32 s62, 0, 0x18000
	s_add_i32 s63, 0, 0x1c000
	ds_read_b128 v[152:155], v144
	ds_read_b128 v[156:159], v144 offset:1024
	ds_read_b128 v[160:163], v144 offset:2048
	ds_read_b128 v[164:167], v144 offset:3072
	ds_read_b128 v[168:171], v145
	ds_read_b128 v[172:175], v145 offset:1024
	ds_read_b128 v[176:179], v145 offset:2048
	ds_read_b128 v[180:183], v145 offset:3072
	s_add_u32 s84, s36, 0x80
	s_addc_u32 s85, s37, 0
	s_add_u32 s36, s36, 0x80000
	s_addc_u32 s37, s37, 0
	s_mov_b32 m0, s46
	ds_read_b128 v[184:187], v151 offset:32768
	ds_read_b128 v[188:191], v151 offset:33792
	ds_read_b128 v[192:195], v151 offset:34816
	ds_read_b128 v[196:199], v151 offset:35840
	ds_read_b128 v[200:203], v151 offset:36864
	ds_read_b128 v[204:207], v151 offset:37888
	ds_read_b128 v[208:211], v151 offset:38912
	ds_read_b128 v[212:215], v151 offset:39936
	global_load_lds_dwordx4 v134, s[36:37]
	s_mov_b32 m0, s47
	s_nop 0
	global_load_lds_dwordx4 v130, s[36:37]
	s_waitcnt vmcnt(8) lgkmcnt(0)
	s_barrier
	v_mfma_f32_16x16x32_bf16 v[124:127], v[152:155], v[184:187], v[124:127]
	v_mfma_f32_16x16x32_bf16 v[120:123], v[160:163], v[184:187], v[120:123]
	v_mfma_f32_16x16x32_bf16 v[108:111], v[152:155], v[192:195], v[108:111]
	v_mfma_f32_16x16x32_bf16 v[104:107], v[160:163], v[192:195], v[104:107]
	v_mfma_f32_16x16x32_bf16 v[92:95], v[152:155], v[200:203], v[92:95]
	v_mfma_f32_16x16x32_bf16 v[88:91], v[160:163], v[200:203], v[88:91]
	v_mfma_f32_16x16x32_bf16 v[76:79], v[152:155], v[208:211], v[76:79]
	v_mfma_f32_16x16x32_bf16 v[72:75], v[160:163], v[208:211], v[72:75]
	v_mfma_f32_16x16x32_bf16 v[124:127], v[156:159], v[188:191], v[124:127]
	v_mfma_f32_16x16x32_bf16 v[120:123], v[164:167], v[188:191], v[120:123]
	v_mfma_f32_16x16x32_bf16 v[108:111], v[156:159], v[196:199], v[108:111]
	v_mfma_f32_16x16x32_bf16 v[104:107], v[164:167], v[196:199], v[104:107]
	v_mfma_f32_16x16x32_bf16 v[92:95], v[156:159], v[204:207], v[92:95]
	v_mfma_f32_16x16x32_bf16 v[88:91], v[164:167], v[204:207], v[88:91]
	v_mfma_f32_16x16x32_bf16 v[76:79], v[156:159], v[212:215], v[76:79]
	v_mfma_f32_16x16x32_bf16 v[72:75], v[164:167], v[212:215], v[72:75]
	v_mfma_f32_16x16x32_bf16 v[116:119], v[168:171], v[184:187], v[116:119]
	v_mfma_f32_16x16x32_bf16 v[112:115], v[176:179], v[184:187], v[112:115]
	v_mfma_f32_16x16x32_bf16 v[100:103], v[168:171], v[192:195], v[100:103]
	v_mfma_f32_16x16x32_bf16 v[96:99], v[176:179], v[192:195], v[96:99]
	v_mfma_f32_16x16x32_bf16 v[84:87], v[168:171], v[200:203], v[84:87]
	v_mfma_f32_16x16x32_bf16 v[80:83], v[176:179], v[200:203], v[80:83]
	v_mfma_f32_16x16x32_bf16 v[68:71], v[168:171], v[208:211], v[68:71]
	v_mfma_f32_16x16x32_bf16 v[64:67], v[176:179], v[208:211], v[64:67]
	v_mfma_f32_16x16x32_bf16 v[116:119], v[172:175], v[188:191], v[116:119]
	v_mfma_f32_16x16x32_bf16 v[112:115], v[180:183], v[188:191], v[112:115]
	v_mfma_f32_16x16x32_bf16 v[100:103], v[172:175], v[196:199], v[100:103]
	v_mfma_f32_16x16x32_bf16 v[96:99], v[180:183], v[196:199], v[96:99]
	v_mfma_f32_16x16x32_bf16 v[84:87], v[172:175], v[204:207], v[84:87]
	v_mfma_f32_16x16x32_bf16 v[80:83], v[180:183], v[204:207], v[80:83]
	v_mfma_f32_16x16x32_bf16 v[68:71], v[172:175], v[212:215], v[68:71]
	v_mfma_f32_16x16x32_bf16 v[64:67], v[180:183], v[212:215], v[64:67]
	s_barrier
; __device__ __forceinline__ float fsilu(float v) { return v * fsigmoid(v); }
; __device__ __forceinline__ u32x4 pack8(const f32x4 a, const f32x4 b) { u32x4 w; w.x = cvt_pk_bf16(a[0], a[1]); w.y = cvt_pk_bf16(a[2], a[3]); w.z = cvt_pk_bf16(b[0], b[1]); w.w = cvt_pk_bf16(b[2], b[3]); return w; }
; #define PG8_STAGE(bufoff, gbase, voff) do { _Pragma("unroll") for (int _i = 0; _i < 2; ++_i) \
;         __builtin_amdgcn_global_load_lds((const unsigned*)((const char*)(gbase) + (voff)[_i]), (PG8_LAS unsigned*)(lds + (bufoff) + ldsw + _i * 8192), 16, 0, 0); } while (0)
; #define PG8_LDA(dst, b, h) do { _Pragma("unroll") for (int m = 0; m < 4; ++m) _Pragma("unroll") for (int k = 0; k < 2; ++k) dst[m][k] = *(const PG8_LAS bf16x8*)(lds + PG8_SA(b, h) + aoff + m * 2048 + k * 1024); } while (0)
; #define PG8_MMA(ai, bj, At, Bt) do { __builtin_amdgcn_s_setprio(1); _Pragma("unroll") for (int m = 0; m < 4; ++m) _Pragma("unroll") for (int n = 0; n < 2; ++n) _Pragma("unroll") for (int k = 0; k < 2; ++k) \
;         acc[ai][bj][m][n] = __builtin_amdgcn_mfma_f32_16x16x32_bf16(Bt[n][k], At[m][k], acc[ai][bj][m][n], 0, 0, 0); __builtin_amdgcn_s_setprio(0); } while (0)
; #define PG8_BAR __builtin_amdgcn_s_barrier()
;     __device__ __forceinline__ void operator()(const f32x4 (&acc)[2][2][4][2], const Unit& u, int wr, int wc, int fr, int fq) const {
;         const int row0 = u.pm * BM + wr * 64 + fr, col0 = u.pn * 128 + wc * 32 + 8 * fq;
; #pragma unroll
;         for (int ai = 0; ai < 2; ++ai)
; #pragma unroll
;             for (int m = 0; m < 4; ++m) {
;                 bf16_t* rowp = O + (size_t)(row0 + ai * HALF + m * 16) * ldc + col0;
;                 f32x4 h0, h1;
; #pragma unroll
;                 for (int j = 0; j < 4; ++j) { h0[j] = fsilu(acc[ai][0][m][0][j]) * acc[ai][1][m][0][j]; h1[j] = fsilu(acc[ai][0][m][1][j]) * acc[ai][1][m][1][j]; }
;                 *(u32x4*)rowp = pack8(h0, h1);
; template <class Epi, class Sched, bool ALIGN_EPI = false, bool SP2 = false>
; __device__ __forceinline__ void gemm_phase(PG8_LAS unsigned char* lds, const Gemm g, const Sched& S, const Epi& E) {
;     ...
;             PG8_LDA(At, 1, 1); PG8_STAGE(PG8_SB(1, 0), b3, voffB); PG8_STAGE(PG8_SB(1, 1), b3 + hstep, voffB); PG8_STAGE(PG8_SA(1, 0), a3, voffA);
;             PG8_WAIT_V(8); PG8_WAIT_L(0); PG8_BAR; PG8_MMA(1, 0, At, B0); PG8_MMA(1, 1, At, B1); PG8_BAR; PG8_SCHED;
	s_add_i32 s36, s62, s42
	s_add_u32 s86, s34, 0x80
	s_addc_u32 s87, s35, 0
	s_mov_b32 m0, s36
	ds_read_b128 v[184:187], v151 offset:49152
	ds_read_b128 v[188:191], v151 offset:50176
	ds_read_b128 v[192:195], v151 offset:51200
	ds_read_b128 v[196:199], v151 offset:52224
	ds_read_b128 v[200:203], v151 offset:53248
	ds_read_b128 v[204:207], v151 offset:54272
	ds_read_b128 v[208:211], v151 offset:55296
	ds_read_b128 v[212:215], v151 offset:56320
	global_load_lds_dwordx4 v132, s[86:87]
	s_add_i32 m0, s36, 0x2000
	s_add_u32 s34, s34, 0x80080
	s_addc_u32 s35, s35, 0
	s_add_i32 s36, s63, s42
	global_load_lds_dwordx4 v128, s[86:87]
	s_mov_b32 m0, s36
	s_nop 0
	global_load_lds_dwordx4 v132, s[34:35]
	s_add_i32 m0, s36, 0x2000
	s_nop 0
	global_load_lds_dwordx4 v128, s[34:35]
	s_mov_b32 m0, s49
	s_nop 0
	global_load_lds_dwordx4 v134, s[84:85]
	s_mov_b32 m0, s50
	s_nop 0
	global_load_lds_dwordx4 v130, s[84:85]
	s_waitcnt vmcnt(8) lgkmcnt(0)
	s_barrier
	v_mfma_f32_16x16x32_bf16 v[60:63], v[152:155], v[184:187], v[60:63]
	v_mfma_f32_16x16x32_bf16 v[56:59], v[160:163], v[184:187], v[56:59]
	v_mfma_f32_16x16x32_bf16 v[44:47], v[152:155], v[192:195], v[44:47]
	v_mfma_f32_16x16x32_bf16 v[40:43], v[160:163], v[192:195], v[40:43]
	v_mfma_f32_16x16x32_bf16 v[28:31], v[152:155], v[200:203], v[28:31]
	v_mfma_f32_16x16x32_bf16 v[24:27], v[160:163], v[200:203], v[24:27]
	v_mfma_f32_16x16x32_bf16 v[12:15], v[152:155], v[208:211], v[12:15]
	v_mfma_f32_16x16x32_bf16 v[8:11], v[160:163], v[208:211], v[8:11]
	v_mfma_f32_16x16x32_bf16 v[60:63], v[156:159], v[188:191], v[60:63]
	v_mfma_f32_16x16x32_bf16 v[56:59], v[164:167], v[188:191], v[56:59]
	v_mfma_f32_16x16x32_bf16 v[44:47], v[156:159], v[196:199], v[44:47]
	v_mfma_f32_16x16x32_bf16 v[40:43], v[164:167], v[196:199], v[40:43]
	v_mfma_f32_16x16x32_bf16 v[28:31], v[156:159], v[204:207], v[28:31]
	v_mfma_f32_16x16x32_bf16 v[24:27], v[164:167], v[204:207], v[24:27]
	v_mfma_f32_16x16x32_bf16 v[12:15], v[156:159], v[212:215], v[12:15]
	v_mfma_f32_16x16x32_bf16 v[8:11], v[164:167], v[212:215], v[8:11]
	v_mfma_f32_16x16x32_bf16 v[52:55], v[168:171], v[184:187], v[52:55]
	v_mfma_f32_16x16x32_bf16 v[48:51], v[176:179], v[184:187], v[48:51]
	v_mfma_f32_16x16x32_bf16 v[36:39], v[168:171], v[192:195], v[36:39]
	v_mfma_f32_16x16x32_bf16 v[32:35], v[176:179], v[192:195], v[32:35]
	v_mfma_f32_16x16x32_bf16 v[20:23], v[168:171], v[200:203], v[20:23]
	v_mfma_f32_16x16x32_bf16 v[16:19], v[176:179], v[200:203], v[16:19]
	v_mfma_f32_16x16x32_bf16 v[4:7], v[168:171], v[208:211], v[4:7]
	v_mfma_f32_16x16x32_bf16 v[0:3], v[176:179], v[208:211], v[0:3]
	v_mfma_f32_16x16x32_bf16 v[52:55], v[172:175], v[188:191], v[52:55]
	v_mfma_f32_16x16x32_bf16 v[48:51], v[180:183], v[188:191], v[48:51]
	v_mfma_f32_16x16x32_bf16 v[36:39], v[172:175], v[196:199], v[36:39]
	v_mfma_f32_16x16x32_bf16 v[32:35], v[180:183], v[196:199], v[32:35]
	v_mfma_f32_16x16x32_bf16 v[20:23], v[172:175], v[204:207], v[20:23]
	v_mfma_f32_16x16x32_bf16 v[16:19], v[180:183], v[204:207], v[16:19]
	v_mfma_f32_16x16x32_bf16 v[4:7], v[172:175], v[212:215], v[4:7]
	v_mfma_f32_16x16x32_bf16 v[0:3], v[180:183], v[212:215], v[0:3]
	s_barrier
	s_add_i32 s61, s61, 2
	s_add_u32 s30, s30, 0x100
	s_addc_u32 s31, s31, 0
	s_add_u32 s59, s59, 0x100
	s_addc_u32 s60, s60, 0
	s_cmp_gt_u32 s61, 29
	s_cbranch_scc0 .LBB0_945
	v_mul_f32_e32 v153, 0xbfb8aa3b, v124
	v_mul_f32_e32 v158, 0xbfb8aa3b, v120
	v_exp_f32_e32 v153, v153
	v_exp_f32_e32 v159, v158
	v_mul_f32_e32 v158, 0xbfb8aa3b, v125
	v_exp_f32_e32 v160, v158
	v_add_f32_e32 v153, 1.0, v153
	v_rcp_f32_e32 v158, v153
	v_add_f32_e32 v153, 1.0, v159
	v_add_f32_e32 v159, 1.0, v160
	v_rcp_f32_e32 v159, v159
	v_mul_f32_e32 v160, 0xbfb8aa3b, v121
	v_exp_f32_e32 v161, v160
	v_rcp_f32_e32 v160, v153
	v_pk_mul_f32 v[124:125], v[124:125], v[158:159]
	v_mul_f32_e32 v153, 0xbfb8aa3b, v127
	v_pk_mul_f32 v[116:117], v[124:125], v[116:117]
	v_add_f32_e32 v124, 1.0, v161
	v_mul_f32_e32 v125, 0xbfb8aa3b, v122
	v_rcp_f32_e32 v161, v124
	v_mul_f32_e32 v124, 0xbfb8aa3b, v126
	v_exp_f32_e32 v125, v125
	v_exp_f32_e32 v124, v124
	v_exp_f32_e32 v153, v153
	v_mul_f32_e32 v158, 0xbfb8aa3b, v123
	v_exp_f32_e32 v159, v158
	v_add_f32_e32 v125, 1.0, v125
	v_add_f32_e32 v124, 1.0, v124
	v_rcp_f32_e32 v158, v125
	v_add_f32_e32 v125, 1.0, v153
	v_rcp_f32_e32 v124, v124
	v_rcp_f32_e32 v125, v125
	v_add_f32_e32 v153, 1.0, v159
	v_rcp_f32_e32 v159, v153
	v_pk_mul_f32 v[120:121], v[120:121], v[160:161]
	v_lshl_or_b32 v154, s56, 7, v148
	v_pk_mul_f32 v[120:121], v[120:121], v[112:113]
	v_pk_mul_f32 v[112:113], v[126:127], v[124:125]
	v_lshl_add_u32 v152, s28, 8, v146
	v_ashrrev_i32_e32 v155, 31, v154
	v_mov_b64_e32 v[144:145], s[10:11]
	v_pk_mul_f32 v[118:119], v[112:113], v[118:119]
	v_pk_mul_f32 v[112:113], v[122:123], v[158:159]
	v_mad_i64_i32 v[156:157], s[30:31], v152, s55, v[144:145]
	v_pk_mul_f32 v[122:123], v[112:113], v[114:115]
	v_lshlrev_b64 v[112:113], 1, v[154:155]
	v_lshl_add_u64 v[124:125], v[156:157], 0, v[112:113]
	v_cvt_pk_bf16_f32 v114, v116, v117
	v_cvt_pk_bf16_f32 v115, v118, v119
	v_cvt_pk_bf16_f32 v116, v120, v121
	v_cvt_pk_bf16_f32 v117, v122, v123
	global_store_dwordx4 v[124:125], v[114:117], off
	v_mul_f32_e32 v118, 0xbfb8aa3b, v109
	v_exp_f32_e32 v118, v118
	v_mul_f32_e32 v116, 0xbfb8aa3b, v108
	v_mul_f32_e32 v117, 0xbfb8aa3b, v104
	v_exp_f32_e32 v116, v116
	v_exp_f32_e32 v117, v117
	v_or_b32_e32 v114, 16, v152
	v_mad_i64_i32 v[114:115], s[30:31], v114, s55, v[144:145]
	v_add_f32_e32 v116, 1.0, v116
	v_add_f32_e32 v119, 1.0, v117
	v_add_f32_e32 v117, 1.0, v118
	v_rcp_f32_e32 v116, v116
	v_rcp_f32_e32 v117, v117
	v_mul_f32_e32 v118, 0xbfb8aa3b, v105
; __device__ __forceinline__ float fsilu(float v) { return v * fsigmoid(v); }
; __device__ __forceinline__ u32x4 pack8(const f32x4 a, const f32x4 b) { u32x4 w; w.x = cvt_pk_bf16(a[0], a[1]); w.y = cvt_pk_bf16(a[2], a[3]); w.z = cvt_pk_bf16(b[0], b[1]); w.w = cvt_pk_bf16(b[2], b[3]); return w; }
;     __device__ __forceinline__ void operator()(const f32x4 (&acc)[2][2][4][2], const Unit& u, int wr, int wc, int fr, int fq) const {
;     ...
;         for (int ai = 0; ai < 2; ++ai)
; #pragma unroll
;             for (int m = 0; m < 4; ++m) {
;                 bf16_t* rowp = O + (size_t)(row0 + ai * HALF + m * 16) * ldc + col0;
;                 f32x4 h0, h1;
; #pragma unroll
;                 for (int j = 0; j < 4; ++j) { h0[j] = fsilu(acc[ai][0][m][0][j]) * acc[ai][1][m][0][j]; h1[j] = fsilu(acc[ai][0][m][1][j]) * acc[ai][1][m][1][j]; }
;                 *(u32x4*)rowp = pack8(h0, h1);
	v_exp_f32_e32 v120, v118
	v_rcp_f32_e32 v118, v119
	v_pk_mul_f32 v[108:109], v[108:109], v[116:117]
	v_mul_f32_e32 v116, 0xbfb8aa3b, v111
	v_pk_mul_f32 v[100:101], v[108:109], v[100:101]
	v_add_f32_e32 v108, 1.0, v120
	v_rcp_f32_e32 v119, v108
	v_mul_f32_e32 v109, 0xbfb8aa3b, v106
	v_mul_f32_e32 v108, 0xbfb8aa3b, v110
	v_exp_f32_e32 v109, v109
	v_exp_f32_e32 v108, v108
	v_exp_f32_e32 v117, v116
	v_mul_f32_e32 v116, 0xbfb8aa3b, v107
	v_pk_mul_f32 v[104:105], v[104:105], v[118:119]
	v_exp_f32_e32 v118, v116
	v_add_f32_e32 v109, 1.0, v109
	v_add_f32_e32 v108, 1.0, v108
	v_rcp_f32_e32 v116, v109
	v_add_f32_e32 v109, 1.0, v117
	v_rcp_f32_e32 v108, v108
	v_rcp_f32_e32 v109, v109
	v_add_f32_e32 v117, 1.0, v118
	v_rcp_f32_e32 v117, v117
	v_pk_mul_f32 v[104:105], v[104:105], v[96:97]
	v_pk_mul_f32 v[96:97], v[110:111], v[108:109]
	v_lshl_add_u64 v[108:109], v[114:115], 0, v[112:113]
	v_pk_mul_f32 v[102:103], v[96:97], v[102:103]
	v_pk_mul_f32 v[96:97], v[106:107], v[116:117]
	s_and_b64 vcc, exec, s[8:9]
	v_pk_mul_f32 v[106:107], v[96:97], v[98:99]
	v_cvt_pk_bf16_f32 v96, v100, v101
	v_cvt_pk_bf16_f32 v97, v102, v103
	v_cvt_pk_bf16_f32 v98, v104, v105
	v_cvt_pk_bf16_f32 v99, v106, v107
	global_store_dwordx4 v[108:109], v[96:99], off
	v_mul_f32_e32 v100, 0xbfb8aa3b, v93
	v_exp_f32_e32 v100, v100
	v_mul_f32_e32 v98, 0xbfb8aa3b, v92
	v_mul_f32_e32 v99, 0xbfb8aa3b, v88
	v_exp_f32_e32 v98, v98
	v_exp_f32_e32 v99, v99
	v_or_b32_e32 v96, 32, v152
	v_mad_i64_i32 v[96:97], s[30:31], v96, s55, v[144:145]
	v_add_f32_e32 v98, 1.0, v98
	v_add_f32_e32 v101, 1.0, v99
	v_add_f32_e32 v99, 1.0, v100
	v_rcp_f32_e32 v98, v98
	v_rcp_f32_e32 v99, v99
	v_mul_f32_e32 v100, 0xbfb8aa3b, v89
	v_exp_f32_e32 v102, v100
	v_rcp_f32_e32 v100, v101
	v_pk_mul_f32 v[92:93], v[92:93], v[98:99]
	v_mul_f32_e32 v98, 0xbfb8aa3b, v95
	v_pk_mul_f32 v[84:85], v[92:93], v[84:85]
	v_add_f32_e32 v92, 1.0, v102
	v_rcp_f32_e32 v101, v92
	v_mul_f32_e32 v93, 0xbfb8aa3b, v90
	v_mul_f32_e32 v92, 0xbfb8aa3b, v94
	v_exp_f32_e32 v93, v93
	v_exp_f32_e32 v92, v92
	v_exp_f32_e32 v99, v98
	v_mul_f32_e32 v98, 0xbfb8aa3b, v91
	v_pk_mul_f32 v[88:89], v[88:89], v[100:101]
	v_exp_f32_e32 v100, v98
	v_add_f32_e32 v93, 1.0, v93
	v_add_f32_e32 v92, 1.0, v92
	v_rcp_f32_e32 v98, v93
	v_add_f32_e32 v93, 1.0, v99
	v_rcp_f32_e32 v92, v92
	v_rcp_f32_e32 v93, v93
	v_add_f32_e32 v99, 1.0, v100
	v_rcp_f32_e32 v99, v99
	v_pk_mul_f32 v[88:89], v[88:89], v[80:81]
	v_pk_mul_f32 v[80:81], v[94:95], v[92:93]
	v_lshl_add_u64 v[92:93], v[96:97], 0, v[112:113]
	v_pk_mul_f32 v[86:87], v[80:81], v[86:87]
	v_pk_mul_f32 v[80:81], v[90:91], v[98:99]
	s_mov_b32 s56, s14
	v_pk_mul_f32 v[90:91], v[80:81], v[82:83]
	v_cvt_pk_bf16_f32 v80, v84, v85
	v_cvt_pk_bf16_f32 v81, v86, v87
	v_cvt_pk_bf16_f32 v82, v88, v89
	v_cvt_pk_bf16_f32 v83, v90, v91
	global_store_dwordx4 v[92:93], v[80:83], off
	v_mul_f32_e32 v84, 0xbfb8aa3b, v77
	v_exp_f32_e32 v84, v84
	v_mul_f32_e32 v82, 0xbfb8aa3b, v76
	v_mul_f32_e32 v83, 0xbfb8aa3b, v72
	v_exp_f32_e32 v82, v82
	v_exp_f32_e32 v83, v83
	v_or_b32_e32 v80, 48, v152
	v_mad_i64_i32 v[80:81], s[30:31], v80, s55, v[144:145]
	v_add_f32_e32 v82, 1.0, v82
	v_add_f32_e32 v85, 1.0, v83
	v_add_f32_e32 v83, 1.0, v84
	v_rcp_f32_e32 v82, v82
	v_rcp_f32_e32 v83, v83
	v_mul_f32_e32 v84, 0xbfb8aa3b, v73
	v_exp_f32_e32 v86, v84
	v_rcp_f32_e32 v84, v85
	v_pk_mul_f32 v[76:77], v[76:77], v[82:83]
	v_mul_f32_e32 v82, 0xbfb8aa3b, v79
	v_pk_mul_f32 v[68:69], v[76:77], v[68:69]
	v_add_f32_e32 v76, 1.0, v86
	v_rcp_f32_e32 v85, v76
	v_mul_f32_e32 v77, 0xbfb8aa3b, v74
	v_mul_f32_e32 v76, 0xbfb8aa3b, v78
	v_exp_f32_e32 v77, v77
	v_exp_f32_e32 v76, v76
	v_exp_f32_e32 v83, v82
	v_mul_f32_e32 v82, 0xbfb8aa3b, v75
	v_pk_mul_f32 v[72:73], v[72:73], v[84:85]
	v_exp_f32_e32 v84, v82
	v_add_f32_e32 v77, 1.0, v77
	v_add_f32_e32 v76, 1.0, v76
	v_rcp_f32_e32 v82, v77
	v_add_f32_e32 v77, 1.0, v83
	v_rcp_f32_e32 v76, v76
	v_rcp_f32_e32 v77, v77
	v_add_f32_e32 v83, 1.0, v84
	v_rcp_f32_e32 v83, v83
	v_pk_mul_f32 v[72:73], v[72:73], v[64:65]
	v_pk_mul_f32 v[64:65], v[78:79], v[76:77]
	v_lshl_add_u64 v[76:77], v[80:81], 0, v[112:113]
	v_pk_mul_f32 v[70:71], v[64:65], v[70:71]
	v_pk_mul_f32 v[64:65], v[74:75], v[82:83]
	s_mov_b32 s28, s22
	v_pk_mul_f32 v[74:75], v[64:65], v[66:67]
	v_cvt_pk_bf16_f32 v64, v68, v69
	v_cvt_pk_bf16_f32 v65, v70, v71
	v_cvt_pk_bf16_f32 v66, v72, v73
	v_cvt_pk_bf16_f32 v67, v74, v75
	global_store_dwordx4 v[76:77], v[64:67], off
	v_mul_f32_e32 v68, 0xbfb8aa3b, v61
	v_exp_f32_e32 v68, v68
	v_mul_f32_e32 v66, 0xbfb8aa3b, v60
	v_mul_f32_e32 v67, 0xbfb8aa3b, v56
	v_exp_f32_e32 v66, v66
	v_exp_f32_e32 v67, v67
	v_add_u32_e32 v64, 0x80, v152
	v_mad_i64_i32 v[64:65], s[30:31], v64, s55, v[144:145]
	v_add_f32_e32 v66, 1.0, v66
	v_add_f32_e32 v69, 1.0, v67
	v_add_f32_e32 v67, 1.0, v68
	v_rcp_f32_e32 v66, v66
	v_rcp_f32_e32 v67, v67
	v_mul_f32_e32 v68, 0xbfb8aa3b, v57
	v_exp_f32_e32 v70, v68
	v_rcp_f32_e32 v68, v69
	v_pk_mul_f32 v[60:61], v[60:61], v[66:67]
	v_mul_f32_e32 v66, 0xbfb8aa3b, v63
	v_pk_mul_f32 v[52:53], v[60:61], v[52:53]
	v_add_f32_e32 v60, 1.0, v70
	v_rcp_f32_e32 v69, v60
	v_mul_f32_e32 v61, 0xbfb8aa3b, v58
	v_mul_f32_e32 v60, 0xbfb8aa3b, v62
	v_exp_f32_e32 v61, v61
	v_exp_f32_e32 v60, v60
	v_exp_f32_e32 v67, v66
	v_mul_f32_e32 v66, 0xbfb8aa3b, v59
	v_pk_mul_f32 v[56:57], v[56:57], v[68:69]
	v_exp_f32_e32 v68, v66
	v_add_f32_e32 v61, 1.0, v61
	v_add_f32_e32 v60, 1.0, v60
	v_rcp_f32_e32 v66, v61
; __device__ __forceinline__ float fsilu(float v) { return v * fsigmoid(v); }
; __device__ __forceinline__ u32x4 pack8(const f32x4 a, const f32x4 b) { u32x4 w; w.x = cvt_pk_bf16(a[0], a[1]); w.y = cvt_pk_bf16(a[2], a[3]); w.z = cvt_pk_bf16(b[0], b[1]); w.w = cvt_pk_bf16(b[2], b[3]); return w; }
; #define PG8_WAIT_V(n) asm volatile("s_waitcnt vmcnt(" #n ")" ::: "memory")
; #define PG8_BAR __builtin_amdgcn_s_barrier()
;     __device__ __forceinline__ void operator()(const f32x4 (&acc)[2][2][4][2], const Unit& u, int wr, int wc, int fr, int fq) const {
;     ...
;         for (int ai = 0; ai < 2; ++ai)
; #pragma unroll
;             for (int m = 0; m < 4; ++m) {
;                 bf16_t* rowp = O + (size_t)(row0 + ai * HALF + m * 16) * ldc + col0;
;                 f32x4 h0, h1;
; #pragma unroll
;                 for (int j = 0; j < 4; ++j) { h0[j] = fsilu(acc[ai][0][m][0][j]) * acc[ai][1][m][0][j]; h1[j] = fsilu(acc[ai][0][m][1][j]) * acc[ai][1][m][1][j]; }
;                 *(u32x4*)rowp = pack8(h0, h1);
; template <class Epi, class Sched, bool ALIGN_EPI = false, bool SP2 = false>
; __device__ __forceinline__ void gemm_phase(PG8_LAS unsigned char* lds, const Gemm g, const Sched& S, const Epi& E) {
;     ...
;         if (!has_next) break;
; #pragma unroll
;         for (int a = 0; a < 2; ++a)
; #pragma unroll
;             for (int b = 0; b < 2; ++b)
; #pragma unroll
;                 for (int m = 0; m < 4; ++m)
; #pragma unroll
;                     for (int n = 0; n < 2; ++n) acc[a][b][m][n] = (f32x4){0.f, 0.f, 0.f, 0.f};
;         cur = nxt; cA = nA; cB = nB; ++ui;
;         if constexpr (ALIGN_EPI) { if (wr == 1) PG8_BAR; }
;     }
;     PG8_WAIT_V(0);
;     if constexpr (!ALIGN_EPI) { if (wr == 0) PG8_BAR; }
;     PG8_BAR;
	v_add_f32_e32 v61, 1.0, v67
	v_rcp_f32_e32 v60, v60
	v_rcp_f32_e32 v61, v61
	v_add_f32_e32 v67, 1.0, v68
	v_rcp_f32_e32 v67, v67
	v_pk_mul_f32 v[56:57], v[56:57], v[48:49]
	v_pk_mul_f32 v[48:49], v[62:63], v[60:61]
	v_lshl_add_u64 v[60:61], v[64:65], 0, v[112:113]
	v_pk_mul_f32 v[54:55], v[48:49], v[54:55]
	v_pk_mul_f32 v[48:49], v[58:59], v[66:67]
	s_mov_b64 s[34:35], s[26:27]
	v_pk_mul_f32 v[58:59], v[48:49], v[50:51]
	v_cvt_pk_bf16_f32 v48, v52, v53
	v_cvt_pk_bf16_f32 v49, v54, v55
	v_cvt_pk_bf16_f32 v50, v56, v57
	v_cvt_pk_bf16_f32 v51, v58, v59
	global_store_dwordx4 v[60:61], v[48:51], off
	v_mul_f32_e32 v52, 0xbfb8aa3b, v45
	v_exp_f32_e32 v52, v52
	v_mul_f32_e32 v50, 0xbfb8aa3b, v44
	v_mul_f32_e32 v51, 0xbfb8aa3b, v40
	v_exp_f32_e32 v50, v50
	v_exp_f32_e32 v51, v51
	v_add_u32_e32 v48, 0x90, v152
	v_mad_i64_i32 v[48:49], s[30:31], v48, s55, v[144:145]
	v_add_f32_e32 v50, 1.0, v50
	v_add_f32_e32 v53, 1.0, v51
	v_add_f32_e32 v51, 1.0, v52
	v_rcp_f32_e32 v50, v50
	v_rcp_f32_e32 v51, v51
	v_mul_f32_e32 v52, 0xbfb8aa3b, v41
	v_exp_f32_e32 v54, v52
	v_rcp_f32_e32 v52, v53
	v_pk_mul_f32 v[44:45], v[44:45], v[50:51]
	v_mul_f32_e32 v50, 0xbfb8aa3b, v47
	v_pk_mul_f32 v[36:37], v[44:45], v[36:37]
	v_add_f32_e32 v44, 1.0, v54
	v_rcp_f32_e32 v53, v44
	v_mul_f32_e32 v45, 0xbfb8aa3b, v42
	v_mul_f32_e32 v44, 0xbfb8aa3b, v46
	v_exp_f32_e32 v45, v45
	v_exp_f32_e32 v44, v44
	v_exp_f32_e32 v51, v50
	v_mul_f32_e32 v50, 0xbfb8aa3b, v43
	v_pk_mul_f32 v[40:41], v[40:41], v[52:53]
	v_exp_f32_e32 v52, v50
	v_add_f32_e32 v45, 1.0, v45
	v_add_f32_e32 v44, 1.0, v44
	v_rcp_f32_e32 v50, v45
	v_add_f32_e32 v45, 1.0, v51
	v_rcp_f32_e32 v44, v44
	v_rcp_f32_e32 v45, v45
	v_add_f32_e32 v51, 1.0, v52
	v_rcp_f32_e32 v51, v51
	v_pk_mul_f32 v[40:41], v[40:41], v[32:33]
	v_pk_mul_f32 v[32:33], v[46:47], v[44:45]
	v_lshl_add_u64 v[44:45], v[48:49], 0, v[112:113]
	v_pk_mul_f32 v[38:39], v[32:33], v[38:39]
	v_pk_mul_f32 v[32:33], v[42:43], v[50:51]
	s_nop 0
	v_pk_mul_f32 v[42:43], v[32:33], v[34:35]
	v_cvt_pk_bf16_f32 v32, v36, v37
	v_cvt_pk_bf16_f32 v33, v38, v39
	v_cvt_pk_bf16_f32 v34, v40, v41
	v_cvt_pk_bf16_f32 v35, v42, v43
	global_store_dwordx4 v[44:45], v[32:35], off
	v_mul_f32_e32 v36, 0xbfb8aa3b, v29
	v_exp_f32_e32 v36, v36
	v_mul_f32_e32 v34, 0xbfb8aa3b, v28
	v_mul_f32_e32 v35, 0xbfb8aa3b, v24
	v_exp_f32_e32 v34, v34
	v_exp_f32_e32 v35, v35
	v_add_u32_e32 v32, 0xa0, v152
	v_mad_i64_i32 v[32:33], s[30:31], v32, s55, v[144:145]
	v_add_f32_e32 v34, 1.0, v34
	v_add_f32_e32 v37, 1.0, v35
	v_add_f32_e32 v35, 1.0, v36
	v_rcp_f32_e32 v34, v34
	v_rcp_f32_e32 v35, v35
	v_mul_f32_e32 v36, 0xbfb8aa3b, v25
	v_exp_f32_e32 v38, v36
	v_rcp_f32_e32 v36, v37
	v_pk_mul_f32 v[28:29], v[28:29], v[34:35]
	v_mul_f32_e32 v34, 0xbfb8aa3b, v31
	v_pk_mul_f32 v[20:21], v[28:29], v[20:21]
	v_add_f32_e32 v28, 1.0, v38
	v_rcp_f32_e32 v37, v28
	v_mul_f32_e32 v29, 0xbfb8aa3b, v26
	v_mul_f32_e32 v28, 0xbfb8aa3b, v30
	v_exp_f32_e32 v29, v29
	v_exp_f32_e32 v28, v28
	v_exp_f32_e32 v35, v34
	v_mul_f32_e32 v34, 0xbfb8aa3b, v27
	v_pk_mul_f32 v[24:25], v[24:25], v[36:37]
	v_exp_f32_e32 v36, v34
	v_add_f32_e32 v29, 1.0, v29
	v_add_f32_e32 v28, 1.0, v28
	v_rcp_f32_e32 v34, v29
	v_add_f32_e32 v29, 1.0, v35
	v_rcp_f32_e32 v28, v28
	v_rcp_f32_e32 v29, v29
	v_add_f32_e32 v35, 1.0, v36
	v_rcp_f32_e32 v35, v35
	v_pk_mul_f32 v[24:25], v[24:25], v[16:17]
	v_pk_mul_f32 v[16:17], v[30:31], v[28:29]
	v_lshl_add_u64 v[28:29], v[32:33], 0, v[112:113]
	v_pk_mul_f32 v[22:23], v[16:17], v[22:23]
	v_pk_mul_f32 v[16:17], v[26:27], v[34:35]
	s_nop 0
	v_pk_mul_f32 v[26:27], v[16:17], v[18:19]
	v_cvt_pk_bf16_f32 v16, v20, v21
	v_cvt_pk_bf16_f32 v17, v22, v23
	v_cvt_pk_bf16_f32 v18, v24, v25
	v_cvt_pk_bf16_f32 v19, v26, v27
	global_store_dwordx4 v[28:29], v[16:19], off
	v_mul_f32_e32 v20, 0xbfb8aa3b, v13
	v_exp_f32_e32 v20, v20
	v_mul_f32_e32 v18, 0xbfb8aa3b, v12
	v_mul_f32_e32 v19, 0xbfb8aa3b, v8
	v_exp_f32_e32 v18, v18
	v_exp_f32_e32 v19, v19
	v_add_u32_e32 v16, 0xb0, v152
	v_mad_i64_i32 v[16:17], s[30:31], v16, s55, v[144:145]
	v_add_f32_e32 v18, 1.0, v18
	v_add_f32_e32 v21, 1.0, v19
	v_add_f32_e32 v19, 1.0, v20
	v_rcp_f32_e32 v18, v18
	v_rcp_f32_e32 v19, v19
	v_mul_f32_e32 v20, 0xbfb8aa3b, v9
	v_exp_f32_e32 v22, v20
	v_rcp_f32_e32 v20, v21
	v_pk_mul_f32 v[12:13], v[12:13], v[18:19]
	v_mul_f32_e32 v18, 0xbfb8aa3b, v15
	v_pk_mul_f32 v[4:5], v[12:13], v[4:5]
	v_add_f32_e32 v12, 1.0, v22
	v_rcp_f32_e32 v21, v12
	v_mul_f32_e32 v13, 0xbfb8aa3b, v10
	v_mul_f32_e32 v12, 0xbfb8aa3b, v14
	v_exp_f32_e32 v13, v13
	v_exp_f32_e32 v12, v12
	v_exp_f32_e32 v19, v18
	v_mul_f32_e32 v18, 0xbfb8aa3b, v11
	v_pk_mul_f32 v[8:9], v[8:9], v[20:21]
	v_exp_f32_e32 v20, v18
	v_add_f32_e32 v13, 1.0, v13
	v_add_f32_e32 v12, 1.0, v12
	v_rcp_f32_e32 v18, v13
	v_add_f32_e32 v13, 1.0, v19
	v_rcp_f32_e32 v12, v12
	v_rcp_f32_e32 v13, v13
	v_add_f32_e32 v19, 1.0, v20
	v_rcp_f32_e32 v19, v19
	v_pk_mul_f32 v[8:9], v[8:9], v[0:1]
	v_pk_mul_f32 v[0:1], v[14:15], v[12:13]
	v_lshl_add_u64 v[12:13], v[16:17], 0, v[112:113]
	v_pk_mul_f32 v[6:7], v[0:1], v[6:7]
	v_pk_mul_f32 v[0:1], v[10:11], v[18:19]
	s_mov_b64 s[30:31], s[24:25]
	v_pk_mul_f32 v[10:11], v[0:1], v[2:3]
	v_cvt_pk_bf16_f32 v0, v4, v5
	v_cvt_pk_bf16_f32 v1, v6, v7
	v_cvt_pk_bf16_f32 v2, v8, v9
	v_cvt_pk_bf16_f32 v3, v10, v11
	global_store_dwordx4 v[12:13], v[0:3], off
	s_cbranch_vccz .LBB0_942
	s_waitcnt vmcnt(0)
	s_cmpk_gt_u32 s3, 0xff
	s_cbranch_scc1 .LBB0_949
	s_barrier

; #define PG8_STAGE(bufoff, gbase, voff) do { _Pragma("unroll") for (int _i = 0; _i < 2; ++_i) \
;         __builtin_amdgcn_global_load_lds((const unsigned*)((const char*)(gbase) + (voff)[_i]), (PG8_LAS unsigned*)(lds + (bufoff) + ldsw + _i * 8192), 16, 0, 0); } while (0)
; #define PG8_LDA(dst, b, h) do { _Pragma("unroll") for (int m = 0; m < 4; ++m) _Pragma("unroll") for (int k = 0; k < 2; ++k) dst[m][k] = *(const PG8_LAS bf16x8*)(lds + PG8_SA(b, h) + aoff + m * 2048 + k * 1024); } while (0)
; #define PG8_LDB(dst, b, h) do { _Pragma("unroll") for (int n = 0; n < 2; ++n) _Pragma("unroll") for (int k = 0; k < 2; ++k) dst[n][k] = *(const PG8_LAS bf16x8*)(lds + PG8_SB(b, h) + boff + n * 2048 + k * 1024); } while (0)
; #define PG8_WAIT_V(n) asm volatile("s_waitcnt vmcnt(" #n ")" ::: "memory")
; #define PG8_WAIT_L(n) asm volatile("s_waitcnt lgkmcnt(" #n ")" ::: "memory")
; #define PG8_BAR __builtin_amdgcn_s_barrier()
; #define PG8_SCHED __builtin_amdgcn_sched_barrier(0)
; template <class Epi, class Sched, bool ALIGN_EPI = false, bool SP2 = false>
; __device__ __forceinline__ void gemm_phase(PG8_LAS unsigned char* lds, const Gemm g, const Sched& S, const Epi& E) {
;     ...
;         const bool has_next = S.next(ui + 1, nxt);
;         const char* nA = has_next ? (const char*)g.A + (size_t)nxt.pm * tstep : cA; const char* nB = has_next ? (const char*)g.Bt + (size_t)nxt.pn * tstep : cB;
;         for (int t = 0; t < nt; t += 2) {
;             const bool last = (t == nt - 2);
;             const char* a1 = cA + (size_t)(t + 1) * kstep;
;             const char* a2 = last ? nA : cA + (size_t)(t + 2) * kstep; const char* b2 = last ? nB : cB + (size_t)(t + 2) * kstep;
;             const char* a3 = a2 + kstep; const char* b3 = b2 + kstep;
;             if (last && has_next) S.a_ready(nxt);
;             if constexpr (SP2) {
;             PG8_LDB(B0, 0, 0); PG8_LDB(B1, 0, 1); PG8_SCHED; PG8_LDA(At, 0, 0); PG8_STAGE(PG8_SA(1, 1), a1 + hstep, voffA);
;             PG8_WAIT_V(8); PG8_WAIT_L(0); PG8_BAR; PG8_MMA(0, 0, At, B0); PG8_MMA(0, 1, At, B1); PG8_BAR; PG8_SCHED;
;             PG8_LDA(At, 0, 1); PG8_STAGE(PG8_SB(0, 0), b2, voffB); PG8_STAGE(PG8_SB(0, 1), b2 + hstep, voffB); PG8_STAGE(PG8_SA(0, 0), a2, voffA);
;             PG8_WAIT_V(8); PG8_WAIT_L(0); PG8_BAR; PG8_MMA(1, 0, At, B0); PG8_MMA(1, 1, At, B1); PG8_BAR; PG8_SCHED;
.LBB0_1020:
	s_add_u32 s54, s26, 0x100
	s_addc_u32 s55, s27, 0
	s_mov_b32 s56, -2
	v_add_u32_e32 v164, 0x18000, v167
	v_add_u32_e32 v165, 0x1c000, v167
	ds_read_b128 v[144:147], v169
	ds_read_b128 v[148:151], v169 offset:1024
	ds_read_b128 v[152:155], v169 offset:2048
	ds_read_b128 v[156:159], v169 offset:3072
	ds_read_b128 v[160:163], v170
	ds_read_b128 v[172:175], v170 offset:1024
	ds_read_b128 v[176:179], v170 offset:2048
	ds_read_b128 v[180:183], v170 offset:3072
	s_add_u32 s26, s24, 0x100
	s_addc_u32 s27, s25, 0
	s_cmpk_eq_i32 s56, 0x54
	s_cselect_b32 s31, s5, s27
	s_cselect_b32 s30, s4, s26
	s_cselect_b32 s29, s7, s55
	s_cselect_b32 s28, s6, s54
	s_add_i32 m0, s38, 0xc000
	ds_read_b128 v[184:187], v171
	ds_read_b128 v[188:191], v171 offset:1024
	ds_read_b128 v[192:195], v171 offset:2048
	ds_read_b128 v[196:199], v171 offset:3072
	ds_read_b128 v[200:203], v171 offset:4096
	ds_read_b128 v[204:207], v171 offset:5120
	ds_read_b128 v[208:211], v171 offset:6144
	ds_read_b128 v[212:215], v171 offset:7168
	global_load_lds_dwordx4 v136, s[24:25]
	s_add_i32 m0, s38, 0xe000
	s_nop 0
	global_load_lds_dwordx4 v138, s[24:25]
	s_waitcnt vmcnt(8) lgkmcnt(0)
	s_barrier
	v_mfma_f32_16x16x32_bf16 v[124:127], v[144:147], v[184:187], 0
	v_mfma_f32_16x16x32_bf16 v[120:123], v[152:155], v[184:187], 0
	v_mfma_f32_16x16x32_bf16 v[116:119], v[144:147], v[192:195], 0
	v_mfma_f32_16x16x32_bf16 v[112:115], v[152:155], v[192:195], 0
	v_mfma_f32_16x16x32_bf16 v[108:111], v[144:147], v[200:203], 0
	v_mfma_f32_16x16x32_bf16 v[96:99], v[152:155], v[200:203], 0
	v_mfma_f32_16x16x32_bf16 v[84:87], v[144:147], v[208:211], 0
	v_mfma_f32_16x16x32_bf16 v[76:79], v[152:155], v[208:211], 0
	v_mfma_f32_16x16x32_bf16 v[124:127], v[148:151], v[188:191], v[124:127]
	v_mfma_f32_16x16x32_bf16 v[120:123], v[156:159], v[188:191], v[120:123]
	v_mfma_f32_16x16x32_bf16 v[116:119], v[148:151], v[196:199], v[116:119]
	v_mfma_f32_16x16x32_bf16 v[112:115], v[156:159], v[196:199], v[112:115]
	v_mfma_f32_16x16x32_bf16 v[108:111], v[148:151], v[204:207], v[108:111]
	v_mfma_f32_16x16x32_bf16 v[96:99], v[156:159], v[204:207], v[96:99]
	v_mfma_f32_16x16x32_bf16 v[84:87], v[148:151], v[212:215], v[84:87]
	v_mfma_f32_16x16x32_bf16 v[76:79], v[156:159], v[212:215], v[76:79]
	v_mfma_f32_16x16x32_bf16 v[104:107], v[160:163], v[184:187], 0
	v_mfma_f32_16x16x32_bf16 v[100:103], v[176:179], v[184:187], 0
	v_mfma_f32_16x16x32_bf16 v[92:95], v[160:163], v[192:195], 0
	v_mfma_f32_16x16x32_bf16 v[88:91], v[176:179], v[192:195], 0
	v_mfma_f32_16x16x32_bf16 v[80:83], v[160:163], v[200:203], 0
	v_mfma_f32_16x16x32_bf16 v[72:75], v[176:179], v[200:203], 0
	v_mfma_f32_16x16x32_bf16 v[68:71], v[160:163], v[208:211], 0
	v_mfma_f32_16x16x32_bf16 v[64:67], v[176:179], v[208:211], 0
	v_mfma_f32_16x16x32_bf16 v[104:107], v[172:175], v[188:191], v[104:107]
	v_mfma_f32_16x16x32_bf16 v[100:103], v[180:183], v[188:191], v[100:103]
	v_mfma_f32_16x16x32_bf16 v[92:95], v[172:175], v[196:199], v[92:95]
	v_mfma_f32_16x16x32_bf16 v[88:91], v[180:183], v[196:199], v[88:91]
	v_mfma_f32_16x16x32_bf16 v[80:83], v[172:175], v[204:207], v[80:83]
	v_mfma_f32_16x16x32_bf16 v[72:75], v[180:183], v[204:207], v[72:75]
	v_mfma_f32_16x16x32_bf16 v[68:71], v[172:175], v[212:215], v[68:71]
	v_mfma_f32_16x16x32_bf16 v[64:67], v[180:183], v[212:215], v[64:67]
	s_barrier
	s_add_i32 s24, s48, s37
	s_mov_b32 m0, s24
	ds_read_b128 v[184:187], v171 offset:16384
	ds_read_b128 v[188:191], v171 offset:17408
	ds_read_b128 v[192:195], v171 offset:18432
	ds_read_b128 v[196:199], v171 offset:19456
	ds_read_b128 v[200:203], v171 offset:20480
	ds_read_b128 v[204:207], v171 offset:21504
	ds_read_b128 v[208:211], v171 offset:22528
	ds_read_b128 v[212:215], v171 offset:23552
	global_load_lds_dwordx4 v130, s[28:29]
	s_add_i32 m0, s24, 0x2000
	s_add_u32 s24, s28, 0x160000
	s_addc_u32 s25, s29, 0
	s_add_i32 s57, s49, s37
	global_load_lds_dwordx4 v134, s[28:29]
	s_mov_b32 m0, s57
	s_nop 0
	global_load_lds_dwordx4 v130, s[24:25]
	s_add_i32 m0, s57, 0x2000
	s_nop 0
	global_load_lds_dwordx4 v134, s[24:25]
	s_mov_b32 m0, s38
	s_nop 0
	global_load_lds_dwordx4 v128, s[30:31]
	s_mov_b32 m0, s39
	s_nop 0
	global_load_lds_dwordx4 v132, s[30:31]
	s_waitcnt vmcnt(8) lgkmcnt(0)
	s_barrier
	v_mfma_f32_16x16x32_bf16 v[60:63], v[144:147], v[184:187], 0
	v_mfma_f32_16x16x32_bf16 v[56:59], v[152:155], v[184:187], 0
	v_mfma_f32_16x16x32_bf16 v[52:55], v[144:147], v[192:195], 0
	v_mfma_f32_16x16x32_bf16 v[48:51], v[152:155], v[192:195], 0
	v_mfma_f32_16x16x32_bf16 v[44:47], v[144:147], v[200:203], 0
	v_mfma_f32_16x16x32_bf16 v[32:35], v[152:155], v[200:203], 0
	v_mfma_f32_16x16x32_bf16 v[20:23], v[144:147], v[208:211], 0
	v_mfma_f32_16x16x32_bf16 v[12:15], v[152:155], v[208:211], 0
	v_mfma_f32_16x16x32_bf16 v[60:63], v[148:151], v[188:191], v[60:63]
	v_mfma_f32_16x16x32_bf16 v[56:59], v[156:159], v[188:191], v[56:59]
	v_mfma_f32_16x16x32_bf16 v[52:55], v[148:151], v[196:199], v[52:55]
	v_mfma_f32_16x16x32_bf16 v[48:51], v[156:159], v[196:199], v[48:51]
	v_mfma_f32_16x16x32_bf16 v[44:47], v[148:151], v[204:207], v[44:47]
	v_mfma_f32_16x16x32_bf16 v[32:35], v[156:159], v[204:207], v[32:35]
	v_mfma_f32_16x16x32_bf16 v[20:23], v[148:151], v[212:215], v[20:23]
	v_mfma_f32_16x16x32_bf16 v[12:15], v[156:159], v[212:215], v[12:15]
	v_mfma_f32_16x16x32_bf16 v[40:43], v[160:163], v[184:187], 0
	v_mfma_f32_16x16x32_bf16 v[36:39], v[176:179], v[184:187], 0
	v_mfma_f32_16x16x32_bf16 v[28:31], v[160:163], v[192:195], 0
	v_mfma_f32_16x16x32_bf16 v[24:27], v[176:179], v[192:195], 0
	v_mfma_f32_16x16x32_bf16 v[16:19], v[160:163], v[200:203], 0
	v_mfma_f32_16x16x32_bf16 v[8:11], v[176:179], v[200:203], 0
	v_mfma_f32_16x16x32_bf16 v[4:7], v[160:163], v[208:211], 0
	v_mfma_f32_16x16x32_bf16 v[0:3], v[176:179], v[208:211], 0
	v_mfma_f32_16x16x32_bf16 v[40:43], v[172:175], v[188:191], v[40:43]
	v_mfma_f32_16x16x32_bf16 v[36:39], v[180:183], v[188:191], v[36:39]
	v_mfma_f32_16x16x32_bf16 v[28:31], v[172:175], v[196:199], v[28:31]
	v_mfma_f32_16x16x32_bf16 v[24:27], v[180:183], v[196:199], v[24:27]
	v_mfma_f32_16x16x32_bf16 v[16:19], v[172:175], v[204:207], v[16:19]
	v_mfma_f32_16x16x32_bf16 v[8:11], v[180:183], v[204:207], v[8:11]
	v_mfma_f32_16x16x32_bf16 v[4:7], v[172:175], v[212:215], v[4:7]
	v_mfma_f32_16x16x32_bf16 v[0:3], v[180:183], v[212:215], v[0:3]
	s_barrier
; #define PG8_STAGE(bufoff, gbase, voff) do { _Pragma("unroll") for (int _i = 0; _i < 2; ++_i) \
;         __builtin_amdgcn_global_load_lds((const unsigned*)((const char*)(gbase) + (voff)[_i]), (PG8_LAS unsigned*)(lds + (bufoff) + ldsw + _i * 8192), 16, 0, 0); } while (0)
; #define PG8_LDA(dst, b, h) do { _Pragma("unroll") for (int m = 0; m < 4; ++m) _Pragma("unroll") for (int k = 0; k < 2; ++k) dst[m][k] = *(const PG8_LAS bf16x8*)(lds + PG8_SA(b, h) + aoff + m * 2048 + k * 1024); } while (0)
; #define PG8_LDB(dst, b, h) do { _Pragma("unroll") for (int n = 0; n < 2; ++n) _Pragma("unroll") for (int k = 0; k < 2; ++k) dst[n][k] = *(const PG8_LAS bf16x8*)(lds + PG8_SB(b, h) + boff + n * 2048 + k * 1024); } while (0)
; #define PG8_MMA(ai, bj, At, Bt) do { __builtin_amdgcn_s_setprio(1); _Pragma("unroll") for (int m = 0; m < 4; ++m) _Pragma("unroll") for (int n = 0; n < 2; ++n) _Pragma("unroll") for (int k = 0; k < 2; ++k) \
;         acc[ai][bj][m][n] = __builtin_amdgcn_mfma_f32_16x16x32_bf16(Bt[n][k], At[m][k], acc[ai][bj][m][n], 0, 0, 0); __builtin_amdgcn_s_setprio(0); } while (0)
; #define PG8_WAIT_V(n) asm volatile("s_waitcnt vmcnt(" #n ")" ::: "memory")
; #define PG8_WAIT_L(n) asm volatile("s_waitcnt lgkmcnt(" #n ")" ::: "memory")
; #define PG8_BAR __builtin_amdgcn_s_barrier()
; #define PG8_SCHED __builtin_amdgcn_sched_barrier(0)
; template <class Epi, class Sched, bool ALIGN_EPI = false, bool SP2 = false>
; __device__ __forceinline__ void gemm_phase(PG8_LAS unsigned char* lds, const Gemm g, const Sched& S, const Epi& E) {
;     ...
;             PG8_WAIT_V(8); PG8_WAIT_L(0); PG8_BAR; PG8_MMA(1, 0, At, B0); PG8_MMA(1, 1, At, B1); PG8_BAR; PG8_SCHED;
;             PG8_LDB(B0, 1, 0); PG8_LDB(B1, 1, 1); PG8_SCHED; PG8_LDA(At, 1, 0); PG8_STAGE(PG8_SA(0, 1), a2 + hstep, voffA);
;             PG8_WAIT_V(8); PG8_WAIT_L(0); PG8_BAR; PG8_MMA(0, 0, At, B0); PG8_MMA(0, 1, At, B1); PG8_BAR; PG8_SCHED;
;             PG8_LDA(At, 1, 1); PG8_STAGE(PG8_SB(1, 0), b3, voffB); PG8_STAGE(PG8_SB(1, 1), b3 + hstep, voffB); PG8_STAGE(PG8_SA(1, 0), a3, voffA);
;             PG8_WAIT_V(8); PG8_WAIT_L(0); PG8_BAR; PG8_MMA(1, 0, At, B0); PG8_MMA(1, 1, At, B1); PG8_BAR; PG8_SCHED;
	s_add_i32 s57, 0, 0x18000
	s_add_i32 s58, 0, 0x1c000
	ds_read_b128 v[144:147], v164
	ds_read_b128 v[148:151], v164 offset:1024
	ds_read_b128 v[152:155], v164 offset:2048
	ds_read_b128 v[156:159], v164 offset:3072
	ds_read_b128 v[160:163], v165
	ds_read_b128 v[172:175], v165 offset:1024
	ds_read_b128 v[176:179], v165 offset:2048
	ds_read_b128 v[180:183], v165 offset:3072
	s_add_u32 s24, s30, 0x160000
	s_addc_u32 s25, s31, 0
	s_mov_b32 m0, s40
	ds_read_b128 v[184:187], v171 offset:32768
	ds_read_b128 v[188:191], v171 offset:33792
	ds_read_b128 v[192:195], v171 offset:34816
	ds_read_b128 v[196:199], v171 offset:35840
	ds_read_b128 v[200:203], v171 offset:36864
	ds_read_b128 v[204:207], v171 offset:37888
	ds_read_b128 v[208:211], v171 offset:38912
	ds_read_b128 v[212:215], v171 offset:39936
	global_load_lds_dwordx4 v128, s[24:25]
	s_mov_b32 m0, s41
	s_nop 0
	global_load_lds_dwordx4 v132, s[24:25]
	s_waitcnt vmcnt(8) lgkmcnt(0)
	s_barrier
	v_mfma_f32_16x16x32_bf16 v[124:127], v[144:147], v[184:187], v[124:127]
	v_mfma_f32_16x16x32_bf16 v[120:123], v[152:155], v[184:187], v[120:123]
	v_mfma_f32_16x16x32_bf16 v[116:119], v[144:147], v[192:195], v[116:119]
	v_mfma_f32_16x16x32_bf16 v[112:115], v[152:155], v[192:195], v[112:115]
	v_mfma_f32_16x16x32_bf16 v[108:111], v[144:147], v[200:203], v[108:111]
	v_mfma_f32_16x16x32_bf16 v[96:99], v[152:155], v[200:203], v[96:99]
	v_mfma_f32_16x16x32_bf16 v[84:87], v[144:147], v[208:211], v[84:87]
	v_mfma_f32_16x16x32_bf16 v[76:79], v[152:155], v[208:211], v[76:79]
	v_mfma_f32_16x16x32_bf16 v[124:127], v[148:151], v[188:191], v[124:127]
	v_mfma_f32_16x16x32_bf16 v[120:123], v[156:159], v[188:191], v[120:123]
	v_mfma_f32_16x16x32_bf16 v[116:119], v[148:151], v[196:199], v[116:119]
	v_mfma_f32_16x16x32_bf16 v[112:115], v[156:159], v[196:199], v[112:115]
	v_mfma_f32_16x16x32_bf16 v[108:111], v[148:151], v[204:207], v[108:111]
	v_mfma_f32_16x16x32_bf16 v[96:99], v[156:159], v[204:207], v[96:99]
	v_mfma_f32_16x16x32_bf16 v[84:87], v[148:151], v[212:215], v[84:87]
	v_mfma_f32_16x16x32_bf16 v[76:79], v[156:159], v[212:215], v[76:79]
	v_mfma_f32_16x16x32_bf16 v[104:107], v[160:163], v[184:187], v[104:107]
	v_mfma_f32_16x16x32_bf16 v[100:103], v[176:179], v[184:187], v[100:103]
	v_mfma_f32_16x16x32_bf16 v[92:95], v[160:163], v[192:195], v[92:95]
	v_mfma_f32_16x16x32_bf16 v[88:91], v[176:179], v[192:195], v[88:91]
	v_mfma_f32_16x16x32_bf16 v[80:83], v[160:163], v[200:203], v[80:83]
	v_mfma_f32_16x16x32_bf16 v[72:75], v[176:179], v[200:203], v[72:75]
	v_mfma_f32_16x16x32_bf16 v[68:71], v[160:163], v[208:211], v[68:71]
	v_mfma_f32_16x16x32_bf16 v[64:67], v[176:179], v[208:211], v[64:67]
	v_mfma_f32_16x16x32_bf16 v[104:107], v[172:175], v[188:191], v[104:107]
	v_mfma_f32_16x16x32_bf16 v[100:103], v[180:183], v[188:191], v[100:103]
	v_mfma_f32_16x16x32_bf16 v[92:95], v[172:175], v[196:199], v[92:95]
	v_mfma_f32_16x16x32_bf16 v[88:91], v[180:183], v[196:199], v[88:91]
	v_mfma_f32_16x16x32_bf16 v[80:83], v[172:175], v[204:207], v[80:83]
	v_mfma_f32_16x16x32_bf16 v[72:75], v[180:183], v[204:207], v[72:75]
	v_mfma_f32_16x16x32_bf16 v[68:71], v[172:175], v[212:215], v[68:71]
	v_mfma_f32_16x16x32_bf16 v[64:67], v[180:183], v[212:215], v[64:67]
	s_barrier
	s_add_i32 s24, s57, s37
	s_add_u32 s86, s28, 0x80
	s_addc_u32 s87, s29, 0
	s_mov_b32 m0, s24
	ds_read_b128 v[184:187], v171 offset:49152
	ds_read_b128 v[188:191], v171 offset:50176
	ds_read_b128 v[192:195], v171 offset:51200
	ds_read_b128 v[196:199], v171 offset:52224
	ds_read_b128 v[200:203], v171 offset:53248
	ds_read_b128 v[204:207], v171 offset:54272
	ds_read_b128 v[208:211], v171 offset:55296
	ds_read_b128 v[212:215], v171 offset:56320
	global_load_lds_dwordx4 v130, s[86:87]
	s_add_i32 m0, s24, 0x2000
	s_add_u32 s24, s28, 0x160080
	s_addc_u32 s25, s29, 0
	s_add_i32 s28, s58, s37
	global_load_lds_dwordx4 v134, s[86:87]
	s_mov_b32 m0, s28
	s_nop 0
	global_load_lds_dwordx4 v130, s[24:25]
	s_add_i32 m0, s28, 0x2000
	s_nop 0
	global_load_lds_dwordx4 v134, s[24:25]
	s_add_u32 s84, s30, 0x80
	s_addc_u32 s85, s31, 0
	s_mov_b32 m0, s45
	s_nop 0
	global_load_lds_dwordx4 v128, s[84:85]
	s_mov_b32 m0, s46
	s_nop 0
	global_load_lds_dwordx4 v132, s[84:85]
	s_waitcnt vmcnt(8) lgkmcnt(0)
	s_barrier
	v_mfma_f32_16x16x32_bf16 v[60:63], v[144:147], v[184:187], v[60:63]
	v_mfma_f32_16x16x32_bf16 v[56:59], v[152:155], v[184:187], v[56:59]
	v_mfma_f32_16x16x32_bf16 v[52:55], v[144:147], v[192:195], v[52:55]
	v_mfma_f32_16x16x32_bf16 v[48:51], v[152:155], v[192:195], v[48:51]
	v_mfma_f32_16x16x32_bf16 v[44:47], v[144:147], v[200:203], v[44:47]
	v_mfma_f32_16x16x32_bf16 v[32:35], v[152:155], v[200:203], v[32:35]
	v_mfma_f32_16x16x32_bf16 v[20:23], v[144:147], v[208:211], v[20:23]
	v_mfma_f32_16x16x32_bf16 v[12:15], v[152:155], v[208:211], v[12:15]
	v_mfma_f32_16x16x32_bf16 v[60:63], v[148:151], v[188:191], v[60:63]
	v_mfma_f32_16x16x32_bf16 v[56:59], v[156:159], v[188:191], v[56:59]
	v_mfma_f32_16x16x32_bf16 v[52:55], v[148:151], v[196:199], v[52:55]
	v_mfma_f32_16x16x32_bf16 v[48:51], v[156:159], v[196:199], v[48:51]
	v_mfma_f32_16x16x32_bf16 v[44:47], v[148:151], v[204:207], v[44:47]
	v_mfma_f32_16x16x32_bf16 v[32:35], v[156:159], v[204:207], v[32:35]
	v_mfma_f32_16x16x32_bf16 v[20:23], v[148:151], v[212:215], v[20:23]
	v_mfma_f32_16x16x32_bf16 v[12:15], v[156:159], v[212:215], v[12:15]
	v_mfma_f32_16x16x32_bf16 v[40:43], v[160:163], v[184:187], v[40:43]
	v_mfma_f32_16x16x32_bf16 v[36:39], v[176:179], v[184:187], v[36:39]
	v_mfma_f32_16x16x32_bf16 v[28:31], v[160:163], v[192:195], v[28:31]
	v_mfma_f32_16x16x32_bf16 v[24:27], v[176:179], v[192:195], v[24:27]
	v_mfma_f32_16x16x32_bf16 v[16:19], v[160:163], v[200:203], v[16:19]
	v_mfma_f32_16x16x32_bf16 v[8:11], v[176:179], v[200:203], v[8:11]
	v_mfma_f32_16x16x32_bf16 v[4:7], v[160:163], v[208:211], v[4:7]
	v_mfma_f32_16x16x32_bf16 v[0:3], v[176:179], v[208:211], v[0:3]
	v_mfma_f32_16x16x32_bf16 v[40:43], v[172:175], v[188:191], v[40:43]
	v_mfma_f32_16x16x32_bf16 v[36:39], v[180:183], v[188:191], v[36:39]
	v_mfma_f32_16x16x32_bf16 v[28:31], v[172:175], v[196:199], v[28:31]
	v_mfma_f32_16x16x32_bf16 v[24:27], v[180:183], v[196:199], v[24:27]
	v_mfma_f32_16x16x32_bf16 v[16:19], v[172:175], v[204:207], v[16:19]
	v_mfma_f32_16x16x32_bf16 v[8:11], v[180:183], v[204:207], v[8:11]
	v_mfma_f32_16x16x32_bf16 v[4:7], v[172:175], v[212:215], v[4:7]
	v_mfma_f32_16x16x32_bf16 v[0:3], v[180:183], v[212:215], v[0:3]
	s_barrier
	s_add_i32 s56, s56, 2
	s_add_u32 s54, s54, 0x100
	s_addc_u32 s55, s55, 0
	s_cmpk_gt_u32 s56, 0x55
	s_mov_b64 s[24:25], s[26:27]
; #define PG8_STAGE(bufoff, gbase, voff) do { _Pragma("unroll") for (int _i = 0; _i < 2; ++_i) \
;         __builtin_amdgcn_global_load_lds((const unsigned*)((const char*)(gbase) + (voff)[_i]), (PG8_LAS unsigned*)(lds + (bufoff) + ldsw + _i * 8192), 16, 0, 0); } while (0)
; #define PG8_LDA(dst, b, h) do { _Pragma("unroll") for (int m = 0; m < 4; ++m) _Pragma("unroll") for (int k = 0; k < 2; ++k) dst[m][k] = *(const PG8_LAS bf16x8*)(lds + PG8_SA(b, h) + aoff + m * 2048 + k * 1024); } while (0)
; #define PG8_LDB(dst, b, h) do { _Pragma("unroll") for (int n = 0; n < 2; ++n) _Pragma("unroll") for (int k = 0; k < 2; ++k) dst[n][k] = *(const PG8_LAS bf16x8*)(lds + PG8_SB(b, h) + boff + n * 2048 + k * 1024); } while (0)
; #define PG8_MMA(ai, bj, At, Bt) do { __builtin_amdgcn_s_setprio(1); _Pragma("unroll") for (int m = 0; m < 4; ++m) _Pragma("unroll") for (int n = 0; n < 2; ++n) _Pragma("unroll") for (int k = 0; k < 2; ++k) \
;         acc[ai][bj][m][n] = __builtin_amdgcn_mfma_f32_16x16x32_bf16(Bt[n][k], At[m][k], acc[ai][bj][m][n], 0, 0, 0); __builtin_amdgcn_s_setprio(0); } while (0)
; #define PG8_WAIT_V(n) asm volatile("s_waitcnt vmcnt(" #n ")" ::: "memory")
; #define PG8_WAIT_L(n) asm volatile("s_waitcnt lgkmcnt(" #n ")" ::: "memory")
; #define PG8_BAR __builtin_amdgcn_s_barrier()
; #define PG8_SCHED __builtin_amdgcn_sched_barrier(0)
; template <class Epi, class Sched, bool ALIGN_EPI = false, bool SP2 = false>
; __device__ __forceinline__ void gemm_phase(PG8_LAS unsigned char* lds, const Gemm g, const Sched& S, const Epi& E) {
;     ...
;             PG8_LDB(B0, 0, 0); PG8_LDB(B1, 0, 1); PG8_SCHED; PG8_LDA(At, 0, 0); PG8_STAGE(PG8_SA(1, 1), a1 + hstep, voffA);
;             PG8_WAIT_V(8); PG8_WAIT_L(0); PG8_BAR; PG8_MMA(0, 0, At, B0); PG8_MMA(0, 1, At, B1); PG8_BAR; PG8_SCHED;
;             PG8_LDA(At, 0, 1); PG8_STAGE(PG8_SB(0, 0), b2, voffB); PG8_STAGE(PG8_SB(0, 1), b2 + hstep, voffB); PG8_STAGE(PG8_SA(0, 0), a2, voffA);
;             PG8_WAIT_V(8); PG8_WAIT_L(0); PG8_BAR; PG8_MMA(1, 0, At, B0); PG8_MMA(1, 1, At, B1); PG8_BAR; PG8_SCHED;
.LBB0_1021:
	ds_read_b128 v[144:147], v169
	ds_read_b128 v[148:151], v169 offset:1024
	ds_read_b128 v[152:155], v169 offset:2048
	ds_read_b128 v[156:159], v169 offset:3072
	ds_read_b128 v[160:163], v170
	ds_read_b128 v[172:175], v170 offset:1024
	ds_read_b128 v[176:179], v170 offset:2048
	ds_read_b128 v[180:183], v170 offset:3072
	s_add_u32 s26, s24, 0x100
	s_addc_u32 s27, s25, 0
	s_cmpk_eq_i32 s56, 0x54
	s_cselect_b32 s31, s5, s27
	s_cselect_b32 s30, s4, s26
	s_cselect_b32 s29, s7, s55
	s_cselect_b32 s28, s6, s54
	s_add_i32 m0, s38, 0xc000
	ds_read_b128 v[184:187], v171
	ds_read_b128 v[188:191], v171 offset:1024
	ds_read_b128 v[192:195], v171 offset:2048
	ds_read_b128 v[196:199], v171 offset:3072
	ds_read_b128 v[200:203], v171 offset:4096
	ds_read_b128 v[204:207], v171 offset:5120
	ds_read_b128 v[208:211], v171 offset:6144
	ds_read_b128 v[212:215], v171 offset:7168
	global_load_lds_dwordx4 v136, s[24:25]
	s_add_i32 m0, s38, 0xe000
	s_nop 0
	global_load_lds_dwordx4 v138, s[24:25]
	s_waitcnt vmcnt(8) lgkmcnt(0)
	s_barrier
	v_mfma_f32_16x16x32_bf16 v[124:127], v[144:147], v[184:187], v[124:127]
	v_mfma_f32_16x16x32_bf16 v[120:123], v[152:155], v[184:187], v[120:123]
	v_mfma_f32_16x16x32_bf16 v[116:119], v[144:147], v[192:195], v[116:119]
	v_mfma_f32_16x16x32_bf16 v[112:115], v[152:155], v[192:195], v[112:115]
	v_mfma_f32_16x16x32_bf16 v[108:111], v[144:147], v[200:203], v[108:111]
	v_mfma_f32_16x16x32_bf16 v[96:99], v[152:155], v[200:203], v[96:99]
	v_mfma_f32_16x16x32_bf16 v[84:87], v[144:147], v[208:211], v[84:87]
	v_mfma_f32_16x16x32_bf16 v[76:79], v[152:155], v[208:211], v[76:79]
	v_mfma_f32_16x16x32_bf16 v[124:127], v[148:151], v[188:191], v[124:127]
	v_mfma_f32_16x16x32_bf16 v[120:123], v[156:159], v[188:191], v[120:123]
	v_mfma_f32_16x16x32_bf16 v[116:119], v[148:151], v[196:199], v[116:119]
	v_mfma_f32_16x16x32_bf16 v[112:115], v[156:159], v[196:199], v[112:115]
	v_mfma_f32_16x16x32_bf16 v[108:111], v[148:151], v[204:207], v[108:111]
	v_mfma_f32_16x16x32_bf16 v[96:99], v[156:159], v[204:207], v[96:99]
	v_mfma_f32_16x16x32_bf16 v[84:87], v[148:151], v[212:215], v[84:87]
	v_mfma_f32_16x16x32_bf16 v[76:79], v[156:159], v[212:215], v[76:79]
	v_mfma_f32_16x16x32_bf16 v[104:107], v[160:163], v[184:187], v[104:107]
	v_mfma_f32_16x16x32_bf16 v[100:103], v[176:179], v[184:187], v[100:103]
	v_mfma_f32_16x16x32_bf16 v[92:95], v[160:163], v[192:195], v[92:95]
	v_mfma_f32_16x16x32_bf16 v[88:91], v[176:179], v[192:195], v[88:91]
	v_mfma_f32_16x16x32_bf16 v[80:83], v[160:163], v[200:203], v[80:83]
	v_mfma_f32_16x16x32_bf16 v[72:75], v[176:179], v[200:203], v[72:75]
	v_mfma_f32_16x16x32_bf16 v[68:71], v[160:163], v[208:211], v[68:71]
	v_mfma_f32_16x16x32_bf16 v[64:67], v[176:179], v[208:211], v[64:67]
	v_mfma_f32_16x16x32_bf16 v[104:107], v[172:175], v[188:191], v[104:107]
	v_mfma_f32_16x16x32_bf16 v[100:103], v[180:183], v[188:191], v[100:103]
	v_mfma_f32_16x16x32_bf16 v[92:95], v[172:175], v[196:199], v[92:95]
	v_mfma_f32_16x16x32_bf16 v[88:91], v[180:183], v[196:199], v[88:91]
	v_mfma_f32_16x16x32_bf16 v[80:83], v[172:175], v[204:207], v[80:83]
	v_mfma_f32_16x16x32_bf16 v[72:75], v[180:183], v[204:207], v[72:75]
	v_mfma_f32_16x16x32_bf16 v[68:71], v[172:175], v[212:215], v[68:71]
	v_mfma_f32_16x16x32_bf16 v[64:67], v[180:183], v[212:215], v[64:67]
	s_barrier
	s_add_i32 s24, s48, s37
	s_mov_b32 m0, s24
	ds_read_b128 v[184:187], v171 offset:16384
	ds_read_b128 v[188:191], v171 offset:17408
	ds_read_b128 v[192:195], v171 offset:18432
	ds_read_b128 v[196:199], v171 offset:19456
	ds_read_b128 v[200:203], v171 offset:20480
	ds_read_b128 v[204:207], v171 offset:21504
	ds_read_b128 v[208:211], v171 offset:22528
	ds_read_b128 v[212:215], v171 offset:23552
	global_load_lds_dwordx4 v130, s[28:29]
	s_add_i32 m0, s24, 0x2000
	s_add_u32 s24, s28, 0x160000
	s_addc_u32 s25, s29, 0
	s_add_i32 s57, s49, s37
	global_load_lds_dwordx4 v134, s[28:29]
	s_mov_b32 m0, s57
	s_nop 0
	global_load_lds_dwordx4 v130, s[24:25]
	s_add_i32 m0, s57, 0x2000
	s_nop 0
	global_load_lds_dwordx4 v134, s[24:25]
	s_mov_b32 m0, s38
	s_nop 0
	global_load_lds_dwordx4 v128, s[30:31]
	s_mov_b32 m0, s39
	s_nop 0
	global_load_lds_dwordx4 v132, s[30:31]
	s_waitcnt vmcnt(8) lgkmcnt(0)
	s_barrier
	v_mfma_f32_16x16x32_bf16 v[60:63], v[144:147], v[184:187], v[60:63]
	v_mfma_f32_16x16x32_bf16 v[56:59], v[152:155], v[184:187], v[56:59]
	v_mfma_f32_16x16x32_bf16 v[52:55], v[144:147], v[192:195], v[52:55]
	v_mfma_f32_16x16x32_bf16 v[48:51], v[152:155], v[192:195], v[48:51]
	v_mfma_f32_16x16x32_bf16 v[44:47], v[144:147], v[200:203], v[44:47]
	v_mfma_f32_16x16x32_bf16 v[32:35], v[152:155], v[200:203], v[32:35]
	v_mfma_f32_16x16x32_bf16 v[20:23], v[144:147], v[208:211], v[20:23]
	v_mfma_f32_16x16x32_bf16 v[12:15], v[152:155], v[208:211], v[12:15]
	v_mfma_f32_16x16x32_bf16 v[60:63], v[148:151], v[188:191], v[60:63]
	v_mfma_f32_16x16x32_bf16 v[56:59], v[156:159], v[188:191], v[56:59]
	v_mfma_f32_16x16x32_bf16 v[52:55], v[148:151], v[196:199], v[52:55]
	v_mfma_f32_16x16x32_bf16 v[48:51], v[156:159], v[196:199], v[48:51]
	v_mfma_f32_16x16x32_bf16 v[44:47], v[148:151], v[204:207], v[44:47]
	v_mfma_f32_16x16x32_bf16 v[32:35], v[156:159], v[204:207], v[32:35]
	v_mfma_f32_16x16x32_bf16 v[20:23], v[148:151], v[212:215], v[20:23]
	v_mfma_f32_16x16x32_bf16 v[12:15], v[156:159], v[212:215], v[12:15]
	v_mfma_f32_16x16x32_bf16 v[40:43], v[160:163], v[184:187], v[40:43]
	v_mfma_f32_16x16x32_bf16 v[36:39], v[176:179], v[184:187], v[36:39]
	v_mfma_f32_16x16x32_bf16 v[28:31], v[160:163], v[192:195], v[28:31]
	v_mfma_f32_16x16x32_bf16 v[24:27], v[176:179], v[192:195], v[24:27]
	v_mfma_f32_16x16x32_bf16 v[16:19], v[160:163], v[200:203], v[16:19]
	v_mfma_f32_16x16x32_bf16 v[8:11], v[176:179], v[200:203], v[8:11]
	v_mfma_f32_16x16x32_bf16 v[4:7], v[160:163], v[208:211], v[4:7]
	v_mfma_f32_16x16x32_bf16 v[0:3], v[176:179], v[208:211], v[0:3]
	v_mfma_f32_16x16x32_bf16 v[40:43], v[172:175], v[188:191], v[40:43]
	v_mfma_f32_16x16x32_bf16 v[36:39], v[180:183], v[188:191], v[36:39]
	v_mfma_f32_16x16x32_bf16 v[28:31], v[172:175], v[196:199], v[28:31]
	v_mfma_f32_16x16x32_bf16 v[24:27], v[180:183], v[196:199], v[24:27]
	v_mfma_f32_16x16x32_bf16 v[16:19], v[172:175], v[204:207], v[16:19]
	v_mfma_f32_16x16x32_bf16 v[8:11], v[180:183], v[204:207], v[8:11]
	v_mfma_f32_16x16x32_bf16 v[4:7], v[172:175], v[212:215], v[4:7]
	v_mfma_f32_16x16x32_bf16 v[0:3], v[180:183], v[212:215], v[0:3]
	s_barrier
; #define PG8_STAGE(bufoff, gbase, voff) do { _Pragma("unroll") for (int _i = 0; _i < 2; ++_i) \
;         __builtin_amdgcn_global_load_lds((const unsigned*)((const char*)(gbase) + (voff)[_i]), (PG8_LAS unsigned*)(lds + (bufoff) + ldsw + _i * 8192), 16, 0, 0); } while (0)
; #define PG8_LDA(dst, b, h) do { _Pragma("unroll") for (int m = 0; m < 4; ++m) _Pragma("unroll") for (int k = 0; k < 2; ++k) dst[m][k] = *(const PG8_LAS bf16x8*)(lds + PG8_SA(b, h) + aoff + m * 2048 + k * 1024); } while (0)
; #define PG8_LDB(dst, b, h) do { _Pragma("unroll") for (int n = 0; n < 2; ++n) _Pragma("unroll") for (int k = 0; k < 2; ++k) dst[n][k] = *(const PG8_LAS bf16x8*)(lds + PG8_SB(b, h) + boff + n * 2048 + k * 1024); } while (0)
; #define PG8_MMA(ai, bj, At, Bt) do { __builtin_amdgcn_s_setprio(1); _Pragma("unroll") for (int m = 0; m < 4; ++m) _Pragma("unroll") for (int n = 0; n < 2; ++n) _Pragma("unroll") for (int k = 0; k < 2; ++k) \
;         acc[ai][bj][m][n] = __builtin_amdgcn_mfma_f32_16x16x32_bf16(Bt[n][k], At[m][k], acc[ai][bj][m][n], 0, 0, 0); __builtin_amdgcn_s_setprio(0); } while (0)
; #define PG8_WAIT_V(n) asm volatile("s_waitcnt vmcnt(" #n ")" ::: "memory")
; #define PG8_WAIT_L(n) asm volatile("s_waitcnt lgkmcnt(" #n ")" ::: "memory")
; #define PG8_BAR __builtin_amdgcn_s_barrier()
; #define PG8_SCHED __builtin_amdgcn_sched_barrier(0)
; template <class Epi, class Sched, bool ALIGN_EPI = false, bool SP2 = false>
; __device__ __forceinline__ void gemm_phase(PG8_LAS unsigned char* lds, const Gemm g, const Sched& S, const Epi& E) {
;     ...
;             PG8_LDB(B0, 1, 0); PG8_LDB(B1, 1, 1); PG8_SCHED; PG8_LDA(At, 1, 0); PG8_STAGE(PG8_SA(0, 1), a2 + hstep, voffA);
;             PG8_WAIT_V(8); PG8_WAIT_L(0); PG8_BAR; PG8_MMA(0, 0, At, B0); PG8_MMA(0, 1, At, B1); PG8_BAR; PG8_SCHED;
;             PG8_LDA(At, 1, 1); PG8_STAGE(PG8_SB(1, 0), b3, voffB); PG8_STAGE(PG8_SB(1, 1), b3 + hstep, voffB); PG8_STAGE(PG8_SA(1, 0), a3, voffA);
;             PG8_WAIT_V(8); PG8_WAIT_L(0); PG8_BAR; PG8_MMA(1, 0, At, B0); PG8_MMA(1, 1, At, B1); PG8_BAR; PG8_SCHED;
	s_add_i32 s57, 0, 0x18000
	s_add_i32 s58, 0, 0x1c000
	ds_read_b128 v[144:147], v164
	ds_read_b128 v[148:151], v164 offset:1024
	ds_read_b128 v[152:155], v164 offset:2048
	ds_read_b128 v[156:159], v164 offset:3072
	ds_read_b128 v[160:163], v165
	ds_read_b128 v[172:175], v165 offset:1024
	ds_read_b128 v[176:179], v165 offset:2048
	ds_read_b128 v[180:183], v165 offset:3072
	s_add_u32 s24, s30, 0x160000
	s_addc_u32 s25, s31, 0
	s_mov_b32 m0, s40
	ds_read_b128 v[184:187], v171 offset:32768
	ds_read_b128 v[188:191], v171 offset:33792
	ds_read_b128 v[192:195], v171 offset:34816
	ds_read_b128 v[196:199], v171 offset:35840
	ds_read_b128 v[200:203], v171 offset:36864
	ds_read_b128 v[204:207], v171 offset:37888
	ds_read_b128 v[208:211], v171 offset:38912
	ds_read_b128 v[212:215], v171 offset:39936
	global_load_lds_dwordx4 v128, s[24:25]
	s_mov_b32 m0, s41
	s_nop 0
	global_load_lds_dwordx4 v132, s[24:25]
	s_waitcnt vmcnt(8) lgkmcnt(0)
	s_barrier
	v_mfma_f32_16x16x32_bf16 v[124:127], v[144:147], v[184:187], v[124:127]
	v_mfma_f32_16x16x32_bf16 v[120:123], v[152:155], v[184:187], v[120:123]
	v_mfma_f32_16x16x32_bf16 v[116:119], v[144:147], v[192:195], v[116:119]
	v_mfma_f32_16x16x32_bf16 v[112:115], v[152:155], v[192:195], v[112:115]
	v_mfma_f32_16x16x32_bf16 v[108:111], v[144:147], v[200:203], v[108:111]
	v_mfma_f32_16x16x32_bf16 v[96:99], v[152:155], v[200:203], v[96:99]
	v_mfma_f32_16x16x32_bf16 v[84:87], v[144:147], v[208:211], v[84:87]
	v_mfma_f32_16x16x32_bf16 v[76:79], v[152:155], v[208:211], v[76:79]
	v_mfma_f32_16x16x32_bf16 v[124:127], v[148:151], v[188:191], v[124:127]
	v_mfma_f32_16x16x32_bf16 v[120:123], v[156:159], v[188:191], v[120:123]
	v_mfma_f32_16x16x32_bf16 v[116:119], v[148:151], v[196:199], v[116:119]
	v_mfma_f32_16x16x32_bf16 v[112:115], v[156:159], v[196:199], v[112:115]
	v_mfma_f32_16x16x32_bf16 v[108:111], v[148:151], v[204:207], v[108:111]
	v_mfma_f32_16x16x32_bf16 v[96:99], v[156:159], v[204:207], v[96:99]
	v_mfma_f32_16x16x32_bf16 v[84:87], v[148:151], v[212:215], v[84:87]
	v_mfma_f32_16x16x32_bf16 v[76:79], v[156:159], v[212:215], v[76:79]
	v_mfma_f32_16x16x32_bf16 v[104:107], v[160:163], v[184:187], v[104:107]
	v_mfma_f32_16x16x32_bf16 v[100:103], v[176:179], v[184:187], v[100:103]
	v_mfma_f32_16x16x32_bf16 v[92:95], v[160:163], v[192:195], v[92:95]
	v_mfma_f32_16x16x32_bf16 v[88:91], v[176:179], v[192:195], v[88:91]
	v_mfma_f32_16x16x32_bf16 v[80:83], v[160:163], v[200:203], v[80:83]
	v_mfma_f32_16x16x32_bf16 v[72:75], v[176:179], v[200:203], v[72:75]
	v_mfma_f32_16x16x32_bf16 v[68:71], v[160:163], v[208:211], v[68:71]
	v_mfma_f32_16x16x32_bf16 v[64:67], v[176:179], v[208:211], v[64:67]
	v_mfma_f32_16x16x32_bf16 v[104:107], v[172:175], v[188:191], v[104:107]
	v_mfma_f32_16x16x32_bf16 v[100:103], v[180:183], v[188:191], v[100:103]
	v_mfma_f32_16x16x32_bf16 v[92:95], v[172:175], v[196:199], v[92:95]
	v_mfma_f32_16x16x32_bf16 v[88:91], v[180:183], v[196:199], v[88:91]
	v_mfma_f32_16x16x32_bf16 v[80:83], v[172:175], v[204:207], v[80:83]
	v_mfma_f32_16x16x32_bf16 v[72:75], v[180:183], v[204:207], v[72:75]
	v_mfma_f32_16x16x32_bf16 v[68:71], v[172:175], v[212:215], v[68:71]
	v_mfma_f32_16x16x32_bf16 v[64:67], v[180:183], v[212:215], v[64:67]
	s_barrier
	s_add_i32 s24, s57, s37
	s_add_u32 s86, s28, 0x80
	s_addc_u32 s87, s29, 0
	s_mov_b32 m0, s24
	ds_read_b128 v[184:187], v171 offset:49152
	ds_read_b128 v[188:191], v171 offset:50176
	ds_read_b128 v[192:195], v171 offset:51200
	ds_read_b128 v[196:199], v171 offset:52224
	ds_read_b128 v[200:203], v171 offset:53248
	ds_read_b128 v[204:207], v171 offset:54272
	ds_read_b128 v[208:211], v171 offset:55296
	ds_read_b128 v[212:215], v171 offset:56320
	global_load_lds_dwordx4 v130, s[86:87]
	s_add_i32 m0, s24, 0x2000
	s_add_u32 s24, s28, 0x160080
	s_addc_u32 s25, s29, 0
	s_add_i32 s28, s58, s37
	global_load_lds_dwordx4 v134, s[86:87]
	s_mov_b32 m0, s28
	s_nop 0
	global_load_lds_dwordx4 v130, s[24:25]
	s_add_i32 m0, s28, 0x2000
	s_nop 0
	global_load_lds_dwordx4 v134, s[24:25]
	s_add_u32 s84, s30, 0x80
	s_addc_u32 s85, s31, 0
	s_mov_b32 m0, s45
	s_nop 0
	global_load_lds_dwordx4 v128, s[84:85]
	s_mov_b32 m0, s46
	s_nop 0
	global_load_lds_dwordx4 v132, s[84:85]
	s_waitcnt vmcnt(8) lgkmcnt(0)
	s_barrier
	v_mfma_f32_16x16x32_bf16 v[60:63], v[144:147], v[184:187], v[60:63]
	v_mfma_f32_16x16x32_bf16 v[56:59], v[152:155], v[184:187], v[56:59]
	v_mfma_f32_16x16x32_bf16 v[52:55], v[144:147], v[192:195], v[52:55]
	v_mfma_f32_16x16x32_bf16 v[48:51], v[152:155], v[192:195], v[48:51]
	v_mfma_f32_16x16x32_bf16 v[44:47], v[144:147], v[200:203], v[44:47]
	v_mfma_f32_16x16x32_bf16 v[32:35], v[152:155], v[200:203], v[32:35]
	v_mfma_f32_16x16x32_bf16 v[20:23], v[144:147], v[208:211], v[20:23]
	v_mfma_f32_16x16x32_bf16 v[12:15], v[152:155], v[208:211], v[12:15]
	v_mfma_f32_16x16x32_bf16 v[60:63], v[148:151], v[188:191], v[60:63]
	v_mfma_f32_16x16x32_bf16 v[56:59], v[156:159], v[188:191], v[56:59]
	v_mfma_f32_16x16x32_bf16 v[52:55], v[148:151], v[196:199], v[52:55]
	v_mfma_f32_16x16x32_bf16 v[48:51], v[156:159], v[196:199], v[48:51]
	v_mfma_f32_16x16x32_bf16 v[44:47], v[148:151], v[204:207], v[44:47]
	v_mfma_f32_16x16x32_bf16 v[32:35], v[156:159], v[204:207], v[32:35]
	v_mfma_f32_16x16x32_bf16 v[20:23], v[148:151], v[212:215], v[20:23]
	v_mfma_f32_16x16x32_bf16 v[12:15], v[156:159], v[212:215], v[12:15]
	v_mfma_f32_16x16x32_bf16 v[40:43], v[160:163], v[184:187], v[40:43]
	v_mfma_f32_16x16x32_bf16 v[36:39], v[176:179], v[184:187], v[36:39]
	v_mfma_f32_16x16x32_bf16 v[28:31], v[160:163], v[192:195], v[28:31]
	v_mfma_f32_16x16x32_bf16 v[24:27], v[176:179], v[192:195], v[24:27]
	v_mfma_f32_16x16x32_bf16 v[16:19], v[160:163], v[200:203], v[16:19]
	v_mfma_f32_16x16x32_bf16 v[8:11], v[176:179], v[200:203], v[8:11]
	v_mfma_f32_16x16x32_bf16 v[4:7], v[160:163], v[208:211], v[4:7]
	v_mfma_f32_16x16x32_bf16 v[0:3], v[176:179], v[208:211], v[0:3]
	v_mfma_f32_16x16x32_bf16 v[40:43], v[172:175], v[188:191], v[40:43]
	v_mfma_f32_16x16x32_bf16 v[36:39], v[180:183], v[188:191], v[36:39]
	v_mfma_f32_16x16x32_bf16 v[28:31], v[172:175], v[196:199], v[28:31]
	v_mfma_f32_16x16x32_bf16 v[24:27], v[180:183], v[196:199], v[24:27]
	v_mfma_f32_16x16x32_bf16 v[16:19], v[172:175], v[204:207], v[16:19]
	v_mfma_f32_16x16x32_bf16 v[8:11], v[180:183], v[204:207], v[8:11]
	v_mfma_f32_16x16x32_bf16 v[4:7], v[172:175], v[212:215], v[4:7]
	v_mfma_f32_16x16x32_bf16 v[0:3], v[180:183], v[212:215], v[0:3]
	s_barrier
;     __device__ __forceinline__ void operator()(const f32x4 (&acc)[2][2][4][2], const Unit& u, int wr, int wc, int fr, int fq) const {
;         const int row0 = u.pm * BM + wr * 64 + fr, col0 = u.pn * BM + wc * 32 + 8 * fq;
;         const float* gp = gate + (u.pm >> 5) * 18432 + col0;
;         f32x4 gv[2][2];
; #pragma unroll
;         for (int bj = 0; bj < 2; ++bj)
; #pragma unroll
;             for (int n = 0; n < 2; ++n) gv[bj][n] = *(const f32x4*)(gp + bj * HALF + 4 * n) * scale;
; #pragma unroll
;         for (int ai = 0; ai < 2; ++ai) { f32x4 r[4][2][2];
; #pragma unroll
;             for (int m = 0; m < 4; ++m) { const size_t off = (size_t)(row0 + ai * HALF + m * 16) * 2048 + col0;
; #pragma unroll
;                 for (int bj = 0; bj < 2; ++bj)
; #pragma unroll
;                     for (int n = 0; n < 2; ++n) r[m][bj][n] = *(const f32x4*)(res + off + bj * HALF + 4 * n); }
; #pragma unroll
;             for (int m = 0; m < 4; ++m) { const size_t off = (size_t)(row0 + ai * HALF + m * 16) * 2048 + col0;
; #pragma unroll
;                 for (int bj = 0; bj < 2; ++bj)
; #pragma unroll
;                     for (int n = 0; n < 2; ++n) *(f32x4*)(out + off + bj * HALF + 4 * n) = r[m][bj][n] + gv[bj][n] * acc[ai][bj][m][n]; } }
	s_add_i32 s56, s56, 2
	s_add_u32 s54, s54, 0x100
	s_addc_u32 s55, s55, 0
	s_cmpk_gt_u32 s56, 0x55
	s_mov_b64 s[24:25], s[26:27]
	s_cbranch_scc0 .LBB0_1021
	s_lshr_b32 s24, s52, 5
	s_mulk_i32 s24, 0x4800
	s_ashr_i32 s25, s24, 31
	v_lshl_or_b32 v144, s53, 8, v168
	s_lshl_b64 s[24:25], s[24:25], 2
	s_add_u32 s24, s43, s24
	v_ashrrev_i32_e32 v145, 31, v144
	s_addc_u32 s25, s44, s25
	v_lshlrev_b64 v[144:145], 2, v[144:145]
	v_lshl_add_u64 v[154:155], s[24:25], 0, v[144:145]
	global_load_dwordx4 v[146:149], v[154:155], off offset:16
	global_load_dwordx4 v[150:153], v[154:155], off
	global_load_dwordx4 v[172:175], v[154:155], off offset:528
	global_load_dwordx4 v[176:179], v[154:155], off offset:512
	v_lshl_add_u32 v154, s52, 8, v166
	v_ashrrev_i32_e32 v155, 31, v154
	v_lshl_add_u64 v[162:163], s[8:9], 0, v[144:145]
	v_lshlrev_b64 v[164:165], 13, v[154:155]
	v_lshl_add_u64 v[156:157], v[162:163], 0, v[164:165]
	global_load_dwordx4 v[180:183], v[156:157], off
	global_load_dwordx4 v[184:187], v[156:157], off offset:16
	global_load_dwordx4 v[188:191], v[156:157], off offset:528
	global_load_dwordx4 v[192:195], v[156:157], off offset:512
	v_or_b32_e32 v156, 16, v154
	v_ashrrev_i32_e32 v157, 31, v156
	v_lshlrev_b64 v[156:157], 13, v[156:157]
	v_lshl_add_u64 v[158:159], v[162:163], 0, v[156:157]
	global_load_dwordx4 v[196:199], v[158:159], off
	global_load_dwordx4 v[200:203], v[158:159], off offset:16
	global_load_dwordx4 v[204:207], v[158:159], off offset:528
	global_load_dwordx4 v[208:211], v[158:159], off offset:512
	v_or_b32_e32 v158, 32, v154
	v_ashrrev_i32_e32 v159, 31, v158
	v_lshlrev_b64 v[158:159], 13, v[158:159]
	v_or_b32_e32 v154, 48, v154
	v_lshl_add_u64 v[160:161], v[162:163], 0, v[158:159]
	v_ashrrev_i32_e32 v155, 31, v154
	global_load_dwordx4 v[212:215], v[160:161], off
	global_load_dwordx4 v[216:219], v[160:161], off offset:16
	global_load_dwordx4 v[220:223], v[160:161], off offset:512
	global_load_dwordx4 v[224:227], v[160:161], off offset:528
	v_lshlrev_b64 v[244:245], 13, v[154:155]
	v_lshl_add_u64 v[154:155], v[162:163], 0, v[244:245]
	global_load_dwordx4 v[228:231], v[154:155], off
	global_load_dwordx4 v[232:235], v[154:155], off offset:16
	global_load_dwordx4 v[236:239], v[154:155], off offset:512
	global_load_dwordx4 v[240:243], v[154:155], off offset:528
	v_lshl_add_u64 v[154:155], s[10:11], 0, v[164:165]
	v_lshl_add_u64 v[246:247], v[154:155], 0, v[144:145]
	v_lshl_add_u64 v[154:155], s[10:11], 0, v[156:157]
	v_lshl_add_u64 v[156:157], s[10:11], 0, v[158:159]
	v_lshl_add_u64 v[248:249], v[154:155], 0, v[144:145]
	v_lshl_add_u64 v[250:251], v[156:157], 0, v[144:145]
	s_and_b64 vcc, exec, s[0:1]
	s_mov_b32 s53, s50
	s_mov_b32 s52, s51
	s_mov_b64 s[26:27], s[6:7]
	s_mov_b64 s[24:25], s[4:5]
	s_waitcnt vmcnt(0)
	v_pk_mul_f32 v[154:155], v[148:149], 0.5 op_sel_hi:[1,0]
	v_pk_mul_f32 v[158:159], v[152:153], 0.5 op_sel_hi:[1,0]
	v_pk_mul_f32 v[160:161], v[150:151], 0.5 op_sel_hi:[1,0]
	v_pk_mul_f32 v[150:151], v[178:179], 0.5 op_sel_hi:[1,0]
	v_pk_mul_f32 v[152:153], v[176:177], 0.5 op_sel_hi:[1,0]
	v_pk_mul_f32 v[156:157], v[146:147], 0.5 op_sel_hi:[1,0]
	v_pk_mul_f32 v[146:147], v[174:175], 0.5 op_sel_hi:[1,0]
	v_pk_mul_f32 v[148:149], v[172:173], 0.5 op_sel_hi:[1,0]
	v_pk_fma_f32 v[126:127], v[126:127], v[158:159], v[182:183]
	v_pk_fma_f32 v[124:125], v[124:125], v[160:161], v[180:181]
	v_pk_fma_f32 v[122:123], v[122:123], v[154:155], v[186:187]
	v_pk_fma_f32 v[120:121], v[120:121], v[156:157], v[184:185]
	v_pk_fma_f32 v[106:107], v[106:107], v[150:151], v[194:195]
	v_pk_fma_f32 v[104:105], v[104:105], v[152:153], v[192:193]
	v_pk_fma_f32 v[102:103], v[102:103], v[146:147], v[190:191]
	v_pk_fma_f32 v[100:101], v[100:101], v[148:149], v[188:189]
	v_pk_fma_f32 v[118:119], v[118:119], v[158:159], v[198:199]
	v_pk_fma_f32 v[116:117], v[116:117], v[160:161], v[196:197]
	v_pk_fma_f32 v[114:115], v[114:115], v[154:155], v[202:203]
	v_pk_fma_f32 v[112:113], v[112:113], v[156:157], v[200:201]
	v_pk_fma_f32 v[82:83], v[82:83], v[150:151], v[222:223]
	v_pk_fma_f32 v[80:81], v[80:81], v[152:153], v[220:221]
	v_pk_fma_f32 v[94:95], v[94:95], v[150:151], v[210:211]
	v_pk_fma_f32 v[92:93], v[92:93], v[152:153], v[208:209]
	v_pk_fma_f32 v[90:91], v[90:91], v[146:147], v[206:207]
	v_pk_fma_f32 v[88:89], v[88:89], v[148:149], v[204:205]
	v_pk_fma_f32 v[110:111], v[110:111], v[158:159], v[214:215]
	v_pk_fma_f32 v[108:109], v[108:109], v[160:161], v[212:213]
	v_pk_fma_f32 v[98:99], v[98:99], v[154:155], v[218:219]
	v_pk_fma_f32 v[96:97], v[96:97], v[156:157], v[216:217]
	global_store_dwordx4 v[246:247], v[124:127], off
	global_store_dwordx4 v[246:247], v[120:123], off offset:16
	global_store_dwordx4 v[246:247], v[104:107], off offset:512
	global_store_dwordx4 v[246:247], v[100:103], off offset:528
	global_store_dwordx4 v[248:249], v[116:119], off
	global_store_dwordx4 v[248:249], v[112:115], off offset:16
	global_store_dwordx4 v[248:249], v[92:95], off offset:512
	global_store_dwordx4 v[248:249], v[88:91], off offset:528
	global_store_dwordx4 v[250:251], v[108:111], off
	global_store_dwordx4 v[250:251], v[96:99], off offset:16
	global_store_dwordx4 v[250:251], v[80:83], off offset:512
	v_pk_fma_f32 v[74:75], v[74:75], v[146:147], v[226:227]
	v_pk_fma_f32 v[72:73], v[72:73], v[148:149], v[224:225]
	v_lshl_add_u64 v[80:81], s[10:11], 0, v[244:245]
	global_store_dwordx4 v[250:251], v[72:75], off offset:528
; #define PG8_WAIT_V(n) asm volatile("s_waitcnt vmcnt(" #n ")" ::: "memory")
; #define PG8_BAR __builtin_amdgcn_s_barrier()
;     __device__ __forceinline__ void operator()(const f32x4 (&acc)[2][2][4][2], const Unit& u, int wr, int wc, int fr, int fq) const {
;     ...
;         for (int ai = 0; ai < 2; ++ai) { f32x4 r[4][2][2];
; #pragma unroll
;             for (int m = 0; m < 4; ++m) { const size_t off = (size_t)(row0 + ai * HALF + m * 16) * 2048 + col0;
; #pragma unroll
;                 for (int bj = 0; bj < 2; ++bj)
; #pragma unroll
;                     for (int n = 0; n < 2; ++n) r[m][bj][n] = *(const f32x4*)(res + off + bj * HALF + 4 * n); }
; #pragma unroll
;             for (int m = 0; m < 4; ++m) { const size_t off = (size_t)(row0 + ai * HALF + m * 16) * 2048 + col0;
; #pragma unroll
;                 for (int bj = 0; bj < 2; ++bj)
; #pragma unroll
;                     for (int n = 0; n < 2; ++n) *(f32x4*)(out + off + bj * HALF + 4 * n) = r[m][bj][n] + gv[bj][n] * acc[ai][bj][m][n]; } }
; template <class Epi, class Sched, bool ALIGN_EPI = false, bool SP2 = false>
; __device__ __forceinline__ void gemm_phase(PG8_LAS unsigned char* lds, const Gemm g, const Sched& S, const Epi& E) {
;     ...
;         if (!has_next) break;
; #pragma unroll
;         for (int a = 0; a < 2; ++a)
; #pragma unroll
;             for (int b = 0; b < 2; ++b)
; #pragma unroll
;                 for (int m = 0; m < 4; ++m)
; #pragma unroll
;                     for (int n = 0; n < 2; ++n) acc[a][b][m][n] = (f32x4){0.f, 0.f, 0.f, 0.f};
;         cur = nxt; cA = nA; cB = nB; ++ui;
;         if constexpr (ALIGN_EPI) { if (wr == 1) PG8_BAR; }
;     }
;     PG8_WAIT_V(0);
;     if constexpr (!ALIGN_EPI) { if (wr == 0) PG8_BAR; }
;     PG8_BAR;
	v_lshl_add_u64 v[80:81], v[80:81], 0, v[144:145]
	v_pk_fma_f32 v[70:71], v[70:71], v[150:151], v[238:239]
	v_pk_fma_f32 v[74:75], v[86:87], v[158:159], v[230:231]
	v_pk_fma_f32 v[72:73], v[84:85], v[160:161], v[228:229]
	global_store_dwordx4 v[80:81], v[72:75], off
	v_pk_fma_f32 v[68:69], v[68:69], v[152:153], v[236:237]
	v_pk_fma_f32 v[66:67], v[66:67], v[146:147], v[242:243]
	v_pk_fma_f32 v[74:75], v[78:79], v[154:155], v[234:235]
	v_pk_fma_f32 v[72:73], v[76:77], v[156:157], v[232:233]
	v_pk_fma_f32 v[64:65], v[64:65], v[148:149], v[240:241]
	v_lshl_add_u64 v[172:173], v[164:165], 0, s[18:19]
	v_lshl_add_u64 v[174:175], v[164:165], 0, s[20:21]
	v_lshl_add_u64 v[176:177], v[164:165], 0, s[22:23]
	global_store_dwordx4 v[80:81], v[72:75], off offset:16
	global_store_dwordx4 v[80:81], v[68:71], off offset:512
	global_store_dwordx4 v[80:81], v[64:67], off offset:528
	v_lshl_add_u64 v[80:81], v[162:163], 0, v[172:173]
	v_lshl_add_u64 v[92:93], v[162:163], 0, v[174:175]
	v_lshl_add_u64 v[108:109], v[162:163], 0, v[176:177]
	global_load_dwordx4 v[64:67], v[80:81], off
	global_load_dwordx4 v[68:71], v[80:81], off offset:16
	global_load_dwordx4 v[72:75], v[80:81], off offset:512
	global_load_dwordx4 v[76:79], v[80:81], off offset:528
	s_nop 0
	global_load_dwordx4 v[80:83], v[92:93], off
	global_load_dwordx4 v[84:87], v[92:93], off offset:16
	global_load_dwordx4 v[88:91], v[92:93], off offset:512
	s_nop 0
	global_load_dwordx4 v[92:95], v[92:93], off offset:528
	s_nop 0
	global_load_dwordx4 v[96:99], v[108:109], off
	global_load_dwordx4 v[100:103], v[108:109], off offset:16
	global_load_dwordx4 v[104:107], v[108:109], off offset:512
	s_nop 0
	global_load_dwordx4 v[108:111], v[108:109], off offset:528
	v_lshl_add_u64 v[164:165], v[164:165], 0, s[12:13]
	v_lshl_add_u64 v[124:125], v[162:163], 0, v[164:165]
	global_load_dwordx4 v[112:115], v[124:125], off
	global_load_dwordx4 v[116:119], v[124:125], off offset:16
	global_load_dwordx4 v[120:123], v[124:125], off offset:512
	s_nop 0
	global_load_dwordx4 v[124:127], v[124:125], off offset:528
	v_lshl_add_u64 v[162:163], s[10:11], 0, v[172:173]
	v_lshl_add_u64 v[172:173], s[10:11], 0, v[174:175]
	v_lshl_add_u64 v[174:175], s[10:11], 0, v[176:177]
	v_lshl_add_u64 v[162:163], v[162:163], 0, v[144:145]
	v_lshl_add_u64 v[174:175], v[174:175], 0, v[144:145]
	v_lshl_add_u64 v[172:173], v[172:173], 0, v[144:145]
	s_waitcnt vmcnt(15)
	v_pk_fma_f32 v[62:63], v[62:63], v[158:159], v[66:67]
	v_pk_fma_f32 v[60:61], v[60:61], v[160:161], v[64:65]
	s_waitcnt vmcnt(14)
	v_pk_fma_f32 v[58:59], v[58:59], v[154:155], v[70:71]
	v_pk_fma_f32 v[56:57], v[56:57], v[156:157], v[68:69]
	s_waitcnt vmcnt(5)
	v_pk_fma_f32 v[18:19], v[18:19], v[150:151], v[106:107]
	v_pk_fma_f32 v[16:17], v[16:17], v[152:153], v[104:105]
	v_pk_fma_f32 v[42:43], v[42:43], v[150:151], v[74:75]
	v_pk_fma_f32 v[40:41], v[40:41], v[152:153], v[72:73]
	v_pk_fma_f32 v[38:39], v[38:39], v[146:147], v[78:79]
	v_pk_fma_f32 v[36:37], v[36:37], v[148:149], v[76:77]
	v_pk_fma_f32 v[54:55], v[54:55], v[158:159], v[82:83]
	v_pk_fma_f32 v[52:53], v[52:53], v[160:161], v[80:81]
	v_pk_fma_f32 v[50:51], v[50:51], v[154:155], v[86:87]
	v_pk_fma_f32 v[48:49], v[48:49], v[156:157], v[84:85]
	v_pk_fma_f32 v[30:31], v[30:31], v[150:151], v[90:91]
	v_pk_fma_f32 v[28:29], v[28:29], v[152:153], v[88:89]
	v_pk_fma_f32 v[26:27], v[26:27], v[146:147], v[94:95]
	v_pk_fma_f32 v[24:25], v[24:25], v[148:149], v[92:93]
	v_pk_fma_f32 v[46:47], v[46:47], v[158:159], v[98:99]
	v_pk_fma_f32 v[44:45], v[44:45], v[160:161], v[96:97]
	v_pk_fma_f32 v[34:35], v[34:35], v[154:155], v[102:103]
	v_pk_fma_f32 v[32:33], v[32:33], v[156:157], v[100:101]
	global_store_dwordx4 v[162:163], v[60:63], off
	global_store_dwordx4 v[162:163], v[56:59], off offset:16
	global_store_dwordx4 v[162:163], v[40:43], off offset:512
	global_store_dwordx4 v[162:163], v[36:39], off offset:528
	global_store_dwordx4 v[172:173], v[52:55], off
	global_store_dwordx4 v[172:173], v[48:51], off offset:16
	global_store_dwordx4 v[172:173], v[28:31], off offset:512
	global_store_dwordx4 v[172:173], v[24:27], off offset:528
	global_store_dwordx4 v[174:175], v[44:47], off
	global_store_dwordx4 v[174:175], v[32:35], off offset:16
	global_store_dwordx4 v[174:175], v[16:19], off offset:512
	s_waitcnt vmcnt(15)
	v_pk_fma_f32 v[10:11], v[10:11], v[146:147], v[110:111]
	v_pk_fma_f32 v[8:9], v[8:9], v[148:149], v[108:109]
	v_lshl_add_u64 v[16:17], s[10:11], 0, v[164:165]
	global_store_dwordx4 v[174:175], v[8:11], off offset:528
	v_lshl_add_u64 v[16:17], v[16:17], 0, v[144:145]
	s_waitcnt vmcnt(13)
	v_pk_fma_f32 v[6:7], v[6:7], v[150:151], v[122:123]
	v_pk_fma_f32 v[10:11], v[22:23], v[158:159], v[114:115]
	v_pk_fma_f32 v[8:9], v[20:21], v[160:161], v[112:113]
	global_store_dwordx4 v[16:17], v[8:11], off
	v_pk_fma_f32 v[4:5], v[4:5], v[152:153], v[120:121]
	s_waitcnt vmcnt(13)
	v_pk_fma_f32 v[2:3], v[2:3], v[146:147], v[126:127]
	v_pk_fma_f32 v[10:11], v[14:15], v[154:155], v[118:119]
	v_pk_fma_f32 v[8:9], v[12:13], v[156:157], v[116:117]
	v_pk_fma_f32 v[0:1], v[0:1], v[148:149], v[124:125]
	global_store_dwordx4 v[16:17], v[8:11], off offset:16
	global_store_dwordx4 v[16:17], v[4:7], off offset:512
	global_store_dwordx4 v[16:17], v[0:3], off offset:528
	s_cbranch_vccz .LBB0_1010
	s_waitcnt vmcnt(0)
	s_cmpk_gt_u32 s3, 0xff
	s_cbranch_scc1 .LBB0_1025
	s_barrier
